# all 16-byte global stores made write-through (sc1) to shrink the L2 flush at each grid barrier
# baseline (speedup 1.0000x reference)
.LBB0_11:
	s_or_b64 exec, exec, s[14:15]
	v_mul_i32_i24_e32 v16, 0x700, v3
	v_ashrrev_i32_e32 v17, 31, v16
	v_lshlrev_b64 v[16:17], 10, v[16:17]
	v_ashrrev_i32_e32 v11, 31, v10
	v_lshl_add_u64 v[16:17], s[10:11], 0, v[16:17]
	v_lshlrev_b64 v[10:11], 10, v[10:11]
	v_add_u32_e32 v2, s16, v2
	v_lshl_add_u64 v[10:11], v[16:17], 0, v[10:11]
	v_cmp_lt_i32_e32 vcc, s20, v2
	v_lshl_add_u64 v[10:11], v[6:7], 1, v[10:11]
	s_or_b64 s[12:13], vcc, s[12:13]
	v_add_u32_e32 v1, s17, v1
	global_store_dwordx4 v[10:11], v[12:15], off sc1
	s_andn2_b64 exec, exec, s[12:13]
	s_cbranch_execz .LBB0_16

.LBB0_106:
	v_mul_hi_i32 v3, v7, s38
	v_lshrrev_b32_e32 v4, 31, v3
	v_ashrrev_i32_e32 v3, 10, v3
	v_add_u32_e32 v12, v3, v4
	v_mul_i32_i24_e32 v3, 0x5b10, v12
	v_sub_u32_e32 v3, v7, v3
	v_cmp_lt_i32_e32 vcc, s39, v3
	s_and_saveexec_b64 s[24:25], vcc
	s_xor_b64 s[24:25], exec, s[24:25]
	s_cbranch_execz .LBB0_140
	v_cmp_lt_u32_e32 vcc, s40, v3
	s_and_saveexec_b64 s[26:27], vcc
	s_xor_b64 s[26:27], exec, s[26:27]
	s_cbranch_execz .LBB0_135
	v_cmp_lt_u32_e32 vcc, s41, v3
	s_and_saveexec_b64 s[28:29], vcc
	s_xor_b64 s[28:29], exec, s[28:29]
	s_cbranch_execz .LBB0_130
	v_cmp_lt_u32_e32 vcc, s42, v3
	s_and_saveexec_b64 s[30:31], vcc
	s_xor_b64 s[30:31], exec, s[30:31]
	s_cbranch_execz .LBB0_125
	v_cmp_lt_u32_e32 vcc, s43, v3
	s_and_saveexec_b64 s[34:35], vcc
	s_xor_b64 s[34:35], exec, s[34:35]
	s_cbranch_execz .LBB0_120
	v_cmp_lt_u32_e32 vcc, s44, v3
	s_and_saveexec_b64 s[36:37], vcc
	s_xor_b64 s[36:37], exec, s[36:37]
	s_cbranch_execz .LBB0_115
	s_load_dwordx2 s[58:59], s[6:7], 0x60
	v_add_u32_e32 v3, 0xffffa530, v3
	v_ashrrev_i32_e32 v13, 31, v12
	v_lshlrev_b32_e32 v4, 5, v3
	v_lshlrev_b64 v[14:15], 19, v[12:13]
	v_and_b32_e32 v11, 0x3e0, v4
	s_waitcnt lgkmcnt(0)
	v_lshl_add_u64 v[16:17], s[58:59], 0, v[14:15]
	v_lshlrev_b32_e32 v3, 1, v3
	v_lshlrev_b32_e32 v4, 2, v11
	v_and_b32_e32 v14, 0x7fffffc0, v3
	v_lshl_add_u64 v[16:17], v[16:17], 0, v[4:5]
	v_mov_b32_e32 v9, v5
	s_mov_b32 s58, 1
	v_lshl_add_u64 v[16:17], v[16:17], 0, v[8:9]
	v_mov_b32_e32 v3, v14
	s_mov_b32 s59, 0
	s_mov_b32 s60, 32
	v_mov_b32_e32 v105, v5
	s_lshl_b32 s61, s58, 1
	s_lshl_b32 s62, s59, 1
	v_or_b32_e32 v113, s62, v2
	s_add_i32 s63, s61, 4
	s_add_i32 s64, s62, 4
	s_add_i32 s66, s62, 8
	v_add_u32_e32 v104, v113, v14
	v_or_b32_e32 v115, s63, v1
	v_or_b32_e32 v129, s64, v2
	v_mov_b32_e32 v131, v5
	v_or_b32_e32 v109, s61, v1
	s_add_i32 s68, s62, 12
	v_or_b32_e32 v151, s66, v2
	v_lshlrev_b64 v[144:145], 12, v[104:105]
	v_add_u32_e32 v130, v115, v3
	v_add_u32_e32 v104, v129, v14
	v_mov_b32_e32 v119, v5
	s_add_i32 s65, s61, 8
	s_add_i32 s67, s61, 12
	s_add_i32 s70, s62, 16
	v_add_u32_e32 v118, v109, v3
	v_or_b32_e32 v153, s68, v2
	v_lshlrev_b64 v[130:131], 12, v[130:131]
	v_lshlrev_b64 v[146:147], 12, v[104:105]
	v_add_u32_e32 v104, v151, v14
	s_add_i32 s72, s62, 20
	v_or_b32_e32 v150, s65, v1
	v_or_b32_e32 v152, s67, v1
	v_or_b32_e32 v155, s70, v2
	v_lshlrev_b64 v[118:119], 12, v[118:119]
	v_lshl_add_u64 v[144:145], v[16:17], 0, v[144:145]
	v_lshl_add_u64 v[130:131], v[16:17], 0, v[130:131]
	v_lshlrev_b64 v[148:149], 12, v[104:105]
	v_add_u32_e32 v104, v153, v14
	v_mov_b32_e32 v133, v5
	v_mov_b32_e32 v135, v5
	s_add_i32 s69, s61, 16
	s_add_i32 s71, s61, 20
	s_add_i32 s74, s62, 24
	v_or_b32_e32 v157, s72, v2
	v_add_u32_e32 v132, v150, v3
	v_add_u32_e32 v134, v152, v3
	v_lshl_add_u64 v[118:119], v[16:17], 0, v[118:119]
	v_lshl_add_u64 v[146:147], v[16:17], 0, v[146:147]
	global_load_dword v162, v[144:145], off
	global_load_dword v163, v[118:119], off
	global_load_dword v164, v[146:147], off
	global_load_dword v165, v[130:131], off
	v_lshlrev_b64 v[130:131], 12, v[104:105]
	v_add_u32_e32 v104, v155, v14
	s_add_i32 s73, s61, 24
	s_add_i32 s61, s61, 28
	s_add_i32 s62, s62, 28
	v_or_b32_e32 v154, s69, v1
	v_or_b32_e32 v156, s71, v1
	v_or_b32_e32 v159, s74, v2
	v_lshlrev_b64 v[132:133], 12, v[132:133]
	v_lshlrev_b64 v[134:135], 12, v[134:135]
	v_lshl_add_u64 v[118:119], v[16:17], 0, v[148:149]
	v_lshl_add_u64 v[130:131], v[16:17], 0, v[130:131]
	v_lshlrev_b64 v[144:145], 12, v[104:105]
	v_add_u32_e32 v104, v157, v14
	v_mov_b32_e32 v137, v5
	v_mov_b32_e32 v139, v5
	v_or_b32_e32 v158, s73, v1
	v_or_b32_e32 v160, s61, v1
	v_or_b32_e32 v161, s62, v2
	v_add_u32_e32 v136, v154, v3
	v_add_u32_e32 v138, v156, v3
	v_lshl_add_u64 v[132:133], v[16:17], 0, v[132:133]
	v_lshl_add_u64 v[134:135], v[16:17], 0, v[134:135]
	global_load_dword v166, v[118:119], off
	global_load_dword v167, v[132:133], off
	global_load_dword v168, v[130:131], off
	global_load_dword v169, v[134:135], off
	v_lshlrev_b64 v[130:131], 12, v[104:105]
	v_add_u32_e32 v104, v159, v14
	v_mov_b32_e32 v141, v5
	v_mov_b32_e32 v143, v5
	v_add_u32_e32 v140, v158, v3
	v_add_u32_e32 v142, v160, v3
	v_lshlrev_b64 v[136:137], 12, v[136:137]
	v_lshlrev_b64 v[138:139], 12, v[138:139]
	v_lshl_add_u64 v[118:119], v[16:17], 0, v[144:145]
	v_lshl_add_u64 v[130:131], v[16:17], 0, v[130:131]
	v_lshlrev_b64 v[132:133], 12, v[104:105]
	v_add_u32_e32 v104, v161, v14
	v_lshlrev_b64 v[140:141], 12, v[140:141]
	v_lshlrev_b64 v[142:143], 12, v[142:143]
	v_lshl_add_u64 v[136:137], v[16:17], 0, v[136:137]
	v_lshl_add_u64 v[138:139], v[16:17], 0, v[138:139]
	global_load_dword v170, v[118:119], off
	global_load_dword v171, v[136:137], off
	global_load_dword v172, v[130:131], off
	global_load_dword v173, v[138:139], off
	v_lshl_add_u64 v[118:119], v[16:17], 0, v[132:133]
	v_lshlrev_b64 v[130:131], 12, v[104:105]
	v_lshl_add_u64 v[140:141], v[16:17], 0, v[140:141]
	v_lshl_add_u64 v[142:143], v[16:17], 0, v[142:143]
	v_lshl_add_u64 v[130:131], v[16:17], 0, v[130:131]
	global_load_dword v104, v[118:119], off
	global_load_dword v174, v[140:141], off
	global_load_dword v175, v[130:131], off
	global_load_dword v176, v[142:143], off
	s_add_i32 s59, s59, 16
	s_add_i32 s58, s58, 16
	s_add_i32 s60, s60, -16
	v_mad_u64_u32 v[118:119], s[62:63], v113, s33, v[6:7]
	v_mad_u64_u32 v[130:131], s[62:63], v109, s33, v[6:7]
	v_mad_u64_u32 v[132:133], s[62:63], v129, s33, v[6:7]
	v_mad_u64_u32 v[134:135], s[62:63], v115, s33, v[6:7]
	v_mad_u64_u32 v[136:137], s[62:63], v151, s33, v[6:7]
	v_mad_u64_u32 v[138:139], s[62:63], v150, s33, v[6:7]
	v_mad_u64_u32 v[140:141], s[62:63], v153, s33, v[6:7]
	v_mad_u64_u32 v[142:143], s[62:63], v152, s33, v[6:7]
	v_mad_u64_u32 v[144:145], s[62:63], v155, s33, v[6:7]
	v_mad_u64_u32 v[146:147], s[62:63], v154, s33, v[6:7]
	v_mad_u64_u32 v[148:149], s[62:63], v157, s33, v[6:7]
	v_mad_u64_u32 v[150:151], s[62:63], v156, s33, v[6:7]
	v_mad_u64_u32 v[152:153], s[62:63], v159, s33, v[6:7]
	v_mad_u64_u32 v[154:155], s[62:63], v158, s33, v[6:7]
	v_mad_u64_u32 v[156:157], s[62:63], v161, s33, v[6:7]
	v_mad_u64_u32 v[158:159], s[62:63], v160, s33, v[6:7]
	s_lshl_b32 s61, s58, 1
	s_lshl_b32 s62, s59, 1
	v_or_b32_e32 v13, s62, v2
	s_add_i32 s63, s61, 4
	s_add_i32 s64, s62, 4
	s_add_i32 s66, s62, 8
	v_add_u32_e32 v4, v13, v14
	v_or_b32_e32 v15, s63, v1
	v_or_b32_e32 v29, s64, v2
	v_mov_b32_e32 v31, v5
	v_or_b32_e32 v9, s61, v1
	s_add_i32 s68, s62, 12
	v_or_b32_e32 v51, s66, v2
	v_lshlrev_b64 v[44:45], 12, v[4:5]
	v_add_u32_e32 v30, v15, v3
	v_add_u32_e32 v4, v29, v14
	v_mov_b32_e32 v19, v5
	s_add_i32 s65, s61, 8
	s_add_i32 s67, s61, 12
	s_add_i32 s70, s62, 16
	v_add_u32_e32 v18, v9, v3
	v_or_b32_e32 v53, s68, v2
	v_lshlrev_b64 v[30:31], 12, v[30:31]
	v_lshlrev_b64 v[46:47], 12, v[4:5]
	v_add_u32_e32 v4, v51, v14
	s_add_i32 s72, s62, 20
	v_or_b32_e32 v50, s65, v1
	v_or_b32_e32 v52, s67, v1
	v_or_b32_e32 v55, s70, v2
	v_lshlrev_b64 v[18:19], 12, v[18:19]
	v_lshl_add_u64 v[44:45], v[16:17], 0, v[44:45]
	v_lshl_add_u64 v[30:31], v[16:17], 0, v[30:31]
	v_lshlrev_b64 v[48:49], 12, v[4:5]
	v_add_u32_e32 v4, v53, v14
	v_mov_b32_e32 v33, v5
	v_mov_b32_e32 v35, v5
	s_add_i32 s69, s61, 16
	s_add_i32 s71, s61, 20
	s_add_i32 s74, s62, 24
	v_or_b32_e32 v57, s72, v2
	v_add_u32_e32 v32, v50, v3
	v_add_u32_e32 v34, v52, v3
	v_lshl_add_u64 v[18:19], v[16:17], 0, v[18:19]
	v_lshl_add_u64 v[46:47], v[16:17], 0, v[46:47]
	global_load_dword v62, v[44:45], off
	global_load_dword v63, v[18:19], off
	global_load_dword v64, v[46:47], off
	global_load_dword v65, v[30:31], off
	v_lshlrev_b64 v[30:31], 12, v[4:5]
	v_add_u32_e32 v4, v55, v14
	s_add_i32 s73, s61, 24
	s_add_i32 s61, s61, 28
	s_add_i32 s62, s62, 28
	v_or_b32_e32 v54, s69, v1
	v_or_b32_e32 v56, s71, v1
	v_or_b32_e32 v59, s74, v2
	v_lshlrev_b64 v[32:33], 12, v[32:33]
	v_lshlrev_b64 v[34:35], 12, v[34:35]
	v_lshl_add_u64 v[18:19], v[16:17], 0, v[48:49]
	v_lshl_add_u64 v[30:31], v[16:17], 0, v[30:31]
	v_lshlrev_b64 v[44:45], 12, v[4:5]
	v_add_u32_e32 v4, v57, v14
	v_mov_b32_e32 v37, v5
	v_mov_b32_e32 v39, v5
	v_or_b32_e32 v58, s73, v1
	v_or_b32_e32 v60, s61, v1
	v_or_b32_e32 v61, s62, v2
	v_add_u32_e32 v36, v54, v3
	v_add_u32_e32 v38, v56, v3
	v_lshl_add_u64 v[32:33], v[16:17], 0, v[32:33]
	v_lshl_add_u64 v[34:35], v[16:17], 0, v[34:35]
	global_load_dword v66, v[18:19], off
	global_load_dword v67, v[32:33], off
	global_load_dword v68, v[30:31], off
	global_load_dword v69, v[34:35], off
	v_lshlrev_b64 v[30:31], 12, v[4:5]
	v_add_u32_e32 v4, v59, v14
	v_mov_b32_e32 v41, v5
	v_mov_b32_e32 v43, v5
	v_add_u32_e32 v40, v58, v3
	v_add_u32_e32 v42, v60, v3
	v_lshlrev_b64 v[36:37], 12, v[36:37]
	v_lshlrev_b64 v[38:39], 12, v[38:39]
	v_lshl_add_u64 v[18:19], v[16:17], 0, v[44:45]
	v_lshl_add_u64 v[30:31], v[16:17], 0, v[30:31]
	v_lshlrev_b64 v[32:33], 12, v[4:5]
	v_add_u32_e32 v4, v61, v14
	v_lshlrev_b64 v[40:41], 12, v[40:41]
	v_lshlrev_b64 v[42:43], 12, v[42:43]
	v_lshl_add_u64 v[36:37], v[16:17], 0, v[36:37]
	v_lshl_add_u64 v[38:39], v[16:17], 0, v[38:39]
	global_load_dword v70, v[18:19], off
	global_load_dword v71, v[36:37], off
	global_load_dword v72, v[30:31], off
	global_load_dword v73, v[38:39], off
	v_lshl_add_u64 v[18:19], v[16:17], 0, v[32:33]
	v_lshlrev_b64 v[30:31], 12, v[4:5]
	v_lshl_add_u64 v[40:41], v[16:17], 0, v[40:41]
	v_lshl_add_u64 v[42:43], v[16:17], 0, v[42:43]
	v_lshl_add_u64 v[30:31], v[16:17], 0, v[30:31]
	global_load_dword v4, v[18:19], off
	global_load_dword v74, v[40:41], off
	global_load_dword v75, v[30:31], off
	global_load_dword v76, v[42:43], off
	s_add_i32 s59, s59, 16
	s_add_i32 s58, s58, 16
	s_add_i32 s60, s60, -16
	v_mad_u64_u32 v[18:19], s[62:63], v13, s33, v[6:7]
	v_mad_u64_u32 v[30:31], s[62:63], v9, s33, v[6:7]
	v_mad_u64_u32 v[32:33], s[62:63], v29, s33, v[6:7]
	v_mad_u64_u32 v[34:35], s[62:63], v15, s33, v[6:7]
	v_mad_u64_u32 v[36:37], s[62:63], v51, s33, v[6:7]
	v_mad_u64_u32 v[38:39], s[62:63], v50, s33, v[6:7]
	v_mad_u64_u32 v[40:41], s[62:63], v53, s33, v[6:7]
	v_mad_u64_u32 v[42:43], s[62:63], v52, s33, v[6:7]
	v_mad_u64_u32 v[44:45], s[62:63], v55, s33, v[6:7]
	v_mad_u64_u32 v[46:47], s[62:63], v54, s33, v[6:7]
	v_mad_u64_u32 v[48:49], s[62:63], v57, s33, v[6:7]
	v_mad_u64_u32 v[50:51], s[62:63], v56, s33, v[6:7]
	v_mad_u64_u32 v[52:53], s[62:63], v59, s33, v[6:7]
	v_mad_u64_u32 v[54:55], s[62:63], v58, s33, v[6:7]
	v_mad_u64_u32 v[56:57], s[62:63], v61, s33, v[6:7]
	v_mad_u64_u32 v[58:59], s[62:63], v60, s33, v[6:7]
	s_waitcnt vmcnt(31)
	ds_write_b32 v118, v162
	s_waitcnt vmcnt(30)
	ds_write_b32 v130, v163
	s_waitcnt vmcnt(29)
	ds_write_b32 v132, v164
	s_waitcnt vmcnt(28)
	ds_write_b32 v134, v165
	s_waitcnt vmcnt(27)
	ds_write_b32 v136, v166
	s_waitcnt vmcnt(26)
	ds_write_b32 v138, v167
	s_waitcnt vmcnt(25)
	ds_write_b32 v140, v168
	s_waitcnt vmcnt(24)
	ds_write_b32 v142, v169
	s_waitcnt vmcnt(23)
	ds_write_b32 v144, v170
	s_waitcnt vmcnt(22)
	ds_write_b32 v146, v171
	s_waitcnt vmcnt(21)
	ds_write_b32 v148, v172
	s_waitcnt vmcnt(20)
	ds_write_b32 v150, v173
	s_waitcnt vmcnt(19)
	ds_write_b32 v152, v104
	s_waitcnt vmcnt(18)
	ds_write_b32 v154, v174
	s_waitcnt vmcnt(17)
	ds_write_b32 v156, v175
	s_waitcnt vmcnt(16)
	ds_write_b32 v158, v176
	s_waitcnt vmcnt(15)
	ds_write_b32 v18, v62
	s_waitcnt vmcnt(14)
	ds_write_b32 v30, v63
	s_waitcnt vmcnt(13)
	ds_write_b32 v32, v64
	s_waitcnt vmcnt(12)
	ds_write_b32 v34, v65
	s_waitcnt vmcnt(11)
	ds_write_b32 v36, v66
	s_waitcnt vmcnt(10)
	ds_write_b32 v38, v67
	s_waitcnt vmcnt(9)
	ds_write_b32 v40, v68
	s_waitcnt vmcnt(8)
	ds_write_b32 v42, v69
	s_waitcnt vmcnt(7)
	ds_write_b32 v44, v70
	s_waitcnt vmcnt(6)
	ds_write_b32 v46, v71
	s_waitcnt vmcnt(5)
	ds_write_b32 v48, v72
	s_waitcnt vmcnt(4)
	ds_write_b32 v50, v73
	s_waitcnt vmcnt(3)
	ds_write_b32 v52, v4
	s_waitcnt vmcnt(2)
	ds_write_b32 v54, v74
	s_waitcnt vmcnt(1)
	ds_write_b32 v56, v75
	s_waitcnt vmcnt(0)
	ds_write_b32 v58, v76
	s_waitcnt lgkmcnt(0)
	ds_read2_b32 v[16:17], v22 offset1:8
	ds_read2_b32 v[30:31], v22 offset0:33 offset1:41
	v_mul_hi_i32_i24_e32 v13, 0x1c0000, v12
	v_mul_i32_i24_e32 v12, 0x1c0000, v12
	ds_read2_b32 v[32:33], v22 offset0:66 offset1:74
	v_lshl_add_u64 v[12:13], s[8:9], 0, v[12:13]
	v_lshlrev_b32_e32 v4, 1, v14
	ds_read2_b32 v[34:35], v22 offset0:99 offset1:107
	v_lshl_add_u64 v[12:13], v[12:13], 0, v[4:5]
	s_waitcnt lgkmcnt(3)
	v_bfe_u32 v4, v16, 16, 1
	v_add_u32_e32 v3, 0x300, v11
	v_mov_b32_e32 v11, v5
	v_add3_u32 v4, v16, v4, s45
	s_waitcnt lgkmcnt(2)
	v_bfe_u32 v9, v30, 16, 1
	ds_read2_b32 v[36:37], v22 offset0:132 offset1:140
	v_lshl_add_u64 v[12:13], v[12:13], 0, v[10:11]
	v_lshrrev_b32_e32 v4, 16, v4
	v_add3_u32 v9, v30, v9, s45
	ds_read2_b32 v[38:39], v22 offset0:165 offset1:173
	v_lshl_add_u64 v[18:19], v[12:13], 0, s[22:23]
	v_and_or_b32 v12, v9, s46, v4
	s_waitcnt lgkmcnt(3)
	v_bfe_u32 v4, v32, 16, 1
	v_add3_u32 v4, v32, v4, s45
	s_waitcnt lgkmcnt(2)
	v_bfe_u32 v9, v34, 16, 1
	ds_read2_b32 v[40:41], v22 offset0:198 offset1:206
	v_lshrrev_b32_e32 v4, 16, v4
	v_add3_u32 v9, v34, v9, s45
	ds_read2_b32 v[42:43], v22 offset0:231 offset1:239
	v_and_or_b32 v13, v9, s46, v4
	s_waitcnt lgkmcnt(3)
	v_bfe_u32 v4, v36, 16, 1
	v_add3_u32 v4, v36, v4, s45
	s_waitcnt lgkmcnt(2)
	v_bfe_u32 v9, v38, 16, 1
	v_lshrrev_b32_e32 v4, 16, v4
	v_add3_u32 v9, v38, v9, s45
	v_and_or_b32 v14, v9, s46, v4
	s_waitcnt lgkmcnt(1)
	v_bfe_u32 v4, v40, 16, 1
	v_add3_u32 v4, v40, v4, s45
	s_waitcnt lgkmcnt(0)
	v_bfe_u32 v9, v42, 16, 1
	v_lshrrev_b32_e32 v4, 16, v4
	v_add3_u32 v9, v42, v9, s45
	v_and_or_b32 v15, v9, s46, v4
	v_or_b32_e32 v4, v3, v21
	v_lshlrev_b32_e32 v4, 10, v4
	v_lshl_add_u64 v[44:45], v[18:19], 0, v[4:5]
	v_bfe_u32 v4, v17, 16, 1
	v_add3_u32 v4, v17, v4, s45
	v_bfe_u32 v9, v31, 16, 1
	v_lshrrev_b32_e32 v4, 16, v4
	v_add3_u32 v9, v31, v9, s45
	global_store_dwordx4 v[44:45], v[12:15], off sc1
	ds_read2_b32 v[16:17], v22 offset0:16 offset1:24
	v_readlane_b32 s66, v253, 1
	v_and_or_b32 v12, v9, s46, v4
	v_bfe_u32 v4, v33, 16, 1
	v_add3_u32 v4, v33, v4, s45
	v_bfe_u32 v9, v35, 16, 1
	v_lshrrev_b32_e32 v4, 16, v4
	v_add3_u32 v9, v35, v9, s45
	v_and_or_b32 v13, v9, s46, v4
	v_bfe_u32 v4, v37, 16, 1
	v_add3_u32 v4, v37, v4, s45
	v_bfe_u32 v9, v39, 16, 1
	v_lshrrev_b32_e32 v4, 16, v4
	v_add3_u32 v9, v39, v9, s45
	v_and_or_b32 v14, v9, s46, v4
	v_bfe_u32 v4, v41, 16, 1
	v_add3_u32 v4, v41, v4, s45
	v_bfe_u32 v9, v43, 16, 1
	v_lshrrev_b32_e32 v4, 16, v4
	v_add3_u32 v9, v43, v9, s45
	v_and_or_b32 v15, v9, s46, v4
	v_or_b32_e32 v4, v3, v23
	v_lshlrev_b32_e32 v4, 10, v4
	v_lshl_add_u64 v[30:31], v[18:19], 0, v[4:5]
	global_store_dwordx4 v[30:31], v[12:15], off sc1
	ds_read2_b32 v[30:31], v22 offset0:49 offset1:57
	ds_read2_b32 v[32:33], v22 offset0:82 offset1:90
	ds_read2_b32 v[34:35], v22 offset0:115 offset1:123
	s_waitcnt lgkmcnt(3)
	v_bfe_u32 v4, v16, 16, 1
	v_add3_u32 v4, v16, v4, s45
	s_waitcnt lgkmcnt(2)
	v_bfe_u32 v9, v30, 16, 1
	ds_read2_b32 v[36:37], v22 offset0:148 offset1:156
	v_lshrrev_b32_e32 v4, 16, v4
	v_add3_u32 v9, v30, v9, s45
	ds_read2_b32 v[38:39], v22 offset0:181 offset1:189
	v_and_or_b32 v12, v9, s46, v4
	s_waitcnt lgkmcnt(3)
	v_bfe_u32 v4, v32, 16, 1
	v_add3_u32 v4, v32, v4, s45
	s_waitcnt lgkmcnt(2)
	v_bfe_u32 v9, v34, 16, 1
	ds_read2_b32 v[40:41], v22 offset0:214 offset1:222
	v_lshrrev_b32_e32 v4, 16, v4
	v_add3_u32 v9, v34, v9, s45
	ds_read2_b32 v[42:43], v22 offset0:247 offset1:255
	v_and_or_b32 v13, v9, s46, v4
	s_waitcnt lgkmcnt(3)
	v_bfe_u32 v4, v36, 16, 1
	v_add3_u32 v4, v36, v4, s45
	s_waitcnt lgkmcnt(2)
	v_bfe_u32 v9, v38, 16, 1
	v_lshrrev_b32_e32 v4, 16, v4
	v_add3_u32 v9, v38, v9, s45
	v_and_or_b32 v14, v9, s46, v4
	s_waitcnt lgkmcnt(1)
	v_bfe_u32 v4, v40, 16, 1
	v_add3_u32 v4, v40, v4, s45
	s_waitcnt lgkmcnt(0)
	v_bfe_u32 v9, v42, 16, 1
	v_lshrrev_b32_e32 v4, 16, v4
	v_add3_u32 v9, v42, v9, s45
	v_and_or_b32 v15, v9, s46, v4
	v_or_b32_e32 v4, v3, v24
	v_lshlrev_b32_e32 v4, 10, v4
	v_lshl_add_u64 v[44:45], v[18:19], 0, v[4:5]
	v_bfe_u32 v4, v17, 16, 1
	v_add3_u32 v4, v17, v4, s45
	v_bfe_u32 v9, v31, 16, 1
	v_lshrrev_b32_e32 v4, 16, v4
	v_add3_u32 v9, v31, v9, s45
	global_store_dwordx4 v[44:45], v[12:15], off sc1
	v_or_b32_e32 v3, v3, v25
	s_nop 0
	v_and_or_b32 v12, v9, s46, v4
	v_bfe_u32 v4, v33, 16, 1
	v_add3_u32 v4, v33, v4, s45
	v_bfe_u32 v9, v35, 16, 1
	v_lshrrev_b32_e32 v4, 16, v4
	v_add3_u32 v9, v35, v9, s45
	v_and_or_b32 v13, v9, s46, v4
	v_bfe_u32 v4, v37, 16, 1
	v_add3_u32 v4, v37, v4, s45
	v_bfe_u32 v9, v39, 16, 1
	v_lshrrev_b32_e32 v4, 16, v4
	v_add3_u32 v9, v39, v9, s45
	v_and_or_b32 v14, v9, s46, v4
	v_bfe_u32 v4, v41, 16, 1
	v_add3_u32 v4, v41, v4, s45
	v_bfe_u32 v9, v43, 16, 1
	v_lshrrev_b32_e32 v4, 16, v4
	v_add3_u32 v9, v43, v9, s45
	v_and_or_b32 v15, v9, s46, v4
	v_lshlrev_b32_e32 v4, 10, v3
	v_lshl_add_u64 v[16:17], v[18:19], 0, v[4:5]
	global_store_dwordx4 v[16:17], v[12:15], off sc1
	s_waitcnt lgkmcnt(0)
.LBB0_115:
	s_andn2_saveexec_b64 s[36:37], s[36:37]
	s_cbranch_execz .LBB0_119
	v_subrev_u16_e32 v3, 64, v3
	s_load_dwordx2 s[58:59], s[6:7], 0x58
	v_mul_lo_u16_sdwa v4, v3, s47 dst_sel:DWORD dst_unused:UNUSED_PAD src0_sel:BYTE_0 src1_sel:DWORD
	v_lshrrev_b16_e32 v4, 12, v4
	v_mul_lo_u16_e32 v9, 24, v4
	v_sub_u16_e32 v3, v3, v9
	v_mul_hi_i32_i24_e32 v15, 0x120000, v12
	v_mul_i32_i24_e32 v14, 0x120000, v12
	s_waitcnt lgkmcnt(0)
	v_lshl_add_u64 v[16:17], s[58:59], 0, v[14:15]
	v_lshlrev_b32_e32 v14, 6, v4
	v_lshlrev_b32_sdwa v4, v27, v3 dst_sel:DWORD dst_unused:UNUSED_PAD src0_sel:DWORD src1_sel:BYTE_0
	v_lshl_add_u64 v[16:17], v[16:17], 0, v[4:5]
	v_mov_b32_e32 v9, v5
	v_lshlrev_b32_sdwa v13, v26, v3 dst_sel:DWORD dst_unused:UNUSED_PAD src0_sel:DWORD src1_sel:BYTE_0
	v_lshl_add_u64 v[16:17], v[16:17], 0, v[8:9]
	v_mov_b32_e32 v3, v14
	s_mov_b32 s58, 1
	s_mov_b32 s59, 0
	s_mov_b32 s60, 32
	s_lshl_b32 s61, s58, 1
	s_lshl_b32 s62, s59, 1
	v_or_b32_e32 v104, s61, v1
	v_or_b32_e32 v109, s62, v2
	s_add_i32 s63, s61, 4
	s_add_i32 s64, s62, 4
	s_add_i32 s65, s61, 8
	s_add_i32 s66, s62, 8
	s_add_i32 s67, s61, 12
	s_add_i32 s68, s62, 12
	s_add_i32 s69, s61, 16
	s_add_i32 s70, s62, 16
	s_add_i32 s71, s61, 20
	s_add_i32 s72, s62, 20
	s_add_i32 s73, s61, 24
	s_add_i32 s74, s62, 24
	s_add_i32 s61, s61, 28
	s_add_i32 s62, s62, 28
	v_add_u32_e32 v111, v104, v3
	v_add_u32_e32 v115, v109, v14
	v_or_b32_e32 v129, s63, v1
	v_or_b32_e32 v160, s64, v2
	v_or_b32_e32 v161, s65, v1
	v_or_b32_e32 v162, s66, v2
	v_or_b32_e32 v163, s67, v1
	v_or_b32_e32 v164, s68, v2
	v_or_b32_e32 v165, s69, v1
	v_or_b32_e32 v166, s70, v2
	v_or_b32_e32 v167, s71, v1
	v_or_b32_e32 v168, s72, v2
	v_or_b32_e32 v169, s73, v1
	v_or_b32_e32 v170, s74, v2
	v_or_b32_e32 v171, s61, v1
	v_or_b32_e32 v172, s62, v2
	v_mad_u64_u32 v[118:119], s[62:63], v115, s48, v[16:17]
	v_mad_u64_u32 v[130:131], s[62:63], v111, s48, v[16:17]
	v_add_u32_e32 v111, v129, v3
	v_add_u32_e32 v115, v160, v14
	v_add_u32_e32 v138, v161, v3
	v_add_u32_e32 v136, v162, v14
	v_add_u32_e32 v142, v163, v3
	v_add_u32_e32 v140, v164, v14
	v_add_u32_e32 v146, v165, v3
	v_add_u32_e32 v144, v166, v14
	v_add_u32_e32 v150, v167, v3
	v_add_u32_e32 v148, v168, v14
	v_add_u32_e32 v154, v169, v3
	v_add_u32_e32 v152, v170, v14
	v_add_u32_e32 v158, v171, v3
	v_add_u32_e32 v156, v172, v14
	v_mad_u64_u32 v[132:133], s[62:63], v115, s48, v[16:17]
	v_mad_u64_u32 v[134:135], s[62:63], v111, s48, v[16:17]
	v_mad_u64_u32 v[136:137], s[62:63], v136, s48, v[16:17]
	v_mad_u64_u32 v[138:139], s[62:63], v138, s48, v[16:17]
	v_mad_u64_u32 v[140:141], s[62:63], v140, s48, v[16:17]
	v_mad_u64_u32 v[142:143], s[62:63], v142, s48, v[16:17]
	v_mad_u64_u32 v[144:145], s[62:63], v144, s48, v[16:17]
	v_mad_u64_u32 v[146:147], s[62:63], v146, s48, v[16:17]
	v_mad_u64_u32 v[148:149], s[62:63], v148, s48, v[16:17]
	v_mad_u64_u32 v[150:151], s[62:63], v150, s48, v[16:17]
	v_mad_u64_u32 v[152:153], s[62:63], v152, s48, v[16:17]
	v_mad_u64_u32 v[154:155], s[62:63], v154, s48, v[16:17]
	v_mad_u64_u32 v[156:157], s[62:63], v156, s48, v[16:17]
	v_mad_u64_u32 v[158:159], s[62:63], v158, s48, v[16:17]
	global_load_dword v111, v[118:119], off
	global_load_dword v115, v[130:131], off
	global_load_dword v173, v[132:133], off
	global_load_dword v174, v[134:135], off
	global_load_dword v175, v[136:137], off
	global_load_dword v176, v[138:139], off
	global_load_dword v177, v[140:141], off
	global_load_dword v178, v[142:143], off
	global_load_dword v179, v[144:145], off
	global_load_dword v180, v[146:147], off
	global_load_dword v181, v[148:149], off
	global_load_dword v182, v[150:151], off
	global_load_dword v183, v[152:153], off
	global_load_dword v184, v[154:155], off
	global_load_dword v185, v[156:157], off
	global_load_dword v186, v[158:159], off
	s_add_i32 s59, s59, 16
	s_add_i32 s58, s58, 16
	s_add_i32 s60, s60, -16
	v_mad_u64_u32 v[118:119], s[62:63], v109, s33, v[6:7]
	v_mad_u64_u32 v[130:131], s[62:63], v104, s33, v[6:7]
	v_mad_u64_u32 v[132:133], s[62:63], v160, s33, v[6:7]
	v_mad_u64_u32 v[134:135], s[62:63], v129, s33, v[6:7]
	v_mad_u64_u32 v[136:137], s[62:63], v162, s33, v[6:7]
	v_mad_u64_u32 v[138:139], s[62:63], v161, s33, v[6:7]
	v_mad_u64_u32 v[140:141], s[62:63], v164, s33, v[6:7]
	v_mad_u64_u32 v[142:143], s[62:63], v163, s33, v[6:7]
	v_mad_u64_u32 v[144:145], s[62:63], v166, s33, v[6:7]
	v_mad_u64_u32 v[146:147], s[62:63], v165, s33, v[6:7]
	v_mad_u64_u32 v[148:149], s[62:63], v168, s33, v[6:7]
	v_mad_u64_u32 v[150:151], s[62:63], v167, s33, v[6:7]
	v_mad_u64_u32 v[152:153], s[62:63], v170, s33, v[6:7]
	v_mad_u64_u32 v[154:155], s[62:63], v169, s33, v[6:7]
	v_mad_u64_u32 v[156:157], s[62:63], v172, s33, v[6:7]
	v_mad_u64_u32 v[158:159], s[62:63], v171, s33, v[6:7]
	s_lshl_b32 s61, s58, 1
	s_lshl_b32 s62, s59, 1
	v_or_b32_e32 v4, s61, v1
	v_or_b32_e32 v9, s62, v2
	s_add_i32 s63, s61, 4
	s_add_i32 s64, s62, 4
	s_add_i32 s65, s61, 8
	s_add_i32 s66, s62, 8
	s_add_i32 s67, s61, 12
	s_add_i32 s68, s62, 12
	s_add_i32 s69, s61, 16
	s_add_i32 s70, s62, 16
	s_add_i32 s71, s61, 20
	s_add_i32 s72, s62, 20
	s_add_i32 s73, s61, 24
	s_add_i32 s74, s62, 24
	s_add_i32 s61, s61, 28
	s_add_i32 s62, s62, 28
	v_add_u32_e32 v11, v4, v3
	v_add_u32_e32 v15, v9, v14
	v_or_b32_e32 v29, s63, v1
	v_or_b32_e32 v60, s64, v2
	v_or_b32_e32 v61, s65, v1
	v_or_b32_e32 v62, s66, v2
	v_or_b32_e32 v63, s67, v1
	v_or_b32_e32 v64, s68, v2
	v_or_b32_e32 v65, s69, v1
	v_or_b32_e32 v66, s70, v2
	v_or_b32_e32 v67, s71, v1
	v_or_b32_e32 v68, s72, v2
	v_or_b32_e32 v69, s73, v1
	v_or_b32_e32 v70, s74, v2
	v_or_b32_e32 v71, s61, v1
	v_or_b32_e32 v72, s62, v2
	v_mad_u64_u32 v[18:19], s[62:63], v15, s48, v[16:17]
	v_mad_u64_u32 v[30:31], s[62:63], v11, s48, v[16:17]
	v_add_u32_e32 v11, v29, v3
	v_add_u32_e32 v15, v60, v14
	v_add_u32_e32 v38, v61, v3
	v_add_u32_e32 v36, v62, v14
	v_add_u32_e32 v42, v63, v3
	v_add_u32_e32 v40, v64, v14
	v_add_u32_e32 v46, v65, v3
	v_add_u32_e32 v44, v66, v14
	v_add_u32_e32 v50, v67, v3
	v_add_u32_e32 v48, v68, v14
	v_add_u32_e32 v54, v69, v3
	v_add_u32_e32 v52, v70, v14
	v_add_u32_e32 v58, v71, v3
	v_add_u32_e32 v56, v72, v14
	v_mad_u64_u32 v[32:33], s[62:63], v15, s48, v[16:17]
	v_mad_u64_u32 v[34:35], s[62:63], v11, s48, v[16:17]
	v_mad_u64_u32 v[36:37], s[62:63], v36, s48, v[16:17]
	v_mad_u64_u32 v[38:39], s[62:63], v38, s48, v[16:17]
	v_mad_u64_u32 v[40:41], s[62:63], v40, s48, v[16:17]
	v_mad_u64_u32 v[42:43], s[62:63], v42, s48, v[16:17]
	v_mad_u64_u32 v[44:45], s[62:63], v44, s48, v[16:17]
	v_mad_u64_u32 v[46:47], s[62:63], v46, s48, v[16:17]
	v_mad_u64_u32 v[48:49], s[62:63], v48, s48, v[16:17]
	v_mad_u64_u32 v[50:51], s[62:63], v50, s48, v[16:17]
	v_mad_u64_u32 v[52:53], s[62:63], v52, s48, v[16:17]
	v_mad_u64_u32 v[54:55], s[62:63], v54, s48, v[16:17]
	v_mad_u64_u32 v[56:57], s[62:63], v56, s48, v[16:17]
	v_mad_u64_u32 v[58:59], s[62:63], v58, s48, v[16:17]
	global_load_dword v11, v[18:19], off
	global_load_dword v15, v[30:31], off
	global_load_dword v73, v[32:33], off
	global_load_dword v74, v[34:35], off
	global_load_dword v75, v[36:37], off
	global_load_dword v76, v[38:39], off
	global_load_dword v77, v[40:41], off
	global_load_dword v78, v[42:43], off
	global_load_dword v79, v[44:45], off
	global_load_dword v80, v[46:47], off
	global_load_dword v81, v[48:49], off
	global_load_dword v82, v[50:51], off
	global_load_dword v83, v[52:53], off
	global_load_dword v84, v[54:55], off
	global_load_dword v85, v[56:57], off
	global_load_dword v86, v[58:59], off
	s_add_i32 s59, s59, 16
	s_add_i32 s58, s58, 16
	s_add_i32 s60, s60, -16
	v_mad_u64_u32 v[18:19], s[62:63], v9, s33, v[6:7]
	v_mad_u64_u32 v[30:31], s[62:63], v4, s33, v[6:7]
	v_mad_u64_u32 v[32:33], s[62:63], v60, s33, v[6:7]
	v_mad_u64_u32 v[34:35], s[62:63], v29, s33, v[6:7]
	v_mad_u64_u32 v[36:37], s[62:63], v62, s33, v[6:7]
	v_mad_u64_u32 v[38:39], s[62:63], v61, s33, v[6:7]
	v_mad_u64_u32 v[40:41], s[62:63], v64, s33, v[6:7]
	v_mad_u64_u32 v[42:43], s[62:63], v63, s33, v[6:7]
	v_mad_u64_u32 v[44:45], s[62:63], v66, s33, v[6:7]
	v_mad_u64_u32 v[46:47], s[62:63], v65, s33, v[6:7]
	v_mad_u64_u32 v[48:49], s[62:63], v68, s33, v[6:7]
	v_mad_u64_u32 v[50:51], s[62:63], v67, s33, v[6:7]
	v_mad_u64_u32 v[52:53], s[62:63], v70, s33, v[6:7]
	v_mad_u64_u32 v[54:55], s[62:63], v69, s33, v[6:7]
	v_mad_u64_u32 v[56:57], s[62:63], v72, s33, v[6:7]
	v_mad_u64_u32 v[58:59], s[62:63], v71, s33, v[6:7]
	s_waitcnt vmcnt(31)
	ds_write_b32 v118, v111
	s_waitcnt vmcnt(30)
	ds_write_b32 v130, v115
	s_waitcnt vmcnt(29)
	ds_write_b32 v132, v173
	s_waitcnt vmcnt(28)
	ds_write_b32 v134, v174
	s_waitcnt vmcnt(27)
	ds_write_b32 v136, v175
	s_waitcnt vmcnt(26)
	ds_write_b32 v138, v176
	s_waitcnt vmcnt(25)
	ds_write_b32 v140, v177
	s_waitcnt vmcnt(24)
	ds_write_b32 v142, v178
	s_waitcnt vmcnt(23)
	ds_write_b32 v144, v179
	s_waitcnt vmcnt(22)
	ds_write_b32 v146, v180
	s_waitcnt vmcnt(21)
	ds_write_b32 v148, v181
	s_waitcnt vmcnt(20)
	ds_write_b32 v150, v182
	s_waitcnt vmcnt(19)
	ds_write_b32 v152, v183
	s_waitcnt vmcnt(18)
	ds_write_b32 v154, v184
	s_waitcnt vmcnt(17)
	ds_write_b32 v156, v185
	s_waitcnt vmcnt(16)
	ds_write_b32 v158, v186
	s_waitcnt vmcnt(15)
	ds_write_b32 v18, v11
	s_waitcnt vmcnt(14)
	ds_write_b32 v30, v15
	s_waitcnt vmcnt(13)
	ds_write_b32 v32, v73
	s_waitcnt vmcnt(12)
	ds_write_b32 v34, v74
	s_waitcnt vmcnt(11)
	ds_write_b32 v36, v75
	s_waitcnt vmcnt(10)
	ds_write_b32 v38, v76
	s_waitcnt vmcnt(9)
	ds_write_b32 v40, v77
	s_waitcnt vmcnt(8)
	ds_write_b32 v42, v78
	s_waitcnt vmcnt(7)
	ds_write_b32 v44, v79
	s_waitcnt vmcnt(6)
	ds_write_b32 v46, v80
	s_waitcnt vmcnt(5)
	ds_write_b32 v48, v81
	s_waitcnt vmcnt(4)
	ds_write_b32 v50, v82
	s_waitcnt vmcnt(3)
	ds_write_b32 v52, v83
	s_waitcnt vmcnt(2)
	ds_write_b32 v54, v84
	s_waitcnt vmcnt(1)
	ds_write_b32 v56, v85
	s_waitcnt vmcnt(0)
	ds_write_b32 v58, v86
	s_waitcnt lgkmcnt(0)
	ds_read2_b32 v[18:19], v22 offset1:8
	ds_read2_b32 v[32:33], v22 offset0:33 offset1:41
	ds_read2_b32 v[34:35], v22 offset0:66 offset1:74
	v_mul_hi_i32_i24_e32 v17, 0x1c0000, v12
	v_mul_i32_i24_e32 v16, 0x1c0000, v12
	ds_read2_b32 v[36:37], v22 offset0:99 offset1:107
	v_lshl_add_u64 v[16:17], s[10:11], 0, v[16:17]
	v_lshlrev_b32_e32 v4, 1, v14
	s_waitcnt lgkmcnt(3)
	v_bfe_u32 v3, v18, 16, 1
	v_lshl_add_u64 v[14:15], v[16:17], 0, v[4:5]
	v_add3_u32 v3, v18, v3, s45
	s_waitcnt lgkmcnt(2)
	v_bfe_u32 v4, v32, 16, 1
	ds_read2_b32 v[38:39], v22 offset0:132 offset1:140
	v_mov_b32_e32 v11, v5
	v_lshrrev_b32_e32 v3, 16, v3
	v_add3_u32 v4, v32, v4, s45
	ds_read2_b32 v[40:41], v22 offset0:165 offset1:173
	v_lshl_add_u64 v[30:31], v[14:15], 0, v[10:11]
	v_and_or_b32 v14, v4, s46, v3
	s_waitcnt lgkmcnt(3)
	v_bfe_u32 v3, v34, 16, 1
	v_add3_u32 v3, v34, v3, s45
	s_waitcnt lgkmcnt(2)
	v_bfe_u32 v4, v36, 16, 1
	ds_read2_b32 v[42:43], v22 offset0:198 offset1:206
	v_lshrrev_b32_e32 v3, 16, v3
	v_add3_u32 v4, v36, v4, s45
	ds_read2_b32 v[44:45], v22 offset0:231 offset1:239
	v_and_or_b32 v15, v4, s46, v3
	s_waitcnt lgkmcnt(3)
	v_bfe_u32 v3, v38, 16, 1
	v_add3_u32 v3, v38, v3, s45
	s_waitcnt lgkmcnt(2)
	v_bfe_u32 v4, v40, 16, 1
	v_lshrrev_b32_e32 v3, 16, v3
	v_add3_u32 v4, v40, v4, s45
	v_and_or_b32 v16, v4, s46, v3
	s_waitcnt lgkmcnt(1)
	v_bfe_u32 v3, v42, 16, 1
	v_add3_u32 v3, v42, v3, s45
	s_waitcnt lgkmcnt(0)
	v_bfe_u32 v4, v44, 16, 1
	v_lshrrev_b32_e32 v3, 16, v3
	v_add3_u32 v4, v44, v4, s45
	v_and_or_b32 v17, v4, s46, v3
	v_or_b32_e32 v3, v13, v21
	v_lshlrev_b32_e32 v4, 10, v3
	v_bfe_u32 v3, v19, 16, 1
	v_lshl_add_u64 v[46:47], v[30:31], 0, v[4:5]
	v_add3_u32 v3, v19, v3, s45
	v_bfe_u32 v4, v33, 16, 1
	v_lshrrev_b32_e32 v3, 16, v3
	v_add3_u32 v4, v33, v4, s45
	global_store_dwordx4 v[46:47], v[14:17], off sc1
	ds_read2_b32 v[18:19], v22 offset0:16 offset1:24
	v_readlane_b32 s66, v253, 1
	v_and_or_b32 v14, v4, s46, v3
	v_bfe_u32 v3, v35, 16, 1
	v_add3_u32 v3, v35, v3, s45
	v_bfe_u32 v4, v37, 16, 1
	v_lshrrev_b32_e32 v3, 16, v3
	v_add3_u32 v4, v37, v4, s45
	v_and_or_b32 v15, v4, s46, v3
	v_bfe_u32 v3, v39, 16, 1
	v_add3_u32 v3, v39, v3, s45
	v_bfe_u32 v4, v41, 16, 1
	v_lshrrev_b32_e32 v3, 16, v3
	v_add3_u32 v4, v41, v4, s45
	v_and_or_b32 v16, v4, s46, v3
	v_bfe_u32 v3, v43, 16, 1
	v_add3_u32 v3, v43, v3, s45
	v_bfe_u32 v4, v45, 16, 1
	v_lshrrev_b32_e32 v3, 16, v3
	v_add3_u32 v4, v45, v4, s45
	v_and_or_b32 v17, v4, s46, v3
	v_or_b32_e32 v3, v13, v23
	v_lshlrev_b32_e32 v4, 10, v3
	v_lshl_add_u64 v[32:33], v[30:31], 0, v[4:5]
	global_store_dwordx4 v[32:33], v[14:17], off sc1
	ds_read2_b32 v[32:33], v22 offset0:49 offset1:57
	ds_read2_b32 v[34:35], v22 offset0:82 offset1:90
	ds_read2_b32 v[36:37], v22 offset0:115 offset1:123
	s_waitcnt lgkmcnt(3)
	v_bfe_u32 v3, v18, 16, 1
	v_add3_u32 v3, v18, v3, s45
	s_waitcnt lgkmcnt(2)
	v_bfe_u32 v4, v32, 16, 1
	ds_read2_b32 v[38:39], v22 offset0:148 offset1:156
	v_lshrrev_b32_e32 v3, 16, v3
	v_add3_u32 v4, v32, v4, s45
	ds_read2_b32 v[40:41], v22 offset0:181 offset1:189
	v_and_or_b32 v14, v4, s46, v3
	s_waitcnt lgkmcnt(3)
	v_bfe_u32 v3, v34, 16, 1
	v_add3_u32 v3, v34, v3, s45
	s_waitcnt lgkmcnt(2)
	v_bfe_u32 v4, v36, 16, 1
	ds_read2_b32 v[42:43], v22 offset0:214 offset1:222
	v_lshrrev_b32_e32 v3, 16, v3
	v_add3_u32 v4, v36, v4, s45
	ds_read2_b32 v[44:45], v22 offset0:247 offset1:255
	v_and_or_b32 v15, v4, s46, v3
	s_waitcnt lgkmcnt(3)
	v_bfe_u32 v3, v38, 16, 1
	v_add3_u32 v3, v38, v3, s45
	s_waitcnt lgkmcnt(2)
	v_bfe_u32 v4, v40, 16, 1
	v_lshrrev_b32_e32 v3, 16, v3
	v_add3_u32 v4, v40, v4, s45
	v_and_or_b32 v16, v4, s46, v3
	s_waitcnt lgkmcnt(1)
	v_bfe_u32 v3, v42, 16, 1
	v_add3_u32 v3, v42, v3, s45
	s_waitcnt lgkmcnt(0)
	v_bfe_u32 v4, v44, 16, 1
	v_lshrrev_b32_e32 v3, 16, v3
	v_add3_u32 v4, v44, v4, s45
	v_and_or_b32 v17, v4, s46, v3
	v_or_b32_e32 v3, v13, v24
	v_lshlrev_b32_e32 v4, 10, v3
	v_bfe_u32 v3, v19, 16, 1
	v_lshl_add_u64 v[46:47], v[30:31], 0, v[4:5]
	v_add3_u32 v3, v19, v3, s45
	v_bfe_u32 v4, v33, 16, 1
	v_lshrrev_b32_e32 v3, 16, v3
	v_add3_u32 v4, v33, v4, s45
	global_store_dwordx4 v[46:47], v[14:17], off sc1
	s_nop 1
	v_and_or_b32 v14, v4, s46, v3
	v_bfe_u32 v3, v35, 16, 1
	v_add3_u32 v3, v35, v3, s45
	v_bfe_u32 v4, v37, 16, 1
	v_lshrrev_b32_e32 v3, 16, v3
	v_add3_u32 v4, v37, v4, s45
	v_and_or_b32 v15, v4, s46, v3
	v_bfe_u32 v3, v39, 16, 1
	v_add3_u32 v3, v39, v3, s45
	v_bfe_u32 v4, v41, 16, 1
	v_lshrrev_b32_e32 v3, 16, v3
	v_add3_u32 v4, v41, v4, s45
	v_and_or_b32 v16, v4, s46, v3
	v_bfe_u32 v3, v43, 16, 1
	v_add3_u32 v3, v43, v3, s45
	v_bfe_u32 v4, v45, 16, 1
	v_lshrrev_b32_e32 v3, 16, v3
	v_add3_u32 v4, v45, v4, s45
	v_and_or_b32 v17, v4, s46, v3
	v_or_b32_e32 v3, v13, v25
	v_lshlrev_b32_e32 v4, 10, v3
	v_lshl_add_u64 v[12:13], v[30:31], 0, v[4:5]
	global_store_dwordx4 v[12:13], v[14:17], off sc1
	s_waitcnt lgkmcnt(0)

.LBB0_120:
	s_andn2_saveexec_b64 s[34:35], s[34:35]
	s_cbranch_execz .LBB0_124
	s_load_dwordx2 s[36:37], s[6:7], 0xb0
	v_and_b32_e32 v4, 0x7fc0, v3
	v_lshlrev_b32_e32 v3, 5, v3
	v_and_b32_e32 v13, 0x7e0, v3
	v_add_u32_e32 v14, 0xffffbbc0, v4
	s_waitcnt lgkmcnt(0)
	v_mov_b64_e32 v[16:17], s[36:37]
	v_mad_i64_i32 v[16:17], s[36:37], v12, s49, v[16:17]
	v_lshlrev_b32_e32 v4, 2, v13
	v_lshl_add_u64 v[16:17], v[16:17], 0, v[4:5]
	v_mov_b32_e32 v9, v5
	v_lshl_add_u64 v[16:17], v[16:17], 0, v[8:9]
	v_mov_b32_e32 v3, v14
	s_mov_b32 s36, 1
	s_mov_b32 s37, 0
	s_mov_b32 s58, 32
	s_lshl_b32 s59, s36, 1
	s_lshl_b32 s60, s37, 1
	v_or_b32_e32 v104, s59, v1
	v_or_b32_e32 v109, s60, v2
	s_add_i32 s61, s59, 4
	s_add_i32 s62, s60, 4
	s_add_i32 s63, s59, 8
	s_add_i32 s64, s60, 8
	s_add_i32 s65, s59, 12
	s_add_i32 s66, s60, 12
	s_add_i32 s67, s59, 16
	s_add_i32 s68, s60, 16
	s_add_i32 s69, s59, 20
	s_add_i32 s70, s60, 20
	s_add_i32 s71, s59, 24
	s_add_i32 s72, s60, 24
	s_add_i32 s59, s59, 28
	s_add_i32 s60, s60, 28
	v_add_u32_e32 v130, v109, v14
	v_or_b32_e32 v111, s61, v1
	v_or_b32_e32 v115, s62, v2
	v_or_b32_e32 v129, s63, v1
	v_or_b32_e32 v160, s64, v2
	v_or_b32_e32 v161, s65, v1
	v_or_b32_e32 v162, s66, v2
	v_or_b32_e32 v163, s67, v1
	v_or_b32_e32 v164, s68, v2
	v_or_b32_e32 v165, s69, v1
	v_or_b32_e32 v166, s70, v2
	v_or_b32_e32 v167, s71, v1
	v_or_b32_e32 v168, s72, v2
	v_or_b32_e32 v169, s59, v1
	v_or_b32_e32 v170, s60, v2
	v_add_u32_e32 v118, v104, v3
	v_ashrrev_i32_e32 v131, 31, v130
	v_add_u32_e32 v132, v111, v3
	v_add_u32_e32 v134, v115, v14
	v_add_u32_e32 v136, v129, v3
	v_add_u32_e32 v138, v160, v14
	v_add_u32_e32 v140, v161, v3
	v_add_u32_e32 v142, v162, v14
	v_add_u32_e32 v144, v163, v3
	v_add_u32_e32 v146, v164, v14
	v_add_u32_e32 v148, v165, v3
	v_add_u32_e32 v150, v166, v14
	v_add_u32_e32 v152, v167, v3
	v_add_u32_e32 v154, v168, v14
	v_add_u32_e32 v156, v169, v3
	v_add_u32_e32 v158, v170, v14
	v_ashrrev_i32_e32 v119, 31, v118
	v_lshlrev_b64 v[130:131], 13, v[130:131]
	v_ashrrev_i32_e32 v135, 31, v134
	v_ashrrev_i32_e32 v133, 31, v132
	v_ashrrev_i32_e32 v139, 31, v138
	v_ashrrev_i32_e32 v137, 31, v136
	v_ashrrev_i32_e32 v143, 31, v142
	v_ashrrev_i32_e32 v141, 31, v140
	v_ashrrev_i32_e32 v147, 31, v146
	v_ashrrev_i32_e32 v145, 31, v144
	v_ashrrev_i32_e32 v151, 31, v150
	v_ashrrev_i32_e32 v149, 31, v148
	v_ashrrev_i32_e32 v155, 31, v154
	v_ashrrev_i32_e32 v153, 31, v152
	v_ashrrev_i32_e32 v159, 31, v158
	v_ashrrev_i32_e32 v157, 31, v156
	v_lshlrev_b64 v[118:119], 13, v[118:119]
	v_lshl_add_u64 v[130:131], v[16:17], 0, v[130:131]
	v_lshlrev_b64 v[132:133], 13, v[132:133]
	v_lshlrev_b64 v[134:135], 13, v[134:135]
	v_lshlrev_b64 v[136:137], 13, v[136:137]
	v_lshlrev_b64 v[138:139], 13, v[138:139]
	v_lshlrev_b64 v[140:141], 13, v[140:141]
	v_lshlrev_b64 v[142:143], 13, v[142:143]
	v_lshlrev_b64 v[144:145], 13, v[144:145]
	v_lshlrev_b64 v[146:147], 13, v[146:147]
	v_lshlrev_b64 v[148:149], 13, v[148:149]
	v_lshlrev_b64 v[150:151], 13, v[150:151]
	v_lshlrev_b64 v[152:153], 13, v[152:153]
	v_lshlrev_b64 v[154:155], 13, v[154:155]
	v_lshlrev_b64 v[156:157], 13, v[156:157]
	v_lshlrev_b64 v[158:159], 13, v[158:159]
	v_lshl_add_u64 v[118:119], v[16:17], 0, v[118:119]
	v_lshl_add_u64 v[134:135], v[16:17], 0, v[134:135]
	v_lshl_add_u64 v[132:133], v[16:17], 0, v[132:133]
	v_lshl_add_u64 v[138:139], v[16:17], 0, v[138:139]
	v_lshl_add_u64 v[136:137], v[16:17], 0, v[136:137]
	v_lshl_add_u64 v[142:143], v[16:17], 0, v[142:143]
	v_lshl_add_u64 v[140:141], v[16:17], 0, v[140:141]
	v_lshl_add_u64 v[146:147], v[16:17], 0, v[146:147]
	v_lshl_add_u64 v[144:145], v[16:17], 0, v[144:145]
	v_lshl_add_u64 v[150:151], v[16:17], 0, v[150:151]
	v_lshl_add_u64 v[148:149], v[16:17], 0, v[148:149]
	v_lshl_add_u64 v[154:155], v[16:17], 0, v[154:155]
	v_lshl_add_u64 v[152:153], v[16:17], 0, v[152:153]
	v_lshl_add_u64 v[158:159], v[16:17], 0, v[158:159]
	v_lshl_add_u64 v[156:157], v[16:17], 0, v[156:157]
	global_load_dword v171, v[130:131], off
	global_load_dword v172, v[118:119], off
	global_load_dword v173, v[134:135], off
	global_load_dword v174, v[132:133], off
	global_load_dword v175, v[138:139], off
	global_load_dword v176, v[136:137], off
	global_load_dword v177, v[142:143], off
	global_load_dword v178, v[140:141], off
	global_load_dword v179, v[146:147], off
	global_load_dword v180, v[144:145], off
	global_load_dword v181, v[150:151], off
	global_load_dword v182, v[148:149], off
	global_load_dword v183, v[154:155], off
	global_load_dword v184, v[152:153], off
	global_load_dword v185, v[158:159], off
	global_load_dword v186, v[156:157], off
	s_add_i32 s37, s37, 16
	s_add_i32 s36, s36, 16
	s_add_i32 s58, s58, -16
	v_mad_u64_u32 v[118:119], s[60:61], v109, s33, v[6:7]
	v_mad_u64_u32 v[130:131], s[60:61], v104, s33, v[6:7]
	v_mad_u64_u32 v[132:133], s[60:61], v115, s33, v[6:7]
	v_mad_u64_u32 v[134:135], s[60:61], v111, s33, v[6:7]
	v_mad_u64_u32 v[136:137], s[60:61], v160, s33, v[6:7]
	v_mad_u64_u32 v[138:139], s[60:61], v129, s33, v[6:7]
	v_mad_u64_u32 v[140:141], s[60:61], v162, s33, v[6:7]
	v_mad_u64_u32 v[142:143], s[60:61], v161, s33, v[6:7]
	v_mad_u64_u32 v[144:145], s[60:61], v164, s33, v[6:7]
	v_mad_u64_u32 v[146:147], s[60:61], v163, s33, v[6:7]
	v_mad_u64_u32 v[148:149], s[60:61], v166, s33, v[6:7]
	v_mad_u64_u32 v[150:151], s[60:61], v165, s33, v[6:7]
	v_mad_u64_u32 v[152:153], s[60:61], v168, s33, v[6:7]
	v_mad_u64_u32 v[154:155], s[60:61], v167, s33, v[6:7]
	v_mad_u64_u32 v[156:157], s[60:61], v170, s33, v[6:7]
	v_mad_u64_u32 v[158:159], s[60:61], v169, s33, v[6:7]
	s_lshl_b32 s59, s36, 1
	s_lshl_b32 s60, s37, 1
	v_or_b32_e32 v4, s59, v1
	v_or_b32_e32 v9, s60, v2
	s_add_i32 s61, s59, 4
	s_add_i32 s62, s60, 4
	s_add_i32 s63, s59, 8
	s_add_i32 s64, s60, 8
	s_add_i32 s65, s59, 12
	s_add_i32 s66, s60, 12
	s_add_i32 s67, s59, 16
	s_add_i32 s68, s60, 16
	s_add_i32 s69, s59, 20
	s_add_i32 s70, s60, 20
	s_add_i32 s71, s59, 24
	s_add_i32 s72, s60, 24
	s_add_i32 s59, s59, 28
	s_add_i32 s60, s60, 28
	v_add_u32_e32 v30, v9, v14
	v_or_b32_e32 v11, s61, v1
	v_or_b32_e32 v15, s62, v2
	v_or_b32_e32 v29, s63, v1
	v_or_b32_e32 v60, s64, v2
	v_or_b32_e32 v61, s65, v1
	v_or_b32_e32 v62, s66, v2
	v_or_b32_e32 v63, s67, v1
	v_or_b32_e32 v64, s68, v2
	v_or_b32_e32 v65, s69, v1
	v_or_b32_e32 v66, s70, v2
	v_or_b32_e32 v67, s71, v1
	v_or_b32_e32 v68, s72, v2
	v_or_b32_e32 v69, s59, v1
	v_or_b32_e32 v70, s60, v2
	v_add_u32_e32 v18, v4, v3
	v_ashrrev_i32_e32 v31, 31, v30
	v_add_u32_e32 v32, v11, v3
	v_add_u32_e32 v34, v15, v14
	v_add_u32_e32 v36, v29, v3
	v_add_u32_e32 v38, v60, v14
	v_add_u32_e32 v40, v61, v3
	v_add_u32_e32 v42, v62, v14
	v_add_u32_e32 v44, v63, v3
	v_add_u32_e32 v46, v64, v14
	v_add_u32_e32 v48, v65, v3
	v_add_u32_e32 v50, v66, v14
	v_add_u32_e32 v52, v67, v3
	v_add_u32_e32 v54, v68, v14
	v_add_u32_e32 v56, v69, v3
	v_add_u32_e32 v58, v70, v14
	v_ashrrev_i32_e32 v19, 31, v18
	v_lshlrev_b64 v[30:31], 13, v[30:31]
	v_ashrrev_i32_e32 v35, 31, v34
	v_ashrrev_i32_e32 v33, 31, v32
	v_ashrrev_i32_e32 v39, 31, v38
	v_ashrrev_i32_e32 v37, 31, v36
	v_ashrrev_i32_e32 v43, 31, v42
	v_ashrrev_i32_e32 v41, 31, v40
	v_ashrrev_i32_e32 v47, 31, v46
	v_ashrrev_i32_e32 v45, 31, v44
	v_ashrrev_i32_e32 v51, 31, v50
	v_ashrrev_i32_e32 v49, 31, v48
	v_ashrrev_i32_e32 v55, 31, v54
	v_ashrrev_i32_e32 v53, 31, v52
	v_ashrrev_i32_e32 v59, 31, v58
	v_ashrrev_i32_e32 v57, 31, v56
	v_lshlrev_b64 v[18:19], 13, v[18:19]
	v_lshl_add_u64 v[30:31], v[16:17], 0, v[30:31]
	v_lshlrev_b64 v[32:33], 13, v[32:33]
	v_lshlrev_b64 v[34:35], 13, v[34:35]
	v_lshlrev_b64 v[36:37], 13, v[36:37]
	v_lshlrev_b64 v[38:39], 13, v[38:39]
	v_lshlrev_b64 v[40:41], 13, v[40:41]
	v_lshlrev_b64 v[42:43], 13, v[42:43]
	v_lshlrev_b64 v[44:45], 13, v[44:45]
	v_lshlrev_b64 v[46:47], 13, v[46:47]
	v_lshlrev_b64 v[48:49], 13, v[48:49]
	v_lshlrev_b64 v[50:51], 13, v[50:51]
	v_lshlrev_b64 v[52:53], 13, v[52:53]
	v_lshlrev_b64 v[54:55], 13, v[54:55]
	v_lshlrev_b64 v[56:57], 13, v[56:57]
	v_lshlrev_b64 v[58:59], 13, v[58:59]
	v_lshl_add_u64 v[18:19], v[16:17], 0, v[18:19]
	v_lshl_add_u64 v[34:35], v[16:17], 0, v[34:35]
	v_lshl_add_u64 v[32:33], v[16:17], 0, v[32:33]
	v_lshl_add_u64 v[38:39], v[16:17], 0, v[38:39]
	v_lshl_add_u64 v[36:37], v[16:17], 0, v[36:37]
	v_lshl_add_u64 v[42:43], v[16:17], 0, v[42:43]
	v_lshl_add_u64 v[40:41], v[16:17], 0, v[40:41]
	v_lshl_add_u64 v[46:47], v[16:17], 0, v[46:47]
	v_lshl_add_u64 v[44:45], v[16:17], 0, v[44:45]
	v_lshl_add_u64 v[50:51], v[16:17], 0, v[50:51]
	v_lshl_add_u64 v[48:49], v[16:17], 0, v[48:49]
	v_lshl_add_u64 v[54:55], v[16:17], 0, v[54:55]
	v_lshl_add_u64 v[52:53], v[16:17], 0, v[52:53]
	v_lshl_add_u64 v[58:59], v[16:17], 0, v[58:59]
	v_lshl_add_u64 v[56:57], v[16:17], 0, v[56:57]
	global_load_dword v71, v[30:31], off
	global_load_dword v72, v[18:19], off
	global_load_dword v73, v[34:35], off
	global_load_dword v74, v[32:33], off
	global_load_dword v75, v[38:39], off
	global_load_dword v76, v[36:37], off
	global_load_dword v77, v[42:43], off
	global_load_dword v78, v[40:41], off
	global_load_dword v79, v[46:47], off
	global_load_dword v80, v[44:45], off
	global_load_dword v81, v[50:51], off
	global_load_dword v82, v[48:49], off
	global_load_dword v83, v[54:55], off
	global_load_dword v84, v[52:53], off
	global_load_dword v85, v[58:59], off
	global_load_dword v86, v[56:57], off
	s_add_i32 s37, s37, 16
	s_add_i32 s36, s36, 16
	s_add_i32 s58, s58, -16
	v_mad_u64_u32 v[18:19], s[60:61], v9, s33, v[6:7]
	v_mad_u64_u32 v[30:31], s[60:61], v4, s33, v[6:7]
	v_mad_u64_u32 v[32:33], s[60:61], v15, s33, v[6:7]
	v_mad_u64_u32 v[34:35], s[60:61], v11, s33, v[6:7]
	v_mad_u64_u32 v[36:37], s[60:61], v60, s33, v[6:7]
	v_mad_u64_u32 v[38:39], s[60:61], v29, s33, v[6:7]
	v_mad_u64_u32 v[40:41], s[60:61], v62, s33, v[6:7]
	v_mad_u64_u32 v[42:43], s[60:61], v61, s33, v[6:7]
	v_mad_u64_u32 v[44:45], s[60:61], v64, s33, v[6:7]
	v_mad_u64_u32 v[46:47], s[60:61], v63, s33, v[6:7]
	v_mad_u64_u32 v[48:49], s[60:61], v66, s33, v[6:7]
	v_mad_u64_u32 v[50:51], s[60:61], v65, s33, v[6:7]
	v_mad_u64_u32 v[52:53], s[60:61], v68, s33, v[6:7]
	v_mad_u64_u32 v[54:55], s[60:61], v67, s33, v[6:7]
	v_mad_u64_u32 v[56:57], s[60:61], v70, s33, v[6:7]
	v_mad_u64_u32 v[58:59], s[60:61], v69, s33, v[6:7]
	s_waitcnt vmcnt(31)
	ds_write_b32 v118, v171
	s_waitcnt vmcnt(30)
	ds_write_b32 v130, v172
	s_waitcnt vmcnt(29)
	ds_write_b32 v132, v173
	s_waitcnt vmcnt(28)
	ds_write_b32 v134, v174
	s_waitcnt vmcnt(27)
	ds_write_b32 v136, v175
	s_waitcnt vmcnt(26)
	ds_write_b32 v138, v176
	s_waitcnt vmcnt(25)
	ds_write_b32 v140, v177
	s_waitcnt vmcnt(24)
	ds_write_b32 v142, v178
	s_waitcnt vmcnt(23)
	ds_write_b32 v144, v179
	s_waitcnt vmcnt(22)
	ds_write_b32 v146, v180
	s_waitcnt vmcnt(21)
	ds_write_b32 v148, v181
	s_waitcnt vmcnt(20)
	ds_write_b32 v150, v182
	s_waitcnt vmcnt(19)
	ds_write_b32 v152, v183
	s_waitcnt vmcnt(18)
	ds_write_b32 v154, v184
	s_waitcnt vmcnt(17)
	ds_write_b32 v156, v185
	s_waitcnt vmcnt(16)
	ds_write_b32 v158, v186
	s_waitcnt vmcnt(15)
	ds_write_b32 v18, v71
	s_waitcnt vmcnt(14)
	ds_write_b32 v30, v72
	s_waitcnt vmcnt(13)
	ds_write_b32 v32, v73
	s_waitcnt vmcnt(12)
	ds_write_b32 v34, v74
	s_waitcnt vmcnt(11)
	ds_write_b32 v36, v75
	s_waitcnt vmcnt(10)
	ds_write_b32 v38, v76
	s_waitcnt vmcnt(9)
	ds_write_b32 v40, v77
	s_waitcnt vmcnt(8)
	ds_write_b32 v42, v78
	s_waitcnt vmcnt(7)
	ds_write_b32 v44, v79
	s_waitcnt vmcnt(6)
	ds_write_b32 v46, v80
	s_waitcnt vmcnt(5)
	ds_write_b32 v48, v81
	s_waitcnt vmcnt(4)
	ds_write_b32 v50, v82
	s_waitcnt vmcnt(3)
	ds_write_b32 v52, v83
	s_waitcnt vmcnt(2)
	ds_write_b32 v54, v84
	s_waitcnt vmcnt(1)
	ds_write_b32 v56, v85
	s_waitcnt vmcnt(0)
	ds_write_b32 v58, v86
	s_waitcnt lgkmcnt(0)
	ds_read2_b32 v[18:19], v22 offset1:8
	ds_read2_b32 v[32:33], v22 offset0:33 offset1:41
	ds_read2_b32 v[34:35], v22 offset0:66 offset1:74
	ds_read2_b32 v[36:37], v22 offset0:99 offset1:107
	v_mov_b64_e32 v[16:17], s[12:13]
	s_waitcnt lgkmcnt(3)
	v_bfe_u32 v3, v18, 16, 1
	v_mad_i64_i32 v[16:17], s[36:37], v12, s50, v[16:17]
	v_mov_b32_e32 v15, v5
	v_add3_u32 v3, v18, v3, s45
	s_waitcnt lgkmcnt(2)
	v_bfe_u32 v4, v32, 16, 1
	ds_read2_b32 v[38:39], v22 offset0:132 offset1:140
	v_lshl_add_u64 v[14:15], v[14:15], 1, v[16:17]
	v_mov_b32_e32 v11, v5
	v_lshrrev_b32_e32 v3, 16, v3
	v_add3_u32 v4, v32, v4, s45
	ds_read2_b32 v[40:41], v22 offset0:165 offset1:173
	v_lshl_add_u64 v[30:31], v[14:15], 0, v[10:11]
	v_and_or_b32 v14, v4, s46, v3
	s_waitcnt lgkmcnt(3)
	v_bfe_u32 v3, v34, 16, 1
	v_add3_u32 v3, v34, v3, s45
	s_waitcnt lgkmcnt(2)
	v_bfe_u32 v4, v36, 16, 1
	ds_read2_b32 v[42:43], v22 offset0:198 offset1:206
	v_lshrrev_b32_e32 v3, 16, v3
	v_add3_u32 v4, v36, v4, s45
	ds_read2_b32 v[44:45], v22 offset0:231 offset1:239
	v_and_or_b32 v15, v4, s46, v3
	s_waitcnt lgkmcnt(3)
	v_bfe_u32 v3, v38, 16, 1
	v_add3_u32 v3, v38, v3, s45
	s_waitcnt lgkmcnt(2)
	v_bfe_u32 v4, v40, 16, 1
	v_lshrrev_b32_e32 v3, 16, v3
	v_add3_u32 v4, v40, v4, s45
	v_and_or_b32 v16, v4, s46, v3
	s_waitcnt lgkmcnt(1)
	v_bfe_u32 v3, v42, 16, 1
	v_add3_u32 v3, v42, v3, s45
	s_waitcnt lgkmcnt(0)
	v_bfe_u32 v4, v44, 16, 1
	v_lshrrev_b32_e32 v3, 16, v3
	v_add3_u32 v4, v44, v4, s45
	v_and_or_b32 v17, v4, s46, v3
	v_or_b32_e32 v3, v13, v21
	v_mul_u32_u24_e32 v3, 0x1600, v3
	v_lshlrev_b32_e32 v4, 1, v3
	v_bfe_u32 v3, v19, 16, 1
	v_lshl_add_u64 v[46:47], v[30:31], 0, v[4:5]
	v_add3_u32 v3, v19, v3, s45
	v_bfe_u32 v4, v33, 16, 1
	v_lshrrev_b32_e32 v3, 16, v3
	v_add3_u32 v4, v33, v4, s45
	global_store_dwordx4 v[46:47], v[14:17], off sc1
	ds_read2_b32 v[18:19], v22 offset0:16 offset1:24
	v_readlane_b32 s66, v253, 1
	v_and_or_b32 v14, v4, s46, v3
	v_bfe_u32 v3, v35, 16, 1
	v_add3_u32 v3, v35, v3, s45
	v_bfe_u32 v4, v37, 16, 1
	v_lshrrev_b32_e32 v3, 16, v3
	v_add3_u32 v4, v37, v4, s45
	v_and_or_b32 v15, v4, s46, v3
	v_bfe_u32 v3, v39, 16, 1
	v_add3_u32 v3, v39, v3, s45
	v_bfe_u32 v4, v41, 16, 1
	v_lshrrev_b32_e32 v3, 16, v3
	v_add3_u32 v4, v41, v4, s45
	v_and_or_b32 v16, v4, s46, v3
	v_bfe_u32 v3, v43, 16, 1
	v_add3_u32 v3, v43, v3, s45
	v_bfe_u32 v4, v45, 16, 1
	v_lshrrev_b32_e32 v3, 16, v3
	v_add3_u32 v4, v45, v4, s45
	v_and_or_b32 v17, v4, s46, v3
	v_or_b32_e32 v3, v13, v23
	v_mul_u32_u24_e32 v3, 0x1600, v3
	v_lshlrev_b32_e32 v4, 1, v3
	v_lshl_add_u64 v[32:33], v[30:31], 0, v[4:5]
	global_store_dwordx4 v[32:33], v[14:17], off sc1
	ds_read2_b32 v[32:33], v22 offset0:49 offset1:57
	ds_read2_b32 v[34:35], v22 offset0:82 offset1:90
	ds_read2_b32 v[36:37], v22 offset0:115 offset1:123
	s_waitcnt lgkmcnt(3)
	v_bfe_u32 v3, v18, 16, 1
	v_add3_u32 v3, v18, v3, s45
	s_waitcnt lgkmcnt(2)
	v_bfe_u32 v4, v32, 16, 1
	ds_read2_b32 v[38:39], v22 offset0:148 offset1:156
	v_lshrrev_b32_e32 v3, 16, v3
	v_add3_u32 v4, v32, v4, s45
	ds_read2_b32 v[40:41], v22 offset0:181 offset1:189
	v_and_or_b32 v14, v4, s46, v3
	s_waitcnt lgkmcnt(3)
	v_bfe_u32 v3, v34, 16, 1
	v_add3_u32 v3, v34, v3, s45
	s_waitcnt lgkmcnt(2)
	v_bfe_u32 v4, v36, 16, 1
	ds_read2_b32 v[42:43], v22 offset0:214 offset1:222
	v_lshrrev_b32_e32 v3, 16, v3
	v_add3_u32 v4, v36, v4, s45
	ds_read2_b32 v[44:45], v22 offset0:247 offset1:255
	v_and_or_b32 v15, v4, s46, v3
	s_waitcnt lgkmcnt(3)
	v_bfe_u32 v3, v38, 16, 1
	v_add3_u32 v3, v38, v3, s45
	s_waitcnt lgkmcnt(2)
	v_bfe_u32 v4, v40, 16, 1
	v_lshrrev_b32_e32 v3, 16, v3
	v_add3_u32 v4, v40, v4, s45
	v_and_or_b32 v16, v4, s46, v3
	s_waitcnt lgkmcnt(1)
	v_bfe_u32 v3, v42, 16, 1
	v_add3_u32 v3, v42, v3, s45
	s_waitcnt lgkmcnt(0)
	v_bfe_u32 v4, v44, 16, 1
	v_lshrrev_b32_e32 v3, 16, v3
	v_add3_u32 v4, v44, v4, s45
	v_and_or_b32 v17, v4, s46, v3
	v_or_b32_e32 v3, v13, v24
	v_mul_u32_u24_e32 v3, 0x1600, v3
	v_lshlrev_b32_e32 v4, 1, v3
	v_bfe_u32 v3, v19, 16, 1
	v_lshl_add_u64 v[46:47], v[30:31], 0, v[4:5]
	v_add3_u32 v3, v19, v3, s45
	v_bfe_u32 v4, v33, 16, 1
	v_lshrrev_b32_e32 v3, 16, v3
	v_add3_u32 v4, v33, v4, s45
	global_store_dwordx4 v[46:47], v[14:17], off sc1
	s_nop 1
	v_and_or_b32 v14, v4, s46, v3
	v_bfe_u32 v3, v35, 16, 1
	v_add3_u32 v3, v35, v3, s45
	v_bfe_u32 v4, v37, 16, 1
	v_lshrrev_b32_e32 v3, 16, v3
	v_add3_u32 v4, v37, v4, s45
	v_and_or_b32 v15, v4, s46, v3
	v_bfe_u32 v3, v39, 16, 1
	v_add3_u32 v3, v39, v3, s45
	v_bfe_u32 v4, v41, 16, 1
	v_lshrrev_b32_e32 v3, 16, v3
	v_add3_u32 v4, v41, v4, s45
	v_and_or_b32 v16, v4, s46, v3
	v_bfe_u32 v3, v43, 16, 1
	v_add3_u32 v3, v43, v3, s45
	v_bfe_u32 v4, v45, 16, 1
	v_lshrrev_b32_e32 v3, 16, v3
	v_add3_u32 v4, v45, v4, s45
	v_and_or_b32 v17, v4, s46, v3
	v_or_b32_e32 v3, v13, v25
	v_mul_u32_u24_e32 v3, 0x1600, v3
	v_lshlrev_b32_e32 v4, 1, v3
	v_lshl_add_u64 v[12:13], v[30:31], 0, v[4:5]
	global_store_dwordx4 v[12:13], v[14:17], off sc1
	s_waitcnt lgkmcnt(0)

.LBB0_125:
	s_andn2_saveexec_b64 s[30:31], s[30:31]
	s_cbranch_execz .LBB0_129
	s_load_dwordx2 s[34:35], s[6:7], 0x98
	v_add_u16_e32 v3, 0xd1c0, v3
	v_mul_u32_u24_e32 v4, 0xba2f, v3
	v_lshrrev_b32_e32 v4, 23, v4
	v_mul_lo_u16_e32 v9, 0xb0, v4
	v_sub_u16_e32 v13, v3, v9
	s_waitcnt lgkmcnt(0)
	v_mov_b64_e32 v[16:17], s[34:35]
	v_mad_i64_i32 v[14:15], s[36:37], v12, s49, 0
	v_mad_i64_i32 v[16:17], s[34:35], v12, s49, v[16:17]
	v_lshlrev_b16_e32 v12, 6, v4
	v_lshlrev_b32_e32 v4, 7, v13
	v_lshl_add_u64 v[16:17], v[16:17], 0, v[4:5]
	v_mov_b32_e32 v9, v5
	v_lshlrev_b32_e32 v11, 5, v13
	v_lshl_add_u64 v[16:17], v[16:17], 0, v[8:9]
	v_mov_b32_e32 v3, v12
	s_mov_b32 s34, 1
	s_mov_b32 s35, 0
	s_mov_b32 s36, 32
	s_lshl_b32 s37, s34, 1
	s_lshl_b32 s58, s35, 1
	v_or_b32_e32 v104, s37, v1
	v_or_b32_e32 v109, s58, v2
	s_add_i32 s59, s37, 4
	s_add_i32 s60, s58, 4
	s_add_i32 s61, s37, 8
	s_add_i32 s62, s58, 8
	s_add_i32 s63, s37, 12
	s_add_i32 s64, s58, 12
	s_add_i32 s65, s37, 16
	s_add_i32 s66, s58, 16
	s_add_i32 s67, s37, 20
	s_add_i32 s68, s58, 20
	s_add_i32 s69, s37, 24
	s_add_i32 s70, s58, 24
	s_add_i32 s37, s37, 28
	s_add_i32 s58, s58, 28
	v_add_u32_e32 v129, v104, v3
	v_add_u32_e32 v118, v109, v12
	v_or_b32_e32 v160, s59, v1
	v_or_b32_e32 v161, s60, v2
	v_or_b32_e32 v162, s61, v1
	v_or_b32_e32 v163, s62, v2
	v_or_b32_e32 v164, s63, v1
	v_or_b32_e32 v165, s64, v2
	v_or_b32_e32 v166, s65, v1
	v_or_b32_e32 v167, s66, v2
	v_or_b32_e32 v168, s67, v1
	v_or_b32_e32 v169, s68, v2
	v_or_b32_e32 v170, s69, v1
	v_or_b32_e32 v171, s70, v2
	v_or_b32_e32 v172, s37, v1
	v_or_b32_e32 v173, s58, v2
	v_mad_u64_u32 v[118:119], s[58:59], v118, s51, v[16:17]
	v_mad_u64_u32 v[130:131], s[58:59], v129, s51, v[16:17]
	v_add_u32_e32 v129, v160, v3
	v_add_u32_e32 v132, v161, v12
	v_add_u32_e32 v138, v162, v3
	v_add_u32_e32 v136, v163, v12
	v_add_u32_e32 v142, v164, v3
	v_add_u32_e32 v140, v165, v12
	v_add_u32_e32 v146, v166, v3
	v_add_u32_e32 v144, v167, v12
	v_add_u32_e32 v150, v168, v3
	v_add_u32_e32 v148, v169, v12
	v_add_u32_e32 v154, v170, v3
	v_add_u32_e32 v152, v171, v12
	v_add_u32_e32 v158, v172, v3
	v_add_u32_e32 v156, v173, v12
	v_mad_u64_u32 v[132:133], s[58:59], v132, s51, v[16:17]
	v_mad_u64_u32 v[134:135], s[58:59], v129, s51, v[16:17]
	v_mad_u64_u32 v[136:137], s[58:59], v136, s51, v[16:17]
	v_mad_u64_u32 v[138:139], s[58:59], v138, s51, v[16:17]
	v_mad_u64_u32 v[140:141], s[58:59], v140, s51, v[16:17]
	v_mad_u64_u32 v[142:143], s[58:59], v142, s51, v[16:17]
	v_mad_u64_u32 v[144:145], s[58:59], v144, s51, v[16:17]
	v_mad_u64_u32 v[146:147], s[58:59], v146, s51, v[16:17]
	v_mad_u64_u32 v[148:149], s[58:59], v148, s51, v[16:17]
	v_mad_u64_u32 v[150:151], s[58:59], v150, s51, v[16:17]
	v_mad_u64_u32 v[152:153], s[58:59], v152, s51, v[16:17]
	v_mad_u64_u32 v[154:155], s[58:59], v154, s51, v[16:17]
	v_mad_u64_u32 v[156:157], s[58:59], v156, s51, v[16:17]
	v_mad_u64_u32 v[158:159], s[58:59], v158, s51, v[16:17]
	global_load_dword v129, v[118:119], off
	global_load_dword v174, v[130:131], off
	global_load_dword v175, v[132:133], off
	global_load_dword v176, v[134:135], off
	global_load_dword v177, v[136:137], off
	global_load_dword v178, v[138:139], off
	global_load_dword v179, v[140:141], off
	global_load_dword v180, v[142:143], off
	global_load_dword v181, v[144:145], off
	global_load_dword v182, v[146:147], off
	global_load_dword v183, v[148:149], off
	global_load_dword v184, v[150:151], off
	global_load_dword v185, v[152:153], off
	global_load_dword v186, v[154:155], off
	global_load_dword v187, v[156:157], off
	global_load_dword v188, v[158:159], off
	s_add_i32 s35, s35, 16
	s_add_i32 s34, s34, 16
	s_add_i32 s36, s36, -16
	v_mad_u64_u32 v[118:119], s[58:59], v109, s33, v[6:7]
	v_mad_u64_u32 v[130:131], s[58:59], v104, s33, v[6:7]
	v_mad_u64_u32 v[132:133], s[58:59], v161, s33, v[6:7]
	v_mad_u64_u32 v[134:135], s[58:59], v160, s33, v[6:7]
	v_mad_u64_u32 v[136:137], s[58:59], v163, s33, v[6:7]
	v_mad_u64_u32 v[138:139], s[58:59], v162, s33, v[6:7]
	v_mad_u64_u32 v[140:141], s[58:59], v165, s33, v[6:7]
	v_mad_u64_u32 v[142:143], s[58:59], v164, s33, v[6:7]
	v_mad_u64_u32 v[144:145], s[58:59], v167, s33, v[6:7]
	v_mad_u64_u32 v[146:147], s[58:59], v166, s33, v[6:7]
	v_mad_u64_u32 v[148:149], s[58:59], v169, s33, v[6:7]
	v_mad_u64_u32 v[150:151], s[58:59], v168, s33, v[6:7]
	v_mad_u64_u32 v[152:153], s[58:59], v171, s33, v[6:7]
	v_mad_u64_u32 v[154:155], s[58:59], v170, s33, v[6:7]
	v_mad_u64_u32 v[156:157], s[58:59], v173, s33, v[6:7]
	v_mad_u64_u32 v[158:159], s[58:59], v172, s33, v[6:7]
	s_lshl_b32 s37, s34, 1
	s_lshl_b32 s58, s35, 1
	v_or_b32_e32 v4, s37, v1
	v_or_b32_e32 v9, s58, v2
	s_add_i32 s59, s37, 4
	s_add_i32 s60, s58, 4
	s_add_i32 s61, s37, 8
	s_add_i32 s62, s58, 8
	s_add_i32 s63, s37, 12
	s_add_i32 s64, s58, 12
	s_add_i32 s65, s37, 16
	s_add_i32 s66, s58, 16
	s_add_i32 s67, s37, 20
	s_add_i32 s68, s58, 20
	s_add_i32 s69, s37, 24
	s_add_i32 s70, s58, 24
	s_add_i32 s37, s37, 28
	s_add_i32 s58, s58, 28
	v_add_u32_e32 v29, v4, v3
	v_add_u32_e32 v18, v9, v12
	v_or_b32_e32 v60, s59, v1
	v_or_b32_e32 v61, s60, v2
	v_or_b32_e32 v62, s61, v1
	v_or_b32_e32 v63, s62, v2
	v_or_b32_e32 v64, s63, v1
	v_or_b32_e32 v65, s64, v2
	v_or_b32_e32 v66, s65, v1
	v_or_b32_e32 v67, s66, v2
	v_or_b32_e32 v68, s67, v1
	v_or_b32_e32 v69, s68, v2
	v_or_b32_e32 v70, s69, v1
	v_or_b32_e32 v71, s70, v2
	v_or_b32_e32 v72, s37, v1
	v_or_b32_e32 v73, s58, v2
	v_mad_u64_u32 v[18:19], s[58:59], v18, s51, v[16:17]
	v_mad_u64_u32 v[30:31], s[58:59], v29, s51, v[16:17]
	v_add_u32_e32 v29, v60, v3
	v_add_u32_e32 v32, v61, v12
	v_add_u32_e32 v38, v62, v3
	v_add_u32_e32 v36, v63, v12
	v_add_u32_e32 v42, v64, v3
	v_add_u32_e32 v40, v65, v12
	v_add_u32_e32 v46, v66, v3
	v_add_u32_e32 v44, v67, v12
	v_add_u32_e32 v50, v68, v3
	v_add_u32_e32 v48, v69, v12
	v_add_u32_e32 v54, v70, v3
	v_add_u32_e32 v52, v71, v12
	v_add_u32_e32 v58, v72, v3
	v_add_u32_e32 v56, v73, v12
	v_mad_u64_u32 v[32:33], s[58:59], v32, s51, v[16:17]
	v_mad_u64_u32 v[34:35], s[58:59], v29, s51, v[16:17]
	v_mad_u64_u32 v[36:37], s[58:59], v36, s51, v[16:17]
	v_mad_u64_u32 v[38:39], s[58:59], v38, s51, v[16:17]
	v_mad_u64_u32 v[40:41], s[58:59], v40, s51, v[16:17]
	v_mad_u64_u32 v[42:43], s[58:59], v42, s51, v[16:17]
	v_mad_u64_u32 v[44:45], s[58:59], v44, s51, v[16:17]
	v_mad_u64_u32 v[46:47], s[58:59], v46, s51, v[16:17]
	v_mad_u64_u32 v[48:49], s[58:59], v48, s51, v[16:17]
	v_mad_u64_u32 v[50:51], s[58:59], v50, s51, v[16:17]
	v_mad_u64_u32 v[52:53], s[58:59], v52, s51, v[16:17]
	v_mad_u64_u32 v[54:55], s[58:59], v54, s51, v[16:17]
	v_mad_u64_u32 v[56:57], s[58:59], v56, s51, v[16:17]
	v_mad_u64_u32 v[58:59], s[58:59], v58, s51, v[16:17]
	global_load_dword v29, v[18:19], off
	global_load_dword v74, v[30:31], off
	global_load_dword v75, v[32:33], off
	global_load_dword v76, v[34:35], off
	global_load_dword v77, v[36:37], off
	global_load_dword v78, v[38:39], off
	global_load_dword v79, v[40:41], off
	global_load_dword v80, v[42:43], off
	global_load_dword v81, v[44:45], off
	global_load_dword v82, v[46:47], off
	global_load_dword v83, v[48:49], off
	global_load_dword v84, v[50:51], off
	global_load_dword v85, v[52:53], off
	global_load_dword v86, v[54:55], off
	global_load_dword v87, v[56:57], off
	global_load_dword v88, v[58:59], off
	s_add_i32 s35, s35, 16
	s_add_i32 s34, s34, 16
	s_add_i32 s36, s36, -16
	v_mad_u64_u32 v[18:19], s[58:59], v9, s33, v[6:7]
	v_mad_u64_u32 v[30:31], s[58:59], v4, s33, v[6:7]
	v_mad_u64_u32 v[32:33], s[58:59], v61, s33, v[6:7]
	v_mad_u64_u32 v[34:35], s[58:59], v60, s33, v[6:7]
	v_mad_u64_u32 v[36:37], s[58:59], v63, s33, v[6:7]
	v_mad_u64_u32 v[38:39], s[58:59], v62, s33, v[6:7]
	v_mad_u64_u32 v[40:41], s[58:59], v65, s33, v[6:7]
	v_mad_u64_u32 v[42:43], s[58:59], v64, s33, v[6:7]
	v_mad_u64_u32 v[44:45], s[58:59], v67, s33, v[6:7]
	v_mad_u64_u32 v[46:47], s[58:59], v66, s33, v[6:7]
	v_mad_u64_u32 v[48:49], s[58:59], v69, s33, v[6:7]
	v_mad_u64_u32 v[50:51], s[58:59], v68, s33, v[6:7]
	v_mad_u64_u32 v[52:53], s[58:59], v71, s33, v[6:7]
	v_mad_u64_u32 v[54:55], s[58:59], v70, s33, v[6:7]
	v_mad_u64_u32 v[56:57], s[58:59], v73, s33, v[6:7]
	v_mad_u64_u32 v[58:59], s[58:59], v72, s33, v[6:7]
	s_waitcnt vmcnt(31)
	ds_write_b32 v118, v129
	s_waitcnt vmcnt(30)
	ds_write_b32 v130, v174
	s_waitcnt vmcnt(29)
	ds_write_b32 v132, v175
	s_waitcnt vmcnt(28)
	ds_write_b32 v134, v176
	s_waitcnt vmcnt(27)
	ds_write_b32 v136, v177
	s_waitcnt vmcnt(26)
	ds_write_b32 v138, v178
	s_waitcnt vmcnt(25)
	ds_write_b32 v140, v179
	s_waitcnt vmcnt(24)
	ds_write_b32 v142, v180
	s_waitcnt vmcnt(23)
	ds_write_b32 v144, v181
	s_waitcnt vmcnt(22)
	ds_write_b32 v146, v182
	s_waitcnt vmcnt(21)
	ds_write_b32 v148, v183
	s_waitcnt vmcnt(20)
	ds_write_b32 v150, v184
	s_waitcnt vmcnt(19)
	ds_write_b32 v152, v185
	s_waitcnt vmcnt(18)
	ds_write_b32 v154, v186
	s_waitcnt vmcnt(17)
	ds_write_b32 v156, v187
	s_waitcnt vmcnt(16)
	ds_write_b32 v158, v188
	s_waitcnt vmcnt(15)
	ds_write_b32 v18, v29
	s_waitcnt vmcnt(14)
	ds_write_b32 v30, v74
	s_waitcnt vmcnt(13)
	ds_write_b32 v32, v75
	s_waitcnt vmcnt(12)
	ds_write_b32 v34, v76
	s_waitcnt vmcnt(11)
	ds_write_b32 v36, v77
	s_waitcnt vmcnt(10)
	ds_write_b32 v38, v78
	s_waitcnt vmcnt(9)
	ds_write_b32 v40, v79
	s_waitcnt vmcnt(8)
	ds_write_b32 v42, v80
	s_waitcnt vmcnt(7)
	ds_write_b32 v44, v81
	s_waitcnt vmcnt(6)
	ds_write_b32 v46, v82
	s_waitcnt vmcnt(5)
	ds_write_b32 v48, v83
	s_waitcnt vmcnt(4)
	ds_write_b32 v50, v84
	s_waitcnt vmcnt(3)
	ds_write_b32 v52, v85
	s_waitcnt vmcnt(2)
	ds_write_b32 v54, v86
	s_waitcnt vmcnt(1)
	ds_write_b32 v56, v87
	s_waitcnt vmcnt(0)
	ds_write_b32 v58, v88
	s_waitcnt lgkmcnt(0)
	ds_read2_b32 v[16:17], v22 offset1:8
	ds_read2_b32 v[30:31], v22 offset0:33 offset1:41
	v_lshlrev_b32_e32 v3, 6, v13
	v_and_b32_e32 v3, 0x3f00, v3
	v_and_b32_e32 v4, 0x60, v11
	ds_read2_b32 v[32:33], v22 offset0:66 offset1:74
	v_lshl_add_u64 v[14:15], s[14:15], 0, v[14:15]
	v_or3_b32 v3, v3, v4, s53
	v_lshlrev_b32_e32 v4, 1, v12
	ds_read2_b32 v[34:35], v22 offset0:99 offset1:107
	v_lshl_add_u64 v[12:13], v[14:15], 0, v[4:5]
	s_waitcnt lgkmcnt(3)
	v_bfe_u32 v4, v16, 16, 1
	v_add3_u32 v4, v16, v4, s45
	s_waitcnt lgkmcnt(2)
	v_bfe_u32 v9, v30, 16, 1
	ds_read2_b32 v[36:37], v22 offset0:132 offset1:140
	v_mov_b32_e32 v11, v5
	v_lshrrev_b32_e32 v4, 16, v4
	v_add3_u32 v9, v30, v9, s45
	ds_read2_b32 v[38:39], v22 offset0:165 offset1:173
	v_lshl_add_u64 v[18:19], v[12:13], 0, v[10:11]
	v_and_or_b32 v12, v9, s46, v4
	s_waitcnt lgkmcnt(3)
	v_bfe_u32 v4, v32, 16, 1
	v_add3_u32 v4, v32, v4, s45
	s_waitcnt lgkmcnt(2)
	v_bfe_u32 v9, v34, 16, 1
	ds_read2_b32 v[40:41], v22 offset0:198 offset1:206
	v_lshrrev_b32_e32 v4, 16, v4
	v_add3_u32 v9, v34, v9, s45
	ds_read2_b32 v[42:43], v22 offset0:231 offset1:239
	v_and_or_b32 v13, v9, s46, v4
	s_waitcnt lgkmcnt(3)
	v_bfe_u32 v4, v36, 16, 1
	v_add3_u32 v4, v36, v4, s45
	s_waitcnt lgkmcnt(2)
	v_bfe_u32 v9, v38, 16, 1
	v_lshrrev_b32_e32 v4, 16, v4
	v_add3_u32 v9, v38, v9, s45
	v_and_or_b32 v14, v9, s46, v4
	s_waitcnt lgkmcnt(1)
	v_bfe_u32 v4, v40, 16, 1
	v_add3_u32 v4, v40, v4, s45
	s_waitcnt lgkmcnt(0)
	v_bfe_u32 v9, v42, 16, 1
	v_lshrrev_b32_e32 v4, 16, v4
	v_add3_u32 v9, v42, v9, s45
	v_and_or_b32 v15, v9, s46, v4
	v_or_b32_e32 v4, v3, v21
	v_lshlrev_b32_e32 v4, 12, v4
	v_lshl_add_u64 v[44:45], v[18:19], 0, v[4:5]
	v_bfe_u32 v4, v17, 16, 1
	v_add3_u32 v4, v17, v4, s45
	v_bfe_u32 v9, v31, 16, 1
	v_lshrrev_b32_e32 v4, 16, v4
	v_add3_u32 v9, v31, v9, s45
	global_store_dwordx4 v[44:45], v[12:15], off sc1
	ds_read2_b32 v[16:17], v22 offset0:16 offset1:24
	v_readlane_b32 s66, v253, 1
	v_and_or_b32 v12, v9, s46, v4
	v_bfe_u32 v4, v33, 16, 1
	v_add3_u32 v4, v33, v4, s45
	v_bfe_u32 v9, v35, 16, 1
	v_lshrrev_b32_e32 v4, 16, v4
	v_add3_u32 v9, v35, v9, s45
	v_and_or_b32 v13, v9, s46, v4
	v_bfe_u32 v4, v37, 16, 1
	v_add3_u32 v4, v37, v4, s45
	v_bfe_u32 v9, v39, 16, 1
	v_lshrrev_b32_e32 v4, 16, v4
	v_add3_u32 v9, v39, v9, s45
	v_and_or_b32 v14, v9, s46, v4
	v_bfe_u32 v4, v41, 16, 1
	v_add3_u32 v4, v41, v4, s45
	v_bfe_u32 v9, v43, 16, 1
	v_lshrrev_b32_e32 v4, 16, v4
	v_add3_u32 v9, v43, v9, s45
	v_and_or_b32 v15, v9, s46, v4
	v_or_b32_e32 v4, v3, v23
	v_lshlrev_b32_e32 v4, 12, v4
	v_lshl_add_u64 v[30:31], v[18:19], 0, v[4:5]
	global_store_dwordx4 v[30:31], v[12:15], off sc1
	ds_read2_b32 v[30:31], v22 offset0:49 offset1:57
	ds_read2_b32 v[32:33], v22 offset0:82 offset1:90
	ds_read2_b32 v[34:35], v22 offset0:115 offset1:123
	s_waitcnt lgkmcnt(3)
	v_bfe_u32 v4, v16, 16, 1
	v_add3_u32 v4, v16, v4, s45
	s_waitcnt lgkmcnt(2)
	v_bfe_u32 v9, v30, 16, 1
	ds_read2_b32 v[36:37], v22 offset0:148 offset1:156
	v_lshrrev_b32_e32 v4, 16, v4
	v_add3_u32 v9, v30, v9, s45
	ds_read2_b32 v[38:39], v22 offset0:181 offset1:189
	v_and_or_b32 v12, v9, s46, v4
	s_waitcnt lgkmcnt(3)
	v_bfe_u32 v4, v32, 16, 1
	v_add3_u32 v4, v32, v4, s45
	s_waitcnt lgkmcnt(2)
	v_bfe_u32 v9, v34, 16, 1
	ds_read2_b32 v[40:41], v22 offset0:214 offset1:222
	v_lshrrev_b32_e32 v4, 16, v4
	v_add3_u32 v9, v34, v9, s45
	ds_read2_b32 v[42:43], v22 offset0:247 offset1:255
	v_and_or_b32 v13, v9, s46, v4
	s_waitcnt lgkmcnt(3)
	v_bfe_u32 v4, v36, 16, 1
	v_add3_u32 v4, v36, v4, s45
	s_waitcnt lgkmcnt(2)
	v_bfe_u32 v9, v38, 16, 1
	v_lshrrev_b32_e32 v4, 16, v4
	v_add3_u32 v9, v38, v9, s45
	v_and_or_b32 v14, v9, s46, v4
	s_waitcnt lgkmcnt(1)
	v_bfe_u32 v4, v40, 16, 1
	v_add3_u32 v4, v40, v4, s45
	s_waitcnt lgkmcnt(0)
	v_bfe_u32 v9, v42, 16, 1
	v_lshrrev_b32_e32 v4, 16, v4
	v_add3_u32 v9, v42, v9, s45
	v_and_or_b32 v15, v9, s46, v4
	v_or_b32_e32 v4, v3, v24
	v_lshlrev_b32_e32 v4, 12, v4
	v_lshl_add_u64 v[44:45], v[18:19], 0, v[4:5]
	v_bfe_u32 v4, v17, 16, 1
	v_add3_u32 v4, v17, v4, s45
	v_bfe_u32 v9, v31, 16, 1
	v_lshrrev_b32_e32 v4, 16, v4
	v_add3_u32 v9, v31, v9, s45
	global_store_dwordx4 v[44:45], v[12:15], off sc1
	v_or_b32_e32 v3, v3, v25
	s_nop 0
	v_and_or_b32 v12, v9, s46, v4
	v_bfe_u32 v4, v33, 16, 1
	v_add3_u32 v4, v33, v4, s45
	v_bfe_u32 v9, v35, 16, 1
	v_lshrrev_b32_e32 v4, 16, v4
	v_add3_u32 v9, v35, v9, s45
	v_and_or_b32 v13, v9, s46, v4
	v_bfe_u32 v4, v37, 16, 1
	v_add3_u32 v4, v37, v4, s45
	v_bfe_u32 v9, v39, 16, 1
	v_lshrrev_b32_e32 v4, 16, v4
	v_add3_u32 v9, v39, v9, s45
	v_and_or_b32 v14, v9, s46, v4
	v_bfe_u32 v4, v41, 16, 1
	v_add3_u32 v4, v41, v4, s45
	v_bfe_u32 v9, v43, 16, 1
	v_lshrrev_b32_e32 v4, 16, v4
	v_add3_u32 v9, v43, v9, s45
	v_and_or_b32 v15, v9, s46, v4
	v_lshlrev_b32_e32 v4, 12, v3
	v_lshl_add_u64 v[16:17], v[18:19], 0, v[4:5]
	global_store_dwordx4 v[16:17], v[12:15], off sc1
	s_waitcnt lgkmcnt(0)

.LBB0_130:
	s_andn2_saveexec_b64 s[28:29], s[28:29]
	s_cbranch_execz .LBB0_134
	s_load_dwordx2 s[30:31], s[6:7], 0x90
	v_add_u16_e32 v3, 0xe7c0, v3
	v_mul_u32_u24_e32 v4, 0xba2f, v3
	v_lshrrev_b32_e32 v4, 23, v4
	v_mul_lo_u16_e32 v9, 0xb0, v4
	v_sub_u16_e32 v11, v3, v9
	s_waitcnt lgkmcnt(0)
	v_mov_b64_e32 v[16:17], s[30:31]
	v_mad_i64_i32 v[14:15], s[34:35], v12, s49, 0
	v_mad_i64_i32 v[16:17], s[30:31], v12, s49, v[16:17]
	v_lshlrev_b16_e32 v12, 6, v4
	v_lshlrev_b32_e32 v4, 7, v11
	v_lshl_add_u64 v[16:17], v[16:17], 0, v[4:5]
	v_mov_b32_e32 v9, v5
	v_lshlrev_b32_e32 v13, 5, v11
	v_lshl_add_u64 v[16:17], v[16:17], 0, v[8:9]
	v_mov_b32_e32 v3, v12
	s_mov_b32 s30, 1
	s_mov_b32 s31, 0
	s_mov_b32 s34, 32
	s_lshl_b32 s35, s30, 1
	s_lshl_b32 s36, s31, 1
	v_or_b32_e32 v104, s35, v1
	v_or_b32_e32 v109, s36, v2
	s_add_i32 s37, s35, 4
	s_add_i32 s58, s36, 4
	s_add_i32 s59, s35, 8
	s_add_i32 s60, s36, 8
	s_add_i32 s61, s35, 12
	s_add_i32 s62, s36, 12
	s_add_i32 s63, s35, 16
	s_add_i32 s64, s36, 16
	s_add_i32 s65, s35, 20
	s_add_i32 s66, s36, 20
	s_add_i32 s67, s35, 24
	s_add_i32 s68, s36, 24
	s_add_i32 s35, s35, 28
	s_add_i32 s36, s36, 28
	v_add_u32_e32 v129, v104, v3
	v_add_u32_e32 v118, v109, v12
	v_or_b32_e32 v160, s37, v1
	v_or_b32_e32 v161, s58, v2
	v_or_b32_e32 v162, s59, v1
	v_or_b32_e32 v163, s60, v2
	v_or_b32_e32 v164, s61, v1
	v_or_b32_e32 v165, s62, v2
	v_or_b32_e32 v166, s63, v1
	v_or_b32_e32 v167, s64, v2
	v_or_b32_e32 v168, s65, v1
	v_or_b32_e32 v169, s66, v2
	v_or_b32_e32 v170, s67, v1
	v_or_b32_e32 v171, s68, v2
	v_or_b32_e32 v172, s35, v1
	v_or_b32_e32 v173, s36, v2
	v_mad_u64_u32 v[118:119], s[36:37], v118, s51, v[16:17]
	v_mad_u64_u32 v[130:131], s[36:37], v129, s51, v[16:17]
	v_add_u32_e32 v129, v160, v3
	v_add_u32_e32 v132, v161, v12
	v_add_u32_e32 v138, v162, v3
	v_add_u32_e32 v136, v163, v12
	v_add_u32_e32 v142, v164, v3
	v_add_u32_e32 v140, v165, v12
	v_add_u32_e32 v146, v166, v3
	v_add_u32_e32 v144, v167, v12
	v_add_u32_e32 v150, v168, v3
	v_add_u32_e32 v148, v169, v12
	v_add_u32_e32 v154, v170, v3
	v_add_u32_e32 v152, v171, v12
	v_add_u32_e32 v158, v172, v3
	v_add_u32_e32 v156, v173, v12
	v_mad_u64_u32 v[132:133], s[36:37], v132, s51, v[16:17]
	v_mad_u64_u32 v[134:135], s[36:37], v129, s51, v[16:17]
	v_mad_u64_u32 v[136:137], s[36:37], v136, s51, v[16:17]
	v_mad_u64_u32 v[138:139], s[36:37], v138, s51, v[16:17]
	v_mad_u64_u32 v[140:141], s[36:37], v140, s51, v[16:17]
	v_mad_u64_u32 v[142:143], s[36:37], v142, s51, v[16:17]
	v_mad_u64_u32 v[144:145], s[36:37], v144, s51, v[16:17]
	v_mad_u64_u32 v[146:147], s[36:37], v146, s51, v[16:17]
	v_mad_u64_u32 v[148:149], s[36:37], v148, s51, v[16:17]
	v_mad_u64_u32 v[150:151], s[36:37], v150, s51, v[16:17]
	v_mad_u64_u32 v[152:153], s[36:37], v152, s51, v[16:17]
	v_mad_u64_u32 v[154:155], s[36:37], v154, s51, v[16:17]
	v_mad_u64_u32 v[156:157], s[36:37], v156, s51, v[16:17]
	v_mad_u64_u32 v[158:159], s[36:37], v158, s51, v[16:17]
	global_load_dword v129, v[118:119], off
	global_load_dword v174, v[130:131], off
	global_load_dword v175, v[132:133], off
	global_load_dword v176, v[134:135], off
	global_load_dword v177, v[136:137], off
	global_load_dword v178, v[138:139], off
	global_load_dword v179, v[140:141], off
	global_load_dword v180, v[142:143], off
	global_load_dword v181, v[144:145], off
	global_load_dword v182, v[146:147], off
	global_load_dword v183, v[148:149], off
	global_load_dword v184, v[150:151], off
	global_load_dword v185, v[152:153], off
	global_load_dword v186, v[154:155], off
	global_load_dword v187, v[156:157], off
	global_load_dword v188, v[158:159], off
	s_add_i32 s31, s31, 16
	s_add_i32 s30, s30, 16
	s_add_i32 s34, s34, -16
	v_mad_u64_u32 v[118:119], s[36:37], v109, s33, v[6:7]
	v_mad_u64_u32 v[130:131], s[36:37], v104, s33, v[6:7]
	v_mad_u64_u32 v[132:133], s[36:37], v161, s33, v[6:7]
	v_mad_u64_u32 v[134:135], s[36:37], v160, s33, v[6:7]
	v_mad_u64_u32 v[136:137], s[36:37], v163, s33, v[6:7]
	v_mad_u64_u32 v[138:139], s[36:37], v162, s33, v[6:7]
	v_mad_u64_u32 v[140:141], s[36:37], v165, s33, v[6:7]
	v_mad_u64_u32 v[142:143], s[36:37], v164, s33, v[6:7]
	v_mad_u64_u32 v[144:145], s[36:37], v167, s33, v[6:7]
	v_mad_u64_u32 v[146:147], s[36:37], v166, s33, v[6:7]
	v_mad_u64_u32 v[148:149], s[36:37], v169, s33, v[6:7]
	v_mad_u64_u32 v[150:151], s[36:37], v168, s33, v[6:7]
	v_mad_u64_u32 v[152:153], s[36:37], v171, s33, v[6:7]
	v_mad_u64_u32 v[154:155], s[36:37], v170, s33, v[6:7]
	v_mad_u64_u32 v[156:157], s[36:37], v173, s33, v[6:7]
	v_mad_u64_u32 v[158:159], s[36:37], v172, s33, v[6:7]
	s_lshl_b32 s35, s30, 1
	s_lshl_b32 s36, s31, 1
	v_or_b32_e32 v4, s35, v1
	v_or_b32_e32 v9, s36, v2
	s_add_i32 s37, s35, 4
	s_add_i32 s58, s36, 4
	s_add_i32 s59, s35, 8
	s_add_i32 s60, s36, 8
	s_add_i32 s61, s35, 12
	s_add_i32 s62, s36, 12
	s_add_i32 s63, s35, 16
	s_add_i32 s64, s36, 16
	s_add_i32 s65, s35, 20
	s_add_i32 s66, s36, 20
	s_add_i32 s67, s35, 24
	s_add_i32 s68, s36, 24
	s_add_i32 s35, s35, 28
	s_add_i32 s36, s36, 28
	v_add_u32_e32 v29, v4, v3
	v_add_u32_e32 v18, v9, v12
	v_or_b32_e32 v60, s37, v1
	v_or_b32_e32 v61, s58, v2
	v_or_b32_e32 v62, s59, v1
	v_or_b32_e32 v63, s60, v2
	v_or_b32_e32 v64, s61, v1
	v_or_b32_e32 v65, s62, v2
	v_or_b32_e32 v66, s63, v1
	v_or_b32_e32 v67, s64, v2
	v_or_b32_e32 v68, s65, v1
	v_or_b32_e32 v69, s66, v2
	v_or_b32_e32 v70, s67, v1
	v_or_b32_e32 v71, s68, v2
	v_or_b32_e32 v72, s35, v1
	v_or_b32_e32 v73, s36, v2
	v_mad_u64_u32 v[18:19], s[36:37], v18, s51, v[16:17]
	v_mad_u64_u32 v[30:31], s[36:37], v29, s51, v[16:17]
	v_add_u32_e32 v29, v60, v3
	v_add_u32_e32 v32, v61, v12
	v_add_u32_e32 v38, v62, v3
	v_add_u32_e32 v36, v63, v12
	v_add_u32_e32 v42, v64, v3
	v_add_u32_e32 v40, v65, v12
	v_add_u32_e32 v46, v66, v3
	v_add_u32_e32 v44, v67, v12
	v_add_u32_e32 v50, v68, v3
	v_add_u32_e32 v48, v69, v12
	v_add_u32_e32 v54, v70, v3
	v_add_u32_e32 v52, v71, v12
	v_add_u32_e32 v58, v72, v3
	v_add_u32_e32 v56, v73, v12
	v_mad_u64_u32 v[32:33], s[36:37], v32, s51, v[16:17]
	v_mad_u64_u32 v[34:35], s[36:37], v29, s51, v[16:17]
	v_mad_u64_u32 v[36:37], s[36:37], v36, s51, v[16:17]
	v_mad_u64_u32 v[38:39], s[36:37], v38, s51, v[16:17]
	v_mad_u64_u32 v[40:41], s[36:37], v40, s51, v[16:17]
	v_mad_u64_u32 v[42:43], s[36:37], v42, s51, v[16:17]
	v_mad_u64_u32 v[44:45], s[36:37], v44, s51, v[16:17]
	v_mad_u64_u32 v[46:47], s[36:37], v46, s51, v[16:17]
	v_mad_u64_u32 v[48:49], s[36:37], v48, s51, v[16:17]
	v_mad_u64_u32 v[50:51], s[36:37], v50, s51, v[16:17]
	v_mad_u64_u32 v[52:53], s[36:37], v52, s51, v[16:17]
	v_mad_u64_u32 v[54:55], s[36:37], v54, s51, v[16:17]
	v_mad_u64_u32 v[56:57], s[36:37], v56, s51, v[16:17]
	v_mad_u64_u32 v[58:59], s[36:37], v58, s51, v[16:17]
	global_load_dword v29, v[18:19], off
	global_load_dword v74, v[30:31], off
	global_load_dword v75, v[32:33], off
	global_load_dword v76, v[34:35], off
	global_load_dword v77, v[36:37], off
	global_load_dword v78, v[38:39], off
	global_load_dword v79, v[40:41], off
	global_load_dword v80, v[42:43], off
	global_load_dword v81, v[44:45], off
	global_load_dword v82, v[46:47], off
	global_load_dword v83, v[48:49], off
	global_load_dword v84, v[50:51], off
	global_load_dword v85, v[52:53], off
	global_load_dword v86, v[54:55], off
	global_load_dword v87, v[56:57], off
	global_load_dword v88, v[58:59], off
	s_add_i32 s31, s31, 16
	s_add_i32 s30, s30, 16
	s_add_i32 s34, s34, -16
	v_mad_u64_u32 v[18:19], s[36:37], v9, s33, v[6:7]
	v_mad_u64_u32 v[30:31], s[36:37], v4, s33, v[6:7]
	v_mad_u64_u32 v[32:33], s[36:37], v61, s33, v[6:7]
	v_mad_u64_u32 v[34:35], s[36:37], v60, s33, v[6:7]
	v_mad_u64_u32 v[36:37], s[36:37], v63, s33, v[6:7]
	v_mad_u64_u32 v[38:39], s[36:37], v62, s33, v[6:7]
	v_mad_u64_u32 v[40:41], s[36:37], v65, s33, v[6:7]
	v_mad_u64_u32 v[42:43], s[36:37], v64, s33, v[6:7]
	v_mad_u64_u32 v[44:45], s[36:37], v67, s33, v[6:7]
	v_mad_u64_u32 v[46:47], s[36:37], v66, s33, v[6:7]
	v_mad_u64_u32 v[48:49], s[36:37], v69, s33, v[6:7]
	v_mad_u64_u32 v[50:51], s[36:37], v68, s33, v[6:7]
	v_mad_u64_u32 v[52:53], s[36:37], v71, s33, v[6:7]
	v_mad_u64_u32 v[54:55], s[36:37], v70, s33, v[6:7]
	v_mad_u64_u32 v[56:57], s[36:37], v73, s33, v[6:7]
	v_mad_u64_u32 v[58:59], s[36:37], v72, s33, v[6:7]
	s_waitcnt vmcnt(31)
	ds_write_b32 v118, v129
	s_waitcnt vmcnt(30)
	ds_write_b32 v130, v174
	s_waitcnt vmcnt(29)
	ds_write_b32 v132, v175
	s_waitcnt vmcnt(28)
	ds_write_b32 v134, v176
	s_waitcnt vmcnt(27)
	ds_write_b32 v136, v177
	s_waitcnt vmcnt(26)
	ds_write_b32 v138, v178
	s_waitcnt vmcnt(25)
	ds_write_b32 v140, v179
	s_waitcnt vmcnt(24)
	ds_write_b32 v142, v180
	s_waitcnt vmcnt(23)
	ds_write_b32 v144, v181
	s_waitcnt vmcnt(22)
	ds_write_b32 v146, v182
	s_waitcnt vmcnt(21)
	ds_write_b32 v148, v183
	s_waitcnt vmcnt(20)
	ds_write_b32 v150, v184
	s_waitcnt vmcnt(19)
	ds_write_b32 v152, v185
	s_waitcnt vmcnt(18)
	ds_write_b32 v154, v186
	s_waitcnt vmcnt(17)
	ds_write_b32 v156, v187
	s_waitcnt vmcnt(16)
	ds_write_b32 v158, v188
	s_waitcnt vmcnt(15)
	ds_write_b32 v18, v29
	s_waitcnt vmcnt(14)
	ds_write_b32 v30, v74
	s_waitcnt vmcnt(13)
	ds_write_b32 v32, v75
	s_waitcnt vmcnt(12)
	ds_write_b32 v34, v76
	s_waitcnt vmcnt(11)
	ds_write_b32 v36, v77
	s_waitcnt vmcnt(10)
	ds_write_b32 v38, v78
	s_waitcnt vmcnt(9)
	ds_write_b32 v40, v79
	s_waitcnt vmcnt(8)
	ds_write_b32 v42, v80
	s_waitcnt vmcnt(7)
	ds_write_b32 v44, v81
	s_waitcnt vmcnt(6)
	ds_write_b32 v46, v82
	s_waitcnt vmcnt(5)
	ds_write_b32 v48, v83
	s_waitcnt vmcnt(4)
	ds_write_b32 v50, v84
	s_waitcnt vmcnt(3)
	ds_write_b32 v52, v85
	s_waitcnt vmcnt(2)
	ds_write_b32 v54, v86
	s_waitcnt vmcnt(1)
	ds_write_b32 v56, v87
	s_waitcnt vmcnt(0)
	ds_write_b32 v58, v88
	s_waitcnt lgkmcnt(0)
	ds_read2_b32 v[16:17], v22 offset1:8
	ds_read2_b32 v[30:31], v22 offset0:33 offset1:41
	v_lshlrev_b32_e32 v3, 6, v11
	v_and_b32_e32 v4, 0x60, v13
	ds_read2_b32 v[32:33], v22 offset0:66 offset1:74
	v_lshl_add_u64 v[14:15], s[14:15], 0, v[14:15]
	v_and_or_b32 v3, v3, s52, v4
	v_lshlrev_b32_e32 v4, 1, v12
	ds_read2_b32 v[34:35], v22 offset0:99 offset1:107
	v_lshl_add_u64 v[12:13], v[14:15], 0, v[4:5]
	s_waitcnt lgkmcnt(3)
	v_bfe_u32 v4, v16, 16, 1
	v_add3_u32 v4, v16, v4, s45
	s_waitcnt lgkmcnt(2)
	v_bfe_u32 v9, v30, 16, 1
	ds_read2_b32 v[36:37], v22 offset0:132 offset1:140
	v_mov_b32_e32 v11, v5
	v_lshrrev_b32_e32 v4, 16, v4
	v_add3_u32 v9, v30, v9, s45
	ds_read2_b32 v[38:39], v22 offset0:165 offset1:173
	v_lshl_add_u64 v[18:19], v[12:13], 0, v[10:11]
	v_and_or_b32 v12, v9, s46, v4
	s_waitcnt lgkmcnt(3)
	v_bfe_u32 v4, v32, 16, 1
	v_add3_u32 v4, v32, v4, s45
	s_waitcnt lgkmcnt(2)
	v_bfe_u32 v9, v34, 16, 1
	ds_read2_b32 v[40:41], v22 offset0:198 offset1:206
	v_lshrrev_b32_e32 v4, 16, v4
	v_add3_u32 v9, v34, v9, s45
	ds_read2_b32 v[42:43], v22 offset0:231 offset1:239
	v_and_or_b32 v13, v9, s46, v4
	s_waitcnt lgkmcnt(3)
	v_bfe_u32 v4, v36, 16, 1
	v_add3_u32 v4, v36, v4, s45
	s_waitcnt lgkmcnt(2)
	v_bfe_u32 v9, v38, 16, 1
	v_lshrrev_b32_e32 v4, 16, v4
	v_add3_u32 v9, v38, v9, s45
	v_and_or_b32 v14, v9, s46, v4
	s_waitcnt lgkmcnt(1)
	v_bfe_u32 v4, v40, 16, 1
	v_add3_u32 v4, v40, v4, s45
	s_waitcnt lgkmcnt(0)
	v_bfe_u32 v9, v42, 16, 1
	v_lshrrev_b32_e32 v4, 16, v4
	v_add3_u32 v9, v42, v9, s45
	v_and_or_b32 v15, v9, s46, v4
	v_or_b32_e32 v4, v3, v21
	v_lshlrev_b32_e32 v4, 12, v4
	v_lshl_add_u64 v[44:45], v[18:19], 0, v[4:5]
	v_bfe_u32 v4, v17, 16, 1
	v_add3_u32 v4, v17, v4, s45
	v_bfe_u32 v9, v31, 16, 1
	v_lshrrev_b32_e32 v4, 16, v4
	v_add3_u32 v9, v31, v9, s45
	global_store_dwordx4 v[44:45], v[12:15], off sc1
	ds_read2_b32 v[16:17], v22 offset0:16 offset1:24
	v_readlane_b32 s66, v253, 1
	v_and_or_b32 v12, v9, s46, v4
	v_bfe_u32 v4, v33, 16, 1
	v_add3_u32 v4, v33, v4, s45
	v_bfe_u32 v9, v35, 16, 1
	v_lshrrev_b32_e32 v4, 16, v4
	v_add3_u32 v9, v35, v9, s45
	v_and_or_b32 v13, v9, s46, v4
	v_bfe_u32 v4, v37, 16, 1
	v_add3_u32 v4, v37, v4, s45
	v_bfe_u32 v9, v39, 16, 1
	v_lshrrev_b32_e32 v4, 16, v4
	v_add3_u32 v9, v39, v9, s45
	v_and_or_b32 v14, v9, s46, v4
	v_bfe_u32 v4, v41, 16, 1
	v_add3_u32 v4, v41, v4, s45
	v_bfe_u32 v9, v43, 16, 1
	v_lshrrev_b32_e32 v4, 16, v4
	v_add3_u32 v9, v43, v9, s45
	v_and_or_b32 v15, v9, s46, v4
	v_or_b32_e32 v4, v3, v23
	v_lshlrev_b32_e32 v4, 12, v4
	v_lshl_add_u64 v[30:31], v[18:19], 0, v[4:5]
	global_store_dwordx4 v[30:31], v[12:15], off sc1
	ds_read2_b32 v[30:31], v22 offset0:49 offset1:57
	ds_read2_b32 v[32:33], v22 offset0:82 offset1:90
	ds_read2_b32 v[34:35], v22 offset0:115 offset1:123
	s_waitcnt lgkmcnt(3)
	v_bfe_u32 v4, v16, 16, 1
	v_add3_u32 v4, v16, v4, s45
	s_waitcnt lgkmcnt(2)
	v_bfe_u32 v9, v30, 16, 1
	ds_read2_b32 v[36:37], v22 offset0:148 offset1:156
	v_lshrrev_b32_e32 v4, 16, v4
	v_add3_u32 v9, v30, v9, s45
	ds_read2_b32 v[38:39], v22 offset0:181 offset1:189
	v_and_or_b32 v12, v9, s46, v4
	s_waitcnt lgkmcnt(3)
	v_bfe_u32 v4, v32, 16, 1
	v_add3_u32 v4, v32, v4, s45
	s_waitcnt lgkmcnt(2)
	v_bfe_u32 v9, v34, 16, 1
	ds_read2_b32 v[40:41], v22 offset0:214 offset1:222
	v_lshrrev_b32_e32 v4, 16, v4
	v_add3_u32 v9, v34, v9, s45
	ds_read2_b32 v[42:43], v22 offset0:247 offset1:255
	v_and_or_b32 v13, v9, s46, v4
	s_waitcnt lgkmcnt(3)
	v_bfe_u32 v4, v36, 16, 1
	v_add3_u32 v4, v36, v4, s45
	s_waitcnt lgkmcnt(2)
	v_bfe_u32 v9, v38, 16, 1
	v_lshrrev_b32_e32 v4, 16, v4
	v_add3_u32 v9, v38, v9, s45
	v_and_or_b32 v14, v9, s46, v4
	s_waitcnt lgkmcnt(1)
	v_bfe_u32 v4, v40, 16, 1
	v_add3_u32 v4, v40, v4, s45
	s_waitcnt lgkmcnt(0)
	v_bfe_u32 v9, v42, 16, 1
	v_lshrrev_b32_e32 v4, 16, v4
	v_add3_u32 v9, v42, v9, s45
	v_and_or_b32 v15, v9, s46, v4
	v_or_b32_e32 v4, v3, v24
	v_lshlrev_b32_e32 v4, 12, v4
	v_lshl_add_u64 v[44:45], v[18:19], 0, v[4:5]
	v_bfe_u32 v4, v17, 16, 1
	v_add3_u32 v4, v17, v4, s45
	v_bfe_u32 v9, v31, 16, 1
	v_lshrrev_b32_e32 v4, 16, v4
	v_add3_u32 v9, v31, v9, s45
	global_store_dwordx4 v[44:45], v[12:15], off sc1
	v_or_b32_e32 v3, v3, v25
	s_nop 0
	v_and_or_b32 v12, v9, s46, v4
	v_bfe_u32 v4, v33, 16, 1
	v_add3_u32 v4, v33, v4, s45
	v_bfe_u32 v9, v35, 16, 1
	v_lshrrev_b32_e32 v4, 16, v4
	v_add3_u32 v9, v35, v9, s45
	v_and_or_b32 v13, v9, s46, v4
	v_bfe_u32 v4, v37, 16, 1
	v_add3_u32 v4, v37, v4, s45
	v_bfe_u32 v9, v39, 16, 1
	v_lshrrev_b32_e32 v4, 16, v4
	v_add3_u32 v9, v39, v9, s45
	v_and_or_b32 v14, v9, s46, v4
	v_bfe_u32 v4, v41, 16, 1
	v_add3_u32 v4, v41, v4, s45
	v_bfe_u32 v9, v43, 16, 1
	v_lshrrev_b32_e32 v4, 16, v4
	v_add3_u32 v9, v43, v9, s45
	v_and_or_b32 v15, v9, s46, v4
	v_lshlrev_b32_e32 v4, 12, v3
	v_lshl_add_u64 v[16:17], v[18:19], 0, v[4:5]
	global_store_dwordx4 v[16:17], v[12:15], off sc1
	s_waitcnt lgkmcnt(0)

.LBB0_135:
	s_andn2_saveexec_b64 s[26:27], s[26:27]
	s_cbranch_execz .LBB0_139
	s_load_dwordx2 s[28:29], s[6:7], 0x78
	v_and_b32_e32 v4, 0x1fc0, v3
	v_ashrrev_i32_e32 v13, 31, v12
	v_lshlrev_b32_e32 v3, 5, v3
	v_lshlrev_b64 v[16:17], 22, v[12:13]
	v_lshlrev_b64 v[12:13], 24, v[12:13]
	v_and_b32_e32 v18, 0x7e0, v3
	v_add_u32_e32 v14, 0xffffefc0, v4
	s_waitcnt lgkmcnt(0)
	v_lshl_add_u64 v[12:13], s[28:29], 0, v[12:13]
	v_lshlrev_b32_e32 v4, 2, v18
	v_lshl_add_u64 v[12:13], v[12:13], 0, v[4:5]
	v_mov_b32_e32 v9, v5
	v_lshl_add_u64 v[12:13], v[12:13], 0, v[8:9]
	v_mov_b32_e32 v3, v14
	s_mov_b32 s28, 1
	s_mov_b32 s29, 0
	s_mov_b32 s30, 32
	s_lshl_b32 s31, s28, 1
	s_lshl_b32 s34, s29, 1
	v_or_b32_e32 v104, s31, v1
	v_or_b32_e32 v109, s34, v2
	s_add_i32 s35, s31, 4
	s_add_i32 s36, s34, 4
	s_add_i32 s37, s31, 8
	s_add_i32 s58, s34, 8
	s_add_i32 s59, s31, 12
	s_add_i32 s60, s34, 12
	s_add_i32 s61, s31, 16
	s_add_i32 s62, s34, 16
	s_add_i32 s63, s31, 20
	s_add_i32 s64, s34, 20
	s_add_i32 s65, s31, 24
	s_add_i32 s66, s34, 24
	s_add_i32 s31, s31, 28
	s_add_i32 s34, s34, 28
	v_add_u32_e32 v132, v109, v14
	v_or_b32_e32 v111, s35, v1
	v_or_b32_e32 v115, s36, v2
	v_or_b32_e32 v119, s37, v1
	v_or_b32_e32 v129, s58, v2
	v_or_b32_e32 v162, s59, v1
	v_or_b32_e32 v163, s60, v2
	v_or_b32_e32 v164, s61, v1
	v_or_b32_e32 v165, s62, v2
	v_or_b32_e32 v166, s63, v1
	v_or_b32_e32 v167, s64, v2
	v_or_b32_e32 v168, s65, v1
	v_or_b32_e32 v169, s66, v2
	v_or_b32_e32 v170, s31, v1
	v_or_b32_e32 v171, s34, v2
	v_add_u32_e32 v130, v104, v3
	v_ashrrev_i32_e32 v133, 31, v132
	v_add_u32_e32 v134, v111, v3
	v_add_u32_e32 v136, v115, v14
	v_add_u32_e32 v138, v119, v3
	v_add_u32_e32 v140, v129, v14
	v_add_u32_e32 v142, v162, v3
	v_add_u32_e32 v144, v163, v14
	v_add_u32_e32 v146, v164, v3
	v_add_u32_e32 v148, v165, v14
	v_add_u32_e32 v150, v166, v3
	v_add_u32_e32 v152, v167, v14
	v_add_u32_e32 v154, v168, v3
	v_add_u32_e32 v156, v169, v14
	v_add_u32_e32 v158, v170, v3
	v_add_u32_e32 v160, v171, v14
	v_ashrrev_i32_e32 v131, 31, v130
	v_lshlrev_b64 v[132:133], 13, v[132:133]
	v_ashrrev_i32_e32 v137, 31, v136
	v_ashrrev_i32_e32 v135, 31, v134
	v_ashrrev_i32_e32 v141, 31, v140
	v_ashrrev_i32_e32 v139, 31, v138
	v_ashrrev_i32_e32 v145, 31, v144
	v_ashrrev_i32_e32 v143, 31, v142
	v_ashrrev_i32_e32 v149, 31, v148
	v_ashrrev_i32_e32 v147, 31, v146
	v_ashrrev_i32_e32 v153, 31, v152
	v_ashrrev_i32_e32 v151, 31, v150
	v_ashrrev_i32_e32 v157, 31, v156
	v_ashrrev_i32_e32 v155, 31, v154
	v_ashrrev_i32_e32 v161, 31, v160
	v_ashrrev_i32_e32 v159, 31, v158
	v_lshlrev_b64 v[130:131], 13, v[130:131]
	v_lshl_add_u64 v[132:133], v[12:13], 0, v[132:133]
	v_lshlrev_b64 v[134:135], 13, v[134:135]
	v_lshlrev_b64 v[136:137], 13, v[136:137]
	v_lshlrev_b64 v[138:139], 13, v[138:139]
	v_lshlrev_b64 v[140:141], 13, v[140:141]
	v_lshlrev_b64 v[142:143], 13, v[142:143]
	v_lshlrev_b64 v[144:145], 13, v[144:145]
	v_lshlrev_b64 v[146:147], 13, v[146:147]
	v_lshlrev_b64 v[148:149], 13, v[148:149]
	v_lshlrev_b64 v[150:151], 13, v[150:151]
	v_lshlrev_b64 v[152:153], 13, v[152:153]
	v_lshlrev_b64 v[154:155], 13, v[154:155]
	v_lshlrev_b64 v[156:157], 13, v[156:157]
	v_lshlrev_b64 v[158:159], 13, v[158:159]
	v_lshlrev_b64 v[160:161], 13, v[160:161]
	v_lshl_add_u64 v[130:131], v[12:13], 0, v[130:131]
	v_lshl_add_u64 v[136:137], v[12:13], 0, v[136:137]
	v_lshl_add_u64 v[134:135], v[12:13], 0, v[134:135]
	v_lshl_add_u64 v[140:141], v[12:13], 0, v[140:141]
	v_lshl_add_u64 v[138:139], v[12:13], 0, v[138:139]
	v_lshl_add_u64 v[144:145], v[12:13], 0, v[144:145]
	v_lshl_add_u64 v[142:143], v[12:13], 0, v[142:143]
	v_lshl_add_u64 v[148:149], v[12:13], 0, v[148:149]
	v_lshl_add_u64 v[146:147], v[12:13], 0, v[146:147]
	v_lshl_add_u64 v[152:153], v[12:13], 0, v[152:153]
	v_lshl_add_u64 v[150:151], v[12:13], 0, v[150:151]
	v_lshl_add_u64 v[156:157], v[12:13], 0, v[156:157]
	v_lshl_add_u64 v[154:155], v[12:13], 0, v[154:155]
	v_lshl_add_u64 v[160:161], v[12:13], 0, v[160:161]
	v_lshl_add_u64 v[158:159], v[12:13], 0, v[158:159]
	global_load_dword v172, v[132:133], off
	global_load_dword v173, v[130:131], off
	global_load_dword v174, v[136:137], off
	global_load_dword v175, v[134:135], off
	global_load_dword v176, v[140:141], off
	global_load_dword v177, v[138:139], off
	global_load_dword v178, v[144:145], off
	global_load_dword v179, v[142:143], off
	global_load_dword v180, v[148:149], off
	global_load_dword v181, v[146:147], off
	global_load_dword v182, v[152:153], off
	global_load_dword v183, v[150:151], off
	global_load_dword v184, v[156:157], off
	global_load_dword v185, v[154:155], off
	global_load_dword v186, v[160:161], off
	global_load_dword v187, v[158:159], off
	s_add_i32 s29, s29, 16
	s_add_i32 s28, s28, 16
	s_add_i32 s30, s30, -16
	v_mad_u64_u32 v[130:131], s[34:35], v109, s33, v[6:7]
	v_mad_u64_u32 v[132:133], s[34:35], v104, s33, v[6:7]
	v_mad_u64_u32 v[134:135], s[34:35], v115, s33, v[6:7]
	v_mad_u64_u32 v[136:137], s[34:35], v111, s33, v[6:7]
	v_mad_u64_u32 v[138:139], s[34:35], v129, s33, v[6:7]
	v_mad_u64_u32 v[140:141], s[34:35], v119, s33, v[6:7]
	v_mad_u64_u32 v[142:143], s[34:35], v163, s33, v[6:7]
	v_mad_u64_u32 v[144:145], s[34:35], v162, s33, v[6:7]
	v_mad_u64_u32 v[146:147], s[34:35], v165, s33, v[6:7]
	v_mad_u64_u32 v[148:149], s[34:35], v164, s33, v[6:7]
	v_mad_u64_u32 v[150:151], s[34:35], v167, s33, v[6:7]
	v_mad_u64_u32 v[152:153], s[34:35], v166, s33, v[6:7]
	v_mad_u64_u32 v[154:155], s[34:35], v169, s33, v[6:7]
	v_mad_u64_u32 v[156:157], s[34:35], v168, s33, v[6:7]
	v_mad_u64_u32 v[158:159], s[34:35], v171, s33, v[6:7]
	v_mad_u64_u32 v[160:161], s[34:35], v170, s33, v[6:7]
	s_lshl_b32 s31, s28, 1
	s_lshl_b32 s34, s29, 1
	v_or_b32_e32 v4, s31, v1
	v_or_b32_e32 v9, s34, v2
	s_add_i32 s35, s31, 4
	s_add_i32 s36, s34, 4
	s_add_i32 s37, s31, 8
	s_add_i32 s58, s34, 8
	s_add_i32 s59, s31, 12
	s_add_i32 s60, s34, 12
	s_add_i32 s61, s31, 16
	s_add_i32 s62, s34, 16
	s_add_i32 s63, s31, 20
	s_add_i32 s64, s34, 20
	s_add_i32 s65, s31, 24
	s_add_i32 s66, s34, 24
	s_add_i32 s31, s31, 28
	s_add_i32 s34, s34, 28
	v_add_u32_e32 v32, v9, v14
	v_or_b32_e32 v11, s35, v1
	v_or_b32_e32 v15, s36, v2
	v_or_b32_e32 v19, s37, v1
	v_or_b32_e32 v29, s58, v2
	v_or_b32_e32 v62, s59, v1
	v_or_b32_e32 v63, s60, v2
	v_or_b32_e32 v64, s61, v1
	v_or_b32_e32 v65, s62, v2
	v_or_b32_e32 v66, s63, v1
	v_or_b32_e32 v67, s64, v2
	v_or_b32_e32 v68, s65, v1
	v_or_b32_e32 v69, s66, v2
	v_or_b32_e32 v70, s31, v1
	v_or_b32_e32 v71, s34, v2
	v_add_u32_e32 v30, v4, v3
	v_ashrrev_i32_e32 v33, 31, v32
	v_add_u32_e32 v34, v11, v3
	v_add_u32_e32 v36, v15, v14
	v_add_u32_e32 v38, v19, v3
	v_add_u32_e32 v40, v29, v14
	v_add_u32_e32 v42, v62, v3
	v_add_u32_e32 v44, v63, v14
	v_add_u32_e32 v46, v64, v3
	v_add_u32_e32 v48, v65, v14
	v_add_u32_e32 v50, v66, v3
	v_add_u32_e32 v52, v67, v14
	v_add_u32_e32 v54, v68, v3
	v_add_u32_e32 v56, v69, v14
	v_add_u32_e32 v58, v70, v3
	v_add_u32_e32 v60, v71, v14
	v_ashrrev_i32_e32 v31, 31, v30
	v_lshlrev_b64 v[32:33], 13, v[32:33]
	v_ashrrev_i32_e32 v37, 31, v36
	v_ashrrev_i32_e32 v35, 31, v34
	v_ashrrev_i32_e32 v41, 31, v40
	v_ashrrev_i32_e32 v39, 31, v38
	v_ashrrev_i32_e32 v45, 31, v44
	v_ashrrev_i32_e32 v43, 31, v42
	v_ashrrev_i32_e32 v49, 31, v48
	v_ashrrev_i32_e32 v47, 31, v46
	v_ashrrev_i32_e32 v53, 31, v52
	v_ashrrev_i32_e32 v51, 31, v50
	v_ashrrev_i32_e32 v57, 31, v56
	v_ashrrev_i32_e32 v55, 31, v54
	v_ashrrev_i32_e32 v61, 31, v60
	v_ashrrev_i32_e32 v59, 31, v58
	v_lshlrev_b64 v[30:31], 13, v[30:31]
	v_lshl_add_u64 v[32:33], v[12:13], 0, v[32:33]
	v_lshlrev_b64 v[34:35], 13, v[34:35]
	v_lshlrev_b64 v[36:37], 13, v[36:37]
	v_lshlrev_b64 v[38:39], 13, v[38:39]
	v_lshlrev_b64 v[40:41], 13, v[40:41]
	v_lshlrev_b64 v[42:43], 13, v[42:43]
	v_lshlrev_b64 v[44:45], 13, v[44:45]
	v_lshlrev_b64 v[46:47], 13, v[46:47]
	v_lshlrev_b64 v[48:49], 13, v[48:49]
	v_lshlrev_b64 v[50:51], 13, v[50:51]
	v_lshlrev_b64 v[52:53], 13, v[52:53]
	v_lshlrev_b64 v[54:55], 13, v[54:55]
	v_lshlrev_b64 v[56:57], 13, v[56:57]
	v_lshlrev_b64 v[58:59], 13, v[58:59]
	v_lshlrev_b64 v[60:61], 13, v[60:61]
	v_lshl_add_u64 v[30:31], v[12:13], 0, v[30:31]
	v_lshl_add_u64 v[36:37], v[12:13], 0, v[36:37]
	v_lshl_add_u64 v[34:35], v[12:13], 0, v[34:35]
	v_lshl_add_u64 v[40:41], v[12:13], 0, v[40:41]
	v_lshl_add_u64 v[38:39], v[12:13], 0, v[38:39]
	v_lshl_add_u64 v[44:45], v[12:13], 0, v[44:45]
	v_lshl_add_u64 v[42:43], v[12:13], 0, v[42:43]
	v_lshl_add_u64 v[48:49], v[12:13], 0, v[48:49]
	v_lshl_add_u64 v[46:47], v[12:13], 0, v[46:47]
	v_lshl_add_u64 v[52:53], v[12:13], 0, v[52:53]
	v_lshl_add_u64 v[50:51], v[12:13], 0, v[50:51]
	v_lshl_add_u64 v[56:57], v[12:13], 0, v[56:57]
	v_lshl_add_u64 v[54:55], v[12:13], 0, v[54:55]
	v_lshl_add_u64 v[60:61], v[12:13], 0, v[60:61]
	v_lshl_add_u64 v[58:59], v[12:13], 0, v[58:59]
	global_load_dword v72, v[32:33], off
	global_load_dword v73, v[30:31], off
	global_load_dword v74, v[36:37], off
	global_load_dword v75, v[34:35], off
	global_load_dword v76, v[40:41], off
	global_load_dword v77, v[38:39], off
	global_load_dword v78, v[44:45], off
	global_load_dword v79, v[42:43], off
	global_load_dword v80, v[48:49], off
	global_load_dword v81, v[46:47], off
	global_load_dword v82, v[52:53], off
	global_load_dword v83, v[50:51], off
	global_load_dword v84, v[56:57], off
	global_load_dword v85, v[54:55], off
	global_load_dword v86, v[60:61], off
	global_load_dword v87, v[58:59], off
	s_add_i32 s29, s29, 16
	s_add_i32 s28, s28, 16
	s_add_i32 s30, s30, -16
	v_mad_u64_u32 v[30:31], s[34:35], v9, s33, v[6:7]
	v_mad_u64_u32 v[32:33], s[34:35], v4, s33, v[6:7]
	v_mad_u64_u32 v[34:35], s[34:35], v15, s33, v[6:7]
	v_mad_u64_u32 v[36:37], s[34:35], v11, s33, v[6:7]
	v_mad_u64_u32 v[38:39], s[34:35], v29, s33, v[6:7]
	v_mad_u64_u32 v[40:41], s[34:35], v19, s33, v[6:7]
	v_mad_u64_u32 v[42:43], s[34:35], v63, s33, v[6:7]
	v_mad_u64_u32 v[44:45], s[34:35], v62, s33, v[6:7]
	v_mad_u64_u32 v[46:47], s[34:35], v65, s33, v[6:7]
	v_mad_u64_u32 v[48:49], s[34:35], v64, s33, v[6:7]
	v_mad_u64_u32 v[50:51], s[34:35], v67, s33, v[6:7]
	v_mad_u64_u32 v[52:53], s[34:35], v66, s33, v[6:7]
	v_mad_u64_u32 v[54:55], s[34:35], v69, s33, v[6:7]
	v_mad_u64_u32 v[56:57], s[34:35], v68, s33, v[6:7]
	v_mad_u64_u32 v[58:59], s[34:35], v71, s33, v[6:7]
	v_mad_u64_u32 v[60:61], s[34:35], v70, s33, v[6:7]
	s_waitcnt vmcnt(31)
	ds_write_b32 v130, v172
	s_waitcnt vmcnt(30)
	ds_write_b32 v132, v173
	s_waitcnt vmcnt(29)
	ds_write_b32 v134, v174
	s_waitcnt vmcnt(28)
	ds_write_b32 v136, v175
	s_waitcnt vmcnt(27)
	ds_write_b32 v138, v176
	s_waitcnt vmcnt(26)
	ds_write_b32 v140, v177
	s_waitcnt vmcnt(25)
	ds_write_b32 v142, v178
	s_waitcnt vmcnt(24)
	ds_write_b32 v144, v179
	s_waitcnt vmcnt(23)
	ds_write_b32 v146, v180
	s_waitcnt vmcnt(22)
	ds_write_b32 v148, v181
	s_waitcnt vmcnt(21)
	ds_write_b32 v150, v182
	s_waitcnt vmcnt(20)
	ds_write_b32 v152, v183
	s_waitcnt vmcnt(19)
	ds_write_b32 v154, v184
	s_waitcnt vmcnt(18)
	ds_write_b32 v156, v185
	s_waitcnt vmcnt(17)
	ds_write_b32 v158, v186
	s_waitcnt vmcnt(16)
	ds_write_b32 v160, v187
	s_waitcnt vmcnt(15)
	ds_write_b32 v30, v72
	s_waitcnt vmcnt(14)
	ds_write_b32 v32, v73
	s_waitcnt vmcnt(13)
	ds_write_b32 v34, v74
	s_waitcnt vmcnt(12)
	ds_write_b32 v36, v75
	s_waitcnt vmcnt(11)
	ds_write_b32 v38, v76
	s_waitcnt vmcnt(10)
	ds_write_b32 v40, v77
	s_waitcnt vmcnt(9)
	ds_write_b32 v42, v78
	s_waitcnt vmcnt(8)
	ds_write_b32 v44, v79
	s_waitcnt vmcnt(7)
	ds_write_b32 v46, v80
	s_waitcnt vmcnt(6)
	ds_write_b32 v48, v81
	s_waitcnt vmcnt(5)
	ds_write_b32 v50, v82
	s_waitcnt vmcnt(4)
	ds_write_b32 v52, v83
	s_waitcnt vmcnt(3)
	ds_write_b32 v54, v84
	s_waitcnt vmcnt(2)
	ds_write_b32 v56, v85
	s_waitcnt vmcnt(1)
	ds_write_b32 v58, v86
	s_waitcnt vmcnt(0)
	ds_write_b32 v60, v87
	s_waitcnt lgkmcnt(0)
	v_lshl_add_u64 v[12:13], v[16:17], 1, s[16:17]
	ds_read2_b32 v[16:17], v22 offset1:8
	ds_read2_b32 v[32:33], v22 offset0:33 offset1:41
	ds_read2_b32 v[34:35], v22 offset0:66 offset1:74
	ds_read2_b32 v[36:37], v22 offset0:99 offset1:107
	v_mov_b32_e32 v15, v5
	s_waitcnt lgkmcnt(3)
	v_bfe_u32 v3, v16, 16, 1
	v_add3_u32 v3, v16, v3, s45
	s_waitcnt lgkmcnt(2)
	v_bfe_u32 v4, v32, 16, 1
	ds_read2_b32 v[38:39], v22 offset0:132 offset1:140
	v_lshl_add_u64 v[12:13], v[14:15], 1, v[12:13]
	v_mov_b32_e32 v11, v5
	v_lshrrev_b32_e32 v3, 16, v3
	v_add3_u32 v4, v32, v4, s45
	ds_read2_b32 v[40:41], v22 offset0:165 offset1:173
	v_lshl_add_u64 v[30:31], v[12:13], 0, v[10:11]
	v_and_or_b32 v12, v4, s46, v3
	s_waitcnt lgkmcnt(3)
	v_bfe_u32 v3, v34, 16, 1
	v_add3_u32 v3, v34, v3, s45
	s_waitcnt lgkmcnt(2)
	v_bfe_u32 v4, v36, 16, 1
	ds_read2_b32 v[42:43], v22 offset0:198 offset1:206
	v_lshrrev_b32_e32 v3, 16, v3
	v_add3_u32 v4, v36, v4, s45
	ds_read2_b32 v[44:45], v22 offset0:231 offset1:239
	v_and_or_b32 v13, v4, s46, v3
	s_waitcnt lgkmcnt(3)
	v_bfe_u32 v3, v38, 16, 1
	v_add3_u32 v3, v38, v3, s45
	s_waitcnt lgkmcnt(2)
	v_bfe_u32 v4, v40, 16, 1
	v_lshrrev_b32_e32 v3, 16, v3
	v_add3_u32 v4, v40, v4, s45
	v_and_or_b32 v14, v4, s46, v3
	s_waitcnt lgkmcnt(1)
	v_bfe_u32 v3, v42, 16, 1
	v_add3_u32 v3, v42, v3, s45
	s_waitcnt lgkmcnt(0)
	v_bfe_u32 v4, v44, 16, 1
	v_lshrrev_b32_e32 v3, 16, v3
	v_add3_u32 v4, v44, v4, s45
	v_and_or_b32 v15, v4, s46, v3
	v_or_b32_e32 v3, v18, v21
	v_lshlrev_b32_e32 v4, 12, v3
	v_bfe_u32 v3, v17, 16, 1
	v_lshl_add_u64 v[46:47], v[30:31], 0, v[4:5]
	v_add3_u32 v3, v17, v3, s45
	v_bfe_u32 v4, v33, 16, 1
	v_lshrrev_b32_e32 v3, 16, v3
	v_add3_u32 v4, v33, v4, s45
	global_store_dwordx4 v[46:47], v[12:15], off sc1
	ds_read2_b32 v[16:17], v22 offset0:16 offset1:24
	v_readlane_b32 s66, v253, 1
	v_and_or_b32 v12, v4, s46, v3
	v_bfe_u32 v3, v35, 16, 1
	v_add3_u32 v3, v35, v3, s45
	v_bfe_u32 v4, v37, 16, 1
	v_lshrrev_b32_e32 v3, 16, v3
	v_add3_u32 v4, v37, v4, s45
	v_and_or_b32 v13, v4, s46, v3
	v_bfe_u32 v3, v39, 16, 1
	v_add3_u32 v3, v39, v3, s45
	v_bfe_u32 v4, v41, 16, 1
	v_lshrrev_b32_e32 v3, 16, v3
	v_add3_u32 v4, v41, v4, s45
	v_and_or_b32 v14, v4, s46, v3
	v_bfe_u32 v3, v43, 16, 1
	v_add3_u32 v3, v43, v3, s45
	v_bfe_u32 v4, v45, 16, 1
	v_lshrrev_b32_e32 v3, 16, v3
	v_add3_u32 v4, v45, v4, s45
	v_and_or_b32 v15, v4, s46, v3
	v_or_b32_e32 v3, v18, v23
	v_lshlrev_b32_e32 v4, 12, v3
	v_lshl_add_u64 v[32:33], v[30:31], 0, v[4:5]
	global_store_dwordx4 v[32:33], v[12:15], off sc1
	ds_read2_b32 v[32:33], v22 offset0:49 offset1:57
	ds_read2_b32 v[34:35], v22 offset0:82 offset1:90
	ds_read2_b32 v[36:37], v22 offset0:115 offset1:123
	s_waitcnt lgkmcnt(3)
	v_bfe_u32 v3, v16, 16, 1
	v_add3_u32 v3, v16, v3, s45
	s_waitcnt lgkmcnt(2)
	v_bfe_u32 v4, v32, 16, 1
	ds_read2_b32 v[38:39], v22 offset0:148 offset1:156
	v_lshrrev_b32_e32 v3, 16, v3
	v_add3_u32 v4, v32, v4, s45
	ds_read2_b32 v[40:41], v22 offset0:181 offset1:189
	v_and_or_b32 v12, v4, s46, v3
	s_waitcnt lgkmcnt(3)
	v_bfe_u32 v3, v34, 16, 1
	v_add3_u32 v3, v34, v3, s45
	s_waitcnt lgkmcnt(2)
	v_bfe_u32 v4, v36, 16, 1
	ds_read2_b32 v[42:43], v22 offset0:214 offset1:222
	v_lshrrev_b32_e32 v3, 16, v3
	v_add3_u32 v4, v36, v4, s45
	ds_read2_b32 v[44:45], v22 offset0:247 offset1:255
	v_and_or_b32 v13, v4, s46, v3
	s_waitcnt lgkmcnt(3)
	v_bfe_u32 v3, v38, 16, 1
	v_add3_u32 v3, v38, v3, s45
	s_waitcnt lgkmcnt(2)
	v_bfe_u32 v4, v40, 16, 1
	v_lshrrev_b32_e32 v3, 16, v3
	v_add3_u32 v4, v40, v4, s45
	v_and_or_b32 v14, v4, s46, v3
	s_waitcnt lgkmcnt(1)
	v_bfe_u32 v3, v42, 16, 1
	v_add3_u32 v3, v42, v3, s45
	s_waitcnt lgkmcnt(0)
	v_bfe_u32 v4, v44, 16, 1
	v_lshrrev_b32_e32 v3, 16, v3
	v_add3_u32 v4, v44, v4, s45
	v_and_or_b32 v15, v4, s46, v3
	v_or_b32_e32 v3, v18, v24
	v_lshlrev_b32_e32 v4, 12, v3
	v_bfe_u32 v3, v17, 16, 1
	v_lshl_add_u64 v[46:47], v[30:31], 0, v[4:5]
	v_add3_u32 v3, v17, v3, s45
	v_bfe_u32 v4, v33, 16, 1
	v_lshrrev_b32_e32 v3, 16, v3
	v_add3_u32 v4, v33, v4, s45
	global_store_dwordx4 v[46:47], v[12:15], off sc1
	s_nop 1
	v_and_or_b32 v12, v4, s46, v3
	v_bfe_u32 v3, v35, 16, 1
	v_add3_u32 v3, v35, v3, s45
	v_bfe_u32 v4, v37, 16, 1
	v_lshrrev_b32_e32 v3, 16, v3
	v_add3_u32 v4, v37, v4, s45
	v_and_or_b32 v13, v4, s46, v3
	v_bfe_u32 v3, v39, 16, 1
	v_add3_u32 v3, v39, v3, s45
	v_bfe_u32 v4, v41, 16, 1
	v_lshrrev_b32_e32 v3, 16, v3
	v_add3_u32 v4, v41, v4, s45
	v_and_or_b32 v14, v4, s46, v3
	v_bfe_u32 v3, v43, 16, 1
	v_add3_u32 v3, v43, v3, s45
	v_bfe_u32 v4, v45, 16, 1
	v_lshrrev_b32_e32 v3, 16, v3
	v_add3_u32 v4, v45, v4, s45
	v_and_or_b32 v15, v4, s46, v3
	v_or_b32_e32 v3, v18, v25
	v_lshlrev_b32_e32 v4, 12, v3
	v_lshl_add_u64 v[16:17], v[30:31], 0, v[4:5]
	global_store_dwordx4 v[16:17], v[12:15], off sc1
	s_waitcnt lgkmcnt(0)

.LBB0_140:
	s_andn2_saveexec_b64 s[24:25], s[24:25]
	s_cbranch_execz .LBB0_105
	s_load_dwordx2 s[26:27], s[6:7], 0x30
	v_mul_i32_i24_e32 v4, 0xfc1, v3
	v_lshrrev_b32_e32 v9, 31, v4
	v_ashrrev_i32_e32 v4, 19, v4
	v_add_u16_e32 v4, v4, v9
	v_mul_lo_u16_e32 v9, 0x82, v4
	v_sub_u16_e32 v3, v3, v9
	s_waitcnt lgkmcnt(0)
	v_mov_b64_e32 v[14:15], s[26:27]
	v_mad_i64_i32 v[18:19], s[26:27], v12, s54, v[14:15]
	v_lshlrev_b32_sdwa v14, v26, sext(v3) dst_sel:DWORD dst_unused:UNUSED_PAD src0_sel:DWORD src1_sel:WORD_0
	v_ashrrev_i32_e32 v15, 31, v14
	v_lshlrev_b32_sdwa v16, v28, sext(v4) dst_sel:DWORD dst_unused:UNUSED_PAD src0_sel:DWORD src1_sel:WORD_0
	v_lshl_add_u64 v[18:19], v[14:15], 2, v[18:19]
	v_mov_b32_e32 v9, v5
	v_lshl_add_u64 v[18:19], v[18:19], 0, v[8:9]
	v_mov_b32_e32 v3, v16
	s_mov_b32 s26, 1
	s_mov_b32 s27, 0
	s_mov_b32 s28, 32
	s_lshl_b32 s29, s26, 1
	s_lshl_b32 s30, s27, 1
	v_or_b32_e32 v104, s29, v1
	v_or_b32_e32 v109, s30, v2
	s_add_i32 s31, s29, 4
	s_add_i32 s34, s30, 4
	s_add_i32 s35, s29, 8
	s_add_i32 s36, s30, 8
	s_add_i32 s37, s29, 12
	s_add_i32 s58, s30, 12
	s_add_i32 s59, s29, 16
	s_add_i32 s60, s30, 16
	s_add_i32 s61, s29, 20
	s_add_i32 s62, s30, 20
	s_add_i32 s63, s29, 24
	s_add_i32 s64, s30, 24
	s_add_i32 s29, s29, 28
	s_add_i32 s30, s30, 28
	v_add_u32_e32 v111, v104, v3
	v_add_u32_e32 v113, v109, v16
	v_or_b32_e32 v115, s31, v1
	v_or_b32_e32 v117, s34, v2
	v_or_b32_e32 v129, s35, v1
	v_or_b32_e32 v162, s36, v2
	v_or_b32_e32 v163, s37, v1
	v_or_b32_e32 v164, s58, v2
	v_or_b32_e32 v165, s59, v1
	v_or_b32_e32 v166, s60, v2
	v_or_b32_e32 v167, s61, v1
	v_or_b32_e32 v168, s62, v2
	v_or_b32_e32 v169, s63, v1
	v_or_b32_e32 v170, s64, v2
	v_or_b32_e32 v171, s29, v1
	v_or_b32_e32 v172, s30, v2
	v_mad_i64_i32 v[130:131], s[30:31], v113, s55, v[18:19]
	v_mad_i64_i32 v[132:133], s[30:31], v111, s55, v[18:19]
	v_add_u32_e32 v111, v115, v3
	v_add_u32_e32 v113, v117, v16
	v_add_u32_e32 v140, v129, v3
	v_add_u32_e32 v138, v162, v16
	v_add_u32_e32 v144, v163, v3
	v_add_u32_e32 v142, v164, v16
	v_add_u32_e32 v148, v165, v3
	v_add_u32_e32 v146, v166, v16
	v_add_u32_e32 v152, v167, v3
	v_add_u32_e32 v150, v168, v16
	v_add_u32_e32 v156, v169, v3
	v_add_u32_e32 v154, v170, v16
	v_add_u32_e32 v160, v171, v3
	v_add_u32_e32 v158, v172, v16
	v_mad_i64_i32 v[134:135], s[30:31], v113, s55, v[18:19]
	v_mad_i64_i32 v[136:137], s[30:31], v111, s55, v[18:19]
	v_mad_i64_i32 v[138:139], s[30:31], v138, s55, v[18:19]
	v_mad_i64_i32 v[140:141], s[30:31], v140, s55, v[18:19]
	v_mad_i64_i32 v[142:143], s[30:31], v142, s55, v[18:19]
	v_mad_i64_i32 v[144:145], s[30:31], v144, s55, v[18:19]
	v_mad_i64_i32 v[146:147], s[30:31], v146, s55, v[18:19]
	v_mad_i64_i32 v[148:149], s[30:31], v148, s55, v[18:19]
	v_mad_i64_i32 v[150:151], s[30:31], v150, s55, v[18:19]
	v_mad_i64_i32 v[152:153], s[30:31], v152, s55, v[18:19]
	v_mad_i64_i32 v[154:155], s[30:31], v154, s55, v[18:19]
	v_mad_i64_i32 v[156:157], s[30:31], v156, s55, v[18:19]
	v_mad_i64_i32 v[158:159], s[30:31], v158, s55, v[18:19]
	v_mad_i64_i32 v[160:161], s[30:31], v160, s55, v[18:19]
	global_load_dword v111, v[130:131], off
	global_load_dword v113, v[132:133], off
	global_load_dword v173, v[134:135], off
	global_load_dword v174, v[136:137], off
	global_load_dword v175, v[138:139], off
	global_load_dword v176, v[140:141], off
	global_load_dword v177, v[142:143], off
	global_load_dword v178, v[144:145], off
	global_load_dword v179, v[146:147], off
	global_load_dword v180, v[148:149], off
	global_load_dword v181, v[150:151], off
	global_load_dword v182, v[152:153], off
	global_load_dword v183, v[154:155], off
	global_load_dword v184, v[156:157], off
	global_load_dword v185, v[158:159], off
	global_load_dword v186, v[160:161], off
	s_add_i32 s27, s27, 16
	s_add_i32 s26, s26, 16
	s_add_i32 s28, s28, -16
	v_mad_u64_u32 v[130:131], s[30:31], v109, s33, v[6:7]
	v_mad_u64_u32 v[132:133], s[30:31], v104, s33, v[6:7]
	v_mad_u64_u32 v[134:135], s[30:31], v117, s33, v[6:7]
	v_mad_u64_u32 v[136:137], s[30:31], v115, s33, v[6:7]
	v_mad_u64_u32 v[138:139], s[30:31], v162, s33, v[6:7]
	v_mad_u64_u32 v[140:141], s[30:31], v129, s33, v[6:7]
	v_mad_u64_u32 v[142:143], s[30:31], v164, s33, v[6:7]
	v_mad_u64_u32 v[144:145], s[30:31], v163, s33, v[6:7]
	v_mad_u64_u32 v[146:147], s[30:31], v166, s33, v[6:7]
	v_mad_u64_u32 v[148:149], s[30:31], v165, s33, v[6:7]
	v_mad_u64_u32 v[150:151], s[30:31], v168, s33, v[6:7]
	v_mad_u64_u32 v[152:153], s[30:31], v167, s33, v[6:7]
	v_mad_u64_u32 v[154:155], s[30:31], v170, s33, v[6:7]
	v_mad_u64_u32 v[156:157], s[30:31], v169, s33, v[6:7]
	v_mad_u64_u32 v[158:159], s[30:31], v172, s33, v[6:7]
	v_mad_u64_u32 v[160:161], s[30:31], v171, s33, v[6:7]
	s_lshl_b32 s29, s26, 1
	s_lshl_b32 s30, s27, 1
	v_or_b32_e32 v4, s29, v1
	v_or_b32_e32 v9, s30, v2
	s_add_i32 s31, s29, 4
	s_add_i32 s34, s30, 4
	s_add_i32 s35, s29, 8
	s_add_i32 s36, s30, 8
	s_add_i32 s37, s29, 12
	s_add_i32 s58, s30, 12
	s_add_i32 s59, s29, 16
	s_add_i32 s60, s30, 16
	s_add_i32 s61, s29, 20
	s_add_i32 s62, s30, 20
	s_add_i32 s63, s29, 24
	s_add_i32 s64, s30, 24
	s_add_i32 s29, s29, 28
	s_add_i32 s30, s30, 28
	v_add_u32_e32 v11, v4, v3
	v_add_u32_e32 v13, v9, v16
	v_or_b32_e32 v15, s31, v1
	v_or_b32_e32 v17, s34, v2
	v_or_b32_e32 v29, s35, v1
	v_or_b32_e32 v62, s36, v2
	v_or_b32_e32 v63, s37, v1
	v_or_b32_e32 v64, s58, v2
	v_or_b32_e32 v65, s59, v1
	v_or_b32_e32 v66, s60, v2
	v_or_b32_e32 v67, s61, v1
	v_or_b32_e32 v68, s62, v2
	v_or_b32_e32 v69, s63, v1
	v_or_b32_e32 v70, s64, v2
	v_or_b32_e32 v71, s29, v1
	v_or_b32_e32 v72, s30, v2
	v_mad_i64_i32 v[30:31], s[30:31], v13, s55, v[18:19]
	v_mad_i64_i32 v[32:33], s[30:31], v11, s55, v[18:19]
	v_add_u32_e32 v11, v15, v3
	v_add_u32_e32 v13, v17, v16
	v_add_u32_e32 v40, v29, v3
	v_add_u32_e32 v38, v62, v16
	v_add_u32_e32 v44, v63, v3
	v_add_u32_e32 v42, v64, v16
	v_add_u32_e32 v48, v65, v3
	v_add_u32_e32 v46, v66, v16
	v_add_u32_e32 v52, v67, v3
	v_add_u32_e32 v50, v68, v16
	v_add_u32_e32 v56, v69, v3
	v_add_u32_e32 v54, v70, v16
	v_add_u32_e32 v60, v71, v3
	v_add_u32_e32 v58, v72, v16
	v_mad_i64_i32 v[34:35], s[30:31], v13, s55, v[18:19]
	v_mad_i64_i32 v[36:37], s[30:31], v11, s55, v[18:19]
	v_mad_i64_i32 v[38:39], s[30:31], v38, s55, v[18:19]
	v_mad_i64_i32 v[40:41], s[30:31], v40, s55, v[18:19]
	v_mad_i64_i32 v[42:43], s[30:31], v42, s55, v[18:19]
	v_mad_i64_i32 v[44:45], s[30:31], v44, s55, v[18:19]
	v_mad_i64_i32 v[46:47], s[30:31], v46, s55, v[18:19]
	v_mad_i64_i32 v[48:49], s[30:31], v48, s55, v[18:19]
	v_mad_i64_i32 v[50:51], s[30:31], v50, s55, v[18:19]
	v_mad_i64_i32 v[52:53], s[30:31], v52, s55, v[18:19]
	v_mad_i64_i32 v[54:55], s[30:31], v54, s55, v[18:19]
	v_mad_i64_i32 v[56:57], s[30:31], v56, s55, v[18:19]
	v_mad_i64_i32 v[58:59], s[30:31], v58, s55, v[18:19]
	v_mad_i64_i32 v[60:61], s[30:31], v60, s55, v[18:19]
	global_load_dword v11, v[30:31], off
	global_load_dword v13, v[32:33], off
	global_load_dword v73, v[34:35], off
	global_load_dword v74, v[36:37], off
	global_load_dword v75, v[38:39], off
	global_load_dword v76, v[40:41], off
	global_load_dword v77, v[42:43], off
	global_load_dword v78, v[44:45], off
	global_load_dword v79, v[46:47], off
	global_load_dword v80, v[48:49], off
	global_load_dword v81, v[50:51], off
	global_load_dword v82, v[52:53], off
	global_load_dword v83, v[54:55], off
	global_load_dword v84, v[56:57], off
	global_load_dword v85, v[58:59], off
	global_load_dword v86, v[60:61], off
	s_add_i32 s27, s27, 16
	s_add_i32 s26, s26, 16
	s_add_i32 s28, s28, -16
	v_mad_u64_u32 v[30:31], s[30:31], v9, s33, v[6:7]
	v_mad_u64_u32 v[32:33], s[30:31], v4, s33, v[6:7]
	v_mad_u64_u32 v[34:35], s[30:31], v17, s33, v[6:7]
	v_mad_u64_u32 v[36:37], s[30:31], v15, s33, v[6:7]
	v_mad_u64_u32 v[38:39], s[30:31], v62, s33, v[6:7]
	v_mad_u64_u32 v[40:41], s[30:31], v29, s33, v[6:7]
	v_mad_u64_u32 v[42:43], s[30:31], v64, s33, v[6:7]
	v_mad_u64_u32 v[44:45], s[30:31], v63, s33, v[6:7]
	v_mad_u64_u32 v[46:47], s[30:31], v66, s33, v[6:7]
	v_mad_u64_u32 v[48:49], s[30:31], v65, s33, v[6:7]
	v_mad_u64_u32 v[50:51], s[30:31], v68, s33, v[6:7]
	v_mad_u64_u32 v[52:53], s[30:31], v67, s33, v[6:7]
	v_mad_u64_u32 v[54:55], s[30:31], v70, s33, v[6:7]
	v_mad_u64_u32 v[56:57], s[30:31], v69, s33, v[6:7]
	v_mad_u64_u32 v[58:59], s[30:31], v72, s33, v[6:7]
	v_mad_u64_u32 v[60:61], s[30:31], v71, s33, v[6:7]
	s_waitcnt vmcnt(31)
	ds_write_b32 v130, v111
	s_waitcnt vmcnt(30)
	ds_write_b32 v132, v113
	s_waitcnt vmcnt(29)
	ds_write_b32 v134, v173
	s_waitcnt vmcnt(28)
	ds_write_b32 v136, v174
	s_waitcnt vmcnt(27)
	ds_write_b32 v138, v175
	s_waitcnt vmcnt(26)
	ds_write_b32 v140, v176
	s_waitcnt vmcnt(25)
	ds_write_b32 v142, v177
	s_waitcnt vmcnt(24)
	ds_write_b32 v144, v178
	s_waitcnt vmcnt(23)
	ds_write_b32 v146, v179
	s_waitcnt vmcnt(22)
	ds_write_b32 v148, v180
	s_waitcnt vmcnt(21)
	ds_write_b32 v150, v181
	s_waitcnt vmcnt(20)
	ds_write_b32 v152, v182
	s_waitcnt vmcnt(19)
	ds_write_b32 v154, v183
	s_waitcnt vmcnt(18)
	ds_write_b32 v156, v184
	s_waitcnt vmcnt(17)
	ds_write_b32 v158, v185
	s_waitcnt vmcnt(16)
	ds_write_b32 v160, v186
	s_waitcnt vmcnt(15)
	ds_write_b32 v30, v11
	s_waitcnt vmcnt(14)
	ds_write_b32 v32, v13
	s_waitcnt vmcnt(13)
	ds_write_b32 v34, v73
	s_waitcnt vmcnt(12)
	ds_write_b32 v36, v74
	s_waitcnt vmcnt(11)
	ds_write_b32 v38, v75
	s_waitcnt vmcnt(10)
	ds_write_b32 v40, v76
	s_waitcnt vmcnt(9)
	ds_write_b32 v42, v77
	s_waitcnt vmcnt(8)
	ds_write_b32 v44, v78
	s_waitcnt vmcnt(7)
	ds_write_b32 v46, v79
	s_waitcnt vmcnt(6)
	ds_write_b32 v48, v80
	s_waitcnt vmcnt(5)
	ds_write_b32 v50, v81
	s_waitcnt vmcnt(4)
	ds_write_b32 v52, v82
	s_waitcnt vmcnt(3)
	ds_write_b32 v54, v83
	s_waitcnt vmcnt(2)
	ds_write_b32 v56, v84
	s_waitcnt vmcnt(1)
	ds_write_b32 v58, v85
	s_waitcnt vmcnt(0)
	ds_write_b32 v60, v86
	s_waitcnt lgkmcnt(0)
	ds_read2_b32 v[30:31], v22 offset1:8
	ds_read2_b32 v[32:33], v22 offset0:33 offset1:41
	ds_read2_b32 v[34:35], v22 offset0:66 offset1:74
	ds_read2_b32 v[36:37], v22 offset0:99 offset1:107
	v_mov_b64_e32 v[18:19], s[18:19]
	s_waitcnt lgkmcnt(3)
	v_bfe_u32 v3, v30, 16, 1
	v_add3_u32 v3, v30, v3, s45
	s_waitcnt lgkmcnt(2)
	v_bfe_u32 v4, v32, 16, 1
	ds_read2_b32 v[38:39], v22 offset0:132 offset1:140
	v_mad_i64_i32 v[12:13], s[26:27], v12, s56, v[18:19]
	v_ashrrev_i32_e32 v17, 31, v16
	v_lshrrev_b32_e32 v3, 16, v3
	v_add3_u32 v4, v32, v4, s45
	ds_read2_b32 v[40:41], v22 offset0:165 offset1:173
	v_lshl_add_u64 v[12:13], v[16:17], 1, v[12:13]
	v_and_or_b32 v16, v4, s46, v3
	s_waitcnt lgkmcnt(3)
	v_bfe_u32 v3, v34, 16, 1
	v_add3_u32 v3, v34, v3, s45
	s_waitcnt lgkmcnt(2)
	v_bfe_u32 v4, v36, 16, 1
	ds_read2_b32 v[42:43], v22 offset0:198 offset1:206
	v_lshrrev_b32_e32 v3, 16, v3
	v_add3_u32 v4, v36, v4, s45
	ds_read2_b32 v[44:45], v22 offset0:231 offset1:239
	v_and_or_b32 v17, v4, s46, v3
	s_waitcnt lgkmcnt(3)
	v_bfe_u32 v3, v38, 16, 1
	v_add3_u32 v3, v38, v3, s45
	s_waitcnt lgkmcnt(2)
	v_bfe_u32 v4, v40, 16, 1
	v_lshrrev_b32_e32 v3, 16, v3
	v_add3_u32 v4, v40, v4, s45
	v_and_or_b32 v18, v4, s46, v3
	s_waitcnt lgkmcnt(1)
	v_bfe_u32 v3, v42, 16, 1
	v_add3_u32 v3, v42, v3, s45
	s_waitcnt lgkmcnt(0)
	v_bfe_u32 v4, v44, 16, 1
	v_lshrrev_b32_e32 v3, 16, v3
	v_add3_u32 v4, v44, v4, s45
	v_or_b32_e32 v46, v14, v21
	v_mov_b32_e32 v11, v5
	v_and_or_b32 v19, v4, s46, v3
	v_ashrrev_i32_e32 v47, 31, v46
	v_bfe_u32 v3, v31, 16, 1
	v_lshl_add_u64 v[12:13], v[12:13], 0, v[10:11]
	v_lshlrev_b64 v[46:47], 12, v[46:47]
	v_add3_u32 v3, v31, v3, s45
	v_bfe_u32 v4, v33, 16, 1
	v_lshl_add_u64 v[46:47], v[12:13], 0, v[46:47]
	v_lshrrev_b32_e32 v3, 16, v3
	v_add3_u32 v4, v33, v4, s45
	global_store_dwordx4 v[46:47], v[16:19], off sc1
	v_or_b32_e32 v30, v14, v23
	v_ashrrev_i32_e32 v31, 31, v30
	v_and_or_b32 v16, v4, s46, v3
	v_bfe_u32 v3, v35, 16, 1
	v_add3_u32 v3, v35, v3, s45
	v_bfe_u32 v4, v37, 16, 1
	v_lshrrev_b32_e32 v3, 16, v3
	v_add3_u32 v4, v37, v4, s45
	v_and_or_b32 v17, v4, s46, v3
	v_bfe_u32 v3, v39, 16, 1
	v_add3_u32 v3, v39, v3, s45
	v_bfe_u32 v4, v41, 16, 1
	v_lshrrev_b32_e32 v3, 16, v3
	v_add3_u32 v4, v41, v4, s45
	v_and_or_b32 v18, v4, s46, v3
	v_bfe_u32 v3, v43, 16, 1
	v_add3_u32 v3, v43, v3, s45
	v_bfe_u32 v4, v45, 16, 1
	v_lshrrev_b32_e32 v3, 16, v3
	v_add3_u32 v4, v45, v4, s45
	v_lshlrev_b64 v[30:31], 12, v[30:31]
	v_and_or_b32 v19, v4, s46, v3
	ds_read2_b32 v[32:33], v22 offset0:16 offset1:24
	v_lshl_add_u64 v[30:31], v[12:13], 0, v[30:31]
	global_store_dwordx4 v[30:31], v[16:19], off sc1
	ds_read2_b32 v[30:31], v22 offset0:49 offset1:57
	ds_read2_b32 v[34:35], v22 offset0:82 offset1:90
	ds_read2_b32 v[36:37], v22 offset0:115 offset1:123
	s_waitcnt lgkmcnt(3)
	v_bfe_u32 v3, v32, 16, 1
	v_add3_u32 v3, v32, v3, s45
	s_waitcnt lgkmcnt(2)
	v_bfe_u32 v4, v30, 16, 1
	ds_read2_b32 v[38:39], v22 offset0:148 offset1:156
	v_lshrrev_b32_e32 v3, 16, v3
	v_add3_u32 v4, v30, v4, s45
	ds_read2_b32 v[40:41], v22 offset0:181 offset1:189
	v_and_or_b32 v16, v4, s46, v3
	s_waitcnt lgkmcnt(3)
	v_bfe_u32 v3, v34, 16, 1
	v_add3_u32 v3, v34, v3, s45
	s_waitcnt lgkmcnt(2)
	v_bfe_u32 v4, v36, 16, 1
	ds_read2_b32 v[42:43], v22 offset0:214 offset1:222
	v_lshrrev_b32_e32 v3, 16, v3
	v_add3_u32 v4, v36, v4, s45
	ds_read2_b32 v[44:45], v22 offset0:247 offset1:255
	v_and_or_b32 v17, v4, s46, v3
	s_waitcnt lgkmcnt(3)
	v_bfe_u32 v3, v38, 16, 1
	v_add3_u32 v3, v38, v3, s45
	s_waitcnt lgkmcnt(2)
	v_bfe_u32 v4, v40, 16, 1
	v_lshrrev_b32_e32 v3, 16, v3
	v_add3_u32 v4, v40, v4, s45
	v_and_or_b32 v18, v4, s46, v3
	s_waitcnt lgkmcnt(1)
	v_bfe_u32 v3, v42, 16, 1
	v_add3_u32 v3, v42, v3, s45
	s_waitcnt lgkmcnt(0)
	v_bfe_u32 v4, v44, 16, 1
	v_lshrrev_b32_e32 v3, 16, v3
	v_add3_u32 v4, v44, v4, s45
	v_or_b32_e32 v46, v14, v24
	v_and_or_b32 v19, v4, s46, v3
	v_ashrrev_i32_e32 v47, 31, v46
	v_bfe_u32 v3, v33, 16, 1
	v_lshlrev_b64 v[46:47], 12, v[46:47]
	v_add3_u32 v3, v33, v3, s45
	v_bfe_u32 v4, v31, 16, 1
	v_lshl_add_u64 v[46:47], v[12:13], 0, v[46:47]
	v_lshrrev_b32_e32 v3, 16, v3
	v_add3_u32 v4, v31, v4, s45
	global_store_dwordx4 v[46:47], v[16:19], off sc1
	v_or_b32_e32 v14, v14, v25
	v_ashrrev_i32_e32 v15, 31, v14
	v_and_or_b32 v16, v4, s46, v3
	v_bfe_u32 v3, v35, 16, 1
	v_add3_u32 v3, v35, v3, s45
	v_bfe_u32 v4, v37, 16, 1
	v_lshrrev_b32_e32 v3, 16, v3
	v_add3_u32 v4, v37, v4, s45
	v_and_or_b32 v17, v4, s46, v3
	v_bfe_u32 v3, v39, 16, 1
	v_add3_u32 v3, v39, v3, s45
	v_bfe_u32 v4, v41, 16, 1
	v_lshrrev_b32_e32 v3, 16, v3
	v_add3_u32 v4, v41, v4, s45
	v_and_or_b32 v18, v4, s46, v3
	v_bfe_u32 v3, v43, 16, 1
	v_add3_u32 v3, v43, v3, s45
	v_bfe_u32 v4, v45, 16, 1
	v_lshrrev_b32_e32 v3, 16, v3
	v_add3_u32 v4, v45, v4, s45
	v_lshlrev_b64 v[14:15], 12, v[14:15]
	v_and_or_b32 v19, v4, s46, v3
	v_lshl_add_u64 v[12:13], v[12:13], 0, v[14:15]
	global_store_dwordx4 v[12:13], v[16:19], off sc1
	s_waitcnt lgkmcnt(0)
	s_branch .LBB0_105

.LBB0_277:
	v_lshl_or_b32 v140, s39, 8, v146
	v_lshl_add_u32 v150, s40, 8, v142
	v_ashrrev_i32_e32 v141, 31, v140
	v_mov_b64_e32 v[138:139], s[8:9]
	v_mad_i64_i32 v[148:149], s[20:21], v150, s3, v[138:139]
	v_lshlrev_b64 v[140:141], 1, v[140:141]
	v_lshl_add_u64 v[148:149], v[148:149], 0, v[140:141]
	v_cvt_pk_bf16_f32 v124, v124, v125
	v_cvt_pk_bf16_f32 v125, v126, v127
	v_cvt_pk_bf16_f32 v126, v120, v121
	v_cvt_pk_bf16_f32 v127, v122, v123
	global_store_dwordx4 v[148:149], v[124:127], off sc1
	v_cvt_pk_bf16_f32 v112, v112, v113
	v_cvt_pk_bf16_f32 v113, v114, v115
	v_cvt_pk_bf16_f32 v114, v104, v105
	v_or_b32_e32 v104, 16, v150
	v_mad_i64_i32 v[104:105], s[20:21], v104, s3, v[138:139]
	v_cvt_pk_bf16_f32 v115, v106, v107
	global_store_dwordx4 v[148:149], v[112:115], off offset:256 sc1
	s_andn2_b64 vcc, exec, s[4:5]
	s_mov_b64 s[4:5], -1
	v_lshl_add_u64 v[112:113], v[104:105], 0, v[140:141]
	v_cvt_pk_bf16_f32 v104, v116, v117
	v_cvt_pk_bf16_f32 v105, v118, v119
	v_cvt_pk_bf16_f32 v106, v108, v109
	v_cvt_pk_bf16_f32 v107, v110, v111
	global_store_dwordx4 v[112:113], v[104:107], off sc1
	v_cvt_pk_bf16_f32 v96, v96, v97
	v_cvt_pk_bf16_f32 v97, v98, v99
	v_cvt_pk_bf16_f32 v98, v88, v89
	v_or_b32_e32 v88, 32, v150
	v_mad_i64_i32 v[88:89], s[20:21], v88, s3, v[138:139]
	v_cvt_pk_bf16_f32 v99, v90, v91
	global_store_dwordx4 v[112:113], v[96:99], off offset:256 sc1
	s_nop 1
	v_lshl_add_u64 v[96:97], v[88:89], 0, v[140:141]
	v_cvt_pk_bf16_f32 v88, v100, v101
	v_cvt_pk_bf16_f32 v89, v102, v103
	v_cvt_pk_bf16_f32 v90, v92, v93
	v_cvt_pk_bf16_f32 v91, v94, v95
	global_store_dwordx4 v[96:97], v[88:91], off sc1
	v_cvt_pk_bf16_f32 v80, v80, v81
	v_cvt_pk_bf16_f32 v81, v82, v83
	v_cvt_pk_bf16_f32 v82, v72, v73
	v_or_b32_e32 v72, 48, v150
	v_mad_i64_i32 v[72:73], s[20:21], v72, s3, v[138:139]
	v_cvt_pk_bf16_f32 v83, v74, v75
	global_store_dwordx4 v[96:97], v[80:83], off offset:256 sc1
	s_nop 1
	v_lshl_add_u64 v[80:81], v[72:73], 0, v[140:141]
	v_cvt_pk_bf16_f32 v72, v84, v85
	v_cvt_pk_bf16_f32 v73, v86, v87
	v_cvt_pk_bf16_f32 v74, v76, v77
	v_cvt_pk_bf16_f32 v75, v78, v79
	global_store_dwordx4 v[80:81], v[72:75], off sc1
	v_cvt_pk_bf16_f32 v68, v68, v69
	v_cvt_pk_bf16_f32 v69, v70, v71
	v_cvt_pk_bf16_f32 v70, v64, v65
	v_add_u32_e32 v64, 0x80, v150
	v_mad_i64_i32 v[64:65], s[20:21], v64, s3, v[138:139]
	v_lshl_add_u64 v[64:65], v[64:65], 0, v[140:141]
	v_cvt_pk_bf16_f32 v71, v66, v67
	global_store_dwordx4 v[80:81], v[68:71], off offset:256 sc1
	v_cvt_pk_bf16_f32 v60, v60, v61
	v_cvt_pk_bf16_f32 v61, v62, v63
	v_cvt_pk_bf16_f32 v62, v56, v57
	v_cvt_pk_bf16_f32 v63, v58, v59
	global_store_dwordx4 v[64:65], v[60:63], off sc1
	v_cvt_pk_bf16_f32 v48, v48, v49
	v_cvt_pk_bf16_f32 v49, v50, v51
	v_cvt_pk_bf16_f32 v50, v40, v41
	v_add_u32_e32 v40, 0x90, v150
	v_mad_i64_i32 v[40:41], s[20:21], v40, s3, v[138:139]
	v_cvt_pk_bf16_f32 v51, v42, v43
	global_store_dwordx4 v[64:65], v[48:51], off offset:256 sc1
	s_nop 1
	v_lshl_add_u64 v[48:49], v[40:41], 0, v[140:141]
	v_cvt_pk_bf16_f32 v40, v52, v53
	v_cvt_pk_bf16_f32 v41, v54, v55
	v_cvt_pk_bf16_f32 v42, v44, v45
	v_cvt_pk_bf16_f32 v43, v46, v47
	global_store_dwordx4 v[48:49], v[40:43], off sc1
	v_cvt_pk_bf16_f32 v32, v32, v33
	v_cvt_pk_bf16_f32 v33, v34, v35
	v_cvt_pk_bf16_f32 v34, v24, v25
	v_add_u32_e32 v24, 0xa0, v150
	v_mad_i64_i32 v[24:25], s[20:21], v24, s3, v[138:139]
	v_cvt_pk_bf16_f32 v35, v26, v27
	global_store_dwordx4 v[48:49], v[32:35], off offset:256 sc1
	s_nop 1
	v_lshl_add_u64 v[32:33], v[24:25], 0, v[140:141]
	v_cvt_pk_bf16_f32 v24, v36, v37
	v_cvt_pk_bf16_f32 v25, v38, v39
	v_cvt_pk_bf16_f32 v26, v28, v29
	v_cvt_pk_bf16_f32 v27, v30, v31
	global_store_dwordx4 v[32:33], v[24:27], off sc1
	v_cvt_pk_bf16_f32 v16, v16, v17
	v_cvt_pk_bf16_f32 v17, v18, v19
	v_cvt_pk_bf16_f32 v18, v8, v9
	v_add_u32_e32 v8, 0xb0, v150
	v_mad_i64_i32 v[8:9], s[20:21], v8, s3, v[138:139]
	v_cvt_pk_bf16_f32 v19, v10, v11
	global_store_dwordx4 v[32:33], v[16:19], off offset:256 sc1
	s_nop 1
	v_lshl_add_u64 v[16:17], v[8:9], 0, v[140:141]
	v_cvt_pk_bf16_f32 v8, v20, v21
	v_cvt_pk_bf16_f32 v9, v22, v23
	v_cvt_pk_bf16_f32 v10, v12, v13
	v_cvt_pk_bf16_f32 v11, v14, v15
	global_store_dwordx4 v[16:17], v[8:11], off sc1
	v_cvt_pk_bf16_f32 v4, v4, v5
	v_cvt_pk_bf16_f32 v5, v6, v7
	v_cvt_pk_bf16_f32 v6, v0, v1
	v_cvt_pk_bf16_f32 v7, v2, v3
	global_store_dwordx4 v[16:17], v[4:7], off offset:256 sc1
	s_cbranch_vccnz .LBB0_266
	s_andn2_b64 vcc, exec, s[6:7]
	s_cbranch_vccnz .LBB0_265
	s_barrier
	s_branch .LBB0_265

.LBB0_397:
	v_lshl_or_b32 v140, s39, 8, v146
	v_lshl_add_u32 v150, s40, 8, v142
	v_ashrrev_i32_e32 v141, 31, v140
	v_mov_b64_e32 v[138:139], s[8:9]
	v_mad_i64_i32 v[148:149], s[20:21], v150, s3, v[138:139]
	v_lshlrev_b64 v[140:141], 1, v[140:141]
	v_lshl_add_u64 v[148:149], v[148:149], 0, v[140:141]
	v_cvt_pk_bf16_f32 v124, v124, v125
	v_cvt_pk_bf16_f32 v125, v126, v127
	v_cvt_pk_bf16_f32 v126, v120, v121
	v_cvt_pk_bf16_f32 v127, v122, v123
	global_store_dwordx4 v[148:149], v[124:127], off sc1
	v_cvt_pk_bf16_f32 v112, v112, v113
	v_cvt_pk_bf16_f32 v113, v114, v115
	v_cvt_pk_bf16_f32 v114, v104, v105
	v_or_b32_e32 v104, 16, v150
	v_mad_i64_i32 v[104:105], s[20:21], v104, s3, v[138:139]
	v_cvt_pk_bf16_f32 v115, v106, v107
	global_store_dwordx4 v[148:149], v[112:115], off offset:256 sc1
	s_andn2_b64 vcc, exec, s[4:5]
	s_mov_b64 s[4:5], -1
	v_lshl_add_u64 v[112:113], v[104:105], 0, v[140:141]
	v_cvt_pk_bf16_f32 v104, v116, v117
	v_cvt_pk_bf16_f32 v105, v118, v119
	v_cvt_pk_bf16_f32 v106, v108, v109
	v_cvt_pk_bf16_f32 v107, v110, v111
	global_store_dwordx4 v[112:113], v[104:107], off sc1
	v_cvt_pk_bf16_f32 v96, v96, v97
	v_cvt_pk_bf16_f32 v97, v98, v99
	v_cvt_pk_bf16_f32 v98, v88, v89
	v_or_b32_e32 v88, 32, v150
	v_mad_i64_i32 v[88:89], s[20:21], v88, s3, v[138:139]
	v_cvt_pk_bf16_f32 v99, v90, v91
	global_store_dwordx4 v[112:113], v[96:99], off offset:256 sc1
	s_nop 1
	v_lshl_add_u64 v[96:97], v[88:89], 0, v[140:141]
	v_cvt_pk_bf16_f32 v88, v100, v101
	v_cvt_pk_bf16_f32 v89, v102, v103
	v_cvt_pk_bf16_f32 v90, v92, v93
	v_cvt_pk_bf16_f32 v91, v94, v95
	global_store_dwordx4 v[96:97], v[88:91], off sc1
	v_cvt_pk_bf16_f32 v80, v80, v81
	v_cvt_pk_bf16_f32 v81, v82, v83
	v_cvt_pk_bf16_f32 v82, v72, v73
	v_or_b32_e32 v72, 48, v150
	v_mad_i64_i32 v[72:73], s[20:21], v72, s3, v[138:139]
	v_cvt_pk_bf16_f32 v83, v74, v75
	global_store_dwordx4 v[96:97], v[80:83], off offset:256 sc1
	s_nop 1
	v_lshl_add_u64 v[80:81], v[72:73], 0, v[140:141]
	v_cvt_pk_bf16_f32 v72, v84, v85
	v_cvt_pk_bf16_f32 v73, v86, v87
	v_cvt_pk_bf16_f32 v74, v76, v77
	v_cvt_pk_bf16_f32 v75, v78, v79
	global_store_dwordx4 v[80:81], v[72:75], off sc1
	v_cvt_pk_bf16_f32 v68, v68, v69
	v_cvt_pk_bf16_f32 v69, v70, v71
	v_cvt_pk_bf16_f32 v70, v64, v65
	v_add_u32_e32 v64, 0x80, v150
	v_mad_i64_i32 v[64:65], s[20:21], v64, s3, v[138:139]
	v_lshl_add_u64 v[64:65], v[64:65], 0, v[140:141]
	v_cvt_pk_bf16_f32 v71, v66, v67
	global_store_dwordx4 v[80:81], v[68:71], off offset:256 sc1
	v_cvt_pk_bf16_f32 v60, v60, v61
	v_cvt_pk_bf16_f32 v61, v62, v63
	v_cvt_pk_bf16_f32 v62, v56, v57
	v_cvt_pk_bf16_f32 v63, v58, v59
	global_store_dwordx4 v[64:65], v[60:63], off sc1
	v_cvt_pk_bf16_f32 v48, v48, v49
	v_cvt_pk_bf16_f32 v49, v50, v51
	v_cvt_pk_bf16_f32 v50, v40, v41
	v_add_u32_e32 v40, 0x90, v150
	v_mad_i64_i32 v[40:41], s[20:21], v40, s3, v[138:139]
	v_cvt_pk_bf16_f32 v51, v42, v43
	global_store_dwordx4 v[64:65], v[48:51], off offset:256 sc1
	s_nop 1
	v_lshl_add_u64 v[48:49], v[40:41], 0, v[140:141]
	v_cvt_pk_bf16_f32 v40, v52, v53
	v_cvt_pk_bf16_f32 v41, v54, v55
	v_cvt_pk_bf16_f32 v42, v44, v45
	v_cvt_pk_bf16_f32 v43, v46, v47
	global_store_dwordx4 v[48:49], v[40:43], off sc1
	v_cvt_pk_bf16_f32 v32, v32, v33
	v_cvt_pk_bf16_f32 v33, v34, v35
	v_cvt_pk_bf16_f32 v34, v24, v25
	v_add_u32_e32 v24, 0xa0, v150
	v_mad_i64_i32 v[24:25], s[20:21], v24, s3, v[138:139]
	v_cvt_pk_bf16_f32 v35, v26, v27
	global_store_dwordx4 v[48:49], v[32:35], off offset:256 sc1
	s_nop 1
	v_lshl_add_u64 v[32:33], v[24:25], 0, v[140:141]
	v_cvt_pk_bf16_f32 v24, v36, v37
	v_cvt_pk_bf16_f32 v25, v38, v39
	v_cvt_pk_bf16_f32 v26, v28, v29
	v_cvt_pk_bf16_f32 v27, v30, v31
	global_store_dwordx4 v[32:33], v[24:27], off sc1
	v_cvt_pk_bf16_f32 v16, v16, v17
	v_cvt_pk_bf16_f32 v17, v18, v19
	v_cvt_pk_bf16_f32 v18, v8, v9
	v_add_u32_e32 v8, 0xb0, v150
	v_mad_i64_i32 v[8:9], s[20:21], v8, s3, v[138:139]
	v_cvt_pk_bf16_f32 v19, v10, v11
	global_store_dwordx4 v[32:33], v[16:19], off offset:256 sc1
	s_nop 1
	v_lshl_add_u64 v[16:17], v[8:9], 0, v[140:141]
	v_cvt_pk_bf16_f32 v8, v20, v21
	v_cvt_pk_bf16_f32 v9, v22, v23
	v_cvt_pk_bf16_f32 v10, v12, v13
	v_cvt_pk_bf16_f32 v11, v14, v15
	global_store_dwordx4 v[16:17], v[8:11], off sc1
	v_cvt_pk_bf16_f32 v4, v4, v5
	v_cvt_pk_bf16_f32 v5, v6, v7
	v_cvt_pk_bf16_f32 v6, v0, v1
	v_cvt_pk_bf16_f32 v7, v2, v3
	global_store_dwordx4 v[16:17], v[4:7], off offset:256 sc1
	s_cbranch_vccnz .LBB0_390
	s_andn2_b64 vcc, exec, s[0:1]
	s_cbranch_vccnz .LBB0_389
	s_barrier
	s_branch .LBB0_389

.LBB0_415:
	v_or_b32_e32 v140, s17, v147
	v_cvt_pk_bf16_f32 v124, v124, v125
	v_cvt_pk_bf16_f32 v125, v126, v127
	v_cvt_pk_bf16_f32 v126, v120, v121
	v_mov_b64_e32 v[120:121], s[10:11]
	s_movk_i32 s17, 0xe00
	v_ashrrev_i32_e32 v141, 31, v140
	v_mad_i64_i32 v[120:121], s[42:43], v152, s17, v[120:121]
	v_cvt_pk_bf16_f32 v127, v122, v123
	v_lshl_add_u64 v[120:121], v[140:141], 1, v[120:121]
	s_and_b64 vcc, exec, s[8:9]
	v_or_b32_e32 v122, 16, v152
	global_store_dwordx4 v[120:121], v[124:127], off sc1
	s_cbranch_vccnz .LBB0_417
	v_cndmask_b32_e64 v123, v122, v151, s[6:7]
	v_lshlrev_b32_e32 v123, 7, v123
	v_and_b32_e32 v123, 0x1f80, v123
	v_add_u32_e32 v123, v149, v123
	ds_bpermute_b32 v166, v148, v116
	ds_bpermute_b32 v167, v148, v117
	ds_read_b128 v[124:127], v123
	ds_read_b128 v[154:157], v123 offset:16
	ds_read_b128 v[158:161], v123 offset:32
	ds_read_b128 v[162:165], v123 offset:48
	ds_bpermute_b32 v168, v148, v112
	ds_bpermute_b32 v169, v148, v113
	ds_bpermute_b32 v123, v148, v118
	ds_bpermute_b32 v153, v148, v114
	s_waitcnt lgkmcnt(0)
	v_mov_b32_e32 v171, v126
	v_pk_mul_f32 v[166:167], v[134:135], v[166:167]
	v_mov_b32_e32 v126, v125
	v_mov_b32_e32 v170, v124
	v_pk_mul_f32 v[124:125], v[126:127], v[166:167]
	v_mov_b32_e32 v127, v160
	v_pk_mul_f32 v[166:167], v[134:135], v[168:169]
	v_mov_b32_e32 v160, v159
	v_mul_f32_e32 v123, v134, v123
	v_mul_f32_e32 v153, v134, v153
	v_mov_b32_e32 v126, v158
	v_pk_mul_f32 v[158:159], v[160:161], v[166:167]
	v_mul_f32_e32 v118, v118, v154
	v_mul_f32_e32 v154, v155, v123
	ds_bpermute_b32 v123, v148, v119
	v_mul_f32_e32 v160, v163, v153
	ds_bpermute_b32 v153, v148, v115
	v_mul_f32_e32 v114, v114, v162
	v_mov_b32_e32 v162, v119
	s_waitcnt lgkmcnt(0)
	v_mul_f32_e32 v163, v134, v123
	v_pk_fma_f32 v[116:117], v[116:117], v[170:171], v[124:125]
	v_mul_f32_e32 v125, v134, v153
	v_mov_b32_e32 v124, v115
	v_pk_mul_f32 v[156:157], v[156:157], v[162:163]
	v_pk_mul_f32 v[124:125], v[164:165], v[124:125]
	v_mov_b32_e32 v119, v156
	v_mov_b32_e32 v155, v157
	v_mov_b32_e32 v115, v124
	v_mov_b32_e32 v161, v125
	v_pk_add_f32 v[118:119], v[118:119], v[154:155]
	v_pk_fma_f32 v[112:113], v[112:113], v[126:127], v[158:159]
	v_pk_add_f32 v[114:115], v[114:115], v[160:161]
.LBB0_417:
	v_cvt_pk_bf16_f32 v116, v116, v117
	v_cvt_pk_bf16_f32 v117, v118, v119
	v_cvt_pk_bf16_f32 v118, v112, v113
	v_mov_b64_e32 v[112:113], s[10:11]
	v_mad_i64_i32 v[112:113], s[42:43], v122, s17, v[112:113]
	v_cvt_pk_bf16_f32 v119, v114, v115
	v_lshl_add_u64 v[112:113], v[140:141], 1, v[112:113]
	s_and_b64 vcc, exec, s[8:9]
	v_or_b32_e32 v114, 32, v152
	global_store_dwordx4 v[112:113], v[116:119], off sc1
	s_cbranch_vccnz .LBB0_419
	v_cndmask_b32_e64 v115, v114, v151, s[6:7]
	v_lshlrev_b32_e32 v115, 7, v115
	v_and_b32_e32 v115, 0x1f80, v115
	v_add_u32_e32 v115, v149, v115
	ds_bpermute_b32 v162, v148, v108
	ds_bpermute_b32 v163, v148, v109
	ds_read_b128 v[116:119], v115
	ds_read_b128 v[124:127], v115 offset:16
	ds_read_b128 v[154:157], v115 offset:32
	ds_read_b128 v[158:161], v115 offset:48
	ds_bpermute_b32 v164, v148, v104
	ds_bpermute_b32 v165, v148, v105
	ds_bpermute_b32 v115, v148, v110
	ds_bpermute_b32 v123, v148, v106
	s_waitcnt lgkmcnt(0)
	v_mov_b32_e32 v167, v118
	v_pk_mul_f32 v[162:163], v[134:135], v[162:163]
	v_mov_b32_e32 v118, v117
	v_mov_b32_e32 v166, v116
	v_pk_mul_f32 v[116:117], v[118:119], v[162:163]
	v_mov_b32_e32 v119, v156
	v_pk_mul_f32 v[162:163], v[134:135], v[164:165]
	v_mov_b32_e32 v156, v155
	v_mul_f32_e32 v115, v134, v115
	v_mul_f32_e32 v123, v134, v123
	v_mov_b32_e32 v118, v154
	v_pk_mul_f32 v[154:155], v[156:157], v[162:163]
	v_mul_f32_e32 v110, v110, v124
	v_mul_f32_e32 v124, v125, v115
	ds_bpermute_b32 v115, v148, v111
	v_mul_f32_e32 v156, v159, v123
	ds_bpermute_b32 v123, v148, v107
	v_mul_f32_e32 v106, v106, v158
	v_mov_b32_e32 v158, v111
	s_waitcnt lgkmcnt(0)
	v_mul_f32_e32 v159, v134, v115
	v_pk_fma_f32 v[108:109], v[108:109], v[166:167], v[116:117]
	v_mul_f32_e32 v117, v134, v123
	v_mov_b32_e32 v116, v107
	v_pk_mul_f32 v[126:127], v[126:127], v[158:159]
	v_pk_mul_f32 v[116:117], v[160:161], v[116:117]
	v_mov_b32_e32 v111, v126
	v_mov_b32_e32 v125, v127
	v_mov_b32_e32 v107, v116
	v_mov_b32_e32 v157, v117
	v_pk_add_f32 v[110:111], v[110:111], v[124:125]
	v_pk_fma_f32 v[104:105], v[104:105], v[118:119], v[154:155]
	v_pk_add_f32 v[106:107], v[106:107], v[156:157]
.LBB0_419:
	v_cvt_pk_bf16_f32 v108, v108, v109
	v_cvt_pk_bf16_f32 v109, v110, v111
	v_cvt_pk_bf16_f32 v110, v104, v105
	v_mov_b64_e32 v[104:105], s[10:11]
	v_mad_i64_i32 v[104:105], s[42:43], v114, s17, v[104:105]
	v_cvt_pk_bf16_f32 v111, v106, v107
	v_lshl_add_u64 v[104:105], v[140:141], 1, v[104:105]
	s_and_b64 vcc, exec, s[8:9]
	v_or_b32_e32 v106, 48, v152
	global_store_dwordx4 v[104:105], v[108:111], off sc1
	s_cbranch_vccnz .LBB0_421
	v_cndmask_b32_e64 v107, v106, v151, s[6:7]
	v_lshlrev_b32_e32 v107, 7, v107
	v_and_b32_e32 v107, 0x1f80, v107
	v_add_u32_e32 v107, v149, v107
	ds_bpermute_b32 v158, v148, v100
	ds_bpermute_b32 v159, v148, v101
	ds_read_b128 v[108:111], v107
	ds_read_b128 v[116:119], v107 offset:16
	ds_read_b128 v[124:127], v107 offset:32
	ds_read_b128 v[154:157], v107 offset:48
	ds_bpermute_b32 v160, v148, v96
	ds_bpermute_b32 v161, v148, v97
	ds_bpermute_b32 v107, v148, v102
	ds_bpermute_b32 v115, v148, v98
	s_waitcnt lgkmcnt(0)
	v_mov_b32_e32 v163, v110
	v_pk_mul_f32 v[158:159], v[134:135], v[158:159]
	v_mov_b32_e32 v110, v109
	v_mov_b32_e32 v162, v108
	v_pk_mul_f32 v[108:109], v[110:111], v[158:159]
	v_mov_b32_e32 v111, v126
	v_pk_mul_f32 v[158:159], v[134:135], v[160:161]
	v_mov_b32_e32 v126, v125
	v_mul_f32_e32 v107, v134, v107
	v_mul_f32_e32 v115, v134, v115
	v_mov_b32_e32 v110, v124
	v_pk_mul_f32 v[124:125], v[126:127], v[158:159]
	v_mul_f32_e32 v102, v102, v116
	v_mul_f32_e32 v116, v117, v107
	ds_bpermute_b32 v107, v148, v103
	v_mul_f32_e32 v126, v155, v115
	ds_bpermute_b32 v115, v148, v99
	v_mul_f32_e32 v98, v98, v154
	v_mov_b32_e32 v154, v103
	s_waitcnt lgkmcnt(0)
	v_mul_f32_e32 v155, v134, v107
	v_pk_fma_f32 v[100:101], v[100:101], v[162:163], v[108:109]
	v_mul_f32_e32 v109, v134, v115
	v_mov_b32_e32 v108, v99
	v_pk_mul_f32 v[118:119], v[118:119], v[154:155]
	v_pk_mul_f32 v[108:109], v[156:157], v[108:109]
	v_mov_b32_e32 v103, v118
	v_mov_b32_e32 v117, v119
	v_mov_b32_e32 v99, v108
	v_mov_b32_e32 v127, v109
	v_pk_add_f32 v[102:103], v[102:103], v[116:117]
	v_pk_fma_f32 v[96:97], v[96:97], v[110:111], v[124:125]
	v_pk_add_f32 v[98:99], v[98:99], v[126:127]
.LBB0_421:
	v_cvt_pk_bf16_f32 v100, v100, v101
	v_cvt_pk_bf16_f32 v101, v102, v103
	v_cvt_pk_bf16_f32 v102, v96, v97
	v_mov_b64_e32 v[96:97], s[10:11]
	v_cvt_pk_bf16_f32 v103, v98, v99
	v_mad_i64_i32 v[96:97], s[42:43], v106, s17, v[96:97]
	v_add_u32_e32 v99, 0x80, v152
	v_lshl_add_u64 v[96:97], v[140:141], 1, v[96:97]
	s_and_b64 vcc, exec, s[8:9]
	v_lshrrev_b32_e32 v98, 6, v99
	global_store_dwordx4 v[96:97], v[100:103], off sc1
	s_cbranch_vccnz .LBB0_423
	s_nop 0
	v_cndmask_b32_e64 v100, v142, v98, s[6:7]
	v_lshlrev_b32_e32 v100, 7, v100
	v_and_b32_e32 v100, 0x1f80, v100
	v_add_u32_e32 v107, v149, v100
	ds_read_b128 v[100:103], v107
	ds_read_b128 v[108:111], v107 offset:16
	ds_read_b128 v[116:119], v107 offset:32
	ds_read_b128 v[124:127], v107 offset:48
	ds_bpermute_b32 v107, v148, v94
	ds_bpermute_b32 v115, v148, v90
	ds_bpermute_b32 v154, v148, v92
	ds_bpermute_b32 v155, v148, v93
	ds_bpermute_b32 v156, v148, v88
	ds_bpermute_b32 v157, v148, v89
	s_waitcnt lgkmcnt(0)
	v_mul_f32_e32 v107, v134, v107
	v_mul_f32_e32 v94, v94, v108
	v_mul_f32_e32 v108, v109, v107
	ds_bpermute_b32 v107, v148, v95
	v_mul_f32_e32 v109, v134, v115
	ds_bpermute_b32 v115, v148, v91
	v_mov_b32_e32 v159, v102
	v_pk_mul_f32 v[154:155], v[134:135], v[154:155]
	v_mov_b32_e32 v102, v101
	v_mov_b32_e32 v158, v100
	v_pk_mul_f32 v[100:101], v[102:103], v[154:155]
	v_mov_b32_e32 v103, v118
	v_pk_mul_f32 v[154:155], v[134:135], v[156:157]
	v_mov_b32_e32 v118, v117
	v_mov_b32_e32 v102, v116
	v_pk_mul_f32 v[116:117], v[118:119], v[154:155]
	v_mul_f32_e32 v90, v90, v124
	v_mul_f32_e32 v118, v125, v109
	s_waitcnt lgkmcnt(0)
	v_mul_f32_e32 v125, v134, v107
	v_mov_b32_e32 v124, v95
	v_pk_fma_f32 v[92:93], v[92:93], v[158:159], v[100:101]
	v_mul_f32_e32 v101, v134, v115
	v_mov_b32_e32 v100, v91
	v_pk_mul_f32 v[110:111], v[110:111], v[124:125]
	v_pk_mul_f32 v[100:101], v[126:127], v[100:101]
	v_mov_b32_e32 v95, v110
	v_mov_b32_e32 v109, v111
	v_mov_b32_e32 v91, v100
	v_mov_b32_e32 v119, v101
	v_pk_add_f32 v[94:95], v[94:95], v[108:109]
	v_pk_fma_f32 v[88:89], v[88:89], v[102:103], v[116:117]
	v_pk_add_f32 v[90:91], v[90:91], v[118:119]
.LBB0_423:
	v_cvt_pk_bf16_f32 v92, v92, v93
	v_cvt_pk_bf16_f32 v93, v94, v95
	v_cvt_pk_bf16_f32 v94, v88, v89
	v_mov_b64_e32 v[88:89], s[10:11]
	v_mad_i64_i32 v[88:89], s[42:43], v99, s17, v[88:89]
	v_cvt_pk_bf16_f32 v95, v90, v91
	v_lshl_add_u64 v[88:89], v[140:141], 1, v[88:89]
	s_and_b64 vcc, exec, s[8:9]
	v_add_u32_e32 v90, 0x90, v152
	global_store_dwordx4 v[88:89], v[92:95], off sc1
	s_cbranch_vccnz .LBB0_425
	v_cndmask_b32_e64 v91, v90, v98, s[6:7]
	v_lshlrev_b32_e32 v91, 7, v91
	v_and_b32_e32 v91, 0x1f80, v91
	v_add_u32_e32 v91, v149, v91
	ds_bpermute_b32 v124, v148, v84
	ds_bpermute_b32 v125, v148, v85
	ds_read_b128 v[92:95], v91
	ds_read_b128 v[100:103], v91 offset:16
	ds_read_b128 v[108:111], v91 offset:32
	ds_read_b128 v[116:119], v91 offset:48
	ds_bpermute_b32 v126, v148, v80
	ds_bpermute_b32 v127, v148, v81
	ds_bpermute_b32 v91, v148, v86
	ds_bpermute_b32 v99, v148, v82
	s_waitcnt lgkmcnt(0)
	v_mov_b32_e32 v155, v94
	v_pk_mul_f32 v[124:125], v[134:135], v[124:125]
	v_mov_b32_e32 v94, v93
	v_mov_b32_e32 v154, v92
	v_pk_mul_f32 v[92:93], v[94:95], v[124:125]
	v_mov_b32_e32 v95, v110
	v_pk_mul_f32 v[124:125], v[134:135], v[126:127]
	v_mov_b32_e32 v110, v109
	v_mul_f32_e32 v91, v134, v91
	v_mul_f32_e32 v99, v134, v99
	v_mov_b32_e32 v94, v108
	v_pk_mul_f32 v[108:109], v[110:111], v[124:125]
	v_mul_f32_e32 v86, v86, v100
	v_mul_f32_e32 v100, v101, v91
	ds_bpermute_b32 v91, v148, v87
	v_mul_f32_e32 v110, v117, v99
	ds_bpermute_b32 v99, v148, v83
	v_mul_f32_e32 v82, v82, v116
	v_mov_b32_e32 v116, v87
	s_waitcnt lgkmcnt(0)
	v_mul_f32_e32 v117, v134, v91
	v_pk_fma_f32 v[84:85], v[84:85], v[154:155], v[92:93]
	v_mul_f32_e32 v93, v134, v99
	v_mov_b32_e32 v92, v83
	v_pk_mul_f32 v[102:103], v[102:103], v[116:117]
	v_pk_mul_f32 v[92:93], v[118:119], v[92:93]
	v_mov_b32_e32 v87, v102
	v_mov_b32_e32 v101, v103
	v_mov_b32_e32 v83, v92
	v_mov_b32_e32 v111, v93
	v_pk_add_f32 v[86:87], v[86:87], v[100:101]
	v_pk_fma_f32 v[80:81], v[80:81], v[94:95], v[108:109]
	v_pk_add_f32 v[82:83], v[82:83], v[110:111]
.LBB0_425:
	v_cvt_pk_bf16_f32 v84, v84, v85
	v_cvt_pk_bf16_f32 v85, v86, v87
	v_cvt_pk_bf16_f32 v86, v80, v81
	v_mov_b64_e32 v[80:81], s[10:11]
	v_mad_i64_i32 v[80:81], s[42:43], v90, s17, v[80:81]
	v_cvt_pk_bf16_f32 v87, v82, v83
	v_lshl_add_u64 v[80:81], v[140:141], 1, v[80:81]
	s_and_b64 vcc, exec, s[8:9]
	v_add_u32_e32 v82, 0xa0, v152
	global_store_dwordx4 v[80:81], v[84:87], off sc1
	s_cbranch_vccnz .LBB0_427
	v_cndmask_b32_e64 v83, v82, v98, s[6:7]
	v_lshlrev_b32_e32 v83, 7, v83
	v_and_b32_e32 v83, 0x1f80, v83
	v_add_u32_e32 v83, v149, v83
	ds_bpermute_b32 v116, v148, v76
	ds_bpermute_b32 v117, v148, v77
	ds_read_b128 v[84:87], v83
	ds_read_b128 v[92:95], v83 offset:16
	ds_read_b128 v[100:103], v83 offset:32
	ds_read_b128 v[108:111], v83 offset:48
	ds_bpermute_b32 v118, v148, v72
	ds_bpermute_b32 v119, v148, v73
	ds_bpermute_b32 v83, v148, v78
	ds_bpermute_b32 v91, v148, v74
	s_waitcnt lgkmcnt(0)
	v_mov_b32_e32 v125, v86
	v_pk_mul_f32 v[116:117], v[134:135], v[116:117]
	v_mov_b32_e32 v86, v85
	v_mov_b32_e32 v124, v84
	v_pk_mul_f32 v[84:85], v[86:87], v[116:117]
	v_mov_b32_e32 v87, v102
	v_pk_mul_f32 v[116:117], v[134:135], v[118:119]
	v_mov_b32_e32 v102, v101
	v_mul_f32_e32 v83, v134, v83
	v_mul_f32_e32 v91, v134, v91
	v_mov_b32_e32 v86, v100
	v_pk_mul_f32 v[100:101], v[102:103], v[116:117]
	v_mul_f32_e32 v78, v78, v92
	v_mul_f32_e32 v92, v93, v83
	ds_bpermute_b32 v83, v148, v79
	v_mul_f32_e32 v102, v109, v91
	ds_bpermute_b32 v91, v148, v75
	v_mul_f32_e32 v74, v74, v108
	v_mov_b32_e32 v108, v79
	s_waitcnt lgkmcnt(0)
	v_mul_f32_e32 v109, v134, v83
	v_pk_fma_f32 v[76:77], v[76:77], v[124:125], v[84:85]
	v_mul_f32_e32 v85, v134, v91
	v_mov_b32_e32 v84, v75
	v_pk_mul_f32 v[94:95], v[94:95], v[108:109]
	v_pk_mul_f32 v[84:85], v[110:111], v[84:85]
	v_mov_b32_e32 v79, v94
	v_mov_b32_e32 v93, v95
	v_mov_b32_e32 v75, v84
	v_mov_b32_e32 v103, v85
	v_pk_add_f32 v[78:79], v[78:79], v[92:93]
	v_pk_fma_f32 v[72:73], v[72:73], v[86:87], v[100:101]
	v_pk_add_f32 v[74:75], v[74:75], v[102:103]
.LBB0_427:
	v_cvt_pk_bf16_f32 v76, v76, v77
	v_cvt_pk_bf16_f32 v77, v78, v79
	v_cvt_pk_bf16_f32 v78, v72, v73
	v_mov_b64_e32 v[72:73], s[10:11]
	v_mad_i64_i32 v[72:73], s[42:43], v82, s17, v[72:73]
	v_cvt_pk_bf16_f32 v79, v74, v75
	v_lshl_add_u64 v[72:73], v[140:141], 1, v[72:73]
	s_and_b64 vcc, exec, s[8:9]
	v_add_u32_e32 v74, 0xb0, v152
	global_store_dwordx4 v[72:73], v[76:79], off sc1
	s_cbranch_vccnz .LBB0_429
	v_cndmask_b32_e64 v75, v74, v98, s[6:7]
	v_lshlrev_b32_e32 v75, 7, v75
	v_and_b32_e32 v75, 0x1f80, v75
	v_add_u32_e32 v75, v149, v75
	ds_bpermute_b32 v108, v148, v68
	ds_bpermute_b32 v109, v148, v69
	ds_read_b128 v[76:79], v75
	ds_read_b128 v[84:87], v75 offset:16
	ds_read_b128 v[92:95], v75 offset:32
	ds_read_b128 v[100:103], v75 offset:48
	ds_bpermute_b32 v110, v148, v64
	ds_bpermute_b32 v111, v148, v65
	ds_bpermute_b32 v75, v148, v70
	ds_bpermute_b32 v83, v148, v66
	s_waitcnt lgkmcnt(0)
	v_mov_b32_e32 v117, v78
	v_pk_mul_f32 v[108:109], v[134:135], v[108:109]
	v_mov_b32_e32 v78, v77
	v_mov_b32_e32 v116, v76
	v_pk_mul_f32 v[76:77], v[78:79], v[108:109]
	v_mov_b32_e32 v79, v94
	v_pk_mul_f32 v[108:109], v[134:135], v[110:111]
	v_mov_b32_e32 v94, v93
	v_mul_f32_e32 v75, v134, v75
	v_mul_f32_e32 v83, v134, v83
	v_mov_b32_e32 v78, v92
	v_pk_mul_f32 v[92:93], v[94:95], v[108:109]
	v_mul_f32_e32 v70, v70, v84
	v_mul_f32_e32 v84, v85, v75
	ds_bpermute_b32 v75, v148, v71
	v_mul_f32_e32 v94, v101, v83
	ds_bpermute_b32 v83, v148, v67
	v_mul_f32_e32 v66, v66, v100
	v_mov_b32_e32 v100, v71
	s_waitcnt lgkmcnt(0)
	v_mul_f32_e32 v101, v134, v75
	v_pk_fma_f32 v[68:69], v[68:69], v[116:117], v[76:77]
	v_mul_f32_e32 v77, v134, v83
	v_mov_b32_e32 v76, v67
	v_pk_mul_f32 v[86:87], v[86:87], v[100:101]
	v_pk_mul_f32 v[76:77], v[102:103], v[76:77]
	v_mov_b32_e32 v71, v86
	v_mov_b32_e32 v85, v87
	v_mov_b32_e32 v67, v76
	v_mov_b32_e32 v95, v77
	v_pk_add_f32 v[70:71], v[70:71], v[84:85]
	v_pk_fma_f32 v[64:65], v[64:65], v[78:79], v[92:93]
	v_pk_add_f32 v[66:67], v[66:67], v[94:95]
.LBB0_429:
	v_cvt_pk_bf16_f32 v68, v68, v69
	v_cvt_pk_bf16_f32 v69, v70, v71
	v_cvt_pk_bf16_f32 v70, v64, v65
	v_mov_b64_e32 v[64:65], s[10:11]
	s_movk_i32 s6, 0xe00
	s_bitset1_b32 s15, 7
	v_mad_i64_i32 v[64:65], s[6:7], v74, s6, v[64:65]
	s_cmpk_lt_i32 s15, 0x300
	s_mul_hi_i32 s8, s15, 0x2aaaaaab
	s_cselect_b64 s[6:7], -1, 0
	s_lshr_b32 s9, s8, 31
	s_lshr_b32 s8, s8, 5
	s_add_i32 s8, s8, s9
	s_mulk_i32 s8, 0xc0
	s_sub_i32 s15, s15, s8
	s_cmpk_gt_i32 s15, 0x7f
	s_cselect_b64 s[8:9], -1, 0
	s_and_b64 s[6:7], s[6:7], s[8:9]
	s_and_b64 s[24:25], s[6:7], s[24:25]
	v_cvt_pk_bf16_f32 v71, v66, v67
	s_cmpk_eq_i32 s15, 0x80
	v_cndmask_b32_e64 v66, 0, 1, s[24:25]
	v_lshl_add_u64 v[64:65], v[140:141], 1, v[64:65]
	s_cselect_b64 s[6:7], -1, 0
	v_cmp_ne_u32_e64 s[8:9], 1, v66
	s_andn2_b64 vcc, exec, s[24:25]
	global_store_dwordx4 v[64:65], v[68:71], off sc1
	s_cbranch_vccnz .LBB0_431
	v_cndmask_b32_e64 v66, v142, v151, s[6:7]
	v_lshlrev_b32_e32 v66, 7, v66
	ds_bpermute_b32 v75, v148, v62
	v_and_b32_e32 v66, 0x1f80, v66
	ds_bpermute_b32 v83, v148, v58
	v_add_u32_e32 v70, v149, v66
	ds_read_b128 v[66:69], v70
	ds_read_b128 v[76:79], v70 offset:16
	ds_read_b128 v[84:87], v70 offset:32
	ds_read_b128 v[92:95], v70 offset:48
	ds_bpermute_b32 v70, v148, v60
	ds_bpermute_b32 v71, v148, v61
	ds_bpermute_b32 v100, v148, v56
	ds_bpermute_b32 v101, v148, v57
	s_waitcnt lgkmcnt(0)
	v_mul_f32_e32 v75, v134, v75
	v_mul_f32_e32 v62, v62, v76
	v_mul_f32_e32 v76, v77, v75
	ds_bpermute_b32 v75, v148, v63
	v_mul_f32_e32 v77, v134, v83
	ds_bpermute_b32 v83, v148, v59
	v_mov_b32_e32 v103, v68
	v_pk_mul_f32 v[70:71], v[134:135], v[70:71]
	v_mov_b32_e32 v68, v67
	v_mov_b32_e32 v102, v66
	v_pk_mul_f32 v[66:67], v[68:69], v[70:71]
	v_mov_b32_e32 v69, v86
	v_pk_mul_f32 v[70:71], v[134:135], v[100:101]
	v_mov_b32_e32 v86, v85
	v_pk_mul_f32 v[70:71], v[86:87], v[70:71]
	s_waitcnt lgkmcnt(0)
	v_mul_f32_e32 v87, v134, v75
	v_mov_b32_e32 v86, v63
	v_pk_fma_f32 v[60:61], v[60:61], v[102:103], v[66:67]
	v_mul_f32_e32 v67, v134, v83
	v_mov_b32_e32 v66, v59
	v_pk_mul_f32 v[78:79], v[78:79], v[86:87]
	v_pk_mul_f32 v[66:67], v[94:95], v[66:67]
	v_mov_b32_e32 v68, v84
	v_mul_f32_e32 v58, v58, v92
	v_mul_f32_e32 v84, v93, v77
	v_mov_b32_e32 v63, v78
	v_mov_b32_e32 v77, v79
	v_mov_b32_e32 v59, v66
	v_mov_b32_e32 v85, v67
	v_pk_add_f32 v[62:63], v[62:63], v[76:77]
	v_pk_fma_f32 v[56:57], v[56:57], v[68:69], v[70:71]
	v_pk_add_f32 v[58:59], v[58:59], v[84:85]
.LBB0_431:
	s_and_b64 vcc, exec, s[8:9]
	v_cvt_pk_bf16_f32 v60, v60, v61
	v_cvt_pk_bf16_f32 v61, v62, v63
	v_cvt_pk_bf16_f32 v62, v56, v57
	v_cvt_pk_bf16_f32 v63, v58, v59
	global_store_dwordx4 v[120:121], v[60:63], off offset:256 sc1
	s_cbranch_vccnz .LBB0_433
	v_cndmask_b32_e64 v56, v122, v151, s[6:7]
	v_lshlrev_b32_e32 v56, 7, v56
	v_and_b32_e32 v56, 0x1f80, v56
	v_add_u32_e32 v70, v149, v56
	ds_read_b128 v[56:59], v70
	ds_read_b128 v[60:63], v70 offset:16
	ds_read_b128 v[66:69], v70 offset:32
	ds_read_b128 v[76:79], v70 offset:48
	ds_bpermute_b32 v70, v148, v52
	ds_bpermute_b32 v71, v148, v53
	ds_bpermute_b32 v84, v148, v48
	ds_bpermute_b32 v85, v148, v49
	ds_bpermute_b32 v75, v148, v54
	s_waitcnt lgkmcnt(0)
	v_mov_b32_e32 v87, v58
	v_pk_mul_f32 v[70:71], v[134:135], v[70:71]
	v_mov_b32_e32 v58, v57
	v_mov_b32_e32 v86, v56
	v_pk_mul_f32 v[56:57], v[58:59], v[70:71]
	v_mov_b32_e32 v59, v68
	v_pk_mul_f32 v[70:71], v[134:135], v[84:85]
	v_mov_b32_e32 v68, v67
	v_mul_f32_e32 v54, v54, v60
	v_mul_f32_e32 v60, v134, v75
	v_mov_b32_e32 v58, v66
	v_pk_mul_f32 v[66:67], v[68:69], v[70:71]
	v_mul_f32_e32 v60, v61, v60
	ds_bpermute_b32 v61, v148, v55
	ds_bpermute_b32 v69, v148, v51
	ds_bpermute_b32 v68, v148, v50
	v_mov_b32_e32 v70, v55
	v_pk_fma_f32 v[52:53], v[52:53], v[86:87], v[56:57]
	s_waitcnt lgkmcnt(0)
	v_mul_f32_e32 v71, v134, v61
	v_mul_f32_e32 v57, v134, v69
	v_mov_b32_e32 v56, v51
	v_mul_f32_e32 v68, v134, v68
	v_pk_mul_f32 v[62:63], v[62:63], v[70:71]
	v_pk_mul_f32 v[56:57], v[78:79], v[56:57]
	v_mul_f32_e32 v50, v50, v76
	v_mul_f32_e32 v68, v77, v68
	v_mov_b32_e32 v55, v62
	v_mov_b32_e32 v61, v63
	v_mov_b32_e32 v51, v56
	v_mov_b32_e32 v69, v57
	v_pk_add_f32 v[54:55], v[54:55], v[60:61]
	v_pk_fma_f32 v[48:49], v[48:49], v[58:59], v[66:67]
	v_pk_add_f32 v[50:51], v[50:51], v[68:69]
.LBB0_433:
	s_and_b64 vcc, exec, s[8:9]
	v_cvt_pk_bf16_f32 v52, v52, v53
	v_cvt_pk_bf16_f32 v53, v54, v55
	v_cvt_pk_bf16_f32 v54, v48, v49
	v_cvt_pk_bf16_f32 v55, v50, v51
	global_store_dwordx4 v[112:113], v[52:55], off offset:256 sc1
	s_cbranch_vccnz .LBB0_435
	v_cndmask_b32_e64 v48, v114, v151, s[6:7]
	v_lshlrev_b32_e32 v48, 7, v48
	ds_bpermute_b32 v66, v148, v44
	ds_bpermute_b32 v67, v148, v45
	v_and_b32_e32 v48, 0x1f80, v48
	ds_bpermute_b32 v68, v148, v40
	ds_bpermute_b32 v69, v148, v41
	v_add_u32_e32 v60, v149, v48
	ds_read_b128 v[48:51], v60
	ds_read_b128 v[52:55], v60 offset:16
	ds_read_b128 v[56:59], v60 offset:32
	ds_read_b128 v[60:63], v60 offset:48
	s_waitcnt lgkmcnt(0)
	v_pk_mul_f32 v[66:67], v[134:135], v[66:67]
	v_mov_b32_e32 v71, v50
	v_mov_b32_e32 v50, v49
	v_mov_b32_e32 v70, v48
	v_pk_mul_f32 v[48:49], v[50:51], v[66:67]
	v_pk_mul_f32 v[66:67], v[134:135], v[68:69]
	ds_bpermute_b32 v68, v148, v46
	v_mov_b32_e32 v51, v58
	v_mov_b32_e32 v58, v57
	v_mov_b32_e32 v50, v56
	v_pk_mul_f32 v[56:57], v[58:59], v[66:67]
	ds_bpermute_b32 v58, v148, v42
	v_mul_f32_e32 v46, v46, v52
	s_waitcnt lgkmcnt(0)
	v_mul_f32_e32 v52, v134, v68
	v_mul_f32_e32 v52, v53, v52
	ds_bpermute_b32 v53, v148, v47
	ds_bpermute_b32 v59, v148, v43
	v_mul_f32_e32 v58, v134, v58
	v_mul_f32_e32 v42, v42, v60
	v_mul_f32_e32 v58, v61, v58
	s_waitcnt lgkmcnt(0)
	v_mul_f32_e32 v61, v134, v53
	v_mov_b32_e32 v60, v47
	v_pk_fma_f32 v[44:45], v[44:45], v[70:71], v[48:49]
	v_mul_f32_e32 v49, v134, v59
	v_mov_b32_e32 v48, v43
	v_pk_mul_f32 v[54:55], v[54:55], v[60:61]
	v_pk_mul_f32 v[48:49], v[62:63], v[48:49]
	v_mov_b32_e32 v47, v54
	v_mov_b32_e32 v53, v55
	v_mov_b32_e32 v43, v48
	v_mov_b32_e32 v59, v49
	v_pk_add_f32 v[46:47], v[46:47], v[52:53]
	v_pk_fma_f32 v[40:41], v[40:41], v[50:51], v[56:57]
	v_pk_add_f32 v[42:43], v[42:43], v[58:59]
.LBB0_435:
	s_and_b64 vcc, exec, s[8:9]
	v_cvt_pk_bf16_f32 v44, v44, v45
	v_cvt_pk_bf16_f32 v45, v46, v47
	v_cvt_pk_bf16_f32 v46, v40, v41
	v_cvt_pk_bf16_f32 v47, v42, v43
	global_store_dwordx4 v[104:105], v[44:47], off offset:256 sc1
	s_cbranch_vccnz .LBB0_437
	v_cndmask_b32_e64 v40, v106, v151, s[6:7]
	v_lshlrev_b32_e32 v40, 7, v40
	ds_bpermute_b32 v56, v148, v36
	ds_bpermute_b32 v57, v148, v37
	v_and_b32_e32 v40, 0x1f80, v40
	ds_bpermute_b32 v58, v148, v32
	ds_bpermute_b32 v59, v148, v33
	v_add_u32_e32 v52, v149, v40
	ds_read_b128 v[40:43], v52
	ds_read_b128 v[44:47], v52 offset:16
	ds_read_b128 v[48:51], v52 offset:32
	ds_read_b128 v[52:55], v52 offset:48
	s_waitcnt lgkmcnt(0)
	v_pk_mul_f32 v[56:57], v[134:135], v[56:57]
	v_mov_b32_e32 v61, v42
	v_mov_b32_e32 v42, v41
	v_mov_b32_e32 v60, v40
	v_pk_mul_f32 v[40:41], v[42:43], v[56:57]
	v_pk_mul_f32 v[56:57], v[134:135], v[58:59]
	ds_bpermute_b32 v58, v148, v38
	v_mov_b32_e32 v43, v50
	v_mov_b32_e32 v50, v49
	v_mov_b32_e32 v42, v48
	v_pk_mul_f32 v[48:49], v[50:51], v[56:57]
	ds_bpermute_b32 v50, v148, v34
	v_mul_f32_e32 v38, v38, v44
	s_waitcnt lgkmcnt(0)
	v_mul_f32_e32 v44, v134, v58
	v_mul_f32_e32 v44, v45, v44
	ds_bpermute_b32 v45, v148, v39
	ds_bpermute_b32 v51, v148, v35
	v_mul_f32_e32 v50, v134, v50
	v_mul_f32_e32 v34, v34, v52
	v_mul_f32_e32 v50, v53, v50
	s_waitcnt lgkmcnt(0)
	v_mul_f32_e32 v53, v134, v45
	v_mov_b32_e32 v52, v39
	v_pk_fma_f32 v[36:37], v[36:37], v[60:61], v[40:41]
	v_mul_f32_e32 v41, v134, v51
	v_mov_b32_e32 v40, v35
	v_pk_mul_f32 v[46:47], v[46:47], v[52:53]
	v_pk_mul_f32 v[40:41], v[54:55], v[40:41]
	v_mov_b32_e32 v39, v46
	v_mov_b32_e32 v45, v47
	v_mov_b32_e32 v35, v40
	v_mov_b32_e32 v51, v41
	v_pk_add_f32 v[38:39], v[38:39], v[44:45]
	v_pk_fma_f32 v[32:33], v[32:33], v[42:43], v[48:49]
	v_pk_add_f32 v[34:35], v[34:35], v[50:51]
.LBB0_437:
	s_and_b64 vcc, exec, s[8:9]
	v_cvt_pk_bf16_f32 v36, v36, v37
	v_cvt_pk_bf16_f32 v37, v38, v39
	v_cvt_pk_bf16_f32 v38, v32, v33
	v_cvt_pk_bf16_f32 v39, v34, v35
	global_store_dwordx4 v[96:97], v[36:39], off offset:256 sc1
	s_cbranch_vccnz .LBB0_439
	v_cndmask_b32_e64 v32, v142, v98, s[6:7]
	v_lshlrev_b32_e32 v32, 7, v32
	ds_bpermute_b32 v48, v148, v28
	ds_bpermute_b32 v49, v148, v29
	v_and_b32_e32 v32, 0x1f80, v32
	ds_bpermute_b32 v50, v148, v24
	ds_bpermute_b32 v51, v148, v25
	v_add_u32_e32 v44, v149, v32
	ds_read_b128 v[32:35], v44
	ds_read_b128 v[36:39], v44 offset:16
	ds_read_b128 v[40:43], v44 offset:32
	ds_read_b128 v[44:47], v44 offset:48
	s_waitcnt lgkmcnt(0)
	v_pk_mul_f32 v[48:49], v[134:135], v[48:49]
	v_mov_b32_e32 v53, v34
	v_mov_b32_e32 v34, v33
	v_mov_b32_e32 v52, v32
	v_pk_mul_f32 v[32:33], v[34:35], v[48:49]
	v_pk_mul_f32 v[48:49], v[134:135], v[50:51]
	ds_bpermute_b32 v50, v148, v30
	v_mov_b32_e32 v35, v42
	v_mov_b32_e32 v42, v41
	v_mov_b32_e32 v34, v40
	v_pk_mul_f32 v[40:41], v[42:43], v[48:49]
	ds_bpermute_b32 v42, v148, v26
	v_mul_f32_e32 v30, v30, v36
	s_waitcnt lgkmcnt(0)
	v_mul_f32_e32 v36, v134, v50
	v_mul_f32_e32 v36, v37, v36
	ds_bpermute_b32 v37, v148, v31
	ds_bpermute_b32 v43, v148, v27
	v_mul_f32_e32 v42, v134, v42
	v_mul_f32_e32 v26, v26, v44
	v_mul_f32_e32 v42, v45, v42
	s_waitcnt lgkmcnt(0)
	v_mul_f32_e32 v45, v134, v37
	v_mov_b32_e32 v44, v31
	v_pk_fma_f32 v[28:29], v[28:29], v[52:53], v[32:33]
	v_mul_f32_e32 v33, v134, v43
	v_mov_b32_e32 v32, v27
	v_pk_mul_f32 v[38:39], v[38:39], v[44:45]
	v_pk_mul_f32 v[32:33], v[46:47], v[32:33]
	v_mov_b32_e32 v31, v38
	v_mov_b32_e32 v37, v39
	v_mov_b32_e32 v27, v32
	v_mov_b32_e32 v43, v33
	v_pk_add_f32 v[30:31], v[30:31], v[36:37]
	v_pk_fma_f32 v[24:25], v[24:25], v[34:35], v[40:41]
	v_pk_add_f32 v[26:27], v[26:27], v[42:43]
.LBB0_439:
	s_and_b64 vcc, exec, s[8:9]
	v_cvt_pk_bf16_f32 v28, v28, v29
	v_cvt_pk_bf16_f32 v29, v30, v31
	v_cvt_pk_bf16_f32 v30, v24, v25
	v_cvt_pk_bf16_f32 v31, v26, v27
	global_store_dwordx4 v[88:89], v[28:31], off offset:256 sc1
	s_cbranch_vccnz .LBB0_441
	v_cndmask_b32_e64 v24, v90, v98, s[6:7]
	v_lshlrev_b32_e32 v24, 7, v24
	ds_bpermute_b32 v40, v148, v20
	ds_bpermute_b32 v41, v148, v21
	v_and_b32_e32 v24, 0x1f80, v24
	ds_bpermute_b32 v42, v148, v16
	ds_bpermute_b32 v43, v148, v17
	v_add_u32_e32 v36, v149, v24
	ds_read_b128 v[24:27], v36
	ds_read_b128 v[28:31], v36 offset:16
	ds_read_b128 v[32:35], v36 offset:32
	ds_read_b128 v[36:39], v36 offset:48
	s_waitcnt lgkmcnt(0)
	v_pk_mul_f32 v[40:41], v[134:135], v[40:41]
	v_mov_b32_e32 v45, v26
	v_mov_b32_e32 v26, v25
	v_mov_b32_e32 v44, v24
	v_pk_mul_f32 v[24:25], v[26:27], v[40:41]
	v_pk_mul_f32 v[40:41], v[134:135], v[42:43]
	ds_bpermute_b32 v42, v148, v22
	v_mov_b32_e32 v27, v34
	v_mov_b32_e32 v34, v33
	v_mov_b32_e32 v26, v32
	v_pk_mul_f32 v[32:33], v[34:35], v[40:41]
	ds_bpermute_b32 v34, v148, v18
	v_mul_f32_e32 v22, v22, v28
	s_waitcnt lgkmcnt(0)
	v_mul_f32_e32 v28, v134, v42
	v_mul_f32_e32 v28, v29, v28
	ds_bpermute_b32 v29, v148, v23
	ds_bpermute_b32 v35, v148, v19
	v_mul_f32_e32 v34, v134, v34
	v_mul_f32_e32 v18, v18, v36
	v_mul_f32_e32 v34, v37, v34
	s_waitcnt lgkmcnt(0)
	v_mul_f32_e32 v37, v134, v29
	v_mov_b32_e32 v36, v23
	v_pk_fma_f32 v[20:21], v[20:21], v[44:45], v[24:25]
	v_mul_f32_e32 v25, v134, v35
	v_mov_b32_e32 v24, v19
	v_pk_mul_f32 v[30:31], v[30:31], v[36:37]
	v_pk_mul_f32 v[24:25], v[38:39], v[24:25]
	v_mov_b32_e32 v23, v30
	v_mov_b32_e32 v29, v31
	v_mov_b32_e32 v19, v24
	v_mov_b32_e32 v35, v25
	v_pk_add_f32 v[22:23], v[22:23], v[28:29]
	v_pk_fma_f32 v[16:17], v[16:17], v[26:27], v[32:33]
	v_pk_add_f32 v[18:19], v[18:19], v[34:35]
.LBB0_441:
	s_and_b64 vcc, exec, s[8:9]
	v_cvt_pk_bf16_f32 v20, v20, v21
	v_cvt_pk_bf16_f32 v21, v22, v23
	v_cvt_pk_bf16_f32 v22, v16, v17
	v_cvt_pk_bf16_f32 v23, v18, v19
	global_store_dwordx4 v[80:81], v[20:23], off offset:256 sc1
	s_cbranch_vccnz .LBB0_443
	v_cndmask_b32_e64 v16, v82, v98, s[6:7]
	v_lshlrev_b32_e32 v16, 7, v16
	ds_bpermute_b32 v32, v148, v12
	ds_bpermute_b32 v33, v148, v13
	v_and_b32_e32 v16, 0x1f80, v16
	ds_bpermute_b32 v34, v148, v8
	ds_bpermute_b32 v35, v148, v9
	v_add_u32_e32 v28, v149, v16
	ds_read_b128 v[16:19], v28
	ds_read_b128 v[20:23], v28 offset:16
	ds_read_b128 v[24:27], v28 offset:32
	ds_read_b128 v[28:31], v28 offset:48
	s_waitcnt lgkmcnt(0)
	v_pk_mul_f32 v[32:33], v[134:135], v[32:33]
	v_mov_b32_e32 v37, v18
	v_mov_b32_e32 v18, v17
	v_mov_b32_e32 v36, v16
	v_pk_mul_f32 v[16:17], v[18:19], v[32:33]
	v_pk_mul_f32 v[32:33], v[134:135], v[34:35]
	ds_bpermute_b32 v34, v148, v14
	v_mov_b32_e32 v19, v26
	v_mov_b32_e32 v26, v25
	v_mov_b32_e32 v18, v24
	v_pk_mul_f32 v[24:25], v[26:27], v[32:33]
	ds_bpermute_b32 v26, v148, v10
	v_mul_f32_e32 v14, v14, v20
	s_waitcnt lgkmcnt(0)
	v_mul_f32_e32 v20, v134, v34
	v_mul_f32_e32 v20, v21, v20
	ds_bpermute_b32 v21, v148, v15
	ds_bpermute_b32 v27, v148, v11
	v_mul_f32_e32 v26, v134, v26
	v_mul_f32_e32 v10, v10, v28
	v_mul_f32_e32 v26, v29, v26
	s_waitcnt lgkmcnt(0)
	v_mul_f32_e32 v29, v134, v21
	v_mov_b32_e32 v28, v15
	v_pk_fma_f32 v[12:13], v[12:13], v[36:37], v[16:17]
	v_mul_f32_e32 v17, v134, v27
	v_mov_b32_e32 v16, v11
	v_pk_mul_f32 v[22:23], v[22:23], v[28:29]
	v_pk_mul_f32 v[16:17], v[30:31], v[16:17]
	v_mov_b32_e32 v15, v22
	v_mov_b32_e32 v21, v23
	v_mov_b32_e32 v11, v16
	v_mov_b32_e32 v27, v17
	v_pk_add_f32 v[14:15], v[14:15], v[20:21]
	v_pk_fma_f32 v[8:9], v[8:9], v[18:19], v[24:25]
	v_pk_add_f32 v[10:11], v[10:11], v[26:27]
.LBB0_443:
	s_and_b64 vcc, exec, s[8:9]
	v_cvt_pk_bf16_f32 v12, v12, v13
	v_cvt_pk_bf16_f32 v13, v14, v15
	v_cvt_pk_bf16_f32 v14, v8, v9
	v_cvt_pk_bf16_f32 v15, v10, v11
	global_store_dwordx4 v[72:73], v[12:15], off offset:256 sc1
	s_cbranch_vccnz .LBB0_445
	v_cndmask_b32_e64 v8, v74, v98, s[6:7]
	v_lshlrev_b32_e32 v8, 7, v8
	ds_bpermute_b32 v24, v148, v4
	ds_bpermute_b32 v25, v148, v5
	v_and_b32_e32 v8, 0x1f80, v8
	ds_bpermute_b32 v26, v148, v0
	ds_bpermute_b32 v27, v148, v1
	v_add_u32_e32 v20, v149, v8
	ds_read_b128 v[8:11], v20
	ds_read_b128 v[12:15], v20 offset:16
	ds_read_b128 v[16:19], v20 offset:32
	ds_read_b128 v[20:23], v20 offset:48
	s_waitcnt lgkmcnt(0)
	v_pk_mul_f32 v[24:25], v[134:135], v[24:25]
	v_mov_b32_e32 v29, v10
	v_mov_b32_e32 v10, v9
	v_mov_b32_e32 v28, v8
	v_pk_mul_f32 v[8:9], v[10:11], v[24:25]
	v_pk_mul_f32 v[24:25], v[134:135], v[26:27]
	ds_bpermute_b32 v26, v148, v6
	v_mov_b32_e32 v11, v18
	v_mov_b32_e32 v18, v17
	v_mov_b32_e32 v10, v16
	v_pk_mul_f32 v[16:17], v[18:19], v[24:25]
	ds_bpermute_b32 v18, v148, v2
	v_mul_f32_e32 v6, v6, v12
	s_waitcnt lgkmcnt(0)
	v_mul_f32_e32 v12, v134, v26
	v_mul_f32_e32 v12, v13, v12
	ds_bpermute_b32 v13, v148, v7
	ds_bpermute_b32 v19, v148, v3
	v_mul_f32_e32 v18, v134, v18
	v_mul_f32_e32 v2, v2, v20
	v_mul_f32_e32 v18, v21, v18
	s_waitcnt lgkmcnt(0)
	v_mul_f32_e32 v21, v134, v13
	v_mov_b32_e32 v20, v7
	v_pk_fma_f32 v[4:5], v[4:5], v[28:29], v[8:9]
	v_mul_f32_e32 v9, v134, v19
	v_mov_b32_e32 v8, v3
	v_pk_mul_f32 v[14:15], v[14:15], v[20:21]
	v_pk_mul_f32 v[8:9], v[22:23], v[8:9]
	v_mov_b32_e32 v7, v14
	v_mov_b32_e32 v13, v15
	v_mov_b32_e32 v3, v8
	v_mov_b32_e32 v19, v9
	v_pk_add_f32 v[6:7], v[6:7], v[12:13]
	v_pk_fma_f32 v[0:1], v[0:1], v[10:11], v[16:17]
	v_pk_add_f32 v[2:3], v[2:3], v[18:19]
.LBB0_445:
	s_andn2_b64 vcc, exec, s[4:5]
	s_mov_b64 s[4:5], -1
	v_cvt_pk_bf16_f32 v4, v4, v5
	v_cvt_pk_bf16_f32 v5, v6, v7
	v_cvt_pk_bf16_f32 v6, v0, v1
	v_cvt_pk_bf16_f32 v7, v2, v3
	global_store_dwordx4 v[64:65], v[4:7], off offset:256 sc1
	s_cbranch_vccnz .LBB0_406
	s_andn2_b64 vcc, exec, s[0:1]
	s_cbranch_vccnz .LBB0_405
	s_barrier
	s_branch .LBB0_405

.LBB0_499:
	s_or_b64 exec, exec, s[0:1]
	v_lshl_add_u32 v66, v177, 4, v180
	s_waitcnt lgkmcnt(0)
	s_barrier
	ds_read_b128 v[68:71], v66
	v_lshl_add_u32 v64, v178, 13, 0
	v_lshlrev_b32_e32 v65, 1, v179
	v_and_b32_e32 v144, 0xf0, v176
	s_waitcnt lgkmcnt(0)
	v_rcp_f32_e32 v67, v68
	v_lshlrev_b32_e32 v68, 10, v177
	v_add3_u32 v65, v64, v65, v68
	v_mul_f32_e32 v0, v0, v67
	v_bfe_u32 v68, v0, 16, 1
	v_add3_u32 v0, v0, v68, s69
	ds_write_b16_d16_hi v65, v0
	v_mul_f32_e32 v0, v48, v67
	v_bfe_u32 v48, v0, 16, 1
	v_add3_u32 v0, v0, v48, s69
	ds_write_b16_d16_hi v65, v0 offset:64
	v_mul_f32_e32 v0, v32, v67
	v_bfe_u32 v32, v0, 16, 1
	v_add3_u32 v0, v0, v32, s69
	ds_write_b16_d16_hi v65, v0 offset:128
	v_mul_f32_e32 v0, v16, v67
	v_bfe_u32 v16, v0, 16, 1
	v_add3_u32 v0, v0, v16, s69
	ds_write_b16_d16_hi v65, v0 offset:192
	v_rcp_f32_e32 v0, v69
	s_nop 0
	v_mul_f32_e32 v1, v1, v0
	v_bfe_u32 v16, v1, 16, 1
	v_add3_u32 v1, v1, v16, s69
	ds_write_b16_d16_hi v65, v1 offset:256
	v_mul_f32_e32 v1, v49, v0
	v_bfe_u32 v16, v1, 16, 1
	v_add3_u32 v1, v1, v16, s69
	ds_write_b16_d16_hi v65, v1 offset:320
	v_mul_f32_e32 v1, v33, v0
	v_bfe_u32 v16, v1, 16, 1
	v_add3_u32 v1, v1, v16, s69
	v_mul_f32_e32 v0, v17, v0
	ds_write_b16_d16_hi v65, v1 offset:384
	v_bfe_u32 v1, v0, 16, 1
	v_add3_u32 v0, v0, v1, s69
	ds_write_b16_d16_hi v65, v0 offset:448
	v_rcp_f32_e32 v0, v70
	s_nop 0
	v_mul_f32_e32 v1, v2, v0
	v_bfe_u32 v2, v1, 16, 1
	v_add3_u32 v1, v1, v2, s69
	ds_write_b16_d16_hi v65, v1 offset:512
	v_mul_f32_e32 v1, v50, v0
	v_bfe_u32 v2, v1, 16, 1
	v_add3_u32 v1, v1, v2, s69
	ds_write_b16_d16_hi v65, v1 offset:576
	v_mul_f32_e32 v1, v34, v0
	v_bfe_u32 v2, v1, 16, 1
	v_add3_u32 v1, v1, v2, s69
	v_mul_f32_e32 v0, v18, v0
	ds_write_b16_d16_hi v65, v1 offset:640
	v_bfe_u32 v1, v0, 16, 1
	v_add3_u32 v0, v0, v1, s69
	ds_write_b16_d16_hi v65, v0 offset:704
	v_rcp_f32_e32 v0, v71
	s_nop 0
	v_mul_f32_e32 v1, v3, v0
	v_bfe_u32 v2, v1, 16, 1
	v_add3_u32 v1, v1, v2, s69
	ds_write_b16_d16_hi v65, v1 offset:768
	v_mul_f32_e32 v1, v51, v0
	v_bfe_u32 v2, v1, 16, 1
	v_add3_u32 v1, v1, v2, s69
	ds_write_b16_d16_hi v65, v1 offset:832
	v_mul_f32_e32 v1, v35, v0
	v_bfe_u32 v2, v1, 16, 1
	v_add3_u32 v1, v1, v2, s69
	v_mul_f32_e32 v0, v19, v0
	ds_write_b16_d16_hi v65, v1 offset:896
	v_bfe_u32 v1, v0, 16, 1
	v_add3_u32 v0, v0, v1, s69
	ds_write_b16_d16_hi v65, v0 offset:960
	ds_read_b128 v[0:3], v66 offset:32
	s_waitcnt lgkmcnt(0)
	v_rcp_f32_e32 v0, v0
	s_nop 0
	v_mul_f32_e32 v4, v4, v0
	v_bfe_u32 v16, v4, 16, 1
	v_add3_u32 v4, v4, v16, s69
	ds_write_b16_d16_hi v65, v4 offset:2048
	v_mul_f32_e32 v4, v52, v0
	v_bfe_u32 v16, v4, 16, 1
	v_add3_u32 v4, v4, v16, s69
	ds_write_b16_d16_hi v65, v4 offset:2112
	v_mul_f32_e32 v4, v36, v0
	v_bfe_u32 v16, v4, 16, 1
	v_add3_u32 v4, v4, v16, s69
	v_mul_f32_e32 v0, v20, v0
	ds_write_b16_d16_hi v65, v4 offset:2176
	v_bfe_u32 v4, v0, 16, 1
	v_add3_u32 v0, v0, v4, s69
	ds_write_b16_d16_hi v65, v0 offset:2240
	v_rcp_f32_e32 v0, v1
	s_nop 0
	v_mul_f32_e32 v1, v5, v0
	v_bfe_u32 v4, v1, 16, 1
	v_add3_u32 v1, v1, v4, s69
	ds_write_b16_d16_hi v65, v1 offset:2304
	v_mul_f32_e32 v1, v53, v0
	v_bfe_u32 v4, v1, 16, 1
	v_add3_u32 v1, v1, v4, s69
	ds_write_b16_d16_hi v65, v1 offset:2368
	v_mul_f32_e32 v1, v37, v0
	v_bfe_u32 v4, v1, 16, 1
	v_add3_u32 v1, v1, v4, s69
	v_mul_f32_e32 v0, v21, v0
	ds_write_b16_d16_hi v65, v1 offset:2432
	v_bfe_u32 v1, v0, 16, 1
	v_add3_u32 v0, v0, v1, s69
	ds_write_b16_d16_hi v65, v0 offset:2496
	v_rcp_f32_e32 v0, v2
	s_nop 0
	v_mul_f32_e32 v1, v6, v0
	v_bfe_u32 v2, v1, 16, 1
	v_add3_u32 v1, v1, v2, s69
	ds_write_b16_d16_hi v65, v1 offset:2560
	v_mul_f32_e32 v1, v54, v0
	v_bfe_u32 v2, v1, 16, 1
	v_add3_u32 v1, v1, v2, s69
	ds_write_b16_d16_hi v65, v1 offset:2624
	v_mul_f32_e32 v1, v38, v0
	v_bfe_u32 v2, v1, 16, 1
	v_add3_u32 v1, v1, v2, s69
	v_mul_f32_e32 v0, v22, v0
	ds_write_b16_d16_hi v65, v1 offset:2688
	v_bfe_u32 v1, v0, 16, 1
	v_add3_u32 v0, v0, v1, s69
	ds_write_b16_d16_hi v65, v0 offset:2752
	v_rcp_f32_e32 v0, v3
	s_nop 0
	v_mul_f32_e32 v1, v7, v0
	v_bfe_u32 v2, v1, 16, 1
	v_add3_u32 v1, v1, v2, s69
	ds_write_b16_d16_hi v65, v1 offset:2816
	v_mul_f32_e32 v1, v55, v0
	v_bfe_u32 v2, v1, 16, 1
	v_add3_u32 v1, v1, v2, s69
	ds_write_b16_d16_hi v65, v1 offset:2880
	v_mul_f32_e32 v1, v39, v0
	v_bfe_u32 v2, v1, 16, 1
	v_add3_u32 v1, v1, v2, s69
	v_mul_f32_e32 v0, v23, v0
	ds_write_b16_d16_hi v65, v1 offset:2944
	v_bfe_u32 v1, v0, 16, 1
	v_add3_u32 v0, v0, v1, s69
	ds_write_b16_d16_hi v65, v0 offset:3008
	ds_read_b128 v[0:3], v66 offset:64
	s_waitcnt lgkmcnt(0)
	v_rcp_f32_e32 v0, v0
	s_nop 0
	v_mul_f32_e32 v4, v8, v0
	v_bfe_u32 v5, v4, 16, 1
	v_add3_u32 v4, v4, v5, s69
	ds_write_b16_d16_hi v65, v4 offset:4096
	v_mul_f32_e32 v4, v56, v0
	v_bfe_u32 v5, v4, 16, 1
	v_add3_u32 v4, v4, v5, s69
	ds_write_b16_d16_hi v65, v4 offset:4160
	v_mul_f32_e32 v4, v40, v0
	v_bfe_u32 v5, v4, 16, 1
	v_add3_u32 v4, v4, v5, s69
	v_mul_f32_e32 v0, v24, v0
	ds_write_b16_d16_hi v65, v4 offset:4224
	v_bfe_u32 v4, v0, 16, 1
	v_add3_u32 v0, v0, v4, s69
	ds_write_b16_d16_hi v65, v0 offset:4288
	v_rcp_f32_e32 v0, v1
	v_lshrrev_b32_e32 v8, 4, v174
	v_mul_f32_e32 v1, v9, v0
	v_bfe_u32 v4, v1, 16, 1
	v_add3_u32 v1, v1, v4, s69
	ds_write_b16_d16_hi v65, v1 offset:4352
	v_mul_f32_e32 v1, v57, v0
	v_bfe_u32 v4, v1, 16, 1
	v_add3_u32 v1, v1, v4, s69
	ds_write_b16_d16_hi v65, v1 offset:4416
	v_mul_f32_e32 v1, v41, v0
	v_bfe_u32 v4, v1, 16, 1
	v_add3_u32 v1, v1, v4, s69
	v_mul_f32_e32 v0, v25, v0
	ds_write_b16_d16_hi v65, v1 offset:4480
	v_bfe_u32 v1, v0, 16, 1
	v_add3_u32 v0, v0, v1, s69
	ds_write_b16_d16_hi v65, v0 offset:4544
	v_rcp_f32_e32 v0, v2
	v_add_u32_e32 v9, v64, v144
	v_mul_f32_e32 v1, v10, v0
	v_bfe_u32 v2, v1, 16, 1
	v_add3_u32 v1, v1, v2, s69
	ds_write_b16_d16_hi v65, v1 offset:4608
	v_mul_f32_e32 v1, v58, v0
	v_bfe_u32 v2, v1, 16, 1
	v_add3_u32 v1, v1, v2, s69
	ds_write_b16_d16_hi v65, v1 offset:4672
	v_mul_f32_e32 v1, v42, v0
	v_bfe_u32 v2, v1, 16, 1
	v_add3_u32 v1, v1, v2, s69
	v_mul_f32_e32 v0, v26, v0
	ds_write_b16_d16_hi v65, v1 offset:4736
	v_bfe_u32 v1, v0, 16, 1
	v_add3_u32 v0, v0, v1, s69
	ds_write_b16_d16_hi v65, v0 offset:4800
	v_rcp_f32_e32 v0, v3
	s_nop 0
	v_mul_f32_e32 v1, v11, v0
	v_bfe_u32 v2, v1, 16, 1
	v_add3_u32 v1, v1, v2, s69
	ds_write_b16_d16_hi v65, v1 offset:4864
	v_mul_f32_e32 v1, v59, v0
	v_bfe_u32 v2, v1, 16, 1
	v_add3_u32 v1, v1, v2, s69
	ds_write_b16_d16_hi v65, v1 offset:4928
	v_mul_f32_e32 v1, v43, v0
	v_bfe_u32 v2, v1, 16, 1
	v_add3_u32 v1, v1, v2, s69
	v_mul_f32_e32 v0, v27, v0
	ds_write_b16_d16_hi v65, v1 offset:4992
	v_bfe_u32 v1, v0, 16, 1
	v_add3_u32 v0, v0, v1, s69
	ds_write_b16_d16_hi v65, v0 offset:5056
	ds_read_b128 v[0:3], v66 offset:96
	s_waitcnt lgkmcnt(0)
	v_rcp_f32_e32 v0, v0
	s_nop 0
	v_mul_f32_e32 v4, v12, v0
	v_bfe_u32 v5, v4, 16, 1
	v_add3_u32 v4, v4, v5, s69
	ds_write_b16_d16_hi v65, v4 offset:6144
	v_mul_f32_e32 v4, v60, v0
	v_bfe_u32 v5, v4, 16, 1
	v_add3_u32 v4, v4, v5, s69
	ds_write_b16_d16_hi v65, v4 offset:6208
	v_mul_f32_e32 v4, v44, v0
	v_bfe_u32 v5, v4, 16, 1
	v_add3_u32 v4, v4, v5, s69
	v_mul_f32_e32 v0, v28, v0
	ds_write_b16_d16_hi v65, v4 offset:6272
	v_bfe_u32 v4, v0, 16, 1
	v_add3_u32 v0, v0, v4, s69
	ds_write_b16_d16_hi v65, v0 offset:6336
	v_rcp_f32_e32 v0, v1
	s_nop 0
	v_mul_f32_e32 v1, v13, v0
	v_bfe_u32 v4, v1, 16, 1
	v_add3_u32 v1, v1, v4, s69
	ds_write_b16_d16_hi v65, v1 offset:6400
	v_mul_f32_e32 v1, v61, v0
	v_bfe_u32 v4, v1, 16, 1
	v_add3_u32 v1, v1, v4, s69
	ds_write_b16_d16_hi v65, v1 offset:6464
	v_mul_f32_e32 v1, v45, v0
	v_bfe_u32 v4, v1, 16, 1
	v_add3_u32 v1, v1, v4, s69
	v_mul_f32_e32 v0, v29, v0
	ds_write_b16_d16_hi v65, v1 offset:6528
	v_bfe_u32 v1, v0, 16, 1
	v_add3_u32 v0, v0, v1, s69
	ds_write_b16_d16_hi v65, v0 offset:6592
	v_rcp_f32_e32 v0, v2
	s_nop 0
	v_mul_f32_e32 v1, v14, v0
	v_bfe_u32 v2, v1, 16, 1
	v_add3_u32 v1, v1, v2, s69
	ds_write_b16_d16_hi v65, v1 offset:6656
	v_mul_f32_e32 v1, v62, v0
	v_bfe_u32 v2, v1, 16, 1
	v_add3_u32 v1, v1, v2, s69
	ds_write_b16_d16_hi v65, v1 offset:6720
	v_mul_f32_e32 v1, v46, v0
	v_bfe_u32 v2, v1, 16, 1
	v_add3_u32 v1, v1, v2, s69
	v_mul_f32_e32 v0, v30, v0
	ds_write_b16_d16_hi v65, v1 offset:6784
	v_bfe_u32 v1, v0, 16, 1
	v_add3_u32 v0, v0, v1, s69
	ds_write_b16_d16_hi v65, v0 offset:6848
	v_rcp_f32_e32 v0, v3
	s_nop 0
	v_mul_f32_e32 v1, v15, v0
	v_bfe_u32 v2, v1, 16, 1
	v_add3_u32 v1, v1, v2, s69
	ds_write_b16_d16_hi v65, v1 offset:6912
	v_mul_f32_e32 v1, v63, v0
	v_bfe_u32 v2, v1, 16, 1
	v_add3_u32 v1, v1, v2, s69
	ds_write_b16_d16_hi v65, v1 offset:6976
	v_mul_f32_e32 v1, v47, v0
	v_bfe_u32 v2, v1, 16, 1
	v_add3_u32 v1, v1, v2, s69
	v_mul_f32_e32 v0, v31, v0
	ds_write_b16_d16_hi v65, v1 offset:7040
	v_bfe_u32 v1, v0, 16, 1
	v_add3_u32 v0, v0, v1, s69
	ds_write_b16_d16_hi v65, v0 offset:7104
	v_add_u32_e32 v0, s86, v175
	v_ashrrev_i32_e32 v1, 31, v0
	v_lshlrev_b64 v[0:1], 12, v[0:1]
	v_lshl_add_u64 v[0:1], s[96:97], 0, v[0:1]
	s_waitcnt lgkmcnt(0)
	v_lshl_add_u64 v[4:5], v[0:1], 0, v[144:145]
	v_lshl_add_u32 v0, v8, 8, v9
	ds_read_b128 v[0:3], v0
	v_lshlrev_b32_e32 v144, 12, v8
	v_lshl_add_u64 v[6:7], v[4:5], 0, v[144:145]
	s_waitcnt lgkmcnt(0)
	global_store_dwordx4 v[6:7], v[0:3], off sc1
	v_or_b32_e32 v6, 4, v8
	s_nop 0
	v_lshl_add_u32 v0, v6, 8, v9
	ds_read_b128 v[0:3], v0
	v_lshlrev_b32_e32 v144, 12, v6
	v_lshl_add_u64 v[6:7], v[4:5], 0, v[144:145]
	s_waitcnt lgkmcnt(0)
	global_store_dwordx4 v[6:7], v[0:3], off sc1
	v_or_b32_e32 v6, 8, v8
	s_nop 0
	v_lshl_add_u32 v0, v6, 8, v9
	ds_read_b128 v[0:3], v0
	v_lshlrev_b32_e32 v144, 12, v6
	v_lshl_add_u64 v[6:7], v[4:5], 0, v[144:145]
	s_waitcnt lgkmcnt(0)
	global_store_dwordx4 v[6:7], v[0:3], off sc1
	v_or_b32_e32 v6, 12, v8
	s_nop 0
	v_lshl_add_u32 v0, v6, 8, v9
	ds_read_b128 v[0:3], v0
	v_lshlrev_b32_e32 v144, 12, v6
	v_lshl_add_u64 v[6:7], v[4:5], 0, v[144:145]
	s_waitcnt lgkmcnt(0)
	global_store_dwordx4 v[6:7], v[0:3], off sc1
	v_or_b32_e32 v6, 16, v8
	s_nop 0
	v_lshl_add_u32 v0, v6, 8, v9
	ds_read_b128 v[0:3], v0
	v_lshlrev_b32_e32 v144, 12, v6
	v_lshl_add_u64 v[6:7], v[4:5], 0, v[144:145]
	s_waitcnt lgkmcnt(0)
	global_store_dwordx4 v[6:7], v[0:3], off sc1
	v_or_b32_e32 v6, 20, v8
	s_nop 0
	v_lshl_add_u32 v0, v6, 8, v9
	ds_read_b128 v[0:3], v0
	v_lshlrev_b32_e32 v144, 12, v6
	v_lshl_add_u64 v[6:7], v[4:5], 0, v[144:145]
	s_waitcnt lgkmcnt(0)
	global_store_dwordx4 v[6:7], v[0:3], off sc1
	v_or_b32_e32 v6, 24, v8
	s_nop 0
	v_lshl_add_u32 v0, v6, 8, v9
	ds_read_b128 v[0:3], v0
	v_lshlrev_b32_e32 v144, 12, v6
	v_lshl_add_u64 v[6:7], v[4:5], 0, v[144:145]
	s_waitcnt lgkmcnt(0)
	global_store_dwordx4 v[6:7], v[0:3], off sc1
	v_or_b32_e32 v6, 28, v8
	s_nop 0
	v_lshl_add_u32 v0, v6, 8, v9
	ds_read_b128 v[0:3], v0
	v_lshlrev_b32_e32 v144, 12, v6
	v_lshl_add_u64 v[4:5], v[4:5], 0, v[144:145]
	s_waitcnt lgkmcnt(0)
	global_store_dwordx4 v[4:5], v[0:3], off sc1
	s_barrier

.LBB0_676:
	s_or_b64 exec, exec, s[6:7]
	v_lshl_add_u32 v65, v242, 2, v239
	s_waitcnt lgkmcnt(0)
	s_barrier
	ds_read_b128 v[66:69], v65
	v_lshl_add_u32 v64, v237, 13, 0
	v_lshl_add_u32 v70, v238, 1, v64
	v_lshl_add_u32 v71, v236, 10, v70
	v_and_b32_e32 v144, 0xf0, v235
	s_waitcnt lgkmcnt(0)
	v_rcp_f32_e32 v66, v66
	s_mov_b64 s[4:5], 0
	v_mul_f32_e32 v0, v0, v66
	v_bfe_u32 v72, v0, 16, 1
	v_add3_u32 v0, v0, v72, s69
	ds_write_b16_d16_hi v71, v0
	v_mul_f32_e32 v0, v48, v66
	v_bfe_u32 v48, v0, 16, 1
	v_add3_u32 v0, v0, v48, s69
	ds_write_b16_d16_hi v71, v0 offset:64
	v_mul_f32_e32 v0, v32, v66
	v_bfe_u32 v32, v0, 16, 1
	v_add3_u32 v0, v0, v32, s69
	ds_write_b16_d16_hi v71, v0 offset:128
	v_mul_f32_e32 v0, v16, v66
	v_bfe_u32 v16, v0, 16, 1
	v_add3_u32 v0, v0, v16, s69
	ds_write_b16_d16_hi v71, v0 offset:192
	v_rcp_f32_e32 v0, v67
	s_nop 0
	v_mul_f32_e32 v1, v1, v0
	v_bfe_u32 v16, v1, 16, 1
	v_add3_u32 v1, v1, v16, s69
	v_lshl_add_u32 v16, v242, 8, v70
	ds_write_b16_d16_hi v16, v1 offset:256
	v_mul_f32_e32 v1, v49, v0
	v_bfe_u32 v32, v1, 16, 1
	v_add3_u32 v1, v1, v32, s69
	ds_write_b16_d16_hi v16, v1 offset:320
	v_mul_f32_e32 v1, v33, v0
	v_bfe_u32 v32, v1, 16, 1
	v_add3_u32 v1, v1, v32, s69
	v_mul_f32_e32 v0, v17, v0
	ds_write_b16_d16_hi v16, v1 offset:384
	v_bfe_u32 v1, v0, 16, 1
	v_add3_u32 v0, v0, v1, s69
	ds_write_b16_d16_hi v16, v0 offset:448
	v_rcp_f32_e32 v0, v68
	s_nop 0
	v_mul_f32_e32 v1, v2, v0
	v_bfe_u32 v2, v1, 16, 1
	v_add3_u32 v1, v1, v2, s69
	ds_write_b16_d16_hi v16, v1 offset:512
	v_mul_f32_e32 v1, v50, v0
	v_bfe_u32 v2, v1, 16, 1
	v_add3_u32 v1, v1, v2, s69
	ds_write_b16_d16_hi v16, v1 offset:576
	v_mul_f32_e32 v1, v34, v0
	v_bfe_u32 v2, v1, 16, 1
	v_add3_u32 v1, v1, v2, s69
	v_mul_f32_e32 v0, v18, v0
	ds_write_b16_d16_hi v16, v1 offset:640
	v_bfe_u32 v1, v0, 16, 1
	v_add3_u32 v0, v0, v1, s69
	ds_write_b16_d16_hi v16, v0 offset:704
	v_rcp_f32_e32 v0, v69
	s_nop 0
	v_mul_f32_e32 v1, v3, v0
	v_bfe_u32 v2, v1, 16, 1
	v_add3_u32 v1, v1, v2, s69
	ds_write_b16_d16_hi v16, v1 offset:768
	v_mul_f32_e32 v1, v51, v0
	v_bfe_u32 v2, v1, 16, 1
	v_add3_u32 v1, v1, v2, s69
	ds_write_b16_d16_hi v16, v1 offset:832
	v_mul_f32_e32 v1, v35, v0
	v_bfe_u32 v2, v1, 16, 1
	v_add3_u32 v1, v1, v2, s69
	v_mul_f32_e32 v0, v19, v0
	ds_write_b16_d16_hi v16, v1 offset:896
	v_bfe_u32 v1, v0, 16, 1
	v_add3_u32 v0, v0, v1, s69
	ds_write_b16_d16_hi v16, v0 offset:960
	ds_read_b128 v[0:3], v65 offset:32
	s_waitcnt lgkmcnt(0)
	v_rcp_f32_e32 v0, v0
	s_nop 0
	v_mul_f32_e32 v4, v4, v0
	v_bfe_u32 v17, v4, 16, 1
	v_add3_u32 v4, v4, v17, s69
	ds_write_b16_d16_hi v16, v4 offset:2048
	v_mul_f32_e32 v4, v52, v0
	v_bfe_u32 v17, v4, 16, 1
	v_add3_u32 v4, v4, v17, s69
	ds_write_b16_d16_hi v16, v4 offset:2112
	v_mul_f32_e32 v4, v36, v0
	v_bfe_u32 v17, v4, 16, 1
	v_add3_u32 v4, v4, v17, s69
	v_mul_f32_e32 v0, v20, v0
	ds_write_b16_d16_hi v16, v4 offset:2176
	v_bfe_u32 v4, v0, 16, 1
	v_add3_u32 v0, v0, v4, s69
	ds_write_b16_d16_hi v16, v0 offset:2240
	v_rcp_f32_e32 v0, v1
	s_nop 0
	v_mul_f32_e32 v1, v5, v0
	v_bfe_u32 v4, v1, 16, 1
	v_add3_u32 v1, v1, v4, s69
	ds_write_b16_d16_hi v16, v1 offset:2304
	v_mul_f32_e32 v1, v53, v0
	v_bfe_u32 v4, v1, 16, 1
	v_add3_u32 v1, v1, v4, s69
	ds_write_b16_d16_hi v16, v1 offset:2368
	v_mul_f32_e32 v1, v37, v0
	v_bfe_u32 v4, v1, 16, 1
	v_add3_u32 v1, v1, v4, s69
	v_mul_f32_e32 v0, v21, v0
	ds_write_b16_d16_hi v16, v1 offset:2432
	v_bfe_u32 v1, v0, 16, 1
	v_add3_u32 v0, v0, v1, s69
	ds_write_b16_d16_hi v16, v0 offset:2496
	v_rcp_f32_e32 v0, v2
	s_nop 0
	v_mul_f32_e32 v1, v6, v0
	v_bfe_u32 v2, v1, 16, 1
	v_add3_u32 v1, v1, v2, s69
	ds_write_b16_d16_hi v16, v1 offset:2560
	v_mul_f32_e32 v1, v54, v0
	v_bfe_u32 v2, v1, 16, 1
	v_add3_u32 v1, v1, v2, s69
	ds_write_b16_d16_hi v16, v1 offset:2624
	v_mul_f32_e32 v1, v38, v0
	v_bfe_u32 v2, v1, 16, 1
	v_add3_u32 v1, v1, v2, s69
	v_mul_f32_e32 v0, v22, v0
	ds_write_b16_d16_hi v16, v1 offset:2688
	v_bfe_u32 v1, v0, 16, 1
	v_add3_u32 v0, v0, v1, s69
	ds_write_b16_d16_hi v16, v0 offset:2752
	v_rcp_f32_e32 v0, v3
	s_nop 0
	v_mul_f32_e32 v1, v7, v0
	v_bfe_u32 v2, v1, 16, 1
	v_add3_u32 v1, v1, v2, s69
	ds_write_b16_d16_hi v16, v1 offset:2816
	v_mul_f32_e32 v1, v55, v0
	v_bfe_u32 v2, v1, 16, 1
	v_add3_u32 v1, v1, v2, s69
	ds_write_b16_d16_hi v16, v1 offset:2880
	v_mul_f32_e32 v1, v39, v0
	v_bfe_u32 v2, v1, 16, 1
	v_add3_u32 v1, v1, v2, s69
	v_mul_f32_e32 v0, v23, v0
	ds_write_b16_d16_hi v16, v1 offset:2944
	v_bfe_u32 v1, v0, 16, 1
	v_add3_u32 v0, v0, v1, s69
	ds_write_b16_d16_hi v16, v0 offset:3008
	ds_read_b128 v[0:3], v65 offset:64
	s_waitcnt lgkmcnt(0)
	v_rcp_f32_e32 v0, v0
	s_nop 0
	v_mul_f32_e32 v4, v8, v0
	v_bfe_u32 v5, v4, 16, 1
	v_add3_u32 v4, v4, v5, s69
	ds_write_b16_d16_hi v16, v4 offset:4096
	v_mul_f32_e32 v4, v56, v0
	v_bfe_u32 v5, v4, 16, 1
	v_add3_u32 v4, v4, v5, s69
	ds_write_b16_d16_hi v16, v4 offset:4160
	v_mul_f32_e32 v4, v40, v0
	v_bfe_u32 v5, v4, 16, 1
	v_add3_u32 v4, v4, v5, s69
	v_mul_f32_e32 v0, v24, v0
	ds_write_b16_d16_hi v16, v4 offset:4224
	v_bfe_u32 v4, v0, 16, 1
	v_add3_u32 v0, v0, v4, s69
	ds_write_b16_d16_hi v16, v0 offset:4288
	v_rcp_f32_e32 v0, v1
	v_lshrrev_b32_e32 v8, 4, v233
	v_mul_f32_e32 v1, v9, v0
	v_bfe_u32 v4, v1, 16, 1
	v_add3_u32 v1, v1, v4, s69
	ds_write_b16_d16_hi v16, v1 offset:4352
	v_mul_f32_e32 v1, v57, v0
	v_bfe_u32 v4, v1, 16, 1
	v_add3_u32 v1, v1, v4, s69
	ds_write_b16_d16_hi v16, v1 offset:4416
	v_mul_f32_e32 v1, v41, v0
	v_bfe_u32 v4, v1, 16, 1
	v_add3_u32 v1, v1, v4, s69
	v_mul_f32_e32 v0, v25, v0
	ds_write_b16_d16_hi v16, v1 offset:4480
	v_bfe_u32 v1, v0, 16, 1
	v_add3_u32 v0, v0, v1, s69
	ds_write_b16_d16_hi v16, v0 offset:4544
	v_rcp_f32_e32 v0, v2
	v_add_u32_e32 v9, v64, v144
	v_mul_f32_e32 v1, v10, v0
	v_bfe_u32 v2, v1, 16, 1
	v_add3_u32 v1, v1, v2, s69
	ds_write_b16_d16_hi v16, v1 offset:4608
	v_mul_f32_e32 v1, v58, v0
	v_bfe_u32 v2, v1, 16, 1
	v_add3_u32 v1, v1, v2, s69
	ds_write_b16_d16_hi v16, v1 offset:4672
	v_mul_f32_e32 v1, v42, v0
	v_bfe_u32 v2, v1, 16, 1
	v_add3_u32 v1, v1, v2, s69
	v_mul_f32_e32 v0, v26, v0
	ds_write_b16_d16_hi v16, v1 offset:4736
	v_bfe_u32 v1, v0, 16, 1
	v_add3_u32 v0, v0, v1, s69
	ds_write_b16_d16_hi v16, v0 offset:4800
	v_rcp_f32_e32 v0, v3
	s_nop 0
	v_mul_f32_e32 v1, v11, v0
	v_bfe_u32 v2, v1, 16, 1
	v_add3_u32 v1, v1, v2, s69
	ds_write_b16_d16_hi v16, v1 offset:4864
	v_mul_f32_e32 v1, v59, v0
	v_bfe_u32 v2, v1, 16, 1
	v_add3_u32 v1, v1, v2, s69
	ds_write_b16_d16_hi v16, v1 offset:4928
	v_mul_f32_e32 v1, v43, v0
	v_bfe_u32 v2, v1, 16, 1
	v_add3_u32 v1, v1, v2, s69
	v_mul_f32_e32 v0, v27, v0
	ds_write_b16_d16_hi v16, v1 offset:4992
	v_bfe_u32 v1, v0, 16, 1
	v_add3_u32 v0, v0, v1, s69
	ds_write_b16_d16_hi v16, v0 offset:5056
	ds_read_b128 v[0:3], v65 offset:96
	s_waitcnt lgkmcnt(0)
	v_rcp_f32_e32 v0, v0
	s_nop 0
	v_mul_f32_e32 v4, v12, v0
	v_bfe_u32 v5, v4, 16, 1
	v_add3_u32 v4, v4, v5, s69
	ds_write_b16_d16_hi v16, v4 offset:6144
	v_mul_f32_e32 v4, v60, v0
	v_bfe_u32 v5, v4, 16, 1
	v_add3_u32 v4, v4, v5, s69
	ds_write_b16_d16_hi v16, v4 offset:6208
	v_mul_f32_e32 v4, v44, v0
	v_bfe_u32 v5, v4, 16, 1
	v_add3_u32 v4, v4, v5, s69
	v_mul_f32_e32 v0, v28, v0
	ds_write_b16_d16_hi v16, v4 offset:6272
	v_bfe_u32 v4, v0, 16, 1
	v_add3_u32 v0, v0, v4, s69
	ds_write_b16_d16_hi v16, v0 offset:6336
	v_rcp_f32_e32 v0, v1
	s_nop 0
	v_mul_f32_e32 v1, v13, v0
	v_bfe_u32 v4, v1, 16, 1
	v_add3_u32 v1, v1, v4, s69
	ds_write_b16_d16_hi v16, v1 offset:6400
	v_mul_f32_e32 v1, v61, v0
	v_bfe_u32 v4, v1, 16, 1
	v_add3_u32 v1, v1, v4, s69
	ds_write_b16_d16_hi v16, v1 offset:6464
	v_mul_f32_e32 v1, v45, v0
	v_bfe_u32 v4, v1, 16, 1
	v_add3_u32 v1, v1, v4, s69
	v_mul_f32_e32 v0, v29, v0
	ds_write_b16_d16_hi v16, v1 offset:6528
	v_bfe_u32 v1, v0, 16, 1
	v_add3_u32 v0, v0, v1, s69
	ds_write_b16_d16_hi v16, v0 offset:6592
	v_rcp_f32_e32 v0, v2
	s_nop 0
	v_mul_f32_e32 v1, v14, v0
	v_bfe_u32 v2, v1, 16, 1
	v_add3_u32 v1, v1, v2, s69
	ds_write_b16_d16_hi v16, v1 offset:6656
	v_mul_f32_e32 v1, v62, v0
	v_bfe_u32 v2, v1, 16, 1
	v_add3_u32 v1, v1, v2, s69
	ds_write_b16_d16_hi v16, v1 offset:6720
	v_mul_f32_e32 v1, v46, v0
	v_bfe_u32 v2, v1, 16, 1
	v_add3_u32 v1, v1, v2, s69
	v_mul_f32_e32 v0, v30, v0
	ds_write_b16_d16_hi v16, v1 offset:6784
	v_bfe_u32 v1, v0, 16, 1
	v_add3_u32 v0, v0, v1, s69
	ds_write_b16_d16_hi v16, v0 offset:6848
	v_rcp_f32_e32 v0, v3
	s_nop 0
	v_mul_f32_e32 v1, v15, v0
	v_bfe_u32 v2, v1, 16, 1
	v_add3_u32 v1, v1, v2, s69
	ds_write_b16_d16_hi v16, v1 offset:6912
	v_mul_f32_e32 v1, v63, v0
	v_bfe_u32 v2, v1, 16, 1
	v_add3_u32 v1, v1, v2, s69
	ds_write_b16_d16_hi v16, v1 offset:6976
	v_mul_f32_e32 v1, v47, v0
	v_bfe_u32 v2, v1, 16, 1
	v_add3_u32 v1, v1, v2, s69
	v_mul_f32_e32 v0, v31, v0
	ds_write_b16_d16_hi v16, v1 offset:7040
	v_bfe_u32 v1, v0, 16, 1
	v_add3_u32 v0, v0, v1, s69
	ds_write_b16_d16_hi v16, v0 offset:7104
	v_add_u32_e32 v0, s86, v234
	v_ashrrev_i32_e32 v1, 31, v0
	v_lshlrev_b64 v[0:1], 12, v[0:1]
	v_lshl_add_u64 v[0:1], s[96:97], 0, v[0:1]
	s_waitcnt lgkmcnt(0)
	v_lshl_add_u64 v[4:5], v[0:1], 0, v[144:145]
	v_lshl_add_u32 v0, v8, 8, v9
	ds_read_b128 v[0:3], v0
	v_lshlrev_b32_e32 v144, 12, v8
	v_lshl_add_u64 v[6:7], v[4:5], 0, v[144:145]
	s_waitcnt lgkmcnt(0)
	global_store_dwordx4 v[6:7], v[0:3], off sc1
	v_or_b32_e32 v6, 4, v8
	s_nop 0
	v_lshl_add_u32 v0, v6, 8, v9
	ds_read_b128 v[0:3], v0
	v_lshlrev_b32_e32 v144, 12, v6
	v_lshl_add_u64 v[6:7], v[4:5], 0, v[144:145]
	s_waitcnt lgkmcnt(0)
	global_store_dwordx4 v[6:7], v[0:3], off sc1
	v_or_b32_e32 v6, 8, v8
	s_nop 0
	v_lshl_add_u32 v0, v6, 8, v9
	ds_read_b128 v[0:3], v0
	v_lshlrev_b32_e32 v144, 12, v6
	v_lshl_add_u64 v[6:7], v[4:5], 0, v[144:145]
	s_waitcnt lgkmcnt(0)
	global_store_dwordx4 v[6:7], v[0:3], off sc1
	v_or_b32_e32 v6, 12, v8
	s_nop 0
	v_lshl_add_u32 v0, v6, 8, v9
	ds_read_b128 v[0:3], v0
	v_lshlrev_b32_e32 v144, 12, v6
	v_lshl_add_u64 v[6:7], v[4:5], 0, v[144:145]
	s_waitcnt lgkmcnt(0)
	global_store_dwordx4 v[6:7], v[0:3], off sc1
	v_or_b32_e32 v6, 16, v8
	s_nop 0
	v_lshl_add_u32 v0, v6, 8, v9
	ds_read_b128 v[0:3], v0
	v_lshlrev_b32_e32 v144, 12, v6
	v_lshl_add_u64 v[6:7], v[4:5], 0, v[144:145]
	s_waitcnt lgkmcnt(0)
	global_store_dwordx4 v[6:7], v[0:3], off sc1
	v_or_b32_e32 v6, 20, v8
	s_nop 0
	v_lshl_add_u32 v0, v6, 8, v9
	ds_read_b128 v[0:3], v0
	v_lshlrev_b32_e32 v144, 12, v6
	v_lshl_add_u64 v[6:7], v[4:5], 0, v[144:145]
	s_waitcnt lgkmcnt(0)
	global_store_dwordx4 v[6:7], v[0:3], off sc1
	v_or_b32_e32 v6, 24, v8
	s_nop 0
	v_lshl_add_u32 v0, v6, 8, v9
	ds_read_b128 v[0:3], v0
	v_lshlrev_b32_e32 v144, 12, v6
	v_lshl_add_u64 v[6:7], v[4:5], 0, v[144:145]
	s_waitcnt lgkmcnt(0)
	global_store_dwordx4 v[6:7], v[0:3], off sc1
	v_or_b32_e32 v6, 28, v8
	s_nop 0
	v_lshl_add_u32 v0, v6, 8, v9
	ds_read_b128 v[0:3], v0
	v_lshlrev_b32_e32 v144, 12, v6
	v_lshl_add_u64 v[4:5], v[4:5], 0, v[144:145]
	s_waitcnt lgkmcnt(0)
	global_store_dwordx4 v[4:5], v[0:3], off sc1
	s_barrier

.LBB0_736:
	s_or_b64 exec, exec, s[6:7]
	v_lshl_add_u32 v65, v210, 2, v208
	s_waitcnt lgkmcnt(0)
	s_barrier
	ds_read_b128 v[66:69], v65
	v_lshl_add_u32 v64, v206, 13, 0
	v_lshl_add_u32 v70, v207, 1, v64
	v_lshl_add_u32 v71, v205, 10, v70
	v_and_b32_e32 v144, 0xf0, v204
	s_waitcnt lgkmcnt(0)
	v_rcp_f32_e32 v66, v66
	s_mov_b64 s[4:5], 0
	v_mul_f32_e32 v0, v0, v66
	v_bfe_u32 v72, v0, 16, 1
	v_add3_u32 v0, v0, v72, s69
	ds_write_b16_d16_hi v71, v0
	v_mul_f32_e32 v0, v48, v66
	v_bfe_u32 v48, v0, 16, 1
	v_add3_u32 v0, v0, v48, s69
	ds_write_b16_d16_hi v71, v0 offset:64
	v_mul_f32_e32 v0, v32, v66
	v_bfe_u32 v32, v0, 16, 1
	v_add3_u32 v0, v0, v32, s69
	ds_write_b16_d16_hi v71, v0 offset:128
	v_mul_f32_e32 v0, v16, v66
	v_bfe_u32 v16, v0, 16, 1
	v_add3_u32 v0, v0, v16, s69
	ds_write_b16_d16_hi v71, v0 offset:192
	v_rcp_f32_e32 v0, v67
	s_nop 0
	v_mul_f32_e32 v1, v1, v0
	v_bfe_u32 v16, v1, 16, 1
	v_add3_u32 v1, v1, v16, s69
	v_lshl_add_u32 v16, v210, 8, v70
	ds_write_b16_d16_hi v16, v1 offset:256
	v_mul_f32_e32 v1, v49, v0
	v_bfe_u32 v32, v1, 16, 1
	v_add3_u32 v1, v1, v32, s69
	ds_write_b16_d16_hi v16, v1 offset:320
	v_mul_f32_e32 v1, v33, v0
	v_bfe_u32 v32, v1, 16, 1
	v_add3_u32 v1, v1, v32, s69
	v_mul_f32_e32 v0, v17, v0
	ds_write_b16_d16_hi v16, v1 offset:384
	v_bfe_u32 v1, v0, 16, 1
	v_add3_u32 v0, v0, v1, s69
	ds_write_b16_d16_hi v16, v0 offset:448
	v_rcp_f32_e32 v0, v68
	s_nop 0
	v_mul_f32_e32 v1, v2, v0
	v_bfe_u32 v2, v1, 16, 1
	v_add3_u32 v1, v1, v2, s69
	ds_write_b16_d16_hi v16, v1 offset:512
	v_mul_f32_e32 v1, v50, v0
	v_bfe_u32 v2, v1, 16, 1
	v_add3_u32 v1, v1, v2, s69
	ds_write_b16_d16_hi v16, v1 offset:576
	v_mul_f32_e32 v1, v34, v0
	v_bfe_u32 v2, v1, 16, 1
	v_add3_u32 v1, v1, v2, s69
	v_mul_f32_e32 v0, v18, v0
	ds_write_b16_d16_hi v16, v1 offset:640
	v_bfe_u32 v1, v0, 16, 1
	v_add3_u32 v0, v0, v1, s69
	ds_write_b16_d16_hi v16, v0 offset:704
	v_rcp_f32_e32 v0, v69
	s_nop 0
	v_mul_f32_e32 v1, v3, v0
	v_bfe_u32 v2, v1, 16, 1
	v_add3_u32 v1, v1, v2, s69
	ds_write_b16_d16_hi v16, v1 offset:768
	v_mul_f32_e32 v1, v51, v0
	v_bfe_u32 v2, v1, 16, 1
	v_add3_u32 v1, v1, v2, s69
	ds_write_b16_d16_hi v16, v1 offset:832
	v_mul_f32_e32 v1, v35, v0
	v_bfe_u32 v2, v1, 16, 1
	v_add3_u32 v1, v1, v2, s69
	v_mul_f32_e32 v0, v19, v0
	ds_write_b16_d16_hi v16, v1 offset:896
	v_bfe_u32 v1, v0, 16, 1
	v_add3_u32 v0, v0, v1, s69
	ds_write_b16_d16_hi v16, v0 offset:960
	ds_read_b128 v[0:3], v65 offset:32
	s_waitcnt lgkmcnt(0)
	v_rcp_f32_e32 v0, v0
	s_nop 0
	v_mul_f32_e32 v4, v4, v0
	v_bfe_u32 v17, v4, 16, 1
	v_add3_u32 v4, v4, v17, s69
	ds_write_b16_d16_hi v16, v4 offset:2048
	v_mul_f32_e32 v4, v52, v0
	v_bfe_u32 v17, v4, 16, 1
	v_add3_u32 v4, v4, v17, s69
	ds_write_b16_d16_hi v16, v4 offset:2112
	v_mul_f32_e32 v4, v36, v0
	v_bfe_u32 v17, v4, 16, 1
	v_add3_u32 v4, v4, v17, s69
	v_mul_f32_e32 v0, v20, v0
	ds_write_b16_d16_hi v16, v4 offset:2176
	v_bfe_u32 v4, v0, 16, 1
	v_add3_u32 v0, v0, v4, s69
	ds_write_b16_d16_hi v16, v0 offset:2240
	v_rcp_f32_e32 v0, v1
	s_nop 0
	v_mul_f32_e32 v1, v5, v0
	v_bfe_u32 v4, v1, 16, 1
	v_add3_u32 v1, v1, v4, s69
	ds_write_b16_d16_hi v16, v1 offset:2304
	v_mul_f32_e32 v1, v53, v0
	v_bfe_u32 v4, v1, 16, 1
	v_add3_u32 v1, v1, v4, s69
	ds_write_b16_d16_hi v16, v1 offset:2368
	v_mul_f32_e32 v1, v37, v0
	v_bfe_u32 v4, v1, 16, 1
	v_add3_u32 v1, v1, v4, s69
	v_mul_f32_e32 v0, v21, v0
	ds_write_b16_d16_hi v16, v1 offset:2432
	v_bfe_u32 v1, v0, 16, 1
	v_add3_u32 v0, v0, v1, s69
	ds_write_b16_d16_hi v16, v0 offset:2496
	v_rcp_f32_e32 v0, v2
	s_nop 0
	v_mul_f32_e32 v1, v6, v0
	v_bfe_u32 v2, v1, 16, 1
	v_add3_u32 v1, v1, v2, s69
	ds_write_b16_d16_hi v16, v1 offset:2560
	v_mul_f32_e32 v1, v54, v0
	v_bfe_u32 v2, v1, 16, 1
	v_add3_u32 v1, v1, v2, s69
	ds_write_b16_d16_hi v16, v1 offset:2624
	v_mul_f32_e32 v1, v38, v0
	v_bfe_u32 v2, v1, 16, 1
	v_add3_u32 v1, v1, v2, s69
	v_mul_f32_e32 v0, v22, v0
	ds_write_b16_d16_hi v16, v1 offset:2688
	v_bfe_u32 v1, v0, 16, 1
	v_add3_u32 v0, v0, v1, s69
	ds_write_b16_d16_hi v16, v0 offset:2752
	v_rcp_f32_e32 v0, v3
	s_nop 0
	v_mul_f32_e32 v1, v7, v0
	v_bfe_u32 v2, v1, 16, 1
	v_add3_u32 v1, v1, v2, s69
	ds_write_b16_d16_hi v16, v1 offset:2816
	v_mul_f32_e32 v1, v55, v0
	v_bfe_u32 v2, v1, 16, 1
	v_add3_u32 v1, v1, v2, s69
	ds_write_b16_d16_hi v16, v1 offset:2880
	v_mul_f32_e32 v1, v39, v0
	v_bfe_u32 v2, v1, 16, 1
	v_add3_u32 v1, v1, v2, s69
	v_mul_f32_e32 v0, v23, v0
	ds_write_b16_d16_hi v16, v1 offset:2944
	v_bfe_u32 v1, v0, 16, 1
	v_add3_u32 v0, v0, v1, s69
	ds_write_b16_d16_hi v16, v0 offset:3008
	ds_read_b128 v[0:3], v65 offset:64
	s_waitcnt lgkmcnt(0)
	v_rcp_f32_e32 v0, v0
	s_nop 0
	v_mul_f32_e32 v4, v8, v0
	v_bfe_u32 v5, v4, 16, 1
	v_add3_u32 v4, v4, v5, s69
	ds_write_b16_d16_hi v16, v4 offset:4096
	v_mul_f32_e32 v4, v56, v0
	v_bfe_u32 v5, v4, 16, 1
	v_add3_u32 v4, v4, v5, s69
	ds_write_b16_d16_hi v16, v4 offset:4160
	v_mul_f32_e32 v4, v40, v0
	v_bfe_u32 v5, v4, 16, 1
	v_add3_u32 v4, v4, v5, s69
	v_mul_f32_e32 v0, v24, v0
	ds_write_b16_d16_hi v16, v4 offset:4224
	v_bfe_u32 v4, v0, 16, 1
	v_add3_u32 v0, v0, v4, s69
	ds_write_b16_d16_hi v16, v0 offset:4288
	v_rcp_f32_e32 v0, v1
	v_lshrrev_b32_e32 v8, 4, v202
	v_mul_f32_e32 v1, v9, v0
	v_bfe_u32 v4, v1, 16, 1
	v_add3_u32 v1, v1, v4, s69
	ds_write_b16_d16_hi v16, v1 offset:4352
	v_mul_f32_e32 v1, v57, v0
	v_bfe_u32 v4, v1, 16, 1
	v_add3_u32 v1, v1, v4, s69
	ds_write_b16_d16_hi v16, v1 offset:4416
	v_mul_f32_e32 v1, v41, v0
	v_bfe_u32 v4, v1, 16, 1
	v_add3_u32 v1, v1, v4, s69
	v_mul_f32_e32 v0, v25, v0
	ds_write_b16_d16_hi v16, v1 offset:4480
	v_bfe_u32 v1, v0, 16, 1
	v_add3_u32 v0, v0, v1, s69
	ds_write_b16_d16_hi v16, v0 offset:4544
	v_rcp_f32_e32 v0, v2
	v_add_u32_e32 v9, v64, v144
	v_mul_f32_e32 v1, v10, v0
	v_bfe_u32 v2, v1, 16, 1
	v_add3_u32 v1, v1, v2, s69
	ds_write_b16_d16_hi v16, v1 offset:4608
	v_mul_f32_e32 v1, v58, v0
	v_bfe_u32 v2, v1, 16, 1
	v_add3_u32 v1, v1, v2, s69
	ds_write_b16_d16_hi v16, v1 offset:4672
	v_mul_f32_e32 v1, v42, v0
	v_bfe_u32 v2, v1, 16, 1
	v_add3_u32 v1, v1, v2, s69
	v_mul_f32_e32 v0, v26, v0
	ds_write_b16_d16_hi v16, v1 offset:4736
	v_bfe_u32 v1, v0, 16, 1
	v_add3_u32 v0, v0, v1, s69
	ds_write_b16_d16_hi v16, v0 offset:4800
	v_rcp_f32_e32 v0, v3
	s_nop 0
	v_mul_f32_e32 v1, v11, v0
	v_bfe_u32 v2, v1, 16, 1
	v_add3_u32 v1, v1, v2, s69
	ds_write_b16_d16_hi v16, v1 offset:4864
	v_mul_f32_e32 v1, v59, v0
	v_bfe_u32 v2, v1, 16, 1
	v_add3_u32 v1, v1, v2, s69
	ds_write_b16_d16_hi v16, v1 offset:4928
	v_mul_f32_e32 v1, v43, v0
	v_bfe_u32 v2, v1, 16, 1
	v_add3_u32 v1, v1, v2, s69
	v_mul_f32_e32 v0, v27, v0
	ds_write_b16_d16_hi v16, v1 offset:4992
	v_bfe_u32 v1, v0, 16, 1
	v_add3_u32 v0, v0, v1, s69
	ds_write_b16_d16_hi v16, v0 offset:5056
	ds_read_b128 v[0:3], v65 offset:96
	s_waitcnt lgkmcnt(0)
	v_rcp_f32_e32 v0, v0
	s_nop 0
	v_mul_f32_e32 v4, v12, v0
	v_bfe_u32 v5, v4, 16, 1
	v_add3_u32 v4, v4, v5, s69
	ds_write_b16_d16_hi v16, v4 offset:6144
	v_mul_f32_e32 v4, v60, v0
	v_bfe_u32 v5, v4, 16, 1
	v_add3_u32 v4, v4, v5, s69
	ds_write_b16_d16_hi v16, v4 offset:6208
	v_mul_f32_e32 v4, v44, v0
	v_bfe_u32 v5, v4, 16, 1
	v_add3_u32 v4, v4, v5, s69
	v_mul_f32_e32 v0, v28, v0
	ds_write_b16_d16_hi v16, v4 offset:6272
	v_bfe_u32 v4, v0, 16, 1
	v_add3_u32 v0, v0, v4, s69
	ds_write_b16_d16_hi v16, v0 offset:6336
	v_rcp_f32_e32 v0, v1
	s_nop 0
	v_mul_f32_e32 v1, v13, v0
	v_bfe_u32 v4, v1, 16, 1
	v_add3_u32 v1, v1, v4, s69
	ds_write_b16_d16_hi v16, v1 offset:6400
	v_mul_f32_e32 v1, v61, v0
	v_bfe_u32 v4, v1, 16, 1
	v_add3_u32 v1, v1, v4, s69
	ds_write_b16_d16_hi v16, v1 offset:6464
	v_mul_f32_e32 v1, v45, v0
	v_bfe_u32 v4, v1, 16, 1
	v_add3_u32 v1, v1, v4, s69
	v_mul_f32_e32 v0, v29, v0
	ds_write_b16_d16_hi v16, v1 offset:6528
	v_bfe_u32 v1, v0, 16, 1
	v_add3_u32 v0, v0, v1, s69
	ds_write_b16_d16_hi v16, v0 offset:6592
	v_rcp_f32_e32 v0, v2
	s_nop 0
	v_mul_f32_e32 v1, v14, v0
	v_bfe_u32 v2, v1, 16, 1
	v_add3_u32 v1, v1, v2, s69
	ds_write_b16_d16_hi v16, v1 offset:6656
	v_mul_f32_e32 v1, v62, v0
	v_bfe_u32 v2, v1, 16, 1
	v_add3_u32 v1, v1, v2, s69
	ds_write_b16_d16_hi v16, v1 offset:6720
	v_mul_f32_e32 v1, v46, v0
	v_bfe_u32 v2, v1, 16, 1
	v_add3_u32 v1, v1, v2, s69
	v_mul_f32_e32 v0, v30, v0
	ds_write_b16_d16_hi v16, v1 offset:6784
	v_bfe_u32 v1, v0, 16, 1
	v_add3_u32 v0, v0, v1, s69
	ds_write_b16_d16_hi v16, v0 offset:6848
	v_rcp_f32_e32 v0, v3
	s_nop 0
	v_mul_f32_e32 v1, v15, v0
	v_bfe_u32 v2, v1, 16, 1
	v_add3_u32 v1, v1, v2, s69
	ds_write_b16_d16_hi v16, v1 offset:6912
	v_mul_f32_e32 v1, v63, v0
	v_bfe_u32 v2, v1, 16, 1
	v_add3_u32 v1, v1, v2, s69
	ds_write_b16_d16_hi v16, v1 offset:6976
	v_mul_f32_e32 v1, v47, v0
	v_bfe_u32 v2, v1, 16, 1
	v_add3_u32 v1, v1, v2, s69
	v_mul_f32_e32 v0, v31, v0
	ds_write_b16_d16_hi v16, v1 offset:7040
	v_bfe_u32 v1, v0, 16, 1
	v_add3_u32 v0, v0, v1, s69
	ds_write_b16_d16_hi v16, v0 offset:7104
	v_add_u32_e32 v0, s86, v203
	v_ashrrev_i32_e32 v1, 31, v0
	v_lshlrev_b64 v[0:1], 12, v[0:1]
	v_lshl_add_u64 v[0:1], s[96:97], 0, v[0:1]
	s_waitcnt lgkmcnt(0)
	v_lshl_add_u64 v[4:5], v[0:1], 0, v[144:145]
	v_lshl_add_u32 v0, v8, 8, v9
	ds_read_b128 v[0:3], v0
	v_lshlrev_b32_e32 v144, 12, v8
	v_lshl_add_u64 v[6:7], v[4:5], 0, v[144:145]
	s_waitcnt lgkmcnt(0)
	global_store_dwordx4 v[6:7], v[0:3], off sc1
	v_or_b32_e32 v6, 4, v8
	s_nop 0
	v_lshl_add_u32 v0, v6, 8, v9
	ds_read_b128 v[0:3], v0
	v_lshlrev_b32_e32 v144, 12, v6
	v_lshl_add_u64 v[6:7], v[4:5], 0, v[144:145]
	s_waitcnt lgkmcnt(0)
	global_store_dwordx4 v[6:7], v[0:3], off sc1
	v_or_b32_e32 v6, 8, v8
	s_nop 0
	v_lshl_add_u32 v0, v6, 8, v9
	ds_read_b128 v[0:3], v0
	v_lshlrev_b32_e32 v144, 12, v6
	v_lshl_add_u64 v[6:7], v[4:5], 0, v[144:145]
	s_waitcnt lgkmcnt(0)
	global_store_dwordx4 v[6:7], v[0:3], off sc1
	v_or_b32_e32 v6, 12, v8
	s_nop 0
	v_lshl_add_u32 v0, v6, 8, v9
	ds_read_b128 v[0:3], v0
	v_lshlrev_b32_e32 v144, 12, v6
	v_lshl_add_u64 v[6:7], v[4:5], 0, v[144:145]
	s_waitcnt lgkmcnt(0)
	global_store_dwordx4 v[6:7], v[0:3], off sc1
	v_or_b32_e32 v6, 16, v8
	s_nop 0
	v_lshl_add_u32 v0, v6, 8, v9
	ds_read_b128 v[0:3], v0
	v_lshlrev_b32_e32 v144, 12, v6
	v_lshl_add_u64 v[6:7], v[4:5], 0, v[144:145]
	s_waitcnt lgkmcnt(0)
	global_store_dwordx4 v[6:7], v[0:3], off sc1
	v_or_b32_e32 v6, 20, v8
	s_nop 0
	v_lshl_add_u32 v0, v6, 8, v9
	ds_read_b128 v[0:3], v0
	v_lshlrev_b32_e32 v144, 12, v6
	v_lshl_add_u64 v[6:7], v[4:5], 0, v[144:145]
	s_waitcnt lgkmcnt(0)
	global_store_dwordx4 v[6:7], v[0:3], off sc1
	v_or_b32_e32 v6, 24, v8
	s_nop 0
	v_lshl_add_u32 v0, v6, 8, v9
	ds_read_b128 v[0:3], v0
	v_lshlrev_b32_e32 v144, 12, v6
	v_lshl_add_u64 v[6:7], v[4:5], 0, v[144:145]
	s_waitcnt lgkmcnt(0)
	global_store_dwordx4 v[6:7], v[0:3], off sc1
	v_or_b32_e32 v6, 28, v8
	s_nop 0
	v_lshl_add_u32 v0, v6, 8, v9
	ds_read_b128 v[0:3], v0
	v_lshlrev_b32_e32 v144, 12, v6
	v_lshl_add_u64 v[4:5], v[4:5], 0, v[144:145]
	s_waitcnt lgkmcnt(0)
	global_store_dwordx4 v[4:5], v[0:3], off sc1
	s_barrier

.LBB0_757:
	s_and_saveexec_b64 s[6:7], s[4:5]
	ds_write_b32 v194, v64
	s_or_b64 exec, exec, s[6:7]
	v_add_u32_e32 v66, v192, v144
	s_waitcnt lgkmcnt(0)
	s_barrier
	ds_read_b128 v[68:71], v66
	v_lshl_add_u32 v64, v190, 13, 0
	v_lshlrev_b32_e32 v65, 1, v191
	v_and_b32_e32 v144, 0xf0, v188
	s_waitcnt lgkmcnt(0)
	v_rcp_f32_e32 v67, v68
	v_lshlrev_b32_e32 v68, 10, v189
	v_add3_u32 v65, v64, v65, v68
	v_mul_f32_e32 v48, v48, v67
	v_bfe_u32 v68, v48, 16, 1
	v_add3_u32 v48, v48, v68, s69
	v_mul_f32_e32 v32, v32, v67
	ds_write_b16_d16_hi v65, v48
	v_bfe_u32 v48, v32, 16, 1
	v_add3_u32 v32, v32, v48, s69
	v_mul_f32_e32 v16, v16, v67
	ds_write_b16_d16_hi v65, v32 offset:64
	v_bfe_u32 v32, v16, 16, 1
	v_add3_u32 v16, v16, v32, s69
	v_mul_f32_e32 v0, v0, v67
	ds_write_b16_d16_hi v65, v16 offset:128
	v_bfe_u32 v16, v0, 16, 1
	v_add3_u32 v0, v0, v16, s69
	ds_write_b16_d16_hi v65, v0 offset:192
	v_rcp_f32_e32 v0, v69
	s_nop 0
	v_mul_f32_e32 v16, v49, v0
	v_bfe_u32 v32, v16, 16, 1
	v_add3_u32 v16, v16, v32, s69
	ds_write_b16_d16_hi v65, v16 offset:256
	v_mul_f32_e32 v16, v33, v0
	v_bfe_u32 v32, v16, 16, 1
	v_add3_u32 v16, v16, v32, s69
	ds_write_b16_d16_hi v65, v16 offset:320
	v_mul_f32_e32 v16, v17, v0
	v_mul_f32_e32 v0, v1, v0
	v_bfe_u32 v1, v0, 16, 1
	v_add3_u32 v0, v0, v1, s69
	ds_write_b16_d16_hi v65, v0 offset:448
	v_rcp_f32_e32 v0, v70
	v_bfe_u32 v17, v16, 16, 1
	v_add3_u32 v16, v16, v17, s69
	ds_write_b16_d16_hi v65, v16 offset:384
	v_mul_f32_e32 v1, v50, v0
	v_bfe_u32 v16, v1, 16, 1
	v_add3_u32 v1, v1, v16, s69
	ds_write_b16_d16_hi v65, v1 offset:512
	v_mul_f32_e32 v1, v34, v0
	v_bfe_u32 v16, v1, 16, 1
	v_add3_u32 v1, v1, v16, s69
	ds_write_b16_d16_hi v65, v1 offset:576
	v_mul_f32_e32 v1, v18, v0
	v_bfe_u32 v16, v1, 16, 1
	v_add3_u32 v1, v1, v16, s69
	v_mul_f32_e32 v0, v2, v0
	ds_write_b16_d16_hi v65, v1 offset:640
	v_bfe_u32 v1, v0, 16, 1
	v_add3_u32 v0, v0, v1, s69
	ds_write_b16_d16_hi v65, v0 offset:704
	v_rcp_f32_e32 v0, v71
	s_nop 0
	v_mul_f32_e32 v1, v51, v0
	v_bfe_u32 v2, v1, 16, 1
	v_add3_u32 v1, v1, v2, s69
	ds_write_b16_d16_hi v65, v1 offset:768
	v_mul_f32_e32 v1, v35, v0
	v_bfe_u32 v2, v1, 16, 1
	v_add3_u32 v1, v1, v2, s69
	ds_write_b16_d16_hi v65, v1 offset:832
	v_mul_f32_e32 v1, v19, v0
	v_bfe_u32 v2, v1, 16, 1
	v_add3_u32 v1, v1, v2, s69
	v_mul_f32_e32 v0, v3, v0
	ds_write_b16_d16_hi v65, v1 offset:896
	v_bfe_u32 v1, v0, 16, 1
	v_add3_u32 v0, v0, v1, s69
	ds_write_b16_d16_hi v65, v0 offset:960
	ds_read_b128 v[0:3], v66 offset:32
	s_waitcnt lgkmcnt(0)
	v_rcp_f32_e32 v0, v0
	s_nop 0
	v_mul_f32_e32 v16, v52, v0
	v_bfe_u32 v17, v16, 16, 1
	v_add3_u32 v16, v16, v17, s69
	ds_write_b16_d16_hi v65, v16 offset:2048
	v_mul_f32_e32 v16, v36, v0
	v_bfe_u32 v17, v16, 16, 1
	v_add3_u32 v16, v16, v17, s69
	ds_write_b16_d16_hi v65, v16 offset:2112
	v_mul_f32_e32 v16, v20, v0
	v_mul_f32_e32 v0, v4, v0
	v_bfe_u32 v4, v0, 16, 1
	v_add3_u32 v0, v0, v4, s69
	ds_write_b16_d16_hi v65, v0 offset:2240
	v_rcp_f32_e32 v0, v1
	v_bfe_u32 v17, v16, 16, 1
	v_add3_u32 v16, v16, v17, s69
	ds_write_b16_d16_hi v65, v16 offset:2176
	v_mul_f32_e32 v1, v53, v0
	v_bfe_u32 v4, v1, 16, 1
	v_add3_u32 v1, v1, v4, s69
	ds_write_b16_d16_hi v65, v1 offset:2304
	v_mul_f32_e32 v1, v37, v0
	v_bfe_u32 v4, v1, 16, 1
	v_add3_u32 v1, v1, v4, s69
	ds_write_b16_d16_hi v65, v1 offset:2368
	v_mul_f32_e32 v1, v21, v0
	v_bfe_u32 v4, v1, 16, 1
	v_add3_u32 v1, v1, v4, s69
	v_mul_f32_e32 v0, v5, v0
	ds_write_b16_d16_hi v65, v1 offset:2432
	v_bfe_u32 v1, v0, 16, 1
	v_add3_u32 v0, v0, v1, s69
	ds_write_b16_d16_hi v65, v0 offset:2496
	v_rcp_f32_e32 v0, v2
	s_nop 0
	v_mul_f32_e32 v1, v54, v0
	v_bfe_u32 v2, v1, 16, 1
	v_add3_u32 v1, v1, v2, s69
	ds_write_b16_d16_hi v65, v1 offset:2560
	v_mul_f32_e32 v1, v38, v0
	v_bfe_u32 v2, v1, 16, 1
	v_add3_u32 v1, v1, v2, s69
	ds_write_b16_d16_hi v65, v1 offset:2624
	v_mul_f32_e32 v1, v22, v0
	v_bfe_u32 v2, v1, 16, 1
	v_add3_u32 v1, v1, v2, s69
	v_mul_f32_e32 v0, v6, v0
	ds_write_b16_d16_hi v65, v1 offset:2688
	v_bfe_u32 v1, v0, 16, 1
	v_add3_u32 v0, v0, v1, s69
	ds_write_b16_d16_hi v65, v0 offset:2752
	v_rcp_f32_e32 v0, v3
	s_nop 0
	v_mul_f32_e32 v1, v55, v0
	v_bfe_u32 v2, v1, 16, 1
	v_add3_u32 v1, v1, v2, s69
	ds_write_b16_d16_hi v65, v1 offset:2816
	v_mul_f32_e32 v1, v39, v0
	v_bfe_u32 v2, v1, 16, 1
	v_add3_u32 v1, v1, v2, s69
	ds_write_b16_d16_hi v65, v1 offset:2880
	v_mul_f32_e32 v1, v23, v0
	v_bfe_u32 v2, v1, 16, 1
	v_add3_u32 v1, v1, v2, s69
	v_mul_f32_e32 v0, v7, v0
	ds_write_b16_d16_hi v65, v1 offset:2944
	v_bfe_u32 v1, v0, 16, 1
	v_add3_u32 v0, v0, v1, s69
	ds_write_b16_d16_hi v65, v0 offset:3008
	ds_read_b128 v[0:3], v66 offset:64
	s_waitcnt lgkmcnt(0)
	v_rcp_f32_e32 v0, v0
	s_nop 0
	v_mul_f32_e32 v4, v56, v0
	v_bfe_u32 v5, v4, 16, 1
	v_add3_u32 v4, v4, v5, s69
	ds_write_b16_d16_hi v65, v4 offset:4096
	v_mul_f32_e32 v4, v40, v0
	v_bfe_u32 v5, v4, 16, 1
	v_add3_u32 v4, v4, v5, s69
	ds_write_b16_d16_hi v65, v4 offset:4160
	v_mul_f32_e32 v4, v24, v0
	v_bfe_u32 v5, v4, 16, 1
	v_add3_u32 v4, v4, v5, s69
	v_mul_f32_e32 v0, v8, v0
	ds_write_b16_d16_hi v65, v4 offset:4224
	v_bfe_u32 v4, v0, 16, 1
	v_add3_u32 v0, v0, v4, s69
	ds_write_b16_d16_hi v65, v0 offset:4288
	v_rcp_f32_e32 v0, v1
	v_lshrrev_b32_e32 v8, 4, v186
	v_mul_f32_e32 v1, v57, v0
	v_bfe_u32 v4, v1, 16, 1
	v_add3_u32 v1, v1, v4, s69
	ds_write_b16_d16_hi v65, v1 offset:4352
	v_mul_f32_e32 v1, v41, v0
	v_bfe_u32 v4, v1, 16, 1
	v_add3_u32 v1, v1, v4, s69
	ds_write_b16_d16_hi v65, v1 offset:4416
	v_mul_f32_e32 v1, v25, v0
	v_bfe_u32 v4, v1, 16, 1
	v_add3_u32 v1, v1, v4, s69
	v_mul_f32_e32 v0, v9, v0
	ds_write_b16_d16_hi v65, v1 offset:4480
	v_bfe_u32 v1, v0, 16, 1
	v_add3_u32 v0, v0, v1, s69
	ds_write_b16_d16_hi v65, v0 offset:4544
	v_rcp_f32_e32 v0, v2
	v_add_u32_e32 v9, v64, v144
	v_mul_f32_e32 v1, v58, v0
	v_bfe_u32 v2, v1, 16, 1
	v_add3_u32 v1, v1, v2, s69
	ds_write_b16_d16_hi v65, v1 offset:4608
	v_mul_f32_e32 v1, v42, v0
	v_bfe_u32 v2, v1, 16, 1
	v_add3_u32 v1, v1, v2, s69
	ds_write_b16_d16_hi v65, v1 offset:4672
	v_mul_f32_e32 v1, v26, v0
	v_bfe_u32 v2, v1, 16, 1
	v_add3_u32 v1, v1, v2, s69
	v_mul_f32_e32 v0, v10, v0
	ds_write_b16_d16_hi v65, v1 offset:4736
	v_bfe_u32 v1, v0, 16, 1
	v_add3_u32 v0, v0, v1, s69
	ds_write_b16_d16_hi v65, v0 offset:4800
	v_rcp_f32_e32 v0, v3
	s_nop 0
	v_mul_f32_e32 v1, v59, v0
	v_bfe_u32 v2, v1, 16, 1
	v_add3_u32 v1, v1, v2, s69
	ds_write_b16_d16_hi v65, v1 offset:4864
	v_mul_f32_e32 v1, v43, v0
	v_bfe_u32 v2, v1, 16, 1
	v_add3_u32 v1, v1, v2, s69
	ds_write_b16_d16_hi v65, v1 offset:4928
	v_mul_f32_e32 v1, v27, v0
	v_bfe_u32 v2, v1, 16, 1
	v_add3_u32 v1, v1, v2, s69
	v_mul_f32_e32 v0, v11, v0
	ds_write_b16_d16_hi v65, v1 offset:4992
	v_bfe_u32 v1, v0, 16, 1
	v_add3_u32 v0, v0, v1, s69
	ds_write_b16_d16_hi v65, v0 offset:5056
	ds_read_b128 v[0:3], v66 offset:96
	s_waitcnt lgkmcnt(0)
	v_rcp_f32_e32 v0, v0
	s_nop 0
	v_mul_f32_e32 v4, v60, v0
	v_bfe_u32 v5, v4, 16, 1
	v_add3_u32 v4, v4, v5, s69
	ds_write_b16_d16_hi v65, v4 offset:6144
	v_mul_f32_e32 v4, v44, v0
	v_bfe_u32 v5, v4, 16, 1
	v_add3_u32 v4, v4, v5, s69
	ds_write_b16_d16_hi v65, v4 offset:6208
	v_mul_f32_e32 v4, v28, v0
	v_bfe_u32 v5, v4, 16, 1
	v_add3_u32 v4, v4, v5, s69
	v_mul_f32_e32 v0, v12, v0
	ds_write_b16_d16_hi v65, v4 offset:6272
	v_bfe_u32 v4, v0, 16, 1
	v_add3_u32 v0, v0, v4, s69
	ds_write_b16_d16_hi v65, v0 offset:6336
	v_rcp_f32_e32 v0, v1
	s_nop 0
	v_mul_f32_e32 v1, v61, v0
	v_bfe_u32 v4, v1, 16, 1
	v_add3_u32 v1, v1, v4, s69
	ds_write_b16_d16_hi v65, v1 offset:6400
	v_mul_f32_e32 v1, v45, v0
	v_bfe_u32 v4, v1, 16, 1
	v_add3_u32 v1, v1, v4, s69
	ds_write_b16_d16_hi v65, v1 offset:6464
	v_mul_f32_e32 v1, v29, v0
	v_bfe_u32 v4, v1, 16, 1
	v_add3_u32 v1, v1, v4, s69
	v_mul_f32_e32 v0, v13, v0
	ds_write_b16_d16_hi v65, v1 offset:6528
	v_bfe_u32 v1, v0, 16, 1
	v_add3_u32 v0, v0, v1, s69
	ds_write_b16_d16_hi v65, v0 offset:6592
	v_rcp_f32_e32 v0, v2
	s_nop 0
	v_mul_f32_e32 v1, v62, v0
	v_bfe_u32 v2, v1, 16, 1
	v_add3_u32 v1, v1, v2, s69
	ds_write_b16_d16_hi v65, v1 offset:6656
	v_mul_f32_e32 v1, v46, v0
	v_bfe_u32 v2, v1, 16, 1
	v_add3_u32 v1, v1, v2, s69
	ds_write_b16_d16_hi v65, v1 offset:6720
	v_mul_f32_e32 v1, v30, v0
	v_bfe_u32 v2, v1, 16, 1
	v_add3_u32 v1, v1, v2, s69
	v_mul_f32_e32 v0, v14, v0
	ds_write_b16_d16_hi v65, v1 offset:6784
	v_bfe_u32 v1, v0, 16, 1
	v_add3_u32 v0, v0, v1, s69
	ds_write_b16_d16_hi v65, v0 offset:6848
	v_rcp_f32_e32 v0, v3
	s_nop 0
	v_mul_f32_e32 v1, v63, v0
	v_bfe_u32 v2, v1, 16, 1
	v_add3_u32 v1, v1, v2, s69
	ds_write_b16_d16_hi v65, v1 offset:6912
	v_mul_f32_e32 v1, v47, v0
	v_bfe_u32 v2, v1, 16, 1
	v_add3_u32 v1, v1, v2, s69
	ds_write_b16_d16_hi v65, v1 offset:6976
	v_mul_f32_e32 v1, v31, v0
	v_bfe_u32 v2, v1, 16, 1
	v_add3_u32 v1, v1, v2, s69
	v_mul_f32_e32 v0, v15, v0
	ds_write_b16_d16_hi v65, v1 offset:7040
	v_bfe_u32 v1, v0, 16, 1
	v_add3_u32 v0, v0, v1, s69
	ds_write_b16_d16_hi v65, v0 offset:7104
	v_add_u32_e32 v0, s86, v187
	v_ashrrev_i32_e32 v1, 31, v0
	v_lshlrev_b64 v[0:1], 12, v[0:1]
	v_lshl_add_u64 v[0:1], s[96:97], 0, v[0:1]
	s_waitcnt lgkmcnt(0)
	v_lshl_add_u64 v[4:5], v[0:1], 0, v[144:145]
	v_lshl_add_u32 v0, v8, 8, v9
	ds_read_b128 v[0:3], v0
	v_lshlrev_b32_e32 v144, 12, v8
	v_lshl_add_u64 v[6:7], v[4:5], 0, v[144:145]
	s_waitcnt lgkmcnt(0)
	global_store_dwordx4 v[6:7], v[0:3], off sc1
	v_or_b32_e32 v6, 4, v8
	s_nop 0
	v_lshl_add_u32 v0, v6, 8, v9
	ds_read_b128 v[0:3], v0
	v_lshlrev_b32_e32 v144, 12, v6
	v_lshl_add_u64 v[6:7], v[4:5], 0, v[144:145]
	s_waitcnt lgkmcnt(0)
	global_store_dwordx4 v[6:7], v[0:3], off sc1
	v_or_b32_e32 v6, 8, v8
	s_nop 0
	v_lshl_add_u32 v0, v6, 8, v9
	ds_read_b128 v[0:3], v0
	v_lshlrev_b32_e32 v144, 12, v6
	v_lshl_add_u64 v[6:7], v[4:5], 0, v[144:145]
	s_waitcnt lgkmcnt(0)
	global_store_dwordx4 v[6:7], v[0:3], off sc1
	v_or_b32_e32 v6, 12, v8
	s_nop 0
	v_lshl_add_u32 v0, v6, 8, v9
	ds_read_b128 v[0:3], v0
	v_lshlrev_b32_e32 v144, 12, v6
	v_lshl_add_u64 v[6:7], v[4:5], 0, v[144:145]
	s_waitcnt lgkmcnt(0)
	global_store_dwordx4 v[6:7], v[0:3], off sc1
	v_or_b32_e32 v6, 16, v8
	s_nop 0
	v_lshl_add_u32 v0, v6, 8, v9
	ds_read_b128 v[0:3], v0
	v_lshlrev_b32_e32 v144, 12, v6
	v_lshl_add_u64 v[6:7], v[4:5], 0, v[144:145]
	s_waitcnt lgkmcnt(0)
	global_store_dwordx4 v[6:7], v[0:3], off sc1
	v_or_b32_e32 v6, 20, v8
	s_nop 0
	v_lshl_add_u32 v0, v6, 8, v9
	ds_read_b128 v[0:3], v0
	v_lshlrev_b32_e32 v144, 12, v6
	v_lshl_add_u64 v[6:7], v[4:5], 0, v[144:145]
	s_waitcnt lgkmcnt(0)
	global_store_dwordx4 v[6:7], v[0:3], off sc1
	v_or_b32_e32 v6, 24, v8
	s_nop 0
	v_lshl_add_u32 v0, v6, 8, v9
	ds_read_b128 v[0:3], v0
	v_lshlrev_b32_e32 v144, 12, v6
	v_lshl_add_u64 v[6:7], v[4:5], 0, v[144:145]
	s_waitcnt lgkmcnt(0)
	global_store_dwordx4 v[6:7], v[0:3], off sc1
	v_or_b32_e32 v6, 28, v8
	s_nop 0
	v_lshl_add_u32 v0, v6, 8, v9
	ds_read_b128 v[0:3], v0
	v_lshlrev_b32_e32 v144, 12, v6
	v_lshl_add_u64 v[4:5], v[4:5], 0, v[144:145]
	s_waitcnt lgkmcnt(0)
	global_store_dwordx4 v[4:5], v[0:3], off sc1
	s_barrier

.LBB0_845:
	v_lshl_add_u32 v146, s42, 8, v140
	v_lshl_or_b32 v138, s41, 8, v142
	v_ashrrev_i32_e32 v147, 31, v146
	v_ashrrev_i32_e32 v139, 31, v138
	v_lshlrev_b64 v[148:149], 12, v[146:147]
	v_lshl_add_u64 v[148:149], s[8:9], 0, v[148:149]
	v_lshlrev_b64 v[150:151], 1, v[138:139]
	v_lshl_add_u64 v[138:139], v[148:149], 0, v[150:151]
	v_cvt_pk_bf16_f32 v124, v124, v125
	v_cvt_pk_bf16_f32 v125, v126, v127
	v_cvt_pk_bf16_f32 v126, v120, v121
	v_cvt_pk_bf16_f32 v127, v122, v123
	global_store_dwordx4 v[138:139], v[124:127], off sc1
	v_cvt_pk_bf16_f32 v112, v112, v113
	v_cvt_pk_bf16_f32 v113, v114, v115
	v_cvt_pk_bf16_f32 v114, v104, v105
	v_or_b32_e32 v104, 16, v146
	v_ashrrev_i32_e32 v105, 31, v104
	v_lshlrev_b64 v[104:105], 12, v[104:105]
	v_lshl_add_u64 v[104:105], s[8:9], 0, v[104:105]
	v_cvt_pk_bf16_f32 v115, v106, v107
	global_store_dwordx4 v[138:139], v[112:115], off offset:256 sc1
	s_mov_b64 s[12:13], 0x80000
	s_nop 0
	v_lshl_add_u64 v[112:113], v[104:105], 0, v[150:151]
	v_cvt_pk_bf16_f32 v104, v116, v117
	v_cvt_pk_bf16_f32 v105, v118, v119
	v_cvt_pk_bf16_f32 v106, v108, v109
	v_cvt_pk_bf16_f32 v107, v110, v111
	global_store_dwordx4 v[112:113], v[104:107], off sc1
	v_cvt_pk_bf16_f32 v96, v96, v97
	v_cvt_pk_bf16_f32 v97, v98, v99
	v_cvt_pk_bf16_f32 v98, v88, v89
	v_or_b32_e32 v88, 32, v146
	v_ashrrev_i32_e32 v89, 31, v88
	v_lshlrev_b64 v[88:89], 12, v[88:89]
	v_lshl_add_u64 v[88:89], s[8:9], 0, v[88:89]
	v_cvt_pk_bf16_f32 v99, v90, v91
	global_store_dwordx4 v[112:113], v[96:99], off offset:256 sc1
	s_nop 1
	v_lshl_add_u64 v[96:97], v[88:89], 0, v[150:151]
	v_cvt_pk_bf16_f32 v88, v100, v101
	v_cvt_pk_bf16_f32 v89, v102, v103
	v_cvt_pk_bf16_f32 v90, v92, v93
	v_cvt_pk_bf16_f32 v91, v94, v95
	global_store_dwordx4 v[96:97], v[88:91], off sc1
	v_cvt_pk_bf16_f32 v80, v80, v81
	v_cvt_pk_bf16_f32 v81, v82, v83
	v_cvt_pk_bf16_f32 v82, v72, v73
	v_or_b32_e32 v72, 48, v146
	v_ashrrev_i32_e32 v73, 31, v72
	v_lshlrev_b64 v[72:73], 12, v[72:73]
	v_lshl_add_u64 v[72:73], s[8:9], 0, v[72:73]
	v_cvt_pk_bf16_f32 v83, v74, v75
	global_store_dwordx4 v[96:97], v[80:83], off offset:256 sc1
	s_nop 1
	v_lshl_add_u64 v[80:81], v[72:73], 0, v[150:151]
	v_cvt_pk_bf16_f32 v72, v84, v85
	v_cvt_pk_bf16_f32 v73, v86, v87
	v_cvt_pk_bf16_f32 v74, v76, v77
	v_cvt_pk_bf16_f32 v75, v78, v79
	global_store_dwordx4 v[80:81], v[72:75], off sc1
	v_cvt_pk_bf16_f32 v68, v68, v69
	v_cvt_pk_bf16_f32 v69, v70, v71
	v_cvt_pk_bf16_f32 v70, v64, v65
	v_lshl_add_u64 v[64:65], v[138:139], 0, s[12:13]
	s_mov_b32 s12, 0x80000
	v_cvt_pk_bf16_f32 v71, v66, v67
	global_store_dwordx4 v[80:81], v[68:71], off offset:256 sc1
	v_cvt_pk_bf16_f32 v60, v60, v61
	v_cvt_pk_bf16_f32 v61, v62, v63
	v_cvt_pk_bf16_f32 v62, v56, v57
	v_add_co_u32_e32 v56, vcc, s12, v138
	v_cvt_pk_bf16_f32 v63, v58, v59
	s_mov_b64 s[12:13], 0x90000
	s_nop 0
	v_addc_co_u32_e32 v57, vcc, 0, v139, vcc
	global_store_dwordx4 v[56:57], v[60:63], off sc1
	v_cvt_pk_bf16_f32 v48, v48, v49
	v_cvt_pk_bf16_f32 v49, v50, v51
	v_cvt_pk_bf16_f32 v50, v40, v41
	v_cvt_pk_bf16_f32 v51, v42, v43
	global_store_dwordx4 v[64:65], v[48:51], off offset:256 sc1
	v_cvt_pk_bf16_f32 v40, v52, v53
	v_cvt_pk_bf16_f32 v41, v54, v55
	v_cvt_pk_bf16_f32 v42, v44, v45
	v_cvt_pk_bf16_f32 v43, v46, v47
	s_nop 1
	v_lshl_add_u64 v[48:49], v[138:139], 0, s[12:13]
	s_mov_b32 s12, 0x90000
	v_add_co_u32_e32 v44, vcc, s12, v138
	s_mov_b64 s[12:13], 0xa0000
	s_nop 0
	v_addc_co_u32_e32 v45, vcc, 0, v139, vcc
	global_store_dwordx4 v[44:45], v[40:43], off sc1
	v_cvt_pk_bf16_f32 v32, v32, v33
	v_cvt_pk_bf16_f32 v33, v34, v35
	v_cvt_pk_bf16_f32 v34, v24, v25
	v_cvt_pk_bf16_f32 v35, v26, v27
	global_store_dwordx4 v[48:49], v[32:35], off offset:256 sc1
	v_cvt_pk_bf16_f32 v24, v36, v37
	v_cvt_pk_bf16_f32 v25, v38, v39
	v_cvt_pk_bf16_f32 v26, v28, v29
	v_cvt_pk_bf16_f32 v27, v30, v31
	s_nop 1
	v_lshl_add_u64 v[32:33], v[138:139], 0, s[12:13]
	s_mov_b32 s12, 0xa0000
	v_add_co_u32_e32 v28, vcc, s12, v138
	s_mov_b64 s[12:13], 0xb0000
	s_nop 0
	v_addc_co_u32_e32 v29, vcc, 0, v139, vcc
	global_store_dwordx4 v[28:29], v[24:27], off sc1
	v_cvt_pk_bf16_f32 v16, v16, v17
	v_cvt_pk_bf16_f32 v17, v18, v19
	v_cvt_pk_bf16_f32 v18, v8, v9
	v_cvt_pk_bf16_f32 v19, v10, v11
	global_store_dwordx4 v[32:33], v[16:19], off offset:256 sc1
	v_cvt_pk_bf16_f32 v8, v20, v21
	v_cvt_pk_bf16_f32 v9, v22, v23
	v_cvt_pk_bf16_f32 v10, v12, v13
	v_cvt_pk_bf16_f32 v11, v14, v15
	s_nop 1
	v_lshl_add_u64 v[16:17], v[138:139], 0, s[12:13]
	s_mov_b32 s12, 0xb0000
	v_add_co_u32_e32 v12, vcc, s12, v138
	s_nop 1
	v_addc_co_u32_e32 v13, vcc, 0, v139, vcc
	s_andn2_b64 vcc, exec, s[4:5]
	s_mov_b64 s[4:5], -1
	global_store_dwordx4 v[12:13], v[8:11], off sc1
	v_cvt_pk_bf16_f32 v4, v4, v5
	v_cvt_pk_bf16_f32 v5, v6, v7
	v_cvt_pk_bf16_f32 v6, v0, v1
	v_cvt_pk_bf16_f32 v7, v2, v3
	global_store_dwordx4 v[16:17], v[4:7], off offset:256 sc1
	s_cbranch_vccnz .LBB0_834
	s_andn2_b64 vcc, exec, s[6:7]
	s_cbranch_vccnz .LBB0_833
	s_barrier
	s_branch .LBB0_833

.LBB0_866:
	v_lshl_or_b32 v138, s25, 8, v142
	s_ashr_i32 s25, s24, 31
	s_lshl_b64 s[24:25], s[24:25], 22
	s_add_u32 s24, s42, s24
	v_lshl_add_u32 v146, s47, 8, v141
	s_addc_u32 s25, s43, s25
	v_ashrrev_i32_e32 v139, 31, v138
	v_ashrrev_i32_e32 v147, 31, v146
	v_lshl_add_u64 v[148:149], v[138:139], 1, s[24:25]
	v_lshlrev_b64 v[138:139], 12, v[146:147]
	v_lshl_add_u64 v[138:139], v[148:149], 0, v[138:139]
	v_cvt_pk_bf16_f32 v124, v124, v125
	v_cvt_pk_bf16_f32 v125, v126, v127
	v_cvt_pk_bf16_f32 v126, v120, v121
	v_cvt_pk_bf16_f32 v127, v122, v123
	global_store_dwordx4 v[138:139], v[124:127], off sc1
	v_cvt_pk_bf16_f32 v112, v112, v113
	v_cvt_pk_bf16_f32 v113, v114, v115
	v_cvt_pk_bf16_f32 v114, v104, v105
	v_or_b32_e32 v104, 16, v146
	v_ashrrev_i32_e32 v105, 31, v104
	v_lshlrev_b64 v[104:105], 12, v[104:105]
	v_cvt_pk_bf16_f32 v115, v106, v107
	global_store_dwordx4 v[138:139], v[112:115], off offset:256 sc1
	s_mov_b64 s[4:5], 0x80000
	s_nop 0
	v_lshl_add_u64 v[112:113], v[148:149], 0, v[104:105]
	v_cvt_pk_bf16_f32 v104, v116, v117
	v_cvt_pk_bf16_f32 v105, v118, v119
	v_cvt_pk_bf16_f32 v106, v108, v109
	v_cvt_pk_bf16_f32 v107, v110, v111
	global_store_dwordx4 v[112:113], v[104:107], off sc1
	v_cvt_pk_bf16_f32 v96, v96, v97
	v_cvt_pk_bf16_f32 v97, v98, v99
	v_cvt_pk_bf16_f32 v98, v88, v89
	v_or_b32_e32 v88, 32, v146
	v_ashrrev_i32_e32 v89, 31, v88
	v_lshlrev_b64 v[88:89], 12, v[88:89]
	v_cvt_pk_bf16_f32 v99, v90, v91
	global_store_dwordx4 v[112:113], v[96:99], off offset:256 sc1
	s_nop 1
	v_lshl_add_u64 v[96:97], v[148:149], 0, v[88:89]
	v_cvt_pk_bf16_f32 v88, v100, v101
	v_cvt_pk_bf16_f32 v89, v102, v103
	v_cvt_pk_bf16_f32 v90, v92, v93
	v_cvt_pk_bf16_f32 v91, v94, v95
	global_store_dwordx4 v[96:97], v[88:91], off sc1
	v_cvt_pk_bf16_f32 v80, v80, v81
	v_cvt_pk_bf16_f32 v81, v82, v83
	v_cvt_pk_bf16_f32 v82, v72, v73
	v_or_b32_e32 v72, 48, v146
	v_ashrrev_i32_e32 v73, 31, v72
	v_lshlrev_b64 v[72:73], 12, v[72:73]
	v_cvt_pk_bf16_f32 v83, v74, v75
	global_store_dwordx4 v[96:97], v[80:83], off offset:256 sc1
	s_nop 1
	v_lshl_add_u64 v[80:81], v[148:149], 0, v[72:73]
	v_cvt_pk_bf16_f32 v72, v84, v85
	v_cvt_pk_bf16_f32 v73, v86, v87
	v_cvt_pk_bf16_f32 v74, v76, v77
	v_cvt_pk_bf16_f32 v75, v78, v79
	global_store_dwordx4 v[80:81], v[72:75], off sc1
	v_cvt_pk_bf16_f32 v68, v68, v69
	v_cvt_pk_bf16_f32 v69, v70, v71
	v_cvt_pk_bf16_f32 v70, v64, v65
	v_lshl_add_u64 v[64:65], v[138:139], 0, s[4:5]
	s_mov_b32 s4, 0x80000
	v_cvt_pk_bf16_f32 v71, v66, v67
	global_store_dwordx4 v[80:81], v[68:71], off offset:256 sc1
	v_cvt_pk_bf16_f32 v60, v60, v61
	v_cvt_pk_bf16_f32 v61, v62, v63
	v_cvt_pk_bf16_f32 v62, v56, v57
	v_add_co_u32_e32 v56, vcc, s4, v138
	v_cvt_pk_bf16_f32 v63, v58, v59
	s_mov_b64 s[4:5], 0x90000
	s_nop 0
	v_addc_co_u32_e32 v57, vcc, 0, v139, vcc
	global_store_dwordx4 v[56:57], v[60:63], off sc1
	v_cvt_pk_bf16_f32 v48, v48, v49
	v_cvt_pk_bf16_f32 v49, v50, v51
	v_cvt_pk_bf16_f32 v50, v40, v41
	v_cvt_pk_bf16_f32 v51, v42, v43
	global_store_dwordx4 v[64:65], v[48:51], off offset:256 sc1
	v_cvt_pk_bf16_f32 v40, v52, v53
	v_cvt_pk_bf16_f32 v41, v54, v55
	v_cvt_pk_bf16_f32 v42, v44, v45
	v_cvt_pk_bf16_f32 v43, v46, v47
	s_nop 1
	v_lshl_add_u64 v[48:49], v[138:139], 0, s[4:5]
	s_mov_b32 s4, 0x90000
	v_add_co_u32_e32 v44, vcc, s4, v138
	s_mov_b64 s[4:5], 0xa0000
	s_nop 0
	v_addc_co_u32_e32 v45, vcc, 0, v139, vcc
	global_store_dwordx4 v[44:45], v[40:43], off sc1
	v_cvt_pk_bf16_f32 v32, v32, v33
	v_cvt_pk_bf16_f32 v33, v34, v35
	v_cvt_pk_bf16_f32 v34, v24, v25
	v_cvt_pk_bf16_f32 v35, v26, v27
	global_store_dwordx4 v[48:49], v[32:35], off offset:256 sc1
	v_cvt_pk_bf16_f32 v24, v36, v37
	v_cvt_pk_bf16_f32 v25, v38, v39
	v_cvt_pk_bf16_f32 v26, v28, v29
	v_cvt_pk_bf16_f32 v27, v30, v31
	s_nop 1
	v_lshl_add_u64 v[32:33], v[138:139], 0, s[4:5]
	s_mov_b32 s4, 0xa0000
	v_add_co_u32_e32 v28, vcc, s4, v138
	s_mov_b64 s[4:5], 0xb0000
	s_nop 0
	v_addc_co_u32_e32 v29, vcc, 0, v139, vcc
	global_store_dwordx4 v[28:29], v[24:27], off sc1
	v_cvt_pk_bf16_f32 v16, v16, v17
	v_cvt_pk_bf16_f32 v17, v18, v19
	v_cvt_pk_bf16_f32 v18, v8, v9
	v_cvt_pk_bf16_f32 v19, v10, v11
	global_store_dwordx4 v[32:33], v[16:19], off offset:256 sc1
	v_cvt_pk_bf16_f32 v8, v20, v21
	v_cvt_pk_bf16_f32 v9, v22, v23
	v_cvt_pk_bf16_f32 v10, v12, v13
	v_cvt_pk_bf16_f32 v11, v14, v15
	s_nop 1
	v_lshl_add_u64 v[16:17], v[138:139], 0, s[4:5]
	s_mov_b32 s4, 0xb0000
	v_add_co_u32_e32 v12, vcc, s4, v138
	s_nop 1
	v_addc_co_u32_e32 v13, vcc, 0, v139, vcc
	s_and_b64 vcc, exec, s[6:7]
	s_mov_b64 s[6:7], -1
	global_store_dwordx4 v[12:13], v[8:11], off sc1
	v_cvt_pk_bf16_f32 v4, v4, v5
	v_cvt_pk_bf16_f32 v5, v6, v7
	v_cvt_pk_bf16_f32 v6, v0, v1
	v_cvt_pk_bf16_f32 v7, v2, v3
	global_store_dwordx4 v[16:17], v[4:7], off offset:256 sc1
	s_cbranch_vccnz .LBB0_855
	s_andn2_b64 vcc, exec, s[14:15]
	s_cbranch_vccnz .LBB0_854
	s_barrier
	s_branch .LBB0_854

.LBB0_1007:
	ds_bpermute_b32 v114, v169, v15
	ds_bpermute_b32 v186, v169, v103
	ds_bpermute_b32 v143, v168, v12
	ds_bpermute_b32 v151, v168, v15
	v_mov_b32_e32 v132, v15
	s_waitcnt lgkmcnt(5)
	v_mov_b32_e32 v133, v127
	s_waitcnt lgkmcnt(2)
	v_cndmask_b32_e64 v115, v114, v186, s[16:17]
	v_mov_b32_e32 v114, v123
	s_waitcnt lgkmcnt(1)
	v_cndmask_b32_e64 v203, v143, v138, s[14:15]
	s_waitcnt lgkmcnt(0)
	v_cndmask_b32_e64 v138, v151, v141, s[14:15]
	v_pk_mul_f32 v[114:115], v[132:133], v[114:115]
	ds_bpermute_b32 v147, v168, v13
	v_fma_f32 v114, v109, v138, v114
	v_add_f32_e32 v114, v114, v115
	v_add_f32_e32 v114, v119, v114
	v_mul_f32_e32 v115, 0xbfb8aa3b, v114
	ds_bpermute_b32 v150, v169, v14
	ds_bpermute_b32 v184, v169, v102
	v_exp_f32_e32 v132, v115
	ds_bpermute_b32 v149, v168, v14
	s_waitcnt lgkmcnt(3)
	v_cndmask_b32_e64 v204, v147, v139, s[14:15]
	v_mov_b32_e32 v138, v14
	v_add_f32_e32 v132, 1.0, v132
	s_waitcnt lgkmcnt(1)
	v_cndmask_b32_e64 v133, v150, v184, s[16:17]
	v_rcp_f32_e32 v141, v132
	v_mov_b32_e32 v139, v126
	v_mov_b32_e32 v132, v122
	s_waitcnt lgkmcnt(0)
	v_cndmask_b32_e64 v140, v149, v140, s[14:15]
	v_pk_mul_f32 v[132:133], v[138:139], v[132:133]
	ds_bpermute_b32 v146, v169, v12
	v_fma_f32 v132, v108, v140, v132
	v_add_f32_e32 v132, v132, v133
	v_add_f32_e32 v140, v118, v132
	v_mul_f32_e32 v132, 0xbfb8aa3b, v140
	ds_bpermute_b32 v148, v169, v13
	ds_bpermute_b32 v153, v169, v100
	ds_bpermute_b32 v182, v169, v101
	v_exp_f32_e32 v132, v132
	v_mul_f32_e32 v114, v114, v141
	v_mul_f32_e32 v141, v23, v114
	s_waitcnt lgkmcnt(1)
	v_cndmask_b32_e64 v133, v146, v153, s[16:17]
	v_add_f32_e32 v114, 1.0, v132
	s_waitcnt lgkmcnt(0)
	v_cndmask_b32_e64 v115, v148, v182, s[16:17]
	v_rcp_f32_e32 v146, v114
	v_mov_b32_e32 v138, v13
	v_mov_b32_e32 v139, v125
	v_mov_b32_e32 v114, v121
	v_pk_mul_f32 v[114:115], v[138:139], v[114:115]
	v_mov_b32_e32 v132, v120
	v_fma_f32 v114, v107, v204, v114
	v_add_f32_e32 v114, v114, v115
	v_add_f32_e32 v138, v117, v114
	v_mul_f32_e32 v114, 0xbfb8aa3b, v138
	v_exp_f32_e32 v139, v114
	v_mov_b32_e32 v114, v12
	v_mov_b32_e32 v115, v124
	v_pk_mul_f32 v[114:115], v[114:115], v[132:133]
	v_add_f32_e32 v133, 1.0, v139
	v_fma_f32 v114, v106, v203, v114
	v_add_f32_e32 v114, v114, v115
	v_add_f32_e32 v114, v116, v114
	v_mul_f32_e32 v115, 0xbfb8aa3b, v114
	v_exp_f32_e32 v115, v115
	v_rcp_f32_e32 v133, v133
	v_mul_f32_e32 v132, v140, v146
	ds_bpermute_b32 v194, v169, v95
	v_add_f32_e32 v115, 1.0, v115
	v_rcp_f32_e32 v115, v115
	v_mul_f32_e32 v139, v22, v132
	v_mul_f32_e32 v132, v138, v133
	v_or_b32_e32 v110, s22, v167
	ds_bpermute_b32 v185, v168, v103
	v_mul_f32_e32 v132, v21, v132
	v_mul_f32_e32 v114, v114, v115
	v_lshl_add_u32 v142, s24, 8, v165
	v_ashrrev_i32_e32 v111, 31, v110
	v_mul_f32_e32 v114, v20, v114
	v_cvt_pk_bf16_f32 v132, v114, v132
	v_cvt_pk_bf16_f32 v133, v139, v141
	v_mov_b64_e32 v[140:141], s[28:29]
	s_movk_i32 s2, 0x2c00
	v_mad_i64_i32 v[114:115], s[20:21], v142, s2, v[140:141]
	v_lshlrev_b64 v[138:139], 1, v[110:111]
	v_lshl_add_u64 v[114:115], v[114:115], 0, v[138:139]
	global_store_dwordx4 v[114:115], v[130:133], off sc1
	s_waitcnt lgkmcnt(1)
	v_cndmask_b32_e64 v114, v186, v194, s[16:17]
	v_mov_b32_e32 v115, v123
	v_mov_b32_e32 v130, v127
	v_mov_b32_e32 v131, v103
	s_waitcnt lgkmcnt(0)
	v_cndmask_b32_e64 v132, v185, v151, s[14:15]
	v_pk_mul_f32 v[114:115], v[130:131], v[114:115]
	ds_bpermute_b32 v192, v169, v94
	v_fma_f32 v103, v109, v132, v115
	v_add_f32_e32 v103, v114, v103
	v_add_f32_e32 v115, v119, v103
	v_mul_f32_e32 v103, 0xbfb8aa3b, v115
	ds_bpermute_b32 v181, v168, v101
	ds_bpermute_b32 v183, v168, v102
	v_exp_f32_e32 v103, v103
	s_waitcnt lgkmcnt(2)
	v_cndmask_b32_e64 v130, v184, v192, s[16:17]
	v_mov_b32_e32 v132, v126
	v_mov_b32_e32 v133, v102
	v_add_f32_e32 v103, 1.0, v103
	v_mov_b32_e32 v131, v122
	s_waitcnt lgkmcnt(1)
	v_cndmask_b32_e64 v146, v181, v147, s[14:15]
	s_waitcnt lgkmcnt(0)
	v_cndmask_b32_e64 v147, v183, v149, s[14:15]
	v_rcp_f32_e32 v148, v103
	v_pk_mul_f32 v[102:103], v[132:133], v[130:131]
	ds_bpermute_b32 v190, v169, v93
	v_fma_f32 v103, v108, v147, v103
	v_add_f32_e32 v102, v102, v103
	v_add_f32_e32 v132, v118, v102
	v_mul_f32_e32 v102, 0xbfb8aa3b, v132
	v_exp_f32_e32 v103, v102
	ds_bpermute_b32 v188, v169, v92
	s_waitcnt lgkmcnt(1)
	v_cndmask_b32_e64 v102, v182, v190, s[16:17]
	v_mov_b32_e32 v130, v125
	v_add_f32_e32 v103, 1.0, v103
	v_rcp_f32_e32 v133, v103
	v_mov_b32_e32 v131, v101
	v_mov_b32_e32 v103, v121
	ds_bpermute_b32 v152, v168, v100
	v_pk_mul_f32 v[102:103], v[130:131], v[102:103]
	v_mul_f32_e32 v115, v115, v148
	v_fma_f32 v101, v107, v146, v103
	v_add_f32_e32 v101, v102, v101
	v_add_f32_e32 v130, v117, v101
	s_waitcnt lgkmcnt(1)
	v_cndmask_b32_e64 v114, v153, v188, s[16:17]
	v_mul_f32_e32 v99, v99, v115
	v_mul_f32_e32 v101, 0xbfb8aa3b, v130
	v_mov_b32_e32 v102, v124
	v_mov_b32_e32 v103, v100
	v_mov_b32_e32 v115, v120
	s_waitcnt lgkmcnt(0)
	v_cndmask_b32_e64 v143, v152, v143, s[14:15]
	v_exp_f32_e32 v131, v101
	v_pk_mul_f32 v[100:101], v[102:103], v[114:115]
	ds_bpermute_b32 v202, v169, v83
	v_fma_f32 v101, v106, v143, v101
	v_add_f32_e32 v100, v100, v101
	v_add_f32_e32 v100, v116, v100
	v_mul_f32_e32 v101, 0xbfb8aa3b, v100
	v_exp_f32_e32 v101, v101
	v_add_f32_e32 v103, 1.0, v131
	v_rcp_f32_e32 v103, v103
	v_mul_f32_e32 v102, v132, v133
	v_add_f32_e32 v101, 1.0, v101
	v_rcp_f32_e32 v101, v101
	ds_bpermute_b32 v193, v168, v95
	v_mul_f32_e32 v98, v98, v102
	v_mul_f32_e32 v102, v130, v103
	v_mul_f32_e32 v100, v100, v101
	v_mul_f32_e32 v96, v96, v100
	v_mul_f32_e32 v97, v97, v102
	v_cvt_pk_bf16_f32 v130, v96, v97
	v_or_b32_e32 v96, 16, v142
	v_mad_i64_i32 v[96:97], s[20:21], v96, s2, v[140:141]
	v_lshl_add_u64 v[96:97], v[96:97], 0, v[138:139]
	v_cvt_pk_bf16_f32 v131, v98, v99
	global_store_dwordx4 v[96:97], v[128:131], off sc1
	s_waitcnt lgkmcnt(1)
	v_cndmask_b32_e64 v96, v194, v202, s[16:17]
	v_mov_b32_e32 v98, v127
	v_mov_b32_e32 v99, v95
	v_mov_b32_e32 v97, v123
	s_waitcnt lgkmcnt(0)
	v_cndmask_b32_e64 v100, v193, v185, s[14:15]
	v_pk_mul_f32 v[96:97], v[98:99], v[96:97]
	ds_bpermute_b32 v200, v169, v82
	v_fma_f32 v95, v109, v100, v97
	v_add_f32_e32 v95, v96, v95
	v_add_f32_e32 v97, v119, v95
	v_mul_f32_e32 v95, 0xbfb8aa3b, v97
	ds_bpermute_b32 v191, v168, v94
	v_exp_f32_e32 v95, v95
	s_waitcnt lgkmcnt(1)
	v_cndmask_b32_e64 v98, v192, v200, s[16:17]
	v_mov_b32_e32 v100, v126
	v_mov_b32_e32 v101, v94
	v_add_f32_e32 v95, 1.0, v95
	v_mov_b32_e32 v99, v122
	s_waitcnt lgkmcnt(0)
	v_cndmask_b32_e64 v114, v191, v183, s[14:15]
	v_rcp_f32_e32 v115, v95
	v_pk_mul_f32 v[94:95], v[100:101], v[98:99]
	ds_bpermute_b32 v198, v169, v81
	v_fma_f32 v95, v108, v114, v95
	v_add_f32_e32 v94, v94, v95
	v_add_f32_e32 v100, v118, v94
	v_mul_f32_e32 v94, 0xbfb8aa3b, v100
	v_exp_f32_e32 v95, v94
	ds_bpermute_b32 v189, v168, v93
	ds_bpermute_b32 v196, v169, v80
	s_waitcnt lgkmcnt(2)
	v_cndmask_b32_e64 v94, v190, v198, s[16:17]
	v_add_f32_e32 v95, 1.0, v95
	v_rcp_f32_e32 v101, v95
	v_mov_b32_e32 v98, v125
	v_mov_b32_e32 v99, v93
	v_mov_b32_e32 v95, v121
	ds_bpermute_b32 v187, v168, v92
	s_waitcnt lgkmcnt(2)
	v_cndmask_b32_e64 v103, v189, v181, s[14:15]
	v_pk_mul_f32 v[94:95], v[98:99], v[94:95]
	v_mul_f32_e32 v97, v97, v115
	v_fma_f32 v93, v107, v103, v95
	v_add_f32_e32 v93, v94, v93
	v_add_f32_e32 v98, v117, v93
	s_waitcnt lgkmcnt(1)
	v_cndmask_b32_e64 v96, v188, v196, s[16:17]
	v_mul_f32_e32 v91, v91, v97
	v_mul_f32_e32 v93, 0xbfb8aa3b, v98
	v_mov_b32_e32 v94, v124
	v_mov_b32_e32 v95, v92
	v_mov_b32_e32 v97, v120
	s_waitcnt lgkmcnt(0)
	v_cndmask_b32_e64 v102, v187, v152, s[14:15]
	v_exp_f32_e32 v99, v93
	v_pk_mul_f32 v[92:93], v[94:95], v[96:97]
	v_mul_f32_e32 v94, v100, v101
	v_fma_f32 v93, v106, v102, v93
	v_add_f32_e32 v92, v92, v93
	v_add_f32_e32 v92, v116, v92
	v_mul_f32_e32 v93, 0xbfb8aa3b, v92
	v_exp_f32_e32 v93, v93
	v_add_f32_e32 v95, 1.0, v99
	v_rcp_f32_e32 v95, v95
	ds_bpermute_b32 v201, v168, v83
	v_add_f32_e32 v93, 1.0, v93
	v_rcp_f32_e32 v93, v93
	v_mul_f32_e32 v90, v90, v94
	v_mul_f32_e32 v94, v98, v95
	v_mul_f32_e32 v89, v89, v94
	v_mul_f32_e32 v92, v92, v93
	v_mul_f32_e32 v88, v88, v92
	v_cvt_pk_bf16_f32 v114, v88, v89
	v_or_b32_e32 v88, 32, v142
	v_mad_i64_i32 v[88:89], s[20:21], v88, s2, v[140:141]
	v_lshl_add_u64 v[88:89], v[88:89], 0, v[138:139]
	v_cvt_pk_bf16_f32 v115, v90, v91
	global_store_dwordx4 v[88:89], v[112:115], off sc1
	v_cndmask_b32_e64 v88, v202, v137, s[16:17]
	v_mov_b32_e32 v90, v127
	v_mov_b32_e32 v91, v83
	v_mov_b32_e32 v89, v123
	s_waitcnt lgkmcnt(0)
	v_cndmask_b32_e64 v94, v201, v193, s[14:15]
	v_pk_mul_f32 v[88:89], v[90:91], v[88:89]
	ds_bpermute_b32 v199, v168, v82
	v_fma_f32 v83, v109, v94, v89
	v_add_f32_e32 v83, v88, v83
	v_add_f32_e32 v89, v119, v83
	v_mul_f32_e32 v83, 0xbfb8aa3b, v89
	v_exp_f32_e32 v83, v83
	v_cndmask_b32_e64 v90, v200, v136, s[16:17]
	v_mov_b32_e32 v127, v82
	v_mov_b32_e32 v91, v122
	v_add_f32_e32 v83, 1.0, v83
	s_waitcnt lgkmcnt(0)
	v_cndmask_b32_e64 v94, v199, v191, s[14:15]
	v_rcp_f32_e32 v95, v83
	v_pk_mul_f32 v[82:83], v[126:127], v[90:91]
	ds_bpermute_b32 v197, v168, v81
	v_fma_f32 v83, v108, v94, v83
	v_add_f32_e32 v82, v82, v83
	v_add_f32_e32 v94, v118, v82
	v_mul_f32_e32 v82, 0xbfb8aa3b, v94
	v_mul_f32_e32 v89, v89, v95
	v_cndmask_b32_e64 v88, v198, v135, s[16:17]
	v_exp_f32_e32 v83, v82
	v_mul_f32_e32 v87, v87, v89
	v_mov_b32_e32 v90, v125
	v_mov_b32_e32 v91, v81
	v_mov_b32_e32 v89, v121
	ds_bpermute_b32 v195, v168, v80
	s_waitcnt lgkmcnt(1)
	v_cndmask_b32_e64 v93, v197, v189, s[14:15]
	v_pk_mul_f32 v[88:89], v[90:91], v[88:89]
	v_add_f32_e32 v83, 1.0, v83
	v_fma_f32 v81, v107, v93, v89
	v_add_f32_e32 v81, v88, v81
	v_add_f32_e32 v88, v117, v81
	v_cndmask_b32_e64 v82, v196, v134, s[16:17]
	v_rcp_f32_e32 v95, v83
	v_mul_f32_e32 v81, 0xbfb8aa3b, v88
	v_mov_b32_e32 v125, v80
	v_mov_b32_e32 v83, v120
	s_waitcnt lgkmcnt(0)
	v_cndmask_b32_e64 v92, v195, v187, s[14:15]
	v_exp_f32_e32 v89, v81
	v_pk_mul_f32 v[80:81], v[124:125], v[82:83]
	v_mul_f32_e32 v82, v94, v95
	v_fma_f32 v81, v106, v92, v81
	v_add_f32_e32 v80, v80, v81
	v_add_f32_e32 v80, v116, v80
	v_mul_f32_e32 v81, 0xbfb8aa3b, v80
	v_exp_f32_e32 v81, v81
	v_add_f32_e32 v83, 1.0, v89
	v_rcp_f32_e32 v83, v83
	v_mul_f32_e32 v82, v86, v82
	v_add_f32_e32 v81, 1.0, v81
	v_rcp_f32_e32 v81, v81
	v_mul_f32_e32 v83, v88, v83
	v_mul_f32_e32 v83, v85, v83
	v_mov_b32_e32 v98, 0
	v_mul_f32_e32 v80, v80, v81
	v_mul_f32_e32 v80, v84, v80
	v_cvt_pk_bf16_f32 v106, v80, v83
	v_or_b32_e32 v80, 48, v142
	v_mad_i64_i32 v[80:81], s[20:21], v80, s2, v[140:141]
	v_lshl_add_u64 v[80:81], v[80:81], 0, v[138:139]
	v_cvt_pk_bf16_f32 v107, v82, v87
	global_store_dwordx4 v[80:81], v[104:107], off sc1
	ds_read_b128 v[94:97], v174
	ds_read_b128 v[90:93], v175
	ds_read_b128 v[82:85], v176
	ds_read_b128 v[86:89], v177
	v_cndmask_b32_e64 v80, 0, 1, s[52:53]
	v_cmp_ne_u32_e64 s[20:21], 1, v80
	s_andn2_b64 vcc, exec, s[52:53]
	v_mov_b32_e32 v102, 0
	v_mov_b32_e32 v103, 0
	v_mov_b32_e32 v104, 0
	v_mov_b32_e32 v105, 0
	s_cbranch_vccnz .LBB0_1009
	ds_read_b128 v[102:105], v172 offset:1536

.LBB0_1015:
	ds_bpermute_b32 v60, v169, v51
	ds_bpermute_b32 v107, v169, v47
	ds_bpermute_b32 v99, v168, v51
	v_mov_b32_e32 v82, v51
	s_waitcnt lgkmcnt(4)
	v_mov_b32_e32 v83, v77
	ds_bpermute_b32 v98, v169, v50
	s_waitcnt lgkmcnt(2)
	v_cndmask_b32_e64 v61, v60, v107, s[16:17]
	v_mov_b32_e32 v60, v73
	s_waitcnt lgkmcnt(1)
	v_cndmask_b32_e64 v91, v99, v91, s[14:15]
	v_pk_mul_f32 v[60:61], v[82:83], v[60:61]
	ds_bpermute_b32 v105, v169, v46
	v_fma_f32 v51, v65, v91, v60
	v_add_f32_e32 v51, v51, v61
	v_add_f32_e32 v60, v69, v51
	v_mul_f32_e32 v51, 0xbfb8aa3b, v60
	v_exp_f32_e32 v51, v51
	ds_bpermute_b32 v97, v168, v50
	ds_bpermute_b32 v96, v169, v49
	ds_bpermute_b32 v103, v169, v45
	v_add_f32_e32 v51, 1.0, v51
	s_waitcnt lgkmcnt(3)
	v_cndmask_b32_e64 v83, v98, v105, s[16:17]
	v_rcp_f32_e32 v91, v51
	v_mov_b32_e32 v51, v76
	v_mov_b32_e32 v82, v72
	ds_bpermute_b32 v95, v168, v49
	s_waitcnt lgkmcnt(3)
	v_cndmask_b32_e64 v90, v97, v90, s[14:15]
	v_pk_mul_f32 v[50:51], v[50:51], v[82:83]
	v_mul_f32_e32 v60, v60, v91
	v_fma_f32 v50, v64, v90, v50
	v_add_f32_e32 v50, v50, v51
	v_add_f32_e32 v90, v68, v50
	s_waitcnt lgkmcnt(1)
	v_cndmask_b32_e64 v61, v96, v103, s[16:17]
	v_mul_f32_e32 v50, 0xbfb8aa3b, v90
	v_mul_f32_e32 v55, v55, v60
	v_mov_b32_e32 v82, v49
	v_mov_b32_e32 v83, v75
	v_mov_b32_e32 v60, v71
	ds_bpermute_b32 v94, v169, v48
	ds_bpermute_b32 v101, v169, v44
	s_waitcnt lgkmcnt(2)
	v_cndmask_b32_e64 v89, v95, v89, s[14:15]
	v_exp_f32_e32 v50, v50
	v_pk_mul_f32 v[60:61], v[82:83], v[60:61]
	ds_bpermute_b32 v93, v168, v48
	v_fma_f32 v49, v63, v89, v60
	v_add_f32_e32 v49, v49, v61
	v_add_f32_e32 v60, v67, v49
	v_add_f32_e32 v50, 1.0, v50
	v_mul_f32_e32 v49, 0xbfb8aa3b, v60
	s_waitcnt lgkmcnt(1)
	v_cndmask_b32_e64 v51, v94, v101, s[16:17]
	v_rcp_f32_e32 v91, v50
	v_exp_f32_e32 v61, v49
	v_mov_b32_e32 v49, v74
	v_mov_b32_e32 v50, v70
	s_waitcnt lgkmcnt(0)
	v_cndmask_b32_e64 v88, v93, v88, s[14:15]
	v_pk_mul_f32 v[48:49], v[48:49], v[50:51]
	v_add_f32_e32 v51, 1.0, v61
	v_fma_f32 v48, v62, v88, v48
	v_add_f32_e32 v48, v48, v49
	v_add_f32_e32 v48, v66, v48
	v_mul_f32_e32 v49, 0xbfb8aa3b, v48
	v_exp_f32_e32 v49, v49
	v_rcp_f32_e32 v51, v51
	ds_bpermute_b32 v117, v169, v39
	ds_bpermute_b32 v106, v168, v47
	v_add_f32_e32 v49, 1.0, v49
	v_rcp_f32_e32 v49, v49
	v_mul_f32_e32 v50, v90, v91
	v_mul_f32_e32 v51, v60, v51
	v_add_u32_e32 v92, 0x80, v142
	v_mul_f32_e32 v48, v48, v49
	v_mul_f32_e32 v48, v52, v48
	v_mul_f32_e32 v50, v54, v50
	v_mul_f32_e32 v51, v53, v51
	v_cvt_pk_bf16_f32 v82, v48, v51
	v_mov_b64_e32 v[48:49], s[28:29]
	v_cvt_pk_bf16_f32 v83, v50, v55
	v_mad_i64_i32 v[50:51], s[20:21], v92, s2, v[48:49]
	v_lshl_add_u64 v[50:51], v[50:51], 0, v[138:139]
	global_store_dwordx4 v[50:51], v[80:83], off sc1
	s_waitcnt lgkmcnt(1)
	v_cndmask_b32_e64 v50, v107, v117, s[16:17]
	v_mov_b32_e32 v52, v77
	v_mov_b32_e32 v53, v47
	v_mov_b32_e32 v51, v73
	s_waitcnt lgkmcnt(0)
	v_cndmask_b32_e64 v54, v106, v99, s[14:15]
	v_pk_mul_f32 v[50:51], v[52:53], v[50:51]
	ds_bpermute_b32 v115, v169, v38
	v_fma_f32 v47, v65, v54, v51
	v_add_f32_e32 v47, v50, v47
	v_add_f32_e32 v51, v69, v47
	v_mul_f32_e32 v47, 0xbfb8aa3b, v51
	ds_bpermute_b32 v104, v168, v46
	v_exp_f32_e32 v47, v47
	s_waitcnt lgkmcnt(1)
	v_cndmask_b32_e64 v52, v105, v115, s[16:17]
	v_mov_b32_e32 v54, v76
	v_mov_b32_e32 v55, v46
	v_add_f32_e32 v47, 1.0, v47
	v_mov_b32_e32 v53, v72
	s_waitcnt lgkmcnt(0)
	v_cndmask_b32_e64 v80, v104, v97, s[14:15]
	v_rcp_f32_e32 v81, v47
	v_pk_mul_f32 v[46:47], v[54:55], v[52:53]
	ds_bpermute_b32 v113, v169, v37
	v_fma_f32 v47, v64, v80, v47
	v_add_f32_e32 v46, v46, v47
	v_add_f32_e32 v54, v68, v46
	v_mul_f32_e32 v46, 0xbfb8aa3b, v54
	v_exp_f32_e32 v47, v46
	ds_bpermute_b32 v102, v168, v45
	ds_bpermute_b32 v109, v169, v36
	s_waitcnt lgkmcnt(2)
	v_cndmask_b32_e64 v46, v103, v113, s[16:17]
	v_add_f32_e32 v47, 1.0, v47
	v_rcp_f32_e32 v55, v47
	v_mov_b32_e32 v52, v75
	v_mov_b32_e32 v53, v45
	v_mov_b32_e32 v47, v71
	ds_bpermute_b32 v100, v168, v44
	s_waitcnt lgkmcnt(2)
	v_cndmask_b32_e64 v61, v102, v95, s[14:15]
	v_pk_mul_f32 v[46:47], v[52:53], v[46:47]
	v_mul_f32_e32 v51, v51, v81
	v_fma_f32 v45, v63, v61, v47
	v_add_f32_e32 v45, v46, v45
	v_add_f32_e32 v52, v67, v45
	s_waitcnt lgkmcnt(1)
	v_cndmask_b32_e64 v50, v101, v109, s[16:17]
	v_mul_f32_e32 v43, v43, v51
	v_mul_f32_e32 v45, 0xbfb8aa3b, v52
	v_mov_b32_e32 v46, v74
	v_mov_b32_e32 v47, v44
	v_mov_b32_e32 v51, v70
	s_waitcnt lgkmcnt(0)
	v_cndmask_b32_e64 v60, v100, v93, s[14:15]
	v_exp_f32_e32 v53, v45
	v_pk_mul_f32 v[44:45], v[46:47], v[50:51]
	ds_bpermute_b32 v125, v169, v3
	v_fma_f32 v45, v62, v60, v45
	v_add_f32_e32 v44, v44, v45
	v_add_f32_e32 v44, v66, v44
	v_mul_f32_e32 v45, 0xbfb8aa3b, v44
	v_exp_f32_e32 v45, v45
	v_add_f32_e32 v47, 1.0, v53
	v_rcp_f32_e32 v47, v47
	v_mul_f32_e32 v46, v54, v55
	v_add_f32_e32 v45, 1.0, v45
	v_rcp_f32_e32 v45, v45
	ds_bpermute_b32 v116, v168, v39
	v_mul_f32_e32 v42, v42, v46
	v_mul_f32_e32 v46, v52, v47
	v_mul_f32_e32 v44, v44, v45
	v_mul_f32_e32 v40, v40, v44
	v_mul_f32_e32 v41, v41, v46
	v_cvt_pk_bf16_f32 v80, v40, v41
	v_add_u32_e32 v40, 0x90, v142
	v_mad_i64_i32 v[40:41], s[20:21], v40, s2, v[48:49]
	v_lshl_add_u64 v[40:41], v[40:41], 0, v[138:139]
	v_cvt_pk_bf16_f32 v81, v42, v43
	global_store_dwordx4 v[40:41], v[78:81], off sc1
	s_waitcnt lgkmcnt(1)
	v_cndmask_b32_e64 v40, v117, v125, s[16:17]
	v_mov_b32_e32 v42, v77
	v_mov_b32_e32 v43, v39
	v_mov_b32_e32 v41, v73
	s_waitcnt lgkmcnt(0)
	v_cndmask_b32_e64 v44, v116, v106, s[14:15]
	v_pk_mul_f32 v[40:41], v[42:43], v[40:41]
	ds_bpermute_b32 v123, v169, v2
	v_fma_f32 v39, v65, v44, v41
	v_add_f32_e32 v39, v40, v39
	v_add_f32_e32 v41, v69, v39
	v_mul_f32_e32 v39, 0xbfb8aa3b, v41
	ds_bpermute_b32 v114, v168, v38
	v_exp_f32_e32 v39, v39
	s_waitcnt lgkmcnt(1)
	v_cndmask_b32_e64 v42, v115, v123, s[16:17]
	v_mov_b32_e32 v44, v76
	v_mov_b32_e32 v45, v38
	v_add_f32_e32 v39, 1.0, v39
	v_mov_b32_e32 v43, v72
	s_waitcnt lgkmcnt(0)
	v_cndmask_b32_e64 v50, v114, v104, s[14:15]
	v_rcp_f32_e32 v51, v39
	v_pk_mul_f32 v[38:39], v[44:45], v[42:43]
	ds_bpermute_b32 v121, v169, v1
	v_fma_f32 v39, v64, v50, v39
	v_add_f32_e32 v38, v38, v39
	v_add_f32_e32 v44, v68, v38
	v_mul_f32_e32 v38, 0xbfb8aa3b, v44
	v_exp_f32_e32 v39, v38
	ds_bpermute_b32 v112, v168, v37
	ds_bpermute_b32 v119, v169, v0
	s_waitcnt lgkmcnt(2)
	v_cndmask_b32_e64 v38, v113, v121, s[16:17]
	v_add_f32_e32 v39, 1.0, v39
	v_rcp_f32_e32 v45, v39
	v_mov_b32_e32 v42, v75
	v_mov_b32_e32 v43, v37
	v_mov_b32_e32 v39, v71
	ds_bpermute_b32 v108, v168, v36
	s_waitcnt lgkmcnt(2)
	v_cndmask_b32_e64 v47, v112, v102, s[14:15]
	v_pk_mul_f32 v[38:39], v[42:43], v[38:39]
	v_mul_f32_e32 v41, v41, v51
	v_fma_f32 v37, v63, v47, v39
	v_add_f32_e32 v37, v38, v37
	v_add_f32_e32 v42, v67, v37
	s_waitcnt lgkmcnt(1)
	v_cndmask_b32_e64 v40, v109, v119, s[16:17]
	v_mul_f32_e32 v35, v35, v41
	v_mul_f32_e32 v37, 0xbfb8aa3b, v42
	v_mov_b32_e32 v38, v74
	v_mov_b32_e32 v39, v36
	v_mov_b32_e32 v41, v70
	s_waitcnt lgkmcnt(0)
	v_cndmask_b32_e64 v46, v108, v100, s[14:15]
	v_exp_f32_e32 v43, v37
	v_pk_mul_f32 v[36:37], v[38:39], v[40:41]
	v_mul_f32_e32 v38, v44, v45
	v_fma_f32 v37, v62, v46, v37
	v_add_f32_e32 v36, v36, v37
	v_add_f32_e32 v36, v66, v36
	v_mul_f32_e32 v37, 0xbfb8aa3b, v36
	v_exp_f32_e32 v37, v37
	v_add_f32_e32 v39, 1.0, v43
	v_rcp_f32_e32 v39, v39
	ds_bpermute_b32 v124, v168, v3
	v_add_f32_e32 v37, 1.0, v37
	v_rcp_f32_e32 v37, v37
	v_mul_f32_e32 v34, v34, v38
	v_mul_f32_e32 v38, v42, v39
	v_mul_f32_e32 v33, v33, v38
	v_mul_f32_e32 v36, v36, v37
	v_mul_f32_e32 v32, v32, v36
	v_cvt_pk_bf16_f32 v60, v32, v33
	v_add_u32_e32 v32, 0xa0, v142
	v_mad_i64_i32 v[32:33], s[20:21], v32, s2, v[48:49]
	v_lshl_add_u64 v[32:33], v[32:33], 0, v[138:139]
	v_cvt_pk_bf16_f32 v61, v34, v35
	global_store_dwordx4 v[32:33], v[58:61], off sc1
	v_cndmask_b32_e64 v32, v125, v87, s[16:17]
	v_mov_b32_e32 v34, v77
	v_mov_b32_e32 v35, v3
	v_mov_b32_e32 v33, v73
	s_waitcnt lgkmcnt(0)
	v_cndmask_b32_e64 v36, v124, v116, s[14:15]
	v_pk_mul_f32 v[32:33], v[34:35], v[32:33]
	ds_bpermute_b32 v122, v168, v2
	v_fma_f32 v33, v65, v36, v33
	v_add_f32_e32 v32, v32, v33
	v_add_f32_e32 v33, v69, v32
	v_mul_f32_e32 v32, 0xbfb8aa3b, v33
	v_exp_f32_e32 v35, v32
	v_cndmask_b32_e64 v34, v123, v86, s[16:17]
	v_mov_b32_e32 v77, v2
	s_waitcnt lgkmcnt(0)
	v_cndmask_b32_e64 v36, v122, v114, s[14:15]
	v_add_f32_e32 v35, 1.0, v35
	v_rcp_f32_e32 v37, v35
	v_mov_b32_e32 v35, v72
	v_pk_mul_f32 v[34:35], v[76:77], v[34:35]
	ds_bpermute_b32 v120, v168, v1
	v_fma_f32 v35, v64, v36, v35
	v_add_f32_e32 v34, v34, v35
	v_add_f32_e32 v40, v68, v34
	v_mul_f32_e32 v34, 0xbfb8aa3b, v40
	v_exp_f32_e32 v35, v34
	v_mul_f32_e32 v33, v33, v37
	v_mul_f32_e32 v41, v7, v33
	v_cndmask_b32_e64 v32, v121, v85, s[16:17]
	v_add_f32_e32 v33, 1.0, v35
	v_rcp_f32_e32 v42, v33
	v_mov_b32_e32 v36, v75
	v_mov_b32_e32 v37, v1
	v_mov_b32_e32 v33, v71
	ds_bpermute_b32 v118, v168, v0
	s_waitcnt lgkmcnt(1)
	v_cndmask_b32_e64 v39, v120, v112, s[14:15]
	v_pk_mul_f32 v[32:33], v[36:37], v[32:33]
	v_cndmask_b32_e64 v34, v119, v84, s[16:17]
	v_fma_f32 v33, v63, v39, v33
	v_add_f32_e32 v32, v32, v33
	v_add_f32_e32 v36, v67, v32
	v_mul_f32_e32 v32, 0xbfb8aa3b, v36
	v_mov_b32_e32 v75, v0
	v_mov_b32_e32 v35, v70
	s_waitcnt lgkmcnt(0)
	v_cndmask_b32_e64 v38, v118, v108, s[14:15]
	v_exp_f32_e32 v37, v32
	v_pk_mul_f32 v[32:33], v[74:75], v[34:35]
	v_mul_f32_e32 v34, v40, v42
	v_fma_f32 v33, v62, v38, v33
	v_add_f32_e32 v32, v32, v33
	v_add_f32_e32 v32, v66, v32
	v_mul_f32_e32 v33, 0xbfb8aa3b, v32
	v_exp_f32_e32 v33, v33
	v_add_f32_e32 v35, 1.0, v37
	v_rcp_f32_e32 v35, v35
	v_mul_f32_e32 v34, v6, v34
	v_add_f32_e32 v33, 1.0, v33
	v_rcp_f32_e32 v33, v33
	v_mul_f32_e32 v35, v36, v35
	v_mul_f32_e32 v35, v5, v35
	v_mul_f32_e32 v32, v32, v33
	v_mul_f32_e32 v32, v4, v32
	v_cvt_pk_bf16_f32 v58, v32, v35
	v_add_u32_e32 v32, 0xb0, v142
	v_mad_i64_i32 v[32:33], s[20:21], v32, s2, v[48:49]
	v_lshl_add_u64 v[32:33], v[32:33], 0, v[138:139]
	v_cvt_pk_bf16_f32 v59, v34, v41
	global_store_dwordx4 v[32:33], v[56:59], off sc1
	s_and_saveexec_b64 s[20:21], s[4:5]
	s_cbranch_execnz .LBB0_1018
	s_or_b64 exec, exec, s[20:21]
	s_and_saveexec_b64 s[20:21], s[26:27]
	s_cbranch_execnz .LBB0_1021

.LBB0_1018:
	v_lshl_or_b32 v34, s24, 2, v164
	v_mov_b64_e32 v[32:33], s[30:31]
	s_movk_i32 s2, 0x5800
	v_mad_i64_i32 v[32:33], s[22:23], v34, s2, v[32:33]
	v_lshl_add_u64 v[34:35], v[110:111], 2, v[32:33]
	global_store_dwordx4 v[34:35], v[24:27], off sc1
	s_and_saveexec_b64 s[22:23], s[14:15]
	s_cbranch_execz .LBB0_1020
	s_lshl_b32 s6, s24, 1
	s_mul_i32 s7, s24, 0xb000
	s_mul_hi_i32 s6, s6, 0x5800
	s_add_u32 s64, s81, s7
	s_addc_u32 s65, s82, s6
	v_lshl_add_u64 v[24:25], v[110:111], 2, s[64:65]
	global_store_dwordx4 v[24:25], v[28:31], off sc1
	global_store_dwordx4 v[34:35], v[12:15], off offset:16 sc1
	v_mov_b64_e32 v[32:33], s[64:65]
	s_nop 0
	v_mov_b64_e32 v[12:13], v[20:21]
	v_mov_b64_e32 v[14:15], v[22:23]
.LBB0_1020:
	s_or_b64 exec, exec, s[22:23]
	v_lshl_add_u64 v[20:21], v[110:111], 2, v[32:33]
	global_store_dwordx4 v[20:21], v[12:15], off offset:16 sc1
	s_or_b64 exec, exec, s[20:21]
	s_and_saveexec_b64 s[20:21], s[26:27]
	s_cbranch_execz .LBB0_1017
.LBB0_1021:
	v_lshl_add_u32 v14, s24, 2, v170
	v_mov_b64_e32 v[12:13], s[30:31]
	s_movk_i32 s2, 0x5800
	v_mad_i64_i32 v[14:15], s[22:23], v14, s2, v[12:13]
	v_lshl_add_u64 v[12:13], v[110:111], 2, v[14:15]
	global_store_dwordx4 v[12:13], v[16:19], off sc1
	s_and_saveexec_b64 s[22:23], s[16:17]
	s_cbranch_execz .LBB0_1023
	s_lshl_b32 s6, s24, 1
	s_or_b32 s6, s6, 1
	s_mul_hi_i32 s7, s6, 0x5800
	s_mulk_i32 s6, 0x5800
	s_add_u32 s64, s81, s6
	s_addc_u32 s65, s82, s7
	v_lshl_add_u64 v[16:17], v[110:111], 2, s[64:65]
	global_store_dwordx4 v[16:17], v[8:11], off sc1
	global_store_dwordx4 v[12:13], v[0:3], off offset:16 sc1
	v_mov_b64_e32 v[14:15], s[64:65]
	s_nop 0
	v_mov_b64_e32 v[0:1], v[4:5]
	v_mov_b64_e32 v[2:3], v[6:7]
.LBB0_1023:
	s_or_b64 exec, exec, s[22:23]
	v_lshl_add_u64 v[4:5], v[110:111], 2, v[14:15]
	global_store_dwordx4 v[4:5], v[0:3], off offset:16 sc1
	s_or_b64 exec, exec, s[20:21]
	s_andn2_b64 vcc, exec, s[18:19]
	s_mov_b64 s[18:19], -1
	s_cbranch_vccnz .LBB0_981

.LBB0_1152:
	v_lshl_add_u32 v146, s55, 8, v140
	v_lshl_or_b32 v138, s54, 8, v142
	v_ashrrev_i32_e32 v147, 31, v146
	v_ashrrev_i32_e32 v139, 31, v138
	v_lshlrev_b64 v[148:149], 12, v[146:147]
	v_lshl_add_u64 v[148:149], s[20:21], 0, v[148:149]
	v_lshlrev_b64 v[150:151], 1, v[138:139]
	v_lshl_add_u64 v[138:139], v[148:149], 0, v[150:151]
	v_cvt_pk_bf16_f32 v124, v124, v125
	v_cvt_pk_bf16_f32 v125, v126, v127
	v_cvt_pk_bf16_f32 v126, v120, v121
	v_cvt_pk_bf16_f32 v127, v122, v123
	global_store_dwordx4 v[138:139], v[124:127], off sc1
	v_cvt_pk_bf16_f32 v112, v112, v113
	v_cvt_pk_bf16_f32 v113, v114, v115
	v_cvt_pk_bf16_f32 v114, v104, v105
	v_or_b32_e32 v104, 16, v146
	v_ashrrev_i32_e32 v105, 31, v104
	v_lshlrev_b64 v[104:105], 12, v[104:105]
	v_lshl_add_u64 v[104:105], s[20:21], 0, v[104:105]
	v_cvt_pk_bf16_f32 v115, v106, v107
	global_store_dwordx4 v[138:139], v[112:115], off offset:256 sc1
	s_mov_b64 s[4:5], 0x80000
	s_mov_b32 s56, 0x413504f3
	v_lshl_add_u64 v[112:113], v[104:105], 0, v[150:151]
	v_cvt_pk_bf16_f32 v104, v116, v117
	v_cvt_pk_bf16_f32 v105, v118, v119
	v_cvt_pk_bf16_f32 v106, v108, v109
	v_cvt_pk_bf16_f32 v107, v110, v111
	global_store_dwordx4 v[112:113], v[104:107], off sc1
	v_cvt_pk_bf16_f32 v96, v96, v97
	v_cvt_pk_bf16_f32 v97, v98, v99
	v_cvt_pk_bf16_f32 v98, v88, v89
	v_or_b32_e32 v88, 32, v146
	v_ashrrev_i32_e32 v89, 31, v88
	v_lshlrev_b64 v[88:89], 12, v[88:89]
	v_lshl_add_u64 v[88:89], s[20:21], 0, v[88:89]
	v_cvt_pk_bf16_f32 v99, v90, v91
	global_store_dwordx4 v[112:113], v[96:99], off offset:256 sc1
	s_nop 1
	v_lshl_add_u64 v[96:97], v[88:89], 0, v[150:151]
	v_cvt_pk_bf16_f32 v88, v100, v101
	v_cvt_pk_bf16_f32 v89, v102, v103
	v_cvt_pk_bf16_f32 v90, v92, v93
	v_cvt_pk_bf16_f32 v91, v94, v95
	global_store_dwordx4 v[96:97], v[88:91], off sc1
	v_cvt_pk_bf16_f32 v80, v80, v81
	v_cvt_pk_bf16_f32 v81, v82, v83
	v_cvt_pk_bf16_f32 v82, v72, v73
	v_or_b32_e32 v72, 48, v146
	v_ashrrev_i32_e32 v73, 31, v72
	v_lshlrev_b64 v[72:73], 12, v[72:73]
	v_lshl_add_u64 v[72:73], s[20:21], 0, v[72:73]
	v_cvt_pk_bf16_f32 v83, v74, v75
	global_store_dwordx4 v[96:97], v[80:83], off offset:256 sc1
	s_nop 1
	v_lshl_add_u64 v[80:81], v[72:73], 0, v[150:151]
	v_cvt_pk_bf16_f32 v72, v84, v85
	v_cvt_pk_bf16_f32 v73, v86, v87
	v_cvt_pk_bf16_f32 v74, v76, v77
	v_cvt_pk_bf16_f32 v75, v78, v79
	global_store_dwordx4 v[80:81], v[72:75], off sc1
	v_cvt_pk_bf16_f32 v68, v68, v69
	v_cvt_pk_bf16_f32 v69, v70, v71
	v_cvt_pk_bf16_f32 v70, v64, v65
	v_lshl_add_u64 v[64:65], v[138:139], 0, s[4:5]
	s_mov_b32 s4, 0x80000
	v_cvt_pk_bf16_f32 v71, v66, v67
	global_store_dwordx4 v[80:81], v[68:71], off offset:256 sc1
	v_cvt_pk_bf16_f32 v60, v60, v61
	v_cvt_pk_bf16_f32 v61, v62, v63
	v_cvt_pk_bf16_f32 v62, v56, v57
	v_add_co_u32_e32 v56, vcc, s4, v138
	v_cvt_pk_bf16_f32 v63, v58, v59
	s_mov_b64 s[4:5], 0x90000
	s_nop 0
	v_addc_co_u32_e32 v57, vcc, 0, v139, vcc
	global_store_dwordx4 v[56:57], v[60:63], off sc1
	v_cvt_pk_bf16_f32 v48, v48, v49
	v_cvt_pk_bf16_f32 v49, v50, v51
	v_cvt_pk_bf16_f32 v50, v40, v41
	v_cvt_pk_bf16_f32 v51, v42, v43
	global_store_dwordx4 v[64:65], v[48:51], off offset:256 sc1
	v_cvt_pk_bf16_f32 v40, v52, v53
	v_cvt_pk_bf16_f32 v41, v54, v55
	v_cvt_pk_bf16_f32 v42, v44, v45
	v_cvt_pk_bf16_f32 v43, v46, v47
	s_nop 1
	v_lshl_add_u64 v[48:49], v[138:139], 0, s[4:5]
	s_mov_b32 s4, 0x90000
	v_add_co_u32_e32 v44, vcc, s4, v138
	s_mov_b64 s[4:5], 0xa0000
	s_nop 0
	v_addc_co_u32_e32 v45, vcc, 0, v139, vcc
	global_store_dwordx4 v[44:45], v[40:43], off sc1
	v_cvt_pk_bf16_f32 v32, v32, v33
	v_cvt_pk_bf16_f32 v33, v34, v35
	v_cvt_pk_bf16_f32 v34, v24, v25
	v_cvt_pk_bf16_f32 v35, v26, v27
	global_store_dwordx4 v[48:49], v[32:35], off offset:256 sc1
	v_cvt_pk_bf16_f32 v24, v36, v37
	v_cvt_pk_bf16_f32 v25, v38, v39
	v_cvt_pk_bf16_f32 v26, v28, v29
	v_cvt_pk_bf16_f32 v27, v30, v31
	s_nop 1
	v_lshl_add_u64 v[32:33], v[138:139], 0, s[4:5]
	s_mov_b32 s4, 0xa0000
	v_add_co_u32_e32 v28, vcc, s4, v138
	s_mov_b64 s[4:5], 0xb0000
	s_nop 0
	v_addc_co_u32_e32 v29, vcc, 0, v139, vcc
	global_store_dwordx4 v[28:29], v[24:27], off sc1
	v_cvt_pk_bf16_f32 v16, v16, v17
	v_cvt_pk_bf16_f32 v17, v18, v19
	v_cvt_pk_bf16_f32 v18, v8, v9
	v_cvt_pk_bf16_f32 v19, v10, v11
	global_store_dwordx4 v[32:33], v[16:19], off offset:256 sc1
	v_cvt_pk_bf16_f32 v8, v20, v21
	v_cvt_pk_bf16_f32 v9, v22, v23
	v_cvt_pk_bf16_f32 v10, v12, v13
	v_cvt_pk_bf16_f32 v11, v14, v15
	s_nop 1
	v_lshl_add_u64 v[16:17], v[138:139], 0, s[4:5]
	s_mov_b32 s4, 0xb0000
	v_add_co_u32_e32 v12, vcc, s4, v138
	s_nop 1
	v_addc_co_u32_e32 v13, vcc, 0, v139, vcc
	s_and_b64 vcc, exec, s[12:13]
	s_mov_b64 s[12:13], -1
	global_store_dwordx4 v[12:13], v[8:11], off sc1
	v_cvt_pk_bf16_f32 v4, v4, v5
	v_cvt_pk_bf16_f32 v5, v6, v7
	v_cvt_pk_bf16_f32 v6, v0, v1
	v_cvt_pk_bf16_f32 v7, v2, v3
	global_store_dwordx4 v[16:17], v[4:7], off offset:256 sc1
	s_cbranch_vccnz .LBB0_1137
	s_andn2_b64 vcc, exec, s[18:19]
	s_cbranch_vccnz .LBB0_1136
	s_barrier
	s_branch .LBB0_1136

.LBB0_1173:
	v_lshl_or_b32 v138, s21, 8, v142
	s_ashr_i32 s21, s20, 31
	s_lshl_b64 s[20:21], s[20:21], 22
	s_add_u32 s20, s40, s20
	v_lshl_add_u32 v146, s49, 8, v141
	s_addc_u32 s21, s41, s21
	v_ashrrev_i32_e32 v139, 31, v138
	v_ashrrev_i32_e32 v147, 31, v146
	v_lshl_add_u64 v[148:149], v[138:139], 1, s[20:21]
	v_lshlrev_b64 v[138:139], 12, v[146:147]
	v_lshl_add_u64 v[138:139], v[148:149], 0, v[138:139]
	v_cvt_pk_bf16_f32 v124, v124, v125
	v_cvt_pk_bf16_f32 v125, v126, v127
	v_cvt_pk_bf16_f32 v126, v120, v121
	v_cvt_pk_bf16_f32 v127, v122, v123
	global_store_dwordx4 v[138:139], v[124:127], off sc1
	v_cvt_pk_bf16_f32 v112, v112, v113
	v_cvt_pk_bf16_f32 v113, v114, v115
	v_cvt_pk_bf16_f32 v114, v104, v105
	v_or_b32_e32 v104, 16, v146
	v_ashrrev_i32_e32 v105, 31, v104
	v_lshlrev_b64 v[104:105], 12, v[104:105]
	v_cvt_pk_bf16_f32 v115, v106, v107
	global_store_dwordx4 v[138:139], v[112:115], off offset:256 sc1
	s_mov_b64 s[4:5], 0x80000
	s_mov_b32 s56, 0x413504f3
	v_lshl_add_u64 v[112:113], v[148:149], 0, v[104:105]
	v_cvt_pk_bf16_f32 v104, v116, v117
	v_cvt_pk_bf16_f32 v105, v118, v119
	v_cvt_pk_bf16_f32 v106, v108, v109
	v_cvt_pk_bf16_f32 v107, v110, v111
	global_store_dwordx4 v[112:113], v[104:107], off sc1
	v_cvt_pk_bf16_f32 v96, v96, v97
	v_cvt_pk_bf16_f32 v97, v98, v99
	v_cvt_pk_bf16_f32 v98, v88, v89
	v_or_b32_e32 v88, 32, v146
	v_ashrrev_i32_e32 v89, 31, v88
	v_lshlrev_b64 v[88:89], 12, v[88:89]
	v_cvt_pk_bf16_f32 v99, v90, v91
	global_store_dwordx4 v[112:113], v[96:99], off offset:256 sc1
	s_nop 1
	v_lshl_add_u64 v[96:97], v[148:149], 0, v[88:89]
	v_cvt_pk_bf16_f32 v88, v100, v101
	v_cvt_pk_bf16_f32 v89, v102, v103
	v_cvt_pk_bf16_f32 v90, v92, v93
	v_cvt_pk_bf16_f32 v91, v94, v95
	global_store_dwordx4 v[96:97], v[88:91], off sc1
	v_cvt_pk_bf16_f32 v80, v80, v81
	v_cvt_pk_bf16_f32 v81, v82, v83
	v_cvt_pk_bf16_f32 v82, v72, v73
	v_or_b32_e32 v72, 48, v146
	v_ashrrev_i32_e32 v73, 31, v72
	v_lshlrev_b64 v[72:73], 12, v[72:73]
	v_cvt_pk_bf16_f32 v83, v74, v75
	global_store_dwordx4 v[96:97], v[80:83], off offset:256 sc1
	s_nop 1
	v_lshl_add_u64 v[80:81], v[148:149], 0, v[72:73]
	v_cvt_pk_bf16_f32 v72, v84, v85
	v_cvt_pk_bf16_f32 v73, v86, v87
	v_cvt_pk_bf16_f32 v74, v76, v77
	v_cvt_pk_bf16_f32 v75, v78, v79
	global_store_dwordx4 v[80:81], v[72:75], off sc1
	v_cvt_pk_bf16_f32 v68, v68, v69
	v_cvt_pk_bf16_f32 v69, v70, v71
	v_cvt_pk_bf16_f32 v70, v64, v65
	v_lshl_add_u64 v[64:65], v[138:139], 0, s[4:5]
	s_mov_b32 s4, 0x80000
	v_cvt_pk_bf16_f32 v71, v66, v67
	global_store_dwordx4 v[80:81], v[68:71], off offset:256 sc1
	v_cvt_pk_bf16_f32 v60, v60, v61
	v_cvt_pk_bf16_f32 v61, v62, v63
	v_cvt_pk_bf16_f32 v62, v56, v57
	v_add_co_u32_e32 v56, vcc, s4, v138
	v_cvt_pk_bf16_f32 v63, v58, v59
	s_mov_b64 s[4:5], 0x90000
	s_nop 0
	v_addc_co_u32_e32 v57, vcc, 0, v139, vcc
	global_store_dwordx4 v[56:57], v[60:63], off sc1
	v_cvt_pk_bf16_f32 v48, v48, v49
	v_cvt_pk_bf16_f32 v49, v50, v51
	v_cvt_pk_bf16_f32 v50, v40, v41
	v_cvt_pk_bf16_f32 v51, v42, v43
	global_store_dwordx4 v[64:65], v[48:51], off offset:256 sc1
	v_cvt_pk_bf16_f32 v40, v52, v53
	v_cvt_pk_bf16_f32 v41, v54, v55
	v_cvt_pk_bf16_f32 v42, v44, v45
	v_cvt_pk_bf16_f32 v43, v46, v47
	s_nop 1
	v_lshl_add_u64 v[48:49], v[138:139], 0, s[4:5]
	s_mov_b32 s4, 0x90000
	v_add_co_u32_e32 v44, vcc, s4, v138
	s_mov_b64 s[4:5], 0xa0000
	s_nop 0
	v_addc_co_u32_e32 v45, vcc, 0, v139, vcc
	global_store_dwordx4 v[44:45], v[40:43], off sc1
	v_cvt_pk_bf16_f32 v32, v32, v33
	v_cvt_pk_bf16_f32 v33, v34, v35
	v_cvt_pk_bf16_f32 v34, v24, v25
	v_cvt_pk_bf16_f32 v35, v26, v27
	global_store_dwordx4 v[48:49], v[32:35], off offset:256 sc1
	v_cvt_pk_bf16_f32 v24, v36, v37
	v_cvt_pk_bf16_f32 v25, v38, v39
	v_cvt_pk_bf16_f32 v26, v28, v29
	v_cvt_pk_bf16_f32 v27, v30, v31
	s_nop 1
	v_lshl_add_u64 v[32:33], v[138:139], 0, s[4:5]
	s_mov_b32 s4, 0xa0000
	v_add_co_u32_e32 v28, vcc, s4, v138
	s_mov_b64 s[4:5], 0xb0000
	s_nop 0
	v_addc_co_u32_e32 v29, vcc, 0, v139, vcc
	global_store_dwordx4 v[28:29], v[24:27], off sc1
	v_cvt_pk_bf16_f32 v16, v16, v17
	v_cvt_pk_bf16_f32 v17, v18, v19
	v_cvt_pk_bf16_f32 v18, v8, v9
	v_cvt_pk_bf16_f32 v19, v10, v11
	global_store_dwordx4 v[32:33], v[16:19], off offset:256 sc1
	v_cvt_pk_bf16_f32 v8, v20, v21
	v_cvt_pk_bf16_f32 v9, v22, v23
	v_cvt_pk_bf16_f32 v10, v12, v13
	v_cvt_pk_bf16_f32 v11, v14, v15
	s_nop 1
	v_lshl_add_u64 v[16:17], v[138:139], 0, s[4:5]
	s_mov_b32 s4, 0xb0000
	v_add_co_u32_e32 v12, vcc, s4, v138
	s_nop 1
	v_addc_co_u32_e32 v13, vcc, 0, v139, vcc
	s_and_b64 vcc, exec, s[10:11]
	s_mov_b64 s[10:11], -1
	global_store_dwordx4 v[12:13], v[8:11], off sc1
	v_cvt_pk_bf16_f32 v4, v4, v5
	v_cvt_pk_bf16_f32 v5, v6, v7
	v_cvt_pk_bf16_f32 v6, v0, v1
	v_cvt_pk_bf16_f32 v7, v2, v3
	global_store_dwordx4 v[16:17], v[4:7], off offset:256 sc1
	s_cbranch_vccnz .LBB0_1162
	s_andn2_b64 vcc, exec, s[14:15]
	s_cbranch_vccnz .LBB0_1161
	s_barrier
	s_branch .LBB0_1161

.LBB0_1228:
	s_waitcnt vmcnt(15)
	v_cvt_f32_f16_sdwa v177, v170 dst_sel:DWORD dst_unused:UNUSED_PAD src0_sel:WORD_1
	v_cvt_f32_f16_e32 v176, v170
	s_waitcnt vmcnt(14)
	v_lshlrev_b32_e32 v174, 16, v172
	v_and_b32_e32 v175, 0xffff0000, v172
	v_lshlrev_b32_e32 v172, 16, v173
	v_and_b32_e32 v173, 0xffff0000, v173
	v_cvt_f32_f16_sdwa v179, v171 dst_sel:DWORD dst_unused:UNUSED_PAD src0_sel:WORD_1
	v_cvt_f32_f16_e32 v178, v171
	s_waitcnt lgkmcnt(7)
	v_pk_mul_f32 v[170:171], v[124:125], v[174:175]
	v_pk_mul_f32 v[124:125], v[126:127], v[172:173]
	s_waitcnt vmcnt(10)
	v_cvt_f32_f16_sdwa v173, v168 dst_sel:DWORD dst_unused:UNUSED_PAD src0_sel:WORD_1
	v_cvt_f32_f16_sdwa v175, v169 dst_sel:DWORD dst_unused:UNUSED_PAD src0_sel:WORD_1
	v_cvt_f32_f16_e32 v174, v169
	v_cvt_f32_f16_e32 v172, v168
	s_mov_b32 s4, 0x3fb504f3
	v_pk_fma_f32 v[126:127], v[176:177], s[4:5], v[170:171] op_sel_hi:[1,0,1]
	v_lshlrev_b32_e32 v170, 16, v166
	v_and_b32_e32 v171, 0xffff0000, v166
	v_lshlrev_b32_e32 v166, 16, v167
	v_and_b32_e32 v167, 0xffff0000, v167
	s_waitcnt lgkmcnt(6)
	v_pk_mul_f32 v[120:121], v[120:121], v[170:171]
	v_pk_mul_f32 v[122:123], v[122:123], v[166:167]
	v_pk_fma_f32 v[168:169], v[172:173], s[4:5], v[120:121] op_sel_hi:[1,0,1]
	v_pk_fma_f32 v[166:167], v[174:175], s[4:5], v[122:123] op_sel_hi:[1,0,1]
	v_lshlrev_b32_e32 v120, 16, v162
	v_and_b32_e32 v121, 0xffff0000, v162
	v_lshlrev_b32_e32 v122, 16, v163
	v_and_b32_e32 v123, 0xffff0000, v163
	s_waitcnt vmcnt(9)
	v_cvt_f32_f16_sdwa v163, v164 dst_sel:DWORD dst_unused:UNUSED_PAD src0_sel:WORD_1
	v_cvt_f32_f16_sdwa v171, v165 dst_sel:DWORD dst_unused:UNUSED_PAD src0_sel:WORD_1
	v_cvt_f32_f16_e32 v170, v165
	v_cvt_f32_f16_e32 v162, v164
	s_waitcnt lgkmcnt(5)
	v_pk_mul_f32 v[116:117], v[116:117], v[120:121]
	v_pk_mul_f32 v[118:119], v[118:119], v[122:123]
	v_pk_fma_f32 v[124:125], v[178:179], s[4:5], v[124:125] op_sel_hi:[1,0,1]
	v_pk_fma_f32 v[120:121], v[170:171], s[4:5], v[118:119] op_sel_hi:[1,0,1]
	v_pk_fma_f32 v[122:123], v[162:163], s[4:5], v[116:117] op_sel_hi:[1,0,1]
	v_lshlrev_b32_e32 v116, 16, v160
	v_and_b32_e32 v117, 0xffff0000, v160
	v_lshlrev_b32_e32 v118, 16, v161
	v_and_b32_e32 v119, 0xffff0000, v161
	s_waitcnt vmcnt(8)
	v_cvt_f32_f16_sdwa v161, v158 dst_sel:DWORD dst_unused:UNUSED_PAD src0_sel:WORD_1
	v_cvt_f32_f16_e32 v160, v158
	v_cvt_f32_f16_sdwa v163, v159 dst_sel:DWORD dst_unused:UNUSED_PAD src0_sel:WORD_1
	v_cvt_f32_f16_e32 v162, v159
	s_waitcnt lgkmcnt(4)
	v_pk_mul_f32 v[112:113], v[112:113], v[116:117]
	s_waitcnt vmcnt(7)
	v_cvt_f32_f16_sdwa v117, v154 dst_sel:DWORD dst_unused:UNUSED_PAD src0_sel:WORD_1
	v_cvt_f32_f16_e32 v116, v154
	v_pk_mul_f32 v[114:115], v[114:115], v[118:119]
	v_cvt_f32_f16_sdwa v119, v155 dst_sel:DWORD dst_unused:UNUSED_PAD src0_sel:WORD_1
	v_cvt_f32_f16_e32 v118, v155
	v_pk_fma_f32 v[160:161], v[160:161], s[4:5], v[112:113] op_sel_hi:[1,0,1]
	s_waitcnt vmcnt(6)
	v_lshlrev_b32_e32 v112, 16, v156
	v_and_b32_e32 v113, 0xffff0000, v156
	v_pk_fma_f32 v[158:159], v[162:163], s[4:5], v[114:115] op_sel_hi:[1,0,1]
	v_lshlrev_b32_e32 v114, 16, v157
	v_and_b32_e32 v115, 0xffff0000, v157
	s_waitcnt lgkmcnt(3)
	v_pk_mul_f32 v[108:109], v[108:109], v[112:113]
	v_pk_mul_f32 v[110:111], v[110:111], v[114:115]
	v_pk_fma_f32 v[114:115], v[116:117], s[4:5], v[108:109] op_sel_hi:[1,0,1]
	s_waitcnt vmcnt(2)
	v_cvt_f32_f16_sdwa v117, v152 dst_sel:DWORD dst_unused:UNUSED_PAD src0_sel:WORD_1
	v_cvt_f32_f16_e32 v116, v152
	v_pk_fma_f32 v[112:113], v[118:119], s[4:5], v[110:111] op_sel_hi:[1,0,1]
	v_lshlrev_b32_e32 v108, 16, v150
	v_and_b32_e32 v109, 0xffff0000, v150
	v_cvt_f32_f16_sdwa v119, v153 dst_sel:DWORD dst_unused:UNUSED_PAD src0_sel:WORD_1
	v_cvt_f32_f16_e32 v118, v153
	s_waitcnt lgkmcnt(2)
	v_pk_mul_f32 v[104:105], v[104:105], v[108:109]
	s_waitcnt vmcnt(1)
	v_cvt_f32_f16_sdwa v109, v148 dst_sel:DWORD dst_unused:UNUSED_PAD src0_sel:WORD_1
	v_cvt_f32_f16_e32 v108, v148
	v_lshlrev_b32_e32 v110, 16, v151
	v_and_b32_e32 v111, 0xffff0000, v151
	v_pk_mul_f32 v[106:107], v[106:107], v[110:111]
	v_pk_fma_f32 v[152:153], v[116:117], s[4:5], v[104:105] op_sel_hi:[1,0,1]
	v_lshlrev_b32_e32 v104, 16, v146
	v_and_b32_e32 v105, 0xffff0000, v146
	v_pk_fma_f32 v[150:151], v[118:119], s[4:5], v[106:107] op_sel_hi:[1,0,1]
	v_lshlrev_b32_e32 v106, 16, v147
	v_and_b32_e32 v107, 0xffff0000, v147
	v_cvt_f32_f16_sdwa v111, v149 dst_sel:DWORD dst_unused:UNUSED_PAD src0_sel:WORD_1
	v_cvt_f32_f16_e32 v110, v149
	s_waitcnt lgkmcnt(1)
	v_pk_mul_f32 v[100:101], v[100:101], v[104:105]
	v_pk_mul_f32 v[102:103], v[102:103], v[106:107]
	v_pk_fma_f32 v[106:107], v[108:109], s[4:5], v[100:101] op_sel_hi:[1,0,1]
	s_waitcnt vmcnt(0)
	v_cvt_f32_f16_sdwa v109, v140 dst_sel:DWORD dst_unused:UNUSED_PAD src0_sel:WORD_1
	v_cvt_f32_f16_e32 v108, v140
	v_lshlrev_b32_e32 v100, 16, v142
	v_and_b32_e32 v101, 0xffff0000, v142
	v_pk_fma_f32 v[104:105], v[110:111], s[4:5], v[102:103] op_sel_hi:[1,0,1]
	v_lshlrev_b32_e32 v102, 16, v143
	v_and_b32_e32 v103, 0xffff0000, v143
	s_waitcnt lgkmcnt(0)
	v_pk_mul_f32 v[100:101], v[96:97], v[100:101]
	v_pk_mul_f32 v[96:97], v[98:99], v[102:103]
	v_pk_fma_f32 v[98:99], v[108:109], s[4:5], v[100:101] op_sel_hi:[1,0,1]
	v_mov_b32_e32 v100, v126
	v_mov_b32_e32 v101, v168
	v_mov_b32_e32 v102, v127
	v_mov_b32_e32 v103, v169
	v_pk_add_f32 v[100:101], v[100:101], v[102:103]
	v_mov_b32_e32 v102, v124
	v_mov_b32_e32 v103, v166
	v_mov_b32_e32 v108, v125
	v_mov_b32_e32 v109, v167
	v_cvt_f32_f16_sdwa v111, v141 dst_sel:DWORD dst_unused:UNUSED_PAD src0_sel:WORD_1
	v_cvt_f32_f16_e32 v110, v141
	v_pk_add_f32 v[102:103], v[102:103], v[108:109]
	v_mov_b32_e32 v108, v122
	v_pk_add_f32 v[100:101], v[100:101], v[102:103]
	v_pk_mov_b32 v[102:103], v[122:123], v[120:121] op_sel:[1,0]
	v_mov_b32_e32 v109, v121
	v_pk_add_f32 v[102:103], v[102:103], v[108:109]
	v_add_f32_e32 v100, 0, v100
	v_pk_add_f32 v[102:103], v[102:103], v[102:103] op_sel:[0,1] op_sel_hi:[1,0]
	v_pk_fma_f32 v[96:97], v[110:111], s[4:5], v[96:97] op_sel_hi:[1,0,1]
	v_add_f32_e32 v100, v100, v101
	v_add_f32_e32 v108, v160, v161
	v_add_f32_e32 v110, v158, v159
	v_mov_b32_e32 v101, v114
	v_mov_b32_e32 v103, v115
	v_mov_b32_e32 v109, v112
	v_mov_b32_e32 v111, v113
	v_pk_add_f32 v[100:101], v[100:101], v[102:103]
	v_pk_add_f32 v[102:103], v[108:109], v[110:111]
	v_mov_b32_e32 v108, v152
	v_pk_add_f32 v[100:101], v[100:101], v[102:103]
	v_pk_mov_b32 v[102:103], v[152:153], v[150:151] op_sel:[1,0]
	v_mov_b32_e32 v109, v151
	v_pk_add_f32 v[102:103], v[102:103], v[108:109]
	v_pk_add_f32 v[100:101], v[100:101], v[100:101] op_sel:[0,1] op_sel_hi:[1,0]
	v_pk_add_f32 v[102:103], v[102:103], v[102:103] op_sel:[0,1] op_sel_hi:[1,0]
	v_add_f32_e32 v108, v106, v107
	v_add_f32_e32 v110, v104, v105
	v_mov_b32_e32 v101, v98
	v_mov_b32_e32 v103, v99
	v_mov_b32_e32 v109, v96
	v_mov_b32_e32 v111, v97
	v_pk_add_f32 v[100:101], v[100:101], v[102:103]
	v_pk_add_f32 v[102:103], v[108:109], v[110:111]
	s_mov_b32 s4, 0xf800000
	v_pk_add_f32 v[100:101], v[100:101], v[102:103]
	s_nop 0
	v_add_f32_e32 v100, v100, v101
	ds_bpermute_b32 v101, v129, v100
	s_waitcnt lgkmcnt(0)
	v_add_f32_e32 v100, v100, v101
	ds_bpermute_b32 v101, v182, v100
	s_waitcnt lgkmcnt(0)
	v_add_f32_e32 v100, v100, v101
	ds_bpermute_b32 v101, v183, v100
	s_waitcnt lgkmcnt(0)
	v_add_f32_e32 v100, v100, v101
	ds_bpermute_b32 v101, v184, v100
	s_waitcnt lgkmcnt(0)
	v_add_f32_e32 v100, v100, v101
	ds_bpermute_b32 v101, v185, v100
	s_waitcnt lgkmcnt(0)
	v_add_f32_e32 v100, v100, v101
	ds_bpermute_b32 v101, v186, v100
	s_waitcnt lgkmcnt(0)
	v_add_f32_e32 v140, v100, v101
	v_fmamk_f32 v127, v140, 0xba000000, v127
	v_fmamk_f32 v125, v140, 0xba000000, v125
	v_fmac_f32_e32 v126, 0xba000000, v140
	v_fmamk_f32 v103, v140, 0xba000000, v169
	v_fmac_f32_e32 v168, 0xba000000, v140
	v_mov_b32_e32 v102, v127
	v_fmac_f32_e32 v124, 0xba000000, v140
	v_fmamk_f32 v101, v140, 0xba000000, v167
	v_fmac_f32_e32 v166, 0xba000000, v140
	v_mov_b32_e32 v108, v126
	v_mov_b32_e32 v109, v168
	v_pk_mul_f32 v[110:111], v[102:103], v[102:103]
	v_mov_b32_e32 v100, v125
	v_pk_fma_f32 v[108:109], v[108:109], v[108:109], v[110:111]
	v_mov_b32_e32 v110, v124
	v_mov_b32_e32 v111, v166
	v_pk_mul_f32 v[116:117], v[100:101], v[100:101]
	v_fmamk_f32 v121, v140, 0xba000000, v121
	v_pk_fma_f32 v[110:111], v[110:111], v[110:111], v[116:117]
	v_fmac_f32_e32 v120, 0xba000000, v140
	v_fmamk_f32 v123, v140, 0xba000000, v123
	v_fmac_f32_e32 v122, 0xba000000, v140
	v_pk_add_f32 v[108:109], v[108:109], v[110:111]
	v_pk_mul_f32 v[110:111], v[120:121], v[120:121]
	v_pk_mul_f32 v[116:117], v[122:123], v[122:123]
	v_fmac_f32_e32 v160, 0xba000000, v140
	v_pk_mov_b32 v[118:119], v[116:117], v[110:111] op_sel:[1,0]
	v_mov_b32_e32 v117, v111
	v_fmac_f32_e32 v158, 0xba000000, v140
	v_fmamk_f32 v161, v140, 0xba000000, v161
	v_mul_f32_e32 v100, v160, v160
	v_pk_add_f32 v[110:111], v[118:119], v[116:117]
	v_fmamk_f32 v159, v140, 0xba000000, v159
	v_pk_fma_f32 v[116:117], v[160:161], v[160:161], v[100:101] op_sel_hi:[1,1,0]
	v_mul_f32_e32 v100, v158, v158
	v_pk_add_f32 v[108:109], v[108:109], v[108:109] op_sel_hi:[0,1]
	v_pk_add_f32 v[110:111], v[110:111], v[110:111] op_sel_hi:[0,1]
	v_pk_fma_f32 v[118:119], v[158:159], v[158:159], v[100:101] op_sel_hi:[1,1,0]
	v_fmamk_f32 v113, v140, 0xba000000, v113
	v_fmac_f32_e32 v112, 0xba000000, v140
	v_fmamk_f32 v115, v140, 0xba000000, v115
	v_fmac_f32_e32 v114, 0xba000000, v140
	v_mul_f32_e32 v116, v114, v114
	v_mul_f32_e32 v118, v115, v115
	v_mul_f32_e32 v110, v112, v112
	v_mul_f32_e32 v108, v113, v113
	v_pk_add_f32 v[116:117], v[116:117], v[118:119]
	v_pk_add_f32 v[108:109], v[110:111], v[108:109]
	v_fmamk_f32 v151, v140, 0xba000000, v151
	v_fmac_f32_e32 v150, 0xba000000, v140
	v_fmamk_f32 v153, v140, 0xba000000, v153
	v_fmac_f32_e32 v152, 0xba000000, v140
	v_pk_add_f32 v[108:109], v[116:117], v[108:109]
	v_pk_mul_f32 v[110:111], v[150:151], v[150:151]
	v_pk_mul_f32 v[116:117], v[152:153], v[152:153]
	v_fmac_f32_e32 v106, 0xba000000, v140
	v_pk_mov_b32 v[118:119], v[116:117], v[110:111] op_sel:[1,0]
	v_mov_b32_e32 v117, v111
	v_fmac_f32_e32 v104, 0xba000000, v140
	v_fmamk_f32 v107, v140, 0xba000000, v107
	v_mul_f32_e32 v100, v106, v106
	v_pk_add_f32 v[110:111], v[118:119], v[116:117]
	v_fmamk_f32 v105, v140, 0xba000000, v105
	v_pk_fma_f32 v[116:117], v[106:107], v[106:107], v[100:101] op_sel_hi:[1,1,0]
	v_mul_f32_e32 v100, v104, v104
	v_pk_add_f32 v[108:109], v[108:109], v[108:109] op_sel_hi:[0,1]
	v_pk_add_f32 v[110:111], v[110:111], v[110:111] op_sel_hi:[0,1]
	v_pk_fma_f32 v[118:119], v[104:105], v[104:105], v[100:101] op_sel_hi:[1,1,0]
	v_fmamk_f32 v97, v140, 0xba000000, v97
	v_fmac_f32_e32 v96, 0xba000000, v140
	v_fmamk_f32 v99, v140, 0xba000000, v99
	v_fmac_f32_e32 v98, 0xba000000, v140
	v_mul_f32_e32 v116, v98, v98
	v_mul_f32_e32 v118, v99, v99
	v_mul_f32_e32 v110, v96, v96
	v_mul_f32_e32 v108, v97, v97
	v_pk_add_f32 v[116:117], v[116:117], v[118:119]
	v_pk_add_f32 v[108:109], v[110:111], v[108:109]
	s_nop 0
	v_pk_add_f32 v[108:109], v[116:117], v[108:109]
	s_nop 0
	v_add_f32_e32 v100, v108, v109
	ds_bpermute_b32 v102, v129, v100
	s_waitcnt lgkmcnt(0)
	v_add_f32_e32 v100, v100, v102
	ds_bpermute_b32 v102, v182, v100
	s_waitcnt lgkmcnt(0)
	v_add_f32_e32 v100, v100, v102
	ds_bpermute_b32 v102, v183, v100
	s_waitcnt lgkmcnt(0)
	v_add_f32_e32 v100, v100, v102
	ds_bpermute_b32 v102, v184, v100
	s_waitcnt lgkmcnt(0)
	v_add_f32_e32 v100, v100, v102
	ds_bpermute_b32 v102, v185, v100
	s_waitcnt lgkmcnt(0)
	v_add_f32_e32 v100, v100, v102
	ds_bpermute_b32 v102, v186, v100
	s_waitcnt lgkmcnt(0)
	v_add_f32_e32 v100, v100, v102
	v_fmamk_f32 v100, v100, 0x3a000000, v229
	v_mul_f32_e32 v102, 0x4f800000, v100
	v_cmp_gt_f32_e32 vcc, s4, v100
	s_nop 1
	v_cndmask_b32_e32 v100, v100, v102, vcc
	v_sqrt_f32_e32 v102, v100
	s_nop 0
	v_add_u32_e32 v108, -1, v102
	v_fma_f32 v109, -v108, v102, v100
	v_cmp_ge_f32_e64 s[8:9], 0, v109
	v_add_u32_e32 v109, 1, v102
	s_nop 0
	v_cndmask_b32_e64 v108, v102, v108, s[8:9]
	v_fma_f32 v102, -v109, v102, v100
	v_cmp_lt_f32_e64 s[8:9], 0, v102
	s_nop 1
	v_cndmask_b32_e64 v102, v108, v109, s[8:9]
	v_mul_f32_e32 v108, 0x37800000, v102
	v_cndmask_b32_e32 v102, v102, v108, vcc
	v_cmp_class_f32_e32 vcc, v100, v230
	s_nop 1
	v_cndmask_b32_e32 v100, v102, v100, vcc
	v_div_scale_f32 v102, s[8:9], v100, v100, 1.0
	v_rcp_f32_e32 v108, v102
	s_mov_b64 s[8:9], -1
	v_fma_f32 v109, -v102, v108, 1.0
	v_fmac_f32_e32 v108, v109, v108
	v_div_scale_f32 v109, vcc, 1.0, v100, 1.0
	v_mul_f32_e32 v110, v109, v108
	v_fma_f32 v111, -v102, v110, v109
	v_fmac_f32_e32 v110, v111, v108
	v_fma_f32 v102, -v102, v110, v109
	v_div_fmas_f32 v102, v102, v108, v110
	v_div_fixup_f32 v140, v102, v100, 1.0
	v_pk_mul_f32 v[108:109], v[126:127], v[140:141] op_sel_hi:[1,0]
	v_pk_mul_f32 v[110:111], v[124:125], v[140:141] op_sel_hi:[1,0]
	v_pk_fma_f32 v[124:125], v[0:1], v[108:109], v[8:9]
	v_pk_fma_f32 v[126:127], v[2:3], v[110:111], v[10:11]
	s_and_b64 vcc, exec, s[0:1]
	s_cbranch_vccz .LBB0_1230
	s_mov_b64 s[8:9], 0
	global_store_dwordx4 v[138:139], v[124:127], off offset:-4096 sc1

.LBB0_1232:
	v_mov_b32_e32 v169, v103
	v_mov_b32_e32 v141, v140
	v_mov_b32_e32 v102, v140
	v_mov_b32_e32 v103, v140
	v_mov_b32_e32 v167, v101
	v_pk_mul_f32 v[100:101], v[166:167], v[102:103]
	v_pk_mul_f32 v[102:103], v[168:169], v[140:141]
	v_pk_fma_f32 v[118:119], v[6:7], v[100:101], v[14:15]
	v_pk_fma_f32 v[116:117], v[4:5], v[102:103], v[12:13]
	s_mov_b64 s[8:9], -1
	s_and_b64 vcc, exec, s[0:1]
	s_cbranch_vccz .LBB0_1234
	global_store_dwordx4 v[138:139], v[116:119], off offset:-3072 sc1
	s_mov_b64 s[8:9], 0

.LBB0_1236:
	v_mov_b32_e32 v100, v140
	v_mov_b32_e32 v101, v140
	v_pk_mul_f32 v[100:101], v[120:121], v[100:101]
	v_pk_mul_f32 v[102:103], v[122:123], v[140:141]
	v_pk_fma_f32 v[122:123], v[18:19], v[100:101], v[26:27]
	v_pk_fma_f32 v[120:121], v[16:17], v[102:103], v[24:25]
	s_mov_b64 s[8:9], -1
	s_and_b64 vcc, exec, s[0:1]
	s_cbranch_vccz .LBB0_1238
	global_store_dwordx4 v[138:139], v[120:123], off offset:-2048 sc1
	s_mov_b64 s[8:9], 0

.LBB0_1240:
	v_mov_b32_e32 v100, v140
	v_mov_b32_e32 v101, v140
	v_pk_mul_f32 v[100:101], v[158:159], v[100:101]
	v_pk_mul_f32 v[102:103], v[160:161], v[140:141]
	v_pk_fma_f32 v[110:111], v[22:23], v[100:101], v[30:31]
	v_pk_fma_f32 v[108:109], v[20:21], v[102:103], v[28:29]
	s_mov_b64 s[8:9], -1
	s_and_b64 vcc, exec, s[0:1]
	s_cbranch_vccz .LBB0_1242
	global_store_dwordx4 v[138:139], v[108:111], off offset:-1024 sc1
	s_mov_b64 s[8:9], 0

.LBB0_1244:
	v_mov_b32_e32 v100, v140
	v_mov_b32_e32 v101, v140
	v_pk_mul_f32 v[100:101], v[112:113], v[100:101]
	v_pk_mul_f32 v[102:103], v[114:115], v[140:141]
	v_pk_fma_f32 v[114:115], v[34:35], v[100:101], v[42:43]
	v_pk_fma_f32 v[112:113], v[32:33], v[102:103], v[40:41]
	s_mov_b64 s[8:9], -1
	s_and_b64 vcc, exec, s[0:1]
	s_cbranch_vccz .LBB0_1246
	global_store_dwordx4 v[138:139], v[112:115], off sc1
	s_mov_b64 s[8:9], 0

.LBB0_1248:
	v_mov_b32_e32 v100, v140
	v_mov_b32_e32 v101, v140
	v_pk_mul_f32 v[100:101], v[150:151], v[100:101]
	v_pk_mul_f32 v[142:143], v[152:153], v[140:141]
	v_pk_fma_f32 v[102:103], v[38:39], v[100:101], v[46:47]
	v_pk_fma_f32 v[100:101], v[36:37], v[142:143], v[44:45]
	s_mov_b64 s[8:9], -1
	s_and_b64 vcc, exec, s[0:1]
	s_cbranch_vccz .LBB0_1250
	global_store_dwordx4 v[138:139], v[100:103], off offset:1024 sc1
	s_mov_b64 s[8:9], 0

.LBB0_1252:
	v_mov_b32_e32 v142, v140
	v_mov_b32_e32 v143, v140
	v_pk_mul_f32 v[104:105], v[104:105], v[142:143]
	v_pk_mul_f32 v[142:143], v[106:107], v[140:141]
	v_pk_fma_f32 v[106:107], v[50:51], v[104:105], v[58:59]
	v_pk_fma_f32 v[104:105], v[48:49], v[142:143], v[56:57]
	s_mov_b64 s[8:9], -1
	s_and_b64 vcc, exec, s[0:1]
	s_cbranch_vccz .LBB0_1254
	global_store_dwordx4 v[138:139], v[104:107], off offset:2048 sc1
	s_mov_b64 s[8:9], 0

.LBB0_1256:
	v_mov_b32_e32 v142, v140
	v_mov_b32_e32 v143, v140
	v_pk_mul_f32 v[96:97], v[96:97], v[142:143]
	v_pk_mul_f32 v[140:141], v[98:99], v[140:141]
	v_pk_fma_f32 v[98:99], v[54:55], v[96:97], v[62:63]
	v_pk_fma_f32 v[96:97], v[52:53], v[140:141], v[60:61]
	s_mov_b64 s[8:9], -1
	s_and_b64 vcc, exec, s[0:1]
	s_cbranch_vccz .LBB0_1258
	global_store_dwordx4 v[138:139], v[96:99], off offset:3072 sc1
	s_mov_b64 s[8:9], 0

.LBB0_1262:
	s_andn2_b64 vcc, exec, s[18:19]
	s_cbranch_vccnz .LBB0_1225
	v_mov_b32_e32 v96, v64
	v_mov_b32_e32 v97, v68
	v_mov_b32_e32 v98, v65
	v_mov_b32_e32 v99, v69
	v_pk_add_f32 v[96:97], v[96:97], v[98:99]
	v_mov_b32_e32 v98, v66
	v_mov_b32_e32 v99, v70
	v_mov_b32_e32 v100, v67
	v_mov_b32_e32 v101, v71
	v_pk_add_f32 v[98:99], v[98:99], v[100:101]
	v_mov_b32_e32 v100, v72
	v_pk_add_f32 v[96:97], v[96:97], v[98:99]
	v_mov_b32_e32 v98, v73
	v_mov_b32_e32 v99, v74
	v_mov_b32_e32 v101, v75
	v_pk_add_f32 v[98:99], v[98:99], v[100:101]
	v_add_f32_e32 v97, 0, v97
	v_pk_add_f32 v[98:99], v[98:99], v[98:99] op_sel_hi:[0,1]
	v_add_f32_e32 v97, v96, v97
	v_add_f32_e32 v101, v76, v77
	v_add_f32_e32 v103, v78, v79
	v_mov_b32_e32 v100, v80
	v_mov_b32_e32 v102, v81
	v_mov_b32_e32 v98, v82
	v_mov_b32_e32 v96, v83
	v_pk_add_f32 v[100:101], v[100:101], v[102:103]
	v_pk_add_f32 v[96:97], v[98:99], v[96:97]
	v_mov_b32_e32 v98, v85
	v_pk_add_f32 v[96:97], v[100:101], v[96:97]
	v_mov_b32_e32 v99, v86
	v_mov_b32_e32 v100, v84
	v_mov_b32_e32 v101, v87
	v_pk_add_f32 v[98:99], v[98:99], v[100:101]
	v_pk_add_f32 v[96:97], v[96:97], v[96:97] op_sel_hi:[0,1]
	v_pk_add_f32 v[98:99], v[98:99], v[98:99] op_sel_hi:[0,1]
	v_add_f32_e32 v101, v88, v89
	v_add_f32_e32 v103, v90, v91
	v_mov_b32_e32 v100, v92
	v_mov_b32_e32 v102, v93
	v_mov_b32_e32 v98, v94
	v_mov_b32_e32 v96, v95
	v_pk_add_f32 v[100:101], v[100:101], v[102:103]
	v_pk_add_f32 v[96:97], v[98:99], v[96:97]
	s_mov_b32 s4, 0xf800000
	v_pk_add_f32 v[96:97], v[100:101], v[96:97]
	s_ashr_i32 s17, s16, 31
	v_add_f32_e32 v96, v96, v97
	ds_bpermute_b32 v97, v129, v96
	s_mov_b64 s[20:21], -1
	s_waitcnt lgkmcnt(0)
	v_add_f32_e32 v96, v96, v97
	ds_bpermute_b32 v97, v182, v96
	s_waitcnt lgkmcnt(0)
	v_add_f32_e32 v96, v96, v97
	ds_bpermute_b32 v97, v183, v96
	s_waitcnt lgkmcnt(0)
	v_add_f32_e32 v96, v96, v97
	ds_bpermute_b32 v97, v184, v96
	s_waitcnt lgkmcnt(0)
	v_add_f32_e32 v96, v96, v97
	ds_bpermute_b32 v97, v185, v96
	s_waitcnt lgkmcnt(0)
	v_add_f32_e32 v96, v96, v97
	ds_bpermute_b32 v97, v186, v96
	s_waitcnt lgkmcnt(0)
	v_add_f32_e32 v104, v96, v97
	v_fmamk_f32 v69, v104, 0xba000000, v69
	v_fmamk_f32 v65, v104, 0xba000000, v65
	v_fmamk_f32 v71, v104, 0xba000000, v71
	v_fmac_f32_e32 v68, 0xba000000, v104
	v_fmamk_f32 v67, v104, 0xba000000, v67
	v_fmac_f32_e32 v64, 0xba000000, v104
	v_mov_b32_e32 v98, v69
	v_mov_b32_e32 v99, v65
	v_fmamk_f32 v70, v104, 0xba000000, v70
	v_fmamk_f32 v66, v104, 0xba000000, v66
	v_mov_b32_e32 v96, v68
	v_mov_b32_e32 v97, v64
	v_pk_mul_f32 v[98:99], v[98:99], v[98:99]
	v_mov_b32_e32 v100, v71
	v_mov_b32_e32 v101, v67
	v_pk_fma_f32 v[96:97], v[96:97], v[96:97], v[98:99]
	v_mov_b32_e32 v98, v70
	v_mov_b32_e32 v99, v66
	v_pk_mul_f32 v[100:101], v[100:101], v[100:101]
	v_fmamk_f32 v75, v104, 0xba000000, v75
	v_pk_fma_f32 v[98:99], v[98:99], v[98:99], v[100:101]
	v_fmamk_f32 v74, v104, 0xba000000, v74
	v_pk_add_f32 v[96:97], v[96:97], v[98:99]
	v_fmamk_f32 v73, v104, 0xba000000, v73
	v_fmac_f32_e32 v72, 0xba000000, v104
	v_pk_add_f32 v[96:97], v[96:97], v[96:97] op_sel_hi:[0,1]
	v_pk_mul_f32 v[98:99], v[74:75], v[74:75]
	v_pk_mul_f32 v[100:101], v[72:73], v[72:73]
	v_fmac_f32_e32 v76, 0xba000000, v104
	v_pk_mov_b32 v[102:103], v[100:101], v[98:99] op_sel:[1,0]
	v_mov_b32_e32 v101, v99
	v_fmamk_f32 v78, v104, 0xba000000, v78
	v_fmamk_f32 v77, v104, 0xba000000, v77
	v_mul_f32_e32 v96, v76, v76
	v_pk_add_f32 v[98:99], v[102:103], v[100:101]
	v_fmamk_f32 v79, v104, 0xba000000, v79
	v_pk_fma_f32 v[100:101], v[76:77], v[76:77], v[96:97] op_sel_hi:[1,1,0]
	v_mul_f32_e32 v96, v78, v78
	v_pk_add_f32 v[98:99], v[98:99], v[98:99] op_sel_hi:[0,1]
	v_pk_fma_f32 v[102:103], v[78:79], v[78:79], v[96:97] op_sel_hi:[1,1,0]
	v_fmamk_f32 v83, v104, 0xba000000, v83
	v_fmamk_f32 v82, v104, 0xba000000, v82
	v_fmamk_f32 v81, v104, 0xba000000, v81
	v_fmac_f32_e32 v80, 0xba000000, v104
	v_mul_f32_e32 v100, v80, v80
	v_mul_f32_e32 v102, v81, v81
	v_mul_f32_e32 v98, v82, v82
	v_mul_f32_e32 v96, v83, v83
	v_pk_add_f32 v[100:101], v[100:101], v[102:103]
	v_pk_add_f32 v[96:97], v[98:99], v[96:97]
	v_fmamk_f32 v87, v104, 0xba000000, v87
	v_pk_add_f32 v[96:97], v[100:101], v[96:97]
	v_fmamk_f32 v86, v104, 0xba000000, v86
	v_fmamk_f32 v85, v104, 0xba000000, v85
	v_fmac_f32_e32 v84, 0xba000000, v104
	v_pk_add_f32 v[96:97], v[96:97], v[96:97] op_sel_hi:[0,1]
	v_pk_mul_f32 v[98:99], v[86:87], v[86:87]
	v_pk_mul_f32 v[100:101], v[84:85], v[84:85]
	v_fmac_f32_e32 v88, 0xba000000, v104
	v_pk_mov_b32 v[102:103], v[100:101], v[98:99] op_sel:[1,0]
	v_mov_b32_e32 v101, v99
	v_fmamk_f32 v90, v104, 0xba000000, v90
	v_fmamk_f32 v89, v104, 0xba000000, v89
	v_mul_f32_e32 v96, v88, v88
	v_pk_add_f32 v[98:99], v[102:103], v[100:101]
	v_fmamk_f32 v91, v104, 0xba000000, v91
	v_pk_fma_f32 v[100:101], v[88:89], v[88:89], v[96:97] op_sel_hi:[1,1,0]
	v_mul_f32_e32 v96, v90, v90
	v_pk_add_f32 v[98:99], v[98:99], v[98:99] op_sel_hi:[0,1]
	v_pk_fma_f32 v[102:103], v[90:91], v[90:91], v[96:97] op_sel_hi:[1,1,0]
	v_fmamk_f32 v95, v104, 0xba000000, v95
	v_fmamk_f32 v94, v104, 0xba000000, v94
	v_fmamk_f32 v93, v104, 0xba000000, v93
	v_fmac_f32_e32 v92, 0xba000000, v104
	v_mul_f32_e32 v100, v92, v92
	v_mul_f32_e32 v102, v93, v93
	v_mul_f32_e32 v98, v94, v94
	v_mul_f32_e32 v96, v95, v95
	v_pk_add_f32 v[100:101], v[100:101], v[102:103]
	v_pk_add_f32 v[96:97], v[98:99], v[96:97]
	s_nop 0
	v_pk_add_f32 v[96:97], v[100:101], v[96:97]
	s_nop 0
	v_add_f32_e32 v96, v96, v97
	ds_bpermute_b32 v97, v129, v96
	s_waitcnt lgkmcnt(0)
	v_add_f32_e32 v96, v96, v97
	ds_bpermute_b32 v97, v182, v96
	s_waitcnt lgkmcnt(0)
	v_add_f32_e32 v96, v96, v97
	ds_bpermute_b32 v97, v183, v96
	s_waitcnt lgkmcnt(0)
	v_add_f32_e32 v96, v96, v97
	ds_bpermute_b32 v97, v184, v96
	s_waitcnt lgkmcnt(0)
	v_add_f32_e32 v96, v96, v97
	ds_bpermute_b32 v97, v185, v96
	s_waitcnt lgkmcnt(0)
	v_add_f32_e32 v96, v96, v97
	ds_bpermute_b32 v97, v186, v96
	s_waitcnt lgkmcnt(0)
	v_add_f32_e32 v96, v96, v97
	v_fmamk_f32 v96, v96, 0x3a000000, v229
	v_mul_f32_e32 v97, 0x4f800000, v96
	v_cmp_gt_f32_e32 vcc, s4, v96
	s_nop 1
	v_cndmask_b32_e32 v96, v96, v97, vcc
	v_sqrt_f32_e32 v97, v96
	s_nop 0
	v_add_u32_e32 v98, -1, v97
	v_fma_f32 v99, -v98, v97, v96
	v_cmp_ge_f32_e64 s[8:9], 0, v99
	v_add_u32_e32 v99, 1, v97
	s_nop 0
	v_cndmask_b32_e64 v98, v97, v98, s[8:9]
	v_fma_f32 v97, -v99, v97, v96
	v_cmp_lt_f32_e64 s[8:9], 0, v97
	s_nop 1
	v_cndmask_b32_e64 v97, v98, v99, s[8:9]
	v_mul_f32_e32 v98, 0x37800000, v97
	v_cndmask_b32_e32 v97, v97, v98, vcc
	v_cmp_class_f32_e32 vcc, v96, v230
	s_nop 1
	v_cndmask_b32_e32 v96, v97, v96, vcc
	v_div_scale_f32 v97, s[8:9], v96, v96, 1.0
	v_rcp_f32_e32 v98, v97
	s_lshl_b64 s[8:9], s[16:17], 13
	s_add_u32 s18, s14, s8
	s_addc_u32 s19, s15, s9
	v_fma_f32 v99, -v97, v98, 1.0
	v_fmac_f32_e32 v98, v99, v98
	v_div_scale_f32 v99, vcc, 1.0, v96, 1.0
	v_mul_f32_e32 v100, v99, v98
	v_fma_f32 v101, -v97, v100, v99
	v_fmac_f32_e32 v100, v101, v98
	v_fma_f32 v97, -v97, v100, v99
	v_div_fmas_f32 v97, v97, v98, v100
	v_div_fixup_f32 v96, v97, v96, 1.0
	s_lshl_b64 s[8:9], s[16:17], 12
	s_add_u32 s8, s12, s8
	v_pk_mul_f32 v[68:69], v[68:69], v[96:97] op_sel_hi:[1,0]
	v_pk_mul_f32 v[70:71], v[70:71], v[96:97] op_sel_hi:[1,0]
	s_addc_u32 s9, s13, s9
	v_pk_fma_f32 v[70:71], v[2:3], v[70:71], v[10:11]
	v_pk_fma_f32 v[68:69], v[0:1], v[68:69], v[8:9]
	s_and_b64 vcc, exec, s[0:1]
	v_lshlrev_b32_e32 v99, 2, v128
	s_cbranch_vccz .LBB0_1265
	global_store_dwordx4 v99, v[68:71], s[18:19] sc1
	s_mov_b64 s[20:21], 0

.LBB0_1267:
	v_mov_b32_e32 v97, v96
	v_mov_b32_e32 v100, v96
	v_mov_b32_e32 v101, v96
	v_pk_mul_f32 v[66:67], v[66:67], v[100:101]
	v_pk_mul_f32 v[64:65], v[64:65], v[96:97]
	v_pk_fma_f32 v[66:67], v[6:7], v[66:67], v[14:15]
	v_pk_fma_f32 v[64:65], v[4:5], v[64:65], v[12:13]
	s_mov_b64 s[20:21], -1
	s_and_b64 vcc, exec, s[0:1]
	s_cbranch_vccz .LBB0_1269
	global_store_dwordx4 v99, v[64:67], s[18:19] offset:1024 sc1
	s_mov_b64 s[20:21], 0

.LBB0_1271:
	v_mov_b32_e32 v100, v96
	v_mov_b32_e32 v101, v96
	v_pk_mul_f32 v[74:75], v[74:75], v[100:101]
	v_pk_mul_f32 v[72:73], v[72:73], v[96:97]
	v_pk_fma_f32 v[74:75], v[18:19], v[74:75], v[26:27]
	v_pk_fma_f32 v[72:73], v[16:17], v[72:73], v[24:25]
	s_mov_b64 s[20:21], -1
	s_and_b64 vcc, exec, s[0:1]
	s_cbranch_vccz .LBB0_1273
	global_store_dwordx4 v99, v[72:75], s[18:19] offset:2048 sc1
	s_mov_b64 s[20:21], 0

.LBB0_1275:
	v_mov_b32_e32 v100, v96
	v_mov_b32_e32 v101, v96
	v_pk_mul_f32 v[78:79], v[78:79], v[100:101]
	v_pk_mul_f32 v[76:77], v[76:77], v[96:97]
	v_pk_fma_f32 v[78:79], v[22:23], v[78:79], v[30:31]
	v_pk_fma_f32 v[76:77], v[20:21], v[76:77], v[28:29]
	s_mov_b64 s[20:21], -1
	s_and_b64 vcc, exec, s[0:1]
	s_cbranch_vccz .LBB0_1277
	global_store_dwordx4 v99, v[76:79], s[18:19] offset:3072 sc1
	s_mov_b64 s[20:21], 0

.LBB0_1279:
	v_mov_b32_e32 v100, v96
	v_mov_b32_e32 v101, v96
	v_pk_mul_f32 v[82:83], v[82:83], v[100:101]
	v_pk_mul_f32 v[80:81], v[80:81], v[96:97]
	v_pk_fma_f32 v[82:83], v[34:35], v[82:83], v[42:43]
	v_pk_fma_f32 v[80:81], v[32:33], v[80:81], v[40:41]
	s_mov_b64 s[20:21], -1
	s_and_b64 vcc, exec, s[0:1]
	s_cbranch_vccz .LBB0_1281
	global_store_dwordx4 v144, v[80:83], s[18:19] sc1
	s_mov_b64 s[20:21], 0

.LBB0_1283:
	v_mov_b32_e32 v100, v96
	v_mov_b32_e32 v101, v96
	v_pk_mul_f32 v[86:87], v[86:87], v[100:101]
	v_pk_mul_f32 v[84:85], v[84:85], v[96:97]
	v_pk_fma_f32 v[86:87], v[38:39], v[86:87], v[46:47]
	v_pk_fma_f32 v[84:85], v[36:37], v[84:85], v[44:45]
	s_mov_b64 s[20:21], -1
	s_and_b64 vcc, exec, s[0:1]
	s_cbranch_vccz .LBB0_1285
	global_store_dwordx4 v188, v[84:87], s[18:19] sc1
	s_mov_b64 s[20:21], 0

.LBB0_1287:
	v_mov_b32_e32 v100, v96
	v_mov_b32_e32 v101, v96
	v_pk_mul_f32 v[90:91], v[90:91], v[100:101]
	v_pk_mul_f32 v[88:89], v[88:89], v[96:97]
	v_pk_fma_f32 v[90:91], v[50:51], v[90:91], v[58:59]
	v_pk_fma_f32 v[88:89], v[48:49], v[88:89], v[56:57]
	s_mov_b64 s[20:21], -1
	s_and_b64 vcc, exec, s[0:1]
	s_cbranch_vccz .LBB0_1289
	global_store_dwordx4 v189, v[88:91], s[18:19] sc1
	s_mov_b64 s[20:21], 0

.LBB0_1291:
	v_mov_b32_e32 v100, v96
	v_mov_b32_e32 v101, v96
	v_pk_mul_f32 v[94:95], v[94:95], v[100:101]
	v_pk_mul_f32 v[92:93], v[92:93], v[96:97]
	v_pk_fma_f32 v[94:95], v[54:55], v[94:95], v[62:63]
	v_pk_fma_f32 v[92:93], v[52:53], v[92:93], v[60:61]
	s_mov_b64 s[20:21], -1
	s_and_b64 vcc, exec, s[0:1]
	s_cbranch_vccz .LBB0_1293
	global_store_dwordx4 v190, v[92:95], s[18:19] sc1
	s_mov_b64 s[20:21], 0
